# x-update: sample-row partial loads in one 8-partial batch (XB row kept outside the buffers)
# speedup vs baseline: 1.0089x; 1.0089x over previous
.LBB0_446:
	s_waitcnt lgkmcnt(0)
	v_cndmask_b32_e64 v0, 0, 1, s[24:25]
	v_cmp_ne_u32_e64 s[0:1], 1, v0
	s_andn2_b64 vcc, exec, s[24:25]
	s_nop 0
	v_writelane_b32 v235, s0, 52
	s_barrier
	s_nop 0
	v_writelane_b32 v235, s1, 53
	v_mbcnt_lo_u32_b32 v0, -1, 0
	v_mbcnt_hi_u32_b32 v0, -1, v0
	s_cbranch_vccnz .LBB0_465
	v_lshlrev_b32_e32 v2, 3, v0
	v_ashrrev_i32_e32 v3, 31, v2
	v_readlane_b32 s4, v235, 4
	v_lshlrev_b64 v[4:5], 1, v[2:3]
	v_lshlrev_b64 v[2:3], 2, v[2:3]
	v_readlane_b32 s5, v235, 5
	v_readlane_b32 s6, v235, 6
	v_readlane_b32 s7, v235, 7
	v_readlane_b32 s8, v235, 8
	v_readlane_b32 s9, v235, 9
	v_readlane_b32 s10, v235, 10
	v_readlane_b32 s11, v235, 11
	v_readlane_b32 s12, v235, 12
	v_readlane_b32 s13, v235, 13
	v_readlane_b32 s14, v235, 14
	v_readlane_b32 s15, v235, 15
	v_readlane_b32 s16, v235, 16
	v_readlane_b32 s17, v235, 17
	v_readlane_b32 s18, v235, 18
	v_readlane_b32 s19, v235, 19
	v_lshl_add_u64 v[60:61], s[86:87], 0, v[4:5]
	v_lshl_add_u64 v[62:63], s[90:91], 0, v[2:3]
	v_lshl_add_u64 v[64:65], s[54:55], 0, v[4:5]
	v_lshl_add_u64 v[66:67], s[14:15], 0, v[2:3]
	s_mov_b32 s1, 0
	v_cmp_eq_u32_e64 s[4:5], 0, v0
	s_mov_b64 s[6:7], 0x200000
	s_mov_b64 s[8:9], 0x200800
	s_mov_b64 s[10:11], 0x400000
	s_mov_b64 s[12:13], 0x400800
	s_mov_b64 s[14:15], 0x600000
	s_mov_b64 s[16:17], 0x600800
	s_mov_b64 s[18:19], 0x800000
	s_mov_b32 s48, 0x800000
	s_mov_b64 s[20:21], 0x800800
	s_mov_b64 s[22:23], 0xa00000
	s_mov_b64 s[24:25], 0xa00800
	s_mov_b64 s[26:27], 0xc00000
	s_mov_b64 s[28:29], 0xc00800
	s_mov_b64 s[34:35], 0xe00000
	s_mov_b64 s[36:37], 0xe00800
	v_mov_b32_e32 v104, 0
	v_mov_b32_e32 v105, 0x358637bd
	s_mov_b32 s40, s80
	v_mbcnt_lo_u32_b32 v176, -1, 0
	v_mbcnt_hi_u32_b32 v176, -1, v176
	v_readlane_b32 s98, v235, 49
	v_readlane_b32 s99, v235, 20
	v_readlane_b32 s100, v235, 14
	v_readlane_b32 s101, v235, 15
	s_nop 3
	s_lshr_b32 vcc_lo, s98, 3
	s_and_b32 vcc_hi, vcc_lo, 7
	s_lshr_b32 vcc_lo, vcc_lo, 3
	s_lshl_b32 vcc_lo, vcc_lo, 3
	s_add_i32 vcc_lo, vcc_lo, s99
	s_lshl_b32 s98, vcc_hi, 8
	s_add_i32 s98, s98, vcc_lo
	s_mov_b32 s99, s98
	v_mov_b32_e32 v183, s99
	v_lshlrev_b32_e32 v177, 4, v176
	s_lshl_b32 s99, s99, 11
	v_add_u32_e32 v177, s99, v177
	v_add_u32_e32 v178, 0x1800000, v177
	v_add_u32_e32 v179, 0x9e00000, v177
	v_lshlrev_b32_e32 v180, 5, v176
	global_load_dwordx4 v[128:131], v180, s[100:101]
	global_load_dwordx4 v[132:135], v180, s[100:101] offset:16
	global_load_dwordx4 v[136:139], v180, s[100:101] offset:2048
	global_load_dwordx4 v[140:143], v180, s[100:101] offset:2064
	v_mov_b32_e32 v182, 0x358637bd
	global_load_dwordx4 v[0:3], v178, s[78:79]
	global_load_dwordx4 v[4:7], v178, s[78:79] offset:1024
	global_load_dwordx4 v[8:11], v179, s[78:79]
	global_load_dwordx4 v[12:15], v179, s[78:79] offset:1024
	v_add_u32_e32 v178, 0x400000, v178
	v_add_u32_e32 v179, 0x400000, v179
	global_load_dwordx4 v[16:19], v178, s[78:79]
	global_load_dwordx4 v[20:23], v178, s[78:79] offset:1024
	global_load_dwordx4 v[24:27], v179, s[78:79]
	global_load_dwordx4 v[28:31], v179, s[78:79] offset:1024
	v_add_u32_e32 v178, 0x400000, v178
	v_add_u32_e32 v179, 0x400000, v179
	global_load_dwordx4 v[32:35], v178, s[78:79]
	global_load_dwordx4 v[36:39], v178, s[78:79] offset:1024
	global_load_dwordx4 v[40:43], v179, s[78:79]
	global_load_dwordx4 v[44:47], v179, s[78:79] offset:1024
	v_add_u32_e32 v178, 0x400000, v178
	v_add_u32_e32 v179, 0x400000, v179
	global_load_dwordx4 v[48:51], v178, s[78:79]
	global_load_dwordx4 v[52:55], v178, s[78:79] offset:1024
	global_load_dwordx4 v[56:59], v179, s[78:79]
	global_load_dwordx4 v[60:63], v179, s[78:79] offset:1024
	v_add_u32_e32 v178, 0x400000, v178
	v_add_u32_e32 v179, 0x400000, v179
	global_load_dwordx4 v[64:67], v178, s[78:79]
	global_load_dwordx4 v[68:71], v178, s[78:79] offset:1024
	global_load_dwordx4 v[72:75], v179, s[78:79]
	global_load_dwordx4 v[76:79], v179, s[78:79] offset:1024
	v_add_u32_e32 v178, 0x400000, v178
	v_add_u32_e32 v179, 0x400000, v179
	global_load_dwordx4 v[80:83], v178, s[78:79]
	global_load_dwordx4 v[84:87], v178, s[78:79] offset:1024
	global_load_dwordx4 v[88:91], v179, s[78:79]
	global_load_dwordx4 v[92:95], v179, s[78:79] offset:1024
	v_add_u32_e32 v178, 0x400000, v178
	v_add_u32_e32 v179, 0x400000, v179
	global_load_dwordx4 v[96:99], v178, s[78:79]
	global_load_dwordx4 v[100:103], v178, s[78:79] offset:1024
	global_load_dwordx4 v[104:107], v179, s[78:79]
	global_load_dwordx4 v[108:111], v179, s[78:79] offset:1024
	v_add_u32_e32 v178, 0x400000, v178
	v_add_u32_e32 v179, 0x400000, v179
	global_load_dwordx4 v[112:115], v178, s[78:79]
	global_load_dwordx4 v[116:119], v178, s[78:79] offset:1024
	global_load_dwordx4 v[120:123], v179, s[78:79]
	global_load_dwordx4 v[124:127], v179, s[78:79] offset:1024
	v_lshlrev_b32_e32 v237, 2, v183
	v_add_u32_e32 v237, 0x10000, v237
	v_mov_b32_e32 v179, s98
	s_waitcnt vmcnt(28)
	v_lshlrev_b32_e32 v144, 16, v0
	v_and_b32_e32 v145, 0xffff0000, v0
	v_lshlrev_b32_e32 v146, 16, v1
	v_and_b32_e32 v147, 0xffff0000, v1
	v_lshlrev_b32_e32 v148, 16, v2
	v_and_b32_e32 v149, 0xffff0000, v2
	v_lshlrev_b32_e32 v150, 16, v3
	v_and_b32_e32 v151, 0xffff0000, v3
	v_lshlrev_b32_e32 v152, 16, v4
	v_and_b32_e32 v153, 0xffff0000, v4
	v_lshlrev_b32_e32 v154, 16, v5
	v_and_b32_e32 v155, 0xffff0000, v5
	v_lshlrev_b32_e32 v156, 16, v6
	v_and_b32_e32 v157, 0xffff0000, v6
	v_lshlrev_b32_e32 v158, 16, v7
	v_and_b32_e32 v159, 0xffff0000, v7
	v_lshlrev_b32_e32 v160, 16, v8
	v_and_b32_e32 v161, 0xffff0000, v8
	v_lshlrev_b32_e32 v162, 16, v9
	v_and_b32_e32 v163, 0xffff0000, v9
	v_lshlrev_b32_e32 v164, 16, v10
	v_and_b32_e32 v165, 0xffff0000, v10
	v_lshlrev_b32_e32 v166, 16, v11
	v_and_b32_e32 v167, 0xffff0000, v11
	v_lshlrev_b32_e32 v168, 16, v12
	v_and_b32_e32 v169, 0xffff0000, v12
	v_lshlrev_b32_e32 v170, 16, v13
	v_and_b32_e32 v171, 0xffff0000, v13
	v_lshlrev_b32_e32 v172, 16, v14
	v_and_b32_e32 v173, 0xffff0000, v14
	v_lshlrev_b32_e32 v174, 16, v15
	v_and_b32_e32 v175, 0xffff0000, v15
	v_pk_mul_f32 v[252:253], v[160:161], v[160:161]
	v_pk_mul_f32 v[254:255], v[162:163], v[162:163]
	v_pk_fma_f32 v[252:253], v[164:165], v[164:165], v[252:253]
	v_pk_fma_f32 v[254:255], v[166:167], v[166:167], v[254:255]
	v_pk_fma_f32 v[252:253], v[168:169], v[168:169], v[252:253]
	v_pk_fma_f32 v[254:255], v[170:171], v[170:171], v[254:255]
	v_pk_fma_f32 v[252:253], v[172:173], v[172:173], v[252:253]
	v_pk_fma_f32 v[254:255], v[174:175], v[174:175], v[254:255]
	v_pk_add_f32 v[252:253], v[252:253], v[254:255]
	s_nop 0
	v_add_f32_e32 v183, v252, v253
	s_nop 1
	v_add_f32_dpp v183, v183, v183 quad_perm:[1,0,3,2] row_mask:0xf bank_mask:0xf bound_ctrl:1
	s_nop 1
	v_add_f32_dpp v183, v183, v183 quad_perm:[2,3,0,1] row_mask:0xf bank_mask:0xf bound_ctrl:1
	s_nop 1
	v_add_f32_dpp v183, v183, v183 row_half_mirror row_mask:0xf bank_mask:0xf bound_ctrl:1
	s_nop 1
	v_add_f32_dpp v183, v183, v183 row_mirror row_mask:0xf bank_mask:0xf bound_ctrl:1
	s_nop 1
	v_readlane_b32 s98, v183, 0
	v_readlane_b32 s99, v183, 16
	v_readlane_b32 s100, v183, 32
	v_readlane_b32 s101, v183, 48
	s_nop 1
	v_mov_b32_e32 v183, s98
	v_add_f32_e32 v183, s99, v183
	v_add_f32_e32 v183, s100, v183
	v_add_f32_e32 v183, s101, v183
	v_fmamk_f32 v183, v183, 0x3a800000, v182
	v_cmp_gt_f32_e32 vcc, 0x800000, v183
	v_mul_f32_e32 v181, 0x4b800000, v183
	s_nop 1
	v_cndmask_b32_e32 v183, v183, v181, vcc
	v_rsq_f32_e32 v183, v183
	s_nop 0
	v_mul_f32_e32 v181, 0x45800000, v183
	v_cndmask_b32_e32 v184, v183, v181, vcc
	v_mov_b32_e32 v185, v184
	v_pk_mul_f32 v[160:161], v[160:161], v[184:185]
	v_pk_mul_f32 v[162:163], v[162:163], v[184:185]
	v_pk_mul_f32 v[164:165], v[164:165], v[184:185]
	v_pk_mul_f32 v[166:167], v[166:167], v[184:185]
	v_pk_mul_f32 v[168:169], v[168:169], v[184:185]
	v_pk_mul_f32 v[170:171], v[170:171], v[184:185]
	v_pk_mul_f32 v[172:173], v[172:173], v[184:185]
	v_pk_mul_f32 v[174:175], v[174:175], v[184:185]
	v_pk_fma_f32 v[144:145], v[160:161], v[128:129], v[144:145]
	v_pk_fma_f32 v[146:147], v[162:163], v[130:131], v[146:147]
	v_pk_fma_f32 v[148:149], v[164:165], v[132:133], v[148:149]
	v_pk_fma_f32 v[150:151], v[166:167], v[134:135], v[150:151]
	v_pk_fma_f32 v[152:153], v[168:169], v[136:137], v[152:153]
	v_pk_fma_f32 v[154:155], v[170:171], v[138:139], v[154:155]
	v_pk_fma_f32 v[156:157], v[172:173], v[140:141], v[156:157]
	v_pk_fma_f32 v[158:159], v[174:175], v[142:143], v[158:159]
	v_pk_mul_f32 v[252:253], v[144:145], v[144:145]
	v_pk_mul_f32 v[254:255], v[146:147], v[146:147]
	v_pk_fma_f32 v[252:253], v[148:149], v[148:149], v[252:253]
	v_pk_fma_f32 v[254:255], v[150:151], v[150:151], v[254:255]
	v_pk_fma_f32 v[252:253], v[152:153], v[152:153], v[252:253]
	v_pk_fma_f32 v[254:255], v[154:155], v[154:155], v[254:255]
	v_pk_fma_f32 v[252:253], v[156:157], v[156:157], v[252:253]
	v_pk_fma_f32 v[254:255], v[158:159], v[158:159], v[254:255]
	v_pk_add_f32 v[252:253], v[252:253], v[254:255]
	s_nop 0
	v_add_f32_e32 v183, v252, v253
	s_nop 1
	v_add_f32_dpp v183, v183, v183 quad_perm:[1,0,3,2] row_mask:0xf bank_mask:0xf bound_ctrl:1
	s_nop 1
	v_add_f32_dpp v183, v183, v183 quad_perm:[2,3,0,1] row_mask:0xf bank_mask:0xf bound_ctrl:1
	s_nop 1
	v_add_f32_dpp v183, v183, v183 row_half_mirror row_mask:0xf bank_mask:0xf bound_ctrl:1
	s_nop 1
	v_add_f32_dpp v183, v183, v183 row_mirror row_mask:0xf bank_mask:0xf bound_ctrl:1
	s_nop 1
	v_readlane_b32 s98, v183, 0
	v_readlane_b32 s99, v183, 16
	v_readlane_b32 s100, v183, 32
	v_readlane_b32 s101, v183, 48
	s_nop 1
	v_mov_b32_e32 v183, s98
	v_add_f32_e32 v183, s99, v183
	v_add_f32_e32 v183, s100, v183
	v_add_f32_e32 v183, s101, v183
	v_fmamk_f32 v183, v183, 0x3a800000, v182
	v_cmp_gt_f32_e32 vcc, 0x800000, v183
	v_mul_f32_e32 v181, 0x4b800000, v183
	s_nop 1
	v_cndmask_b32_e32 v183, v183, v181, vcc
	v_rsq_f32_e32 v183, v183
	s_nop 0
	v_mul_f32_e32 v181, 0x45800000, v183
	v_cndmask_b32_e32 v184, v183, v181, vcc
	v_mov_b32_e32 v185, v184
	v_cvt_pk_bf16_f32 v0, v144, v145
	v_cvt_pk_bf16_f32 v1, v146, v147
	v_cvt_pk_bf16_f32 v2, v148, v149
	v_cvt_pk_bf16_f32 v3, v150, v151
	v_cvt_pk_bf16_f32 v4, v152, v153
	v_cvt_pk_bf16_f32 v5, v154, v155
	v_cvt_pk_bf16_f32 v6, v156, v157
	v_cvt_pk_bf16_f32 v7, v158, v159
	v_add_u32_e32 v181, 0x1800000, v177
	global_store_dwordx4 v181, v[0:3], s[78:79]
	global_store_dwordx4 v181, v[4:7], s[78:79] offset:1024
	v_add_u32_e32 v236, 0x0, v237
	s_mov_b64 exec, 1
	global_store_dword v236, v184, s[78:79]
	s_mov_b64 exec, -1
	s_waitcnt vmcnt(24)
	v_lshlrev_b32_e32 v144, 16, v16
	v_and_b32_e32 v145, 0xffff0000, v16
	v_lshlrev_b32_e32 v146, 16, v17
	v_and_b32_e32 v147, 0xffff0000, v17
	v_lshlrev_b32_e32 v148, 16, v18
	v_and_b32_e32 v149, 0xffff0000, v18
	v_lshlrev_b32_e32 v150, 16, v19
	v_and_b32_e32 v151, 0xffff0000, v19
	v_lshlrev_b32_e32 v152, 16, v20
	v_and_b32_e32 v153, 0xffff0000, v20
	v_lshlrev_b32_e32 v154, 16, v21
	v_and_b32_e32 v155, 0xffff0000, v21
	v_lshlrev_b32_e32 v156, 16, v22
	v_and_b32_e32 v157, 0xffff0000, v22
	v_lshlrev_b32_e32 v158, 16, v23
	v_and_b32_e32 v159, 0xffff0000, v23
	v_lshlrev_b32_e32 v160, 16, v24
	v_and_b32_e32 v161, 0xffff0000, v24
	v_lshlrev_b32_e32 v162, 16, v25
	v_and_b32_e32 v163, 0xffff0000, v25
	v_lshlrev_b32_e32 v164, 16, v26
	v_and_b32_e32 v165, 0xffff0000, v26
	v_lshlrev_b32_e32 v166, 16, v27
	v_and_b32_e32 v167, 0xffff0000, v27
	v_lshlrev_b32_e32 v168, 16, v28
	v_and_b32_e32 v169, 0xffff0000, v28
	v_lshlrev_b32_e32 v170, 16, v29
	v_and_b32_e32 v171, 0xffff0000, v29
	v_lshlrev_b32_e32 v172, 16, v30
	v_and_b32_e32 v173, 0xffff0000, v30
	v_lshlrev_b32_e32 v174, 16, v31
	v_and_b32_e32 v175, 0xffff0000, v31
	v_pk_mul_f32 v[252:253], v[160:161], v[160:161]
	v_pk_mul_f32 v[254:255], v[162:163], v[162:163]
	v_pk_fma_f32 v[252:253], v[164:165], v[164:165], v[252:253]
	v_pk_fma_f32 v[254:255], v[166:167], v[166:167], v[254:255]
	v_pk_fma_f32 v[252:253], v[168:169], v[168:169], v[252:253]
	v_pk_fma_f32 v[254:255], v[170:171], v[170:171], v[254:255]
	v_pk_fma_f32 v[252:253], v[172:173], v[172:173], v[252:253]
	v_pk_fma_f32 v[254:255], v[174:175], v[174:175], v[254:255]
	v_pk_add_f32 v[252:253], v[252:253], v[254:255]
	s_nop 0
	v_add_f32_e32 v183, v252, v253
	s_nop 1
	v_add_f32_dpp v183, v183, v183 quad_perm:[1,0,3,2] row_mask:0xf bank_mask:0xf bound_ctrl:1
	s_nop 1
	v_add_f32_dpp v183, v183, v183 quad_perm:[2,3,0,1] row_mask:0xf bank_mask:0xf bound_ctrl:1
	s_nop 1
	v_add_f32_dpp v183, v183, v183 row_half_mirror row_mask:0xf bank_mask:0xf bound_ctrl:1
	s_nop 1
	v_add_f32_dpp v183, v183, v183 row_mirror row_mask:0xf bank_mask:0xf bound_ctrl:1
	s_nop 1
	v_readlane_b32 s98, v183, 0
	v_readlane_b32 s99, v183, 16
	v_readlane_b32 s100, v183, 32
	v_readlane_b32 s101, v183, 48
	s_nop 1
	v_mov_b32_e32 v183, s98
	v_add_f32_e32 v183, s99, v183
	v_add_f32_e32 v183, s100, v183
	v_add_f32_e32 v183, s101, v183
	v_fmamk_f32 v183, v183, 0x3a800000, v182
	v_cmp_gt_f32_e32 vcc, 0x800000, v183
	v_mul_f32_e32 v181, 0x4b800000, v183
	s_nop 1
	v_cndmask_b32_e32 v183, v183, v181, vcc
	v_rsq_f32_e32 v183, v183
	s_nop 0
	v_mul_f32_e32 v181, 0x45800000, v183
	v_cndmask_b32_e32 v184, v183, v181, vcc
	v_mov_b32_e32 v185, v184
	v_pk_mul_f32 v[160:161], v[160:161], v[184:185]
	v_pk_mul_f32 v[162:163], v[162:163], v[184:185]
	v_pk_mul_f32 v[164:165], v[164:165], v[184:185]
	v_pk_mul_f32 v[166:167], v[166:167], v[184:185]
	v_pk_mul_f32 v[168:169], v[168:169], v[184:185]
	v_pk_mul_f32 v[170:171], v[170:171], v[184:185]
	v_pk_mul_f32 v[172:173], v[172:173], v[184:185]
	v_pk_mul_f32 v[174:175], v[174:175], v[184:185]
	v_pk_fma_f32 v[144:145], v[160:161], v[128:129], v[144:145]
	v_pk_fma_f32 v[146:147], v[162:163], v[130:131], v[146:147]
	v_pk_fma_f32 v[148:149], v[164:165], v[132:133], v[148:149]
	v_pk_fma_f32 v[150:151], v[166:167], v[134:135], v[150:151]
	v_pk_fma_f32 v[152:153], v[168:169], v[136:137], v[152:153]
	v_pk_fma_f32 v[154:155], v[170:171], v[138:139], v[154:155]
	v_pk_fma_f32 v[156:157], v[172:173], v[140:141], v[156:157]
	v_pk_fma_f32 v[158:159], v[174:175], v[142:143], v[158:159]
	v_pk_mul_f32 v[252:253], v[144:145], v[144:145]
	v_pk_mul_f32 v[254:255], v[146:147], v[146:147]
	v_pk_fma_f32 v[252:253], v[148:149], v[148:149], v[252:253]
	v_pk_fma_f32 v[254:255], v[150:151], v[150:151], v[254:255]
	v_pk_fma_f32 v[252:253], v[152:153], v[152:153], v[252:253]
	v_pk_fma_f32 v[254:255], v[154:155], v[154:155], v[254:255]
	v_pk_fma_f32 v[252:253], v[156:157], v[156:157], v[252:253]
	v_pk_fma_f32 v[254:255], v[158:159], v[158:159], v[254:255]
	v_pk_add_f32 v[252:253], v[252:253], v[254:255]
	s_nop 0
	v_add_f32_e32 v183, v252, v253
	s_nop 1
	v_add_f32_dpp v183, v183, v183 quad_perm:[1,0,3,2] row_mask:0xf bank_mask:0xf bound_ctrl:1
	s_nop 1
	v_add_f32_dpp v183, v183, v183 quad_perm:[2,3,0,1] row_mask:0xf bank_mask:0xf bound_ctrl:1
	s_nop 1
	v_add_f32_dpp v183, v183, v183 row_half_mirror row_mask:0xf bank_mask:0xf bound_ctrl:1
	s_nop 1
	v_add_f32_dpp v183, v183, v183 row_mirror row_mask:0xf bank_mask:0xf bound_ctrl:1
	s_nop 1
	v_readlane_b32 s98, v183, 0
	v_readlane_b32 s99, v183, 16
	v_readlane_b32 s100, v183, 32
	v_readlane_b32 s101, v183, 48
	s_nop 1
	v_mov_b32_e32 v183, s98
	v_add_f32_e32 v183, s99, v183
	v_add_f32_e32 v183, s100, v183
	v_add_f32_e32 v183, s101, v183
	v_fmamk_f32 v183, v183, 0x3a800000, v182
	v_cmp_gt_f32_e32 vcc, 0x800000, v183
	v_mul_f32_e32 v181, 0x4b800000, v183
	s_nop 1
	v_cndmask_b32_e32 v183, v183, v181, vcc
	v_rsq_f32_e32 v183, v183
	s_nop 0
	v_mul_f32_e32 v181, 0x45800000, v183
	v_cndmask_b32_e32 v184, v183, v181, vcc
	v_mov_b32_e32 v185, v184
	v_cvt_pk_bf16_f32 v16, v144, v145
	v_cvt_pk_bf16_f32 v17, v146, v147
	v_cvt_pk_bf16_f32 v18, v148, v149
	v_cvt_pk_bf16_f32 v19, v150, v151
	v_cvt_pk_bf16_f32 v20, v152, v153
	v_cvt_pk_bf16_f32 v21, v154, v155
	v_cvt_pk_bf16_f32 v22, v156, v157
	v_cvt_pk_bf16_f32 v23, v158, v159
	v_add_u32_e32 v181, 0x1c00000, v177
	global_store_dwordx4 v181, v[16:19], s[78:79]
	global_store_dwordx4 v181, v[20:23], s[78:79] offset:1024
	v_add_u32_e32 v236, 0x2000, v237
	s_mov_b64 exec, 1
	global_store_dword v236, v184, s[78:79]
	s_mov_b64 exec, -1
	s_waitcnt vmcnt(20)
	v_lshlrev_b32_e32 v144, 16, v32
	v_and_b32_e32 v145, 0xffff0000, v32
	v_lshlrev_b32_e32 v146, 16, v33
	v_and_b32_e32 v147, 0xffff0000, v33
	v_lshlrev_b32_e32 v148, 16, v34
	v_and_b32_e32 v149, 0xffff0000, v34
	v_lshlrev_b32_e32 v150, 16, v35
	v_and_b32_e32 v151, 0xffff0000, v35
	v_lshlrev_b32_e32 v152, 16, v36
	v_and_b32_e32 v153, 0xffff0000, v36
	v_lshlrev_b32_e32 v154, 16, v37
	v_and_b32_e32 v155, 0xffff0000, v37
	v_lshlrev_b32_e32 v156, 16, v38
	v_and_b32_e32 v157, 0xffff0000, v38
	v_lshlrev_b32_e32 v158, 16, v39
	v_and_b32_e32 v159, 0xffff0000, v39
	v_lshlrev_b32_e32 v160, 16, v40
	v_and_b32_e32 v161, 0xffff0000, v40
	v_lshlrev_b32_e32 v162, 16, v41
	v_and_b32_e32 v163, 0xffff0000, v41
	v_lshlrev_b32_e32 v164, 16, v42
	v_and_b32_e32 v165, 0xffff0000, v42
	v_lshlrev_b32_e32 v166, 16, v43
	v_and_b32_e32 v167, 0xffff0000, v43
	v_lshlrev_b32_e32 v168, 16, v44
	v_and_b32_e32 v169, 0xffff0000, v44
	v_lshlrev_b32_e32 v170, 16, v45
	v_and_b32_e32 v171, 0xffff0000, v45
	v_lshlrev_b32_e32 v172, 16, v46
	v_and_b32_e32 v173, 0xffff0000, v46
	v_lshlrev_b32_e32 v174, 16, v47
	v_and_b32_e32 v175, 0xffff0000, v47
	v_pk_mul_f32 v[252:253], v[160:161], v[160:161]
	v_pk_mul_f32 v[254:255], v[162:163], v[162:163]
	v_pk_fma_f32 v[252:253], v[164:165], v[164:165], v[252:253]
	v_pk_fma_f32 v[254:255], v[166:167], v[166:167], v[254:255]
	v_pk_fma_f32 v[252:253], v[168:169], v[168:169], v[252:253]
	v_pk_fma_f32 v[254:255], v[170:171], v[170:171], v[254:255]
	v_pk_fma_f32 v[252:253], v[172:173], v[172:173], v[252:253]
	v_pk_fma_f32 v[254:255], v[174:175], v[174:175], v[254:255]
	v_pk_add_f32 v[252:253], v[252:253], v[254:255]
	s_nop 0
	v_add_f32_e32 v183, v252, v253
	s_nop 1
	v_add_f32_dpp v183, v183, v183 quad_perm:[1,0,3,2] row_mask:0xf bank_mask:0xf bound_ctrl:1
	s_nop 1
	v_add_f32_dpp v183, v183, v183 quad_perm:[2,3,0,1] row_mask:0xf bank_mask:0xf bound_ctrl:1
	s_nop 1
	v_add_f32_dpp v183, v183, v183 row_half_mirror row_mask:0xf bank_mask:0xf bound_ctrl:1
	s_nop 1
	v_add_f32_dpp v183, v183, v183 row_mirror row_mask:0xf bank_mask:0xf bound_ctrl:1
	s_nop 1
	v_readlane_b32 s98, v183, 0
	v_readlane_b32 s99, v183, 16
	v_readlane_b32 s100, v183, 32
	v_readlane_b32 s101, v183, 48
	s_nop 1
	v_mov_b32_e32 v183, s98
	v_add_f32_e32 v183, s99, v183
	v_add_f32_e32 v183, s100, v183
	v_add_f32_e32 v183, s101, v183
	v_fmamk_f32 v183, v183, 0x3a800000, v182
	v_cmp_gt_f32_e32 vcc, 0x800000, v183
	v_mul_f32_e32 v181, 0x4b800000, v183
	s_nop 1
	v_cndmask_b32_e32 v183, v183, v181, vcc
	v_rsq_f32_e32 v183, v183
	s_nop 0
	v_mul_f32_e32 v181, 0x45800000, v183
	v_cndmask_b32_e32 v184, v183, v181, vcc
	v_mov_b32_e32 v185, v184
	v_pk_mul_f32 v[160:161], v[160:161], v[184:185]
	v_pk_mul_f32 v[162:163], v[162:163], v[184:185]
	v_pk_mul_f32 v[164:165], v[164:165], v[184:185]
	v_pk_mul_f32 v[166:167], v[166:167], v[184:185]
	v_pk_mul_f32 v[168:169], v[168:169], v[184:185]
	v_pk_mul_f32 v[170:171], v[170:171], v[184:185]
	v_pk_mul_f32 v[172:173], v[172:173], v[184:185]
	v_pk_mul_f32 v[174:175], v[174:175], v[184:185]
	v_pk_fma_f32 v[144:145], v[160:161], v[128:129], v[144:145]
	v_pk_fma_f32 v[146:147], v[162:163], v[130:131], v[146:147]
	v_pk_fma_f32 v[148:149], v[164:165], v[132:133], v[148:149]
	v_pk_fma_f32 v[150:151], v[166:167], v[134:135], v[150:151]
	v_pk_fma_f32 v[152:153], v[168:169], v[136:137], v[152:153]
	v_pk_fma_f32 v[154:155], v[170:171], v[138:139], v[154:155]
	v_pk_fma_f32 v[156:157], v[172:173], v[140:141], v[156:157]
	v_pk_fma_f32 v[158:159], v[174:175], v[142:143], v[158:159]
	v_pk_mul_f32 v[252:253], v[144:145], v[144:145]
	v_pk_mul_f32 v[254:255], v[146:147], v[146:147]
	v_pk_fma_f32 v[252:253], v[148:149], v[148:149], v[252:253]
	v_pk_fma_f32 v[254:255], v[150:151], v[150:151], v[254:255]
	v_pk_fma_f32 v[252:253], v[152:153], v[152:153], v[252:253]
	v_pk_fma_f32 v[254:255], v[154:155], v[154:155], v[254:255]
	v_pk_fma_f32 v[252:253], v[156:157], v[156:157], v[252:253]
	v_pk_fma_f32 v[254:255], v[158:159], v[158:159], v[254:255]
	v_pk_add_f32 v[252:253], v[252:253], v[254:255]
	s_nop 0
	v_add_f32_e32 v183, v252, v253
	s_nop 1
	v_add_f32_dpp v183, v183, v183 quad_perm:[1,0,3,2] row_mask:0xf bank_mask:0xf bound_ctrl:1
	s_nop 1
	v_add_f32_dpp v183, v183, v183 quad_perm:[2,3,0,1] row_mask:0xf bank_mask:0xf bound_ctrl:1
	s_nop 1
	v_add_f32_dpp v183, v183, v183 row_half_mirror row_mask:0xf bank_mask:0xf bound_ctrl:1
	s_nop 1
	v_add_f32_dpp v183, v183, v183 row_mirror row_mask:0xf bank_mask:0xf bound_ctrl:1
	s_nop 1
	v_readlane_b32 s98, v183, 0
	v_readlane_b32 s99, v183, 16
	v_readlane_b32 s100, v183, 32
	v_readlane_b32 s101, v183, 48
	s_nop 1
	v_mov_b32_e32 v183, s98
	v_add_f32_e32 v183, s99, v183
	v_add_f32_e32 v183, s100, v183
	v_add_f32_e32 v183, s101, v183
	v_fmamk_f32 v183, v183, 0x3a800000, v182
	v_cmp_gt_f32_e32 vcc, 0x800000, v183
	v_mul_f32_e32 v181, 0x4b800000, v183
	s_nop 1
	v_cndmask_b32_e32 v183, v183, v181, vcc
	v_rsq_f32_e32 v183, v183
	s_nop 0
	v_mul_f32_e32 v181, 0x45800000, v183
	v_cndmask_b32_e32 v184, v183, v181, vcc
	v_mov_b32_e32 v185, v184
	v_cvt_pk_bf16_f32 v32, v144, v145
	v_cvt_pk_bf16_f32 v33, v146, v147
	v_cvt_pk_bf16_f32 v34, v148, v149
	v_cvt_pk_bf16_f32 v35, v150, v151
	v_cvt_pk_bf16_f32 v36, v152, v153
	v_cvt_pk_bf16_f32 v37, v154, v155
	v_cvt_pk_bf16_f32 v38, v156, v157
	v_cvt_pk_bf16_f32 v39, v158, v159
	v_add_u32_e32 v181, 0x2000000, v177
	global_store_dwordx4 v181, v[32:35], s[78:79]
	global_store_dwordx4 v181, v[36:39], s[78:79] offset:1024
	v_add_u32_e32 v236, 0x4000, v237
	s_mov_b64 exec, 1
	global_store_dword v236, v184, s[78:79]
	s_mov_b64 exec, -1
	s_waitcnt vmcnt(16)
	v_lshlrev_b32_e32 v144, 16, v48
	v_and_b32_e32 v145, 0xffff0000, v48
	v_lshlrev_b32_e32 v146, 16, v49
	v_and_b32_e32 v147, 0xffff0000, v49
	v_lshlrev_b32_e32 v148, 16, v50
	v_and_b32_e32 v149, 0xffff0000, v50
	v_lshlrev_b32_e32 v150, 16, v51
	v_and_b32_e32 v151, 0xffff0000, v51
	v_lshlrev_b32_e32 v152, 16, v52
	v_and_b32_e32 v153, 0xffff0000, v52
	v_lshlrev_b32_e32 v154, 16, v53
	v_and_b32_e32 v155, 0xffff0000, v53
	v_lshlrev_b32_e32 v156, 16, v54
	v_and_b32_e32 v157, 0xffff0000, v54
	v_lshlrev_b32_e32 v158, 16, v55
	v_and_b32_e32 v159, 0xffff0000, v55
	v_lshlrev_b32_e32 v160, 16, v56
	v_and_b32_e32 v161, 0xffff0000, v56
	v_lshlrev_b32_e32 v162, 16, v57
	v_and_b32_e32 v163, 0xffff0000, v57
	v_lshlrev_b32_e32 v164, 16, v58
	v_and_b32_e32 v165, 0xffff0000, v58
	v_lshlrev_b32_e32 v166, 16, v59
	v_and_b32_e32 v167, 0xffff0000, v59
	v_lshlrev_b32_e32 v168, 16, v60
	v_and_b32_e32 v169, 0xffff0000, v60
	v_lshlrev_b32_e32 v170, 16, v61
	v_and_b32_e32 v171, 0xffff0000, v61
	v_lshlrev_b32_e32 v172, 16, v62
	v_and_b32_e32 v173, 0xffff0000, v62
	v_lshlrev_b32_e32 v174, 16, v63
	v_and_b32_e32 v175, 0xffff0000, v63
	v_pk_mul_f32 v[252:253], v[160:161], v[160:161]
	v_pk_mul_f32 v[254:255], v[162:163], v[162:163]
	v_pk_fma_f32 v[252:253], v[164:165], v[164:165], v[252:253]
	v_pk_fma_f32 v[254:255], v[166:167], v[166:167], v[254:255]
	v_pk_fma_f32 v[252:253], v[168:169], v[168:169], v[252:253]
	v_pk_fma_f32 v[254:255], v[170:171], v[170:171], v[254:255]
	v_pk_fma_f32 v[252:253], v[172:173], v[172:173], v[252:253]
	v_pk_fma_f32 v[254:255], v[174:175], v[174:175], v[254:255]
	v_pk_add_f32 v[252:253], v[252:253], v[254:255]
	s_nop 0
	v_add_f32_e32 v183, v252, v253
	s_nop 1
	v_add_f32_dpp v183, v183, v183 quad_perm:[1,0,3,2] row_mask:0xf bank_mask:0xf bound_ctrl:1
	s_nop 1
	v_add_f32_dpp v183, v183, v183 quad_perm:[2,3,0,1] row_mask:0xf bank_mask:0xf bound_ctrl:1
	s_nop 1
	v_add_f32_dpp v183, v183, v183 row_half_mirror row_mask:0xf bank_mask:0xf bound_ctrl:1
	s_nop 1
	v_add_f32_dpp v183, v183, v183 row_mirror row_mask:0xf bank_mask:0xf bound_ctrl:1
	s_nop 1
	v_readlane_b32 s98, v183, 0
	v_readlane_b32 s99, v183, 16
	v_readlane_b32 s100, v183, 32
	v_readlane_b32 s101, v183, 48
	s_nop 1
	v_mov_b32_e32 v183, s98
	v_add_f32_e32 v183, s99, v183
	v_add_f32_e32 v183, s100, v183
	v_add_f32_e32 v183, s101, v183
	v_fmamk_f32 v183, v183, 0x3a800000, v182
	v_cmp_gt_f32_e32 vcc, 0x800000, v183
	v_mul_f32_e32 v181, 0x4b800000, v183
	s_nop 1
	v_cndmask_b32_e32 v183, v183, v181, vcc
	v_rsq_f32_e32 v183, v183
	s_nop 0
	v_mul_f32_e32 v181, 0x45800000, v183
	v_cndmask_b32_e32 v184, v183, v181, vcc
	v_mov_b32_e32 v185, v184
	v_pk_mul_f32 v[160:161], v[160:161], v[184:185]
	v_pk_mul_f32 v[162:163], v[162:163], v[184:185]
	v_pk_mul_f32 v[164:165], v[164:165], v[184:185]
	v_pk_mul_f32 v[166:167], v[166:167], v[184:185]
	v_pk_mul_f32 v[168:169], v[168:169], v[184:185]
	v_pk_mul_f32 v[170:171], v[170:171], v[184:185]
	v_pk_mul_f32 v[172:173], v[172:173], v[184:185]
	v_pk_mul_f32 v[174:175], v[174:175], v[184:185]
	v_pk_fma_f32 v[144:145], v[160:161], v[128:129], v[144:145]
	v_pk_fma_f32 v[146:147], v[162:163], v[130:131], v[146:147]
	v_pk_fma_f32 v[148:149], v[164:165], v[132:133], v[148:149]
	v_pk_fma_f32 v[150:151], v[166:167], v[134:135], v[150:151]
	v_pk_fma_f32 v[152:153], v[168:169], v[136:137], v[152:153]
	v_pk_fma_f32 v[154:155], v[170:171], v[138:139], v[154:155]
	v_pk_fma_f32 v[156:157], v[172:173], v[140:141], v[156:157]
	v_pk_fma_f32 v[158:159], v[174:175], v[142:143], v[158:159]
	v_pk_mul_f32 v[252:253], v[144:145], v[144:145]
	v_pk_mul_f32 v[254:255], v[146:147], v[146:147]
	v_pk_fma_f32 v[252:253], v[148:149], v[148:149], v[252:253]
	v_pk_fma_f32 v[254:255], v[150:151], v[150:151], v[254:255]
	v_pk_fma_f32 v[252:253], v[152:153], v[152:153], v[252:253]
	v_pk_fma_f32 v[254:255], v[154:155], v[154:155], v[254:255]
	v_pk_fma_f32 v[252:253], v[156:157], v[156:157], v[252:253]
	v_pk_fma_f32 v[254:255], v[158:159], v[158:159], v[254:255]
	v_pk_add_f32 v[252:253], v[252:253], v[254:255]
	s_nop 0
	v_add_f32_e32 v183, v252, v253
	s_nop 1
	v_add_f32_dpp v183, v183, v183 quad_perm:[1,0,3,2] row_mask:0xf bank_mask:0xf bound_ctrl:1
	s_nop 1
	v_add_f32_dpp v183, v183, v183 quad_perm:[2,3,0,1] row_mask:0xf bank_mask:0xf bound_ctrl:1
	s_nop 1
	v_add_f32_dpp v183, v183, v183 row_half_mirror row_mask:0xf bank_mask:0xf bound_ctrl:1
	s_nop 1
	v_add_f32_dpp v183, v183, v183 row_mirror row_mask:0xf bank_mask:0xf bound_ctrl:1
	s_nop 1
	v_readlane_b32 s98, v183, 0
	v_readlane_b32 s99, v183, 16
	v_readlane_b32 s100, v183, 32
	v_readlane_b32 s101, v183, 48
	s_nop 1
	v_mov_b32_e32 v183, s98
	v_add_f32_e32 v183, s99, v183
	v_add_f32_e32 v183, s100, v183
	v_add_f32_e32 v183, s101, v183
	v_fmamk_f32 v183, v183, 0x3a800000, v182
	v_cmp_gt_f32_e32 vcc, 0x800000, v183
	v_mul_f32_e32 v181, 0x4b800000, v183
	s_nop 1
	v_cndmask_b32_e32 v183, v183, v181, vcc
	v_rsq_f32_e32 v183, v183
	s_nop 0
	v_mul_f32_e32 v181, 0x45800000, v183
	v_cndmask_b32_e32 v184, v183, v181, vcc
	v_mov_b32_e32 v185, v184
	v_cvt_pk_bf16_f32 v48, v144, v145
	v_cvt_pk_bf16_f32 v49, v146, v147
	v_cvt_pk_bf16_f32 v50, v148, v149
	v_cvt_pk_bf16_f32 v51, v150, v151
	v_cvt_pk_bf16_f32 v52, v152, v153
	v_cvt_pk_bf16_f32 v53, v154, v155
	v_cvt_pk_bf16_f32 v54, v156, v157
	v_cvt_pk_bf16_f32 v55, v158, v159
	v_add_u32_e32 v181, 0x2400000, v177
	global_store_dwordx4 v181, v[48:51], s[78:79]
	global_store_dwordx4 v181, v[52:55], s[78:79] offset:1024
	v_add_u32_e32 v236, 0x6000, v237
	s_mov_b64 exec, 1
	global_store_dword v236, v184, s[78:79]
	s_mov_b64 exec, -1
	s_waitcnt vmcnt(12)
	v_lshlrev_b32_e32 v144, 16, v64
	v_and_b32_e32 v145, 0xffff0000, v64
	v_lshlrev_b32_e32 v146, 16, v65
	v_and_b32_e32 v147, 0xffff0000, v65
	v_lshlrev_b32_e32 v148, 16, v66
	v_and_b32_e32 v149, 0xffff0000, v66
	v_lshlrev_b32_e32 v150, 16, v67
	v_and_b32_e32 v151, 0xffff0000, v67
	v_lshlrev_b32_e32 v152, 16, v68
	v_and_b32_e32 v153, 0xffff0000, v68
	v_lshlrev_b32_e32 v154, 16, v69
	v_and_b32_e32 v155, 0xffff0000, v69
	v_lshlrev_b32_e32 v156, 16, v70
	v_and_b32_e32 v157, 0xffff0000, v70
	v_lshlrev_b32_e32 v158, 16, v71
	v_and_b32_e32 v159, 0xffff0000, v71
	v_lshlrev_b32_e32 v160, 16, v72
	v_and_b32_e32 v161, 0xffff0000, v72
	v_lshlrev_b32_e32 v162, 16, v73
	v_and_b32_e32 v163, 0xffff0000, v73
	v_lshlrev_b32_e32 v164, 16, v74
	v_and_b32_e32 v165, 0xffff0000, v74
	v_lshlrev_b32_e32 v166, 16, v75
	v_and_b32_e32 v167, 0xffff0000, v75
	v_lshlrev_b32_e32 v168, 16, v76
	v_and_b32_e32 v169, 0xffff0000, v76
	v_lshlrev_b32_e32 v170, 16, v77
	v_and_b32_e32 v171, 0xffff0000, v77
	v_lshlrev_b32_e32 v172, 16, v78
	v_and_b32_e32 v173, 0xffff0000, v78
	v_lshlrev_b32_e32 v174, 16, v79
	v_and_b32_e32 v175, 0xffff0000, v79
	v_pk_mul_f32 v[252:253], v[160:161], v[160:161]
	v_pk_mul_f32 v[254:255], v[162:163], v[162:163]
	v_pk_fma_f32 v[252:253], v[164:165], v[164:165], v[252:253]
	v_pk_fma_f32 v[254:255], v[166:167], v[166:167], v[254:255]
	v_pk_fma_f32 v[252:253], v[168:169], v[168:169], v[252:253]
	v_pk_fma_f32 v[254:255], v[170:171], v[170:171], v[254:255]
	v_pk_fma_f32 v[252:253], v[172:173], v[172:173], v[252:253]
	v_pk_fma_f32 v[254:255], v[174:175], v[174:175], v[254:255]
	v_pk_add_f32 v[252:253], v[252:253], v[254:255]
	s_nop 0
	v_add_f32_e32 v183, v252, v253
	s_nop 1
	v_add_f32_dpp v183, v183, v183 quad_perm:[1,0,3,2] row_mask:0xf bank_mask:0xf bound_ctrl:1
	s_nop 1
	v_add_f32_dpp v183, v183, v183 quad_perm:[2,3,0,1] row_mask:0xf bank_mask:0xf bound_ctrl:1
	s_nop 1
	v_add_f32_dpp v183, v183, v183 row_half_mirror row_mask:0xf bank_mask:0xf bound_ctrl:1
	s_nop 1
	v_add_f32_dpp v183, v183, v183 row_mirror row_mask:0xf bank_mask:0xf bound_ctrl:1
	s_nop 1
	v_readlane_b32 s98, v183, 0
	v_readlane_b32 s99, v183, 16
	v_readlane_b32 s100, v183, 32
	v_readlane_b32 s101, v183, 48
	s_nop 1
	v_mov_b32_e32 v183, s98
	v_add_f32_e32 v183, s99, v183
	v_add_f32_e32 v183, s100, v183
	v_add_f32_e32 v183, s101, v183
	v_fmamk_f32 v183, v183, 0x3a800000, v182
	v_cmp_gt_f32_e32 vcc, 0x800000, v183
	v_mul_f32_e32 v181, 0x4b800000, v183
	s_nop 1
	v_cndmask_b32_e32 v183, v183, v181, vcc
	v_rsq_f32_e32 v183, v183
	s_nop 0
	v_mul_f32_e32 v181, 0x45800000, v183
	v_cndmask_b32_e32 v184, v183, v181, vcc
	v_mov_b32_e32 v185, v184
	v_pk_mul_f32 v[160:161], v[160:161], v[184:185]
	v_pk_mul_f32 v[162:163], v[162:163], v[184:185]
	v_pk_mul_f32 v[164:165], v[164:165], v[184:185]
	v_pk_mul_f32 v[166:167], v[166:167], v[184:185]
	v_pk_mul_f32 v[168:169], v[168:169], v[184:185]
	v_pk_mul_f32 v[170:171], v[170:171], v[184:185]
	v_pk_mul_f32 v[172:173], v[172:173], v[184:185]
	v_pk_mul_f32 v[174:175], v[174:175], v[184:185]
	v_pk_fma_f32 v[144:145], v[160:161], v[128:129], v[144:145]
	v_pk_fma_f32 v[146:147], v[162:163], v[130:131], v[146:147]
	v_pk_fma_f32 v[148:149], v[164:165], v[132:133], v[148:149]
	v_pk_fma_f32 v[150:151], v[166:167], v[134:135], v[150:151]
	v_pk_fma_f32 v[152:153], v[168:169], v[136:137], v[152:153]
	v_pk_fma_f32 v[154:155], v[170:171], v[138:139], v[154:155]
	v_pk_fma_f32 v[156:157], v[172:173], v[140:141], v[156:157]
	v_pk_fma_f32 v[158:159], v[174:175], v[142:143], v[158:159]
	v_pk_mul_f32 v[252:253], v[144:145], v[144:145]
	v_pk_mul_f32 v[254:255], v[146:147], v[146:147]
	v_pk_fma_f32 v[252:253], v[148:149], v[148:149], v[252:253]
	v_pk_fma_f32 v[254:255], v[150:151], v[150:151], v[254:255]
	v_pk_fma_f32 v[252:253], v[152:153], v[152:153], v[252:253]
	v_pk_fma_f32 v[254:255], v[154:155], v[154:155], v[254:255]
	v_pk_fma_f32 v[252:253], v[156:157], v[156:157], v[252:253]
	v_pk_fma_f32 v[254:255], v[158:159], v[158:159], v[254:255]
	v_pk_add_f32 v[252:253], v[252:253], v[254:255]
	s_nop 0
	v_add_f32_e32 v183, v252, v253
	s_nop 1
	v_add_f32_dpp v183, v183, v183 quad_perm:[1,0,3,2] row_mask:0xf bank_mask:0xf bound_ctrl:1
	s_nop 1
	v_add_f32_dpp v183, v183, v183 quad_perm:[2,3,0,1] row_mask:0xf bank_mask:0xf bound_ctrl:1
	s_nop 1
	v_add_f32_dpp v183, v183, v183 row_half_mirror row_mask:0xf bank_mask:0xf bound_ctrl:1
	s_nop 1
	v_add_f32_dpp v183, v183, v183 row_mirror row_mask:0xf bank_mask:0xf bound_ctrl:1
	s_nop 1
	v_readlane_b32 s98, v183, 0
	v_readlane_b32 s99, v183, 16
	v_readlane_b32 s100, v183, 32
	v_readlane_b32 s101, v183, 48
	s_nop 1
	v_mov_b32_e32 v183, s98
	v_add_f32_e32 v183, s99, v183
	v_add_f32_e32 v183, s100, v183
	v_add_f32_e32 v183, s101, v183
	v_fmamk_f32 v183, v183, 0x3a800000, v182
	v_cmp_gt_f32_e32 vcc, 0x800000, v183
	v_mul_f32_e32 v181, 0x4b800000, v183
	s_nop 1
	v_cndmask_b32_e32 v183, v183, v181, vcc
	v_rsq_f32_e32 v183, v183
	s_nop 0
	v_mul_f32_e32 v181, 0x45800000, v183
	v_cndmask_b32_e32 v184, v183, v181, vcc
	v_mov_b32_e32 v185, v184
	v_cvt_pk_bf16_f32 v64, v144, v145
	v_cvt_pk_bf16_f32 v65, v146, v147
	v_cvt_pk_bf16_f32 v66, v148, v149
	v_cvt_pk_bf16_f32 v67, v150, v151
	v_cvt_pk_bf16_f32 v68, v152, v153
	v_cvt_pk_bf16_f32 v69, v154, v155
	v_cvt_pk_bf16_f32 v70, v156, v157
	v_cvt_pk_bf16_f32 v71, v158, v159
	v_add_u32_e32 v181, 0x2800000, v177
	global_store_dwordx4 v181, v[64:67], s[78:79]
	global_store_dwordx4 v181, v[68:71], s[78:79] offset:1024
	v_add_u32_e32 v236, 0x8000, v237
	s_mov_b64 exec, 1
	global_store_dword v236, v184, s[78:79]
	s_mov_b64 exec, -1
	s_waitcnt vmcnt(8)
	v_lshlrev_b32_e32 v144, 16, v80
	v_and_b32_e32 v145, 0xffff0000, v80
	v_lshlrev_b32_e32 v146, 16, v81
	v_and_b32_e32 v147, 0xffff0000, v81
	v_lshlrev_b32_e32 v148, 16, v82
	v_and_b32_e32 v149, 0xffff0000, v82
	v_lshlrev_b32_e32 v150, 16, v83
	v_and_b32_e32 v151, 0xffff0000, v83
	v_lshlrev_b32_e32 v152, 16, v84
	v_and_b32_e32 v153, 0xffff0000, v84
	v_lshlrev_b32_e32 v154, 16, v85
	v_and_b32_e32 v155, 0xffff0000, v85
	v_lshlrev_b32_e32 v156, 16, v86
	v_and_b32_e32 v157, 0xffff0000, v86
	v_lshlrev_b32_e32 v158, 16, v87
	v_and_b32_e32 v159, 0xffff0000, v87
	v_lshlrev_b32_e32 v160, 16, v88
	v_and_b32_e32 v161, 0xffff0000, v88
	v_lshlrev_b32_e32 v162, 16, v89
	v_and_b32_e32 v163, 0xffff0000, v89
	v_lshlrev_b32_e32 v164, 16, v90
	v_and_b32_e32 v165, 0xffff0000, v90
	v_lshlrev_b32_e32 v166, 16, v91
	v_and_b32_e32 v167, 0xffff0000, v91
	v_lshlrev_b32_e32 v168, 16, v92
	v_and_b32_e32 v169, 0xffff0000, v92
	v_lshlrev_b32_e32 v170, 16, v93
	v_and_b32_e32 v171, 0xffff0000, v93
	v_lshlrev_b32_e32 v172, 16, v94
	v_and_b32_e32 v173, 0xffff0000, v94
	v_lshlrev_b32_e32 v174, 16, v95
	v_and_b32_e32 v175, 0xffff0000, v95
	v_pk_mul_f32 v[252:253], v[160:161], v[160:161]
	v_pk_mul_f32 v[254:255], v[162:163], v[162:163]
	v_pk_fma_f32 v[252:253], v[164:165], v[164:165], v[252:253]
	v_pk_fma_f32 v[254:255], v[166:167], v[166:167], v[254:255]
	v_pk_fma_f32 v[252:253], v[168:169], v[168:169], v[252:253]
	v_pk_fma_f32 v[254:255], v[170:171], v[170:171], v[254:255]
	v_pk_fma_f32 v[252:253], v[172:173], v[172:173], v[252:253]
	v_pk_fma_f32 v[254:255], v[174:175], v[174:175], v[254:255]
	v_pk_add_f32 v[252:253], v[252:253], v[254:255]
	s_nop 0
	v_add_f32_e32 v183, v252, v253
	s_nop 1
	v_add_f32_dpp v183, v183, v183 quad_perm:[1,0,3,2] row_mask:0xf bank_mask:0xf bound_ctrl:1
	s_nop 1
	v_add_f32_dpp v183, v183, v183 quad_perm:[2,3,0,1] row_mask:0xf bank_mask:0xf bound_ctrl:1
	s_nop 1
	v_add_f32_dpp v183, v183, v183 row_half_mirror row_mask:0xf bank_mask:0xf bound_ctrl:1
	s_nop 1
	v_add_f32_dpp v183, v183, v183 row_mirror row_mask:0xf bank_mask:0xf bound_ctrl:1
	s_nop 1
	v_readlane_b32 s98, v183, 0
	v_readlane_b32 s99, v183, 16
	v_readlane_b32 s100, v183, 32
	v_readlane_b32 s101, v183, 48
	s_nop 1
	v_mov_b32_e32 v183, s98
	v_add_f32_e32 v183, s99, v183
	v_add_f32_e32 v183, s100, v183
	v_add_f32_e32 v183, s101, v183
	v_fmamk_f32 v183, v183, 0x3a800000, v182
	v_cmp_gt_f32_e32 vcc, 0x800000, v183
	v_mul_f32_e32 v181, 0x4b800000, v183
	s_nop 1
	v_cndmask_b32_e32 v183, v183, v181, vcc
	v_rsq_f32_e32 v183, v183
	s_nop 0
	v_mul_f32_e32 v181, 0x45800000, v183
	v_cndmask_b32_e32 v184, v183, v181, vcc
	v_mov_b32_e32 v185, v184
	v_pk_mul_f32 v[160:161], v[160:161], v[184:185]
	v_pk_mul_f32 v[162:163], v[162:163], v[184:185]
	v_pk_mul_f32 v[164:165], v[164:165], v[184:185]
	v_pk_mul_f32 v[166:167], v[166:167], v[184:185]
	v_pk_mul_f32 v[168:169], v[168:169], v[184:185]
	v_pk_mul_f32 v[170:171], v[170:171], v[184:185]
	v_pk_mul_f32 v[172:173], v[172:173], v[184:185]
	v_pk_mul_f32 v[174:175], v[174:175], v[184:185]
	v_pk_fma_f32 v[144:145], v[160:161], v[128:129], v[144:145]
	v_pk_fma_f32 v[146:147], v[162:163], v[130:131], v[146:147]
	v_pk_fma_f32 v[148:149], v[164:165], v[132:133], v[148:149]
	v_pk_fma_f32 v[150:151], v[166:167], v[134:135], v[150:151]
	v_pk_fma_f32 v[152:153], v[168:169], v[136:137], v[152:153]
	v_pk_fma_f32 v[154:155], v[170:171], v[138:139], v[154:155]
	v_pk_fma_f32 v[156:157], v[172:173], v[140:141], v[156:157]
	v_pk_fma_f32 v[158:159], v[174:175], v[142:143], v[158:159]
	v_pk_mul_f32 v[252:253], v[144:145], v[144:145]
	v_pk_mul_f32 v[254:255], v[146:147], v[146:147]
	v_pk_fma_f32 v[252:253], v[148:149], v[148:149], v[252:253]
	v_pk_fma_f32 v[254:255], v[150:151], v[150:151], v[254:255]
	v_pk_fma_f32 v[252:253], v[152:153], v[152:153], v[252:253]
	v_pk_fma_f32 v[254:255], v[154:155], v[154:155], v[254:255]
	v_pk_fma_f32 v[252:253], v[156:157], v[156:157], v[252:253]
	v_pk_fma_f32 v[254:255], v[158:159], v[158:159], v[254:255]
	v_pk_add_f32 v[252:253], v[252:253], v[254:255]
	s_nop 0
	v_add_f32_e32 v183, v252, v253
	s_nop 1
	v_add_f32_dpp v183, v183, v183 quad_perm:[1,0,3,2] row_mask:0xf bank_mask:0xf bound_ctrl:1
	s_nop 1
	v_add_f32_dpp v183, v183, v183 quad_perm:[2,3,0,1] row_mask:0xf bank_mask:0xf bound_ctrl:1
	s_nop 1
	v_add_f32_dpp v183, v183, v183 row_half_mirror row_mask:0xf bank_mask:0xf bound_ctrl:1
	s_nop 1
	v_add_f32_dpp v183, v183, v183 row_mirror row_mask:0xf bank_mask:0xf bound_ctrl:1
	s_nop 1
	v_readlane_b32 s98, v183, 0
	v_readlane_b32 s99, v183, 16
	v_readlane_b32 s100, v183, 32
	v_readlane_b32 s101, v183, 48
	s_nop 1
	v_mov_b32_e32 v183, s98
	v_add_f32_e32 v183, s99, v183
	v_add_f32_e32 v183, s100, v183
	v_add_f32_e32 v183, s101, v183
	v_fmamk_f32 v183, v183, 0x3a800000, v182
	v_cmp_gt_f32_e32 vcc, 0x800000, v183
	v_mul_f32_e32 v181, 0x4b800000, v183
	s_nop 1
	v_cndmask_b32_e32 v183, v183, v181, vcc
	v_rsq_f32_e32 v183, v183
	s_nop 0
	v_mul_f32_e32 v181, 0x45800000, v183
	v_cndmask_b32_e32 v184, v183, v181, vcc
	v_mov_b32_e32 v185, v184
	v_cvt_pk_bf16_f32 v80, v144, v145
	v_cvt_pk_bf16_f32 v81, v146, v147
	v_cvt_pk_bf16_f32 v82, v148, v149
	v_cvt_pk_bf16_f32 v83, v150, v151
	v_cvt_pk_bf16_f32 v84, v152, v153
	v_cvt_pk_bf16_f32 v85, v154, v155
	v_cvt_pk_bf16_f32 v86, v156, v157
	v_cvt_pk_bf16_f32 v87, v158, v159
	v_add_u32_e32 v181, 0x2c00000, v177
	global_store_dwordx4 v181, v[80:83], s[78:79]
	global_store_dwordx4 v181, v[84:87], s[78:79] offset:1024
	v_add_u32_e32 v236, 0xa000, v237
	s_mov_b64 exec, 1
	global_store_dword v236, v184, s[78:79]
	s_mov_b64 exec, -1
	s_waitcnt vmcnt(4)
	v_lshlrev_b32_e32 v144, 16, v96
	v_and_b32_e32 v145, 0xffff0000, v96
	v_lshlrev_b32_e32 v146, 16, v97
	v_and_b32_e32 v147, 0xffff0000, v97
	v_lshlrev_b32_e32 v148, 16, v98
	v_and_b32_e32 v149, 0xffff0000, v98
	v_lshlrev_b32_e32 v150, 16, v99
	v_and_b32_e32 v151, 0xffff0000, v99
	v_lshlrev_b32_e32 v152, 16, v100
	v_and_b32_e32 v153, 0xffff0000, v100
	v_lshlrev_b32_e32 v154, 16, v101
	v_and_b32_e32 v155, 0xffff0000, v101
	v_lshlrev_b32_e32 v156, 16, v102
	v_and_b32_e32 v157, 0xffff0000, v102
	v_lshlrev_b32_e32 v158, 16, v103
	v_and_b32_e32 v159, 0xffff0000, v103
	v_lshlrev_b32_e32 v160, 16, v104
	v_and_b32_e32 v161, 0xffff0000, v104
	v_lshlrev_b32_e32 v162, 16, v105
	v_and_b32_e32 v163, 0xffff0000, v105
	v_lshlrev_b32_e32 v164, 16, v106
	v_and_b32_e32 v165, 0xffff0000, v106
	v_lshlrev_b32_e32 v166, 16, v107
	v_and_b32_e32 v167, 0xffff0000, v107
	v_lshlrev_b32_e32 v168, 16, v108
	v_and_b32_e32 v169, 0xffff0000, v108
	v_lshlrev_b32_e32 v170, 16, v109
	v_and_b32_e32 v171, 0xffff0000, v109
	v_lshlrev_b32_e32 v172, 16, v110
	v_and_b32_e32 v173, 0xffff0000, v110
	v_lshlrev_b32_e32 v174, 16, v111
	v_and_b32_e32 v175, 0xffff0000, v111
	v_pk_mul_f32 v[252:253], v[160:161], v[160:161]
	v_pk_mul_f32 v[254:255], v[162:163], v[162:163]
	v_pk_fma_f32 v[252:253], v[164:165], v[164:165], v[252:253]
	v_pk_fma_f32 v[254:255], v[166:167], v[166:167], v[254:255]
	v_pk_fma_f32 v[252:253], v[168:169], v[168:169], v[252:253]
	v_pk_fma_f32 v[254:255], v[170:171], v[170:171], v[254:255]
	v_pk_fma_f32 v[252:253], v[172:173], v[172:173], v[252:253]
	v_pk_fma_f32 v[254:255], v[174:175], v[174:175], v[254:255]
	v_pk_add_f32 v[252:253], v[252:253], v[254:255]
	s_nop 0
	v_add_f32_e32 v183, v252, v253
	s_nop 1
	v_add_f32_dpp v183, v183, v183 quad_perm:[1,0,3,2] row_mask:0xf bank_mask:0xf bound_ctrl:1
	s_nop 1
	v_add_f32_dpp v183, v183, v183 quad_perm:[2,3,0,1] row_mask:0xf bank_mask:0xf bound_ctrl:1
	s_nop 1
	v_add_f32_dpp v183, v183, v183 row_half_mirror row_mask:0xf bank_mask:0xf bound_ctrl:1
	s_nop 1
	v_add_f32_dpp v183, v183, v183 row_mirror row_mask:0xf bank_mask:0xf bound_ctrl:1
	s_nop 1
	v_readlane_b32 s98, v183, 0
	v_readlane_b32 s99, v183, 16
	v_readlane_b32 s100, v183, 32
	v_readlane_b32 s101, v183, 48
	s_nop 1
	v_mov_b32_e32 v183, s98
	v_add_f32_e32 v183, s99, v183
	v_add_f32_e32 v183, s100, v183
	v_add_f32_e32 v183, s101, v183
	v_fmamk_f32 v183, v183, 0x3a800000, v182
	v_cmp_gt_f32_e32 vcc, 0x800000, v183
	v_mul_f32_e32 v181, 0x4b800000, v183
	s_nop 1
	v_cndmask_b32_e32 v183, v183, v181, vcc
	v_rsq_f32_e32 v183, v183
	s_nop 0
	v_mul_f32_e32 v181, 0x45800000, v183
	v_cndmask_b32_e32 v184, v183, v181, vcc
	v_mov_b32_e32 v185, v184
	v_pk_mul_f32 v[160:161], v[160:161], v[184:185]
	v_pk_mul_f32 v[162:163], v[162:163], v[184:185]
	v_pk_mul_f32 v[164:165], v[164:165], v[184:185]
	v_pk_mul_f32 v[166:167], v[166:167], v[184:185]
	v_pk_mul_f32 v[168:169], v[168:169], v[184:185]
	v_pk_mul_f32 v[170:171], v[170:171], v[184:185]
	v_pk_mul_f32 v[172:173], v[172:173], v[184:185]
	v_pk_mul_f32 v[174:175], v[174:175], v[184:185]
	v_pk_fma_f32 v[144:145], v[160:161], v[128:129], v[144:145]
	v_pk_fma_f32 v[146:147], v[162:163], v[130:131], v[146:147]
	v_pk_fma_f32 v[148:149], v[164:165], v[132:133], v[148:149]
	v_pk_fma_f32 v[150:151], v[166:167], v[134:135], v[150:151]
	v_pk_fma_f32 v[152:153], v[168:169], v[136:137], v[152:153]
	v_pk_fma_f32 v[154:155], v[170:171], v[138:139], v[154:155]
	v_pk_fma_f32 v[156:157], v[172:173], v[140:141], v[156:157]
	v_pk_fma_f32 v[158:159], v[174:175], v[142:143], v[158:159]
	v_pk_mul_f32 v[252:253], v[144:145], v[144:145]
	v_pk_mul_f32 v[254:255], v[146:147], v[146:147]
	v_pk_fma_f32 v[252:253], v[148:149], v[148:149], v[252:253]
	v_pk_fma_f32 v[254:255], v[150:151], v[150:151], v[254:255]
	v_pk_fma_f32 v[252:253], v[152:153], v[152:153], v[252:253]
	v_pk_fma_f32 v[254:255], v[154:155], v[154:155], v[254:255]
	v_pk_fma_f32 v[252:253], v[156:157], v[156:157], v[252:253]
	v_pk_fma_f32 v[254:255], v[158:159], v[158:159], v[254:255]
	v_pk_add_f32 v[252:253], v[252:253], v[254:255]
	s_nop 0
	v_add_f32_e32 v183, v252, v253
	s_nop 1
	v_add_f32_dpp v183, v183, v183 quad_perm:[1,0,3,2] row_mask:0xf bank_mask:0xf bound_ctrl:1
	s_nop 1
	v_add_f32_dpp v183, v183, v183 quad_perm:[2,3,0,1] row_mask:0xf bank_mask:0xf bound_ctrl:1
	s_nop 1
	v_add_f32_dpp v183, v183, v183 row_half_mirror row_mask:0xf bank_mask:0xf bound_ctrl:1
	s_nop 1
	v_add_f32_dpp v183, v183, v183 row_mirror row_mask:0xf bank_mask:0xf bound_ctrl:1
	s_nop 1
	v_readlane_b32 s98, v183, 0
	v_readlane_b32 s99, v183, 16
	v_readlane_b32 s100, v183, 32
	v_readlane_b32 s101, v183, 48
	s_nop 1
	v_mov_b32_e32 v183, s98
	v_add_f32_e32 v183, s99, v183
	v_add_f32_e32 v183, s100, v183
	v_add_f32_e32 v183, s101, v183
	v_fmamk_f32 v183, v183, 0x3a800000, v182
	v_cmp_gt_f32_e32 vcc, 0x800000, v183
	v_mul_f32_e32 v181, 0x4b800000, v183
	s_nop 1
	v_cndmask_b32_e32 v183, v183, v181, vcc
	v_rsq_f32_e32 v183, v183
	s_nop 0
	v_mul_f32_e32 v181, 0x45800000, v183
	v_cndmask_b32_e32 v184, v183, v181, vcc
	v_mov_b32_e32 v185, v184
	v_cvt_pk_bf16_f32 v96, v144, v145
	v_cvt_pk_bf16_f32 v97, v146, v147
	v_cvt_pk_bf16_f32 v98, v148, v149
	v_cvt_pk_bf16_f32 v99, v150, v151
	v_cvt_pk_bf16_f32 v100, v152, v153
	v_cvt_pk_bf16_f32 v101, v154, v155
	v_cvt_pk_bf16_f32 v102, v156, v157
	v_cvt_pk_bf16_f32 v103, v158, v159
	v_add_u32_e32 v181, 0x3000000, v177
	global_store_dwordx4 v181, v[96:99], s[78:79]
	global_store_dwordx4 v181, v[100:103], s[78:79] offset:1024
	v_add_u32_e32 v236, 0xc000, v237
	s_mov_b64 exec, 1
	global_store_dword v236, v184, s[78:79]
	s_mov_b64 exec, -1
	s_waitcnt vmcnt(0)
	v_lshlrev_b32_e32 v144, 16, v112
	v_and_b32_e32 v145, 0xffff0000, v112
	v_lshlrev_b32_e32 v146, 16, v113
	v_and_b32_e32 v147, 0xffff0000, v113
	v_lshlrev_b32_e32 v148, 16, v114
	v_and_b32_e32 v149, 0xffff0000, v114
	v_lshlrev_b32_e32 v150, 16, v115
	v_and_b32_e32 v151, 0xffff0000, v115
	v_lshlrev_b32_e32 v152, 16, v116
	v_and_b32_e32 v153, 0xffff0000, v116
	v_lshlrev_b32_e32 v154, 16, v117
	v_and_b32_e32 v155, 0xffff0000, v117
	v_lshlrev_b32_e32 v156, 16, v118
	v_and_b32_e32 v157, 0xffff0000, v118
	v_lshlrev_b32_e32 v158, 16, v119
	v_and_b32_e32 v159, 0xffff0000, v119
	v_lshlrev_b32_e32 v160, 16, v120
	v_and_b32_e32 v161, 0xffff0000, v120
	v_lshlrev_b32_e32 v162, 16, v121
	v_and_b32_e32 v163, 0xffff0000, v121
	v_lshlrev_b32_e32 v164, 16, v122
	v_and_b32_e32 v165, 0xffff0000, v122
	v_lshlrev_b32_e32 v166, 16, v123
	v_and_b32_e32 v167, 0xffff0000, v123
	v_lshlrev_b32_e32 v168, 16, v124
	v_and_b32_e32 v169, 0xffff0000, v124
	v_lshlrev_b32_e32 v170, 16, v125
	v_and_b32_e32 v171, 0xffff0000, v125
	v_lshlrev_b32_e32 v172, 16, v126
	v_and_b32_e32 v173, 0xffff0000, v126
	v_lshlrev_b32_e32 v174, 16, v127
	v_and_b32_e32 v175, 0xffff0000, v127
	v_pk_mul_f32 v[252:253], v[160:161], v[160:161]
	v_pk_mul_f32 v[254:255], v[162:163], v[162:163]
	v_pk_fma_f32 v[252:253], v[164:165], v[164:165], v[252:253]
	v_pk_fma_f32 v[254:255], v[166:167], v[166:167], v[254:255]
	v_pk_fma_f32 v[252:253], v[168:169], v[168:169], v[252:253]
	v_pk_fma_f32 v[254:255], v[170:171], v[170:171], v[254:255]
	v_pk_fma_f32 v[252:253], v[172:173], v[172:173], v[252:253]
	v_pk_fma_f32 v[254:255], v[174:175], v[174:175], v[254:255]
	v_pk_add_f32 v[252:253], v[252:253], v[254:255]
	s_nop 0
	v_add_f32_e32 v183, v252, v253
	s_nop 1
	v_add_f32_dpp v183, v183, v183 quad_perm:[1,0,3,2] row_mask:0xf bank_mask:0xf bound_ctrl:1
	s_nop 1
	v_add_f32_dpp v183, v183, v183 quad_perm:[2,3,0,1] row_mask:0xf bank_mask:0xf bound_ctrl:1
	s_nop 1
	v_add_f32_dpp v183, v183, v183 row_half_mirror row_mask:0xf bank_mask:0xf bound_ctrl:1
	s_nop 1
	v_add_f32_dpp v183, v183, v183 row_mirror row_mask:0xf bank_mask:0xf bound_ctrl:1
	s_nop 1
	v_readlane_b32 s98, v183, 0
	v_readlane_b32 s99, v183, 16
	v_readlane_b32 s100, v183, 32
	v_readlane_b32 s101, v183, 48
	s_nop 1
	v_mov_b32_e32 v183, s98
	v_add_f32_e32 v183, s99, v183
	v_add_f32_e32 v183, s100, v183
	v_add_f32_e32 v183, s101, v183
	v_fmamk_f32 v183, v183, 0x3a800000, v182
	v_cmp_gt_f32_e32 vcc, 0x800000, v183
	v_mul_f32_e32 v181, 0x4b800000, v183
	s_nop 1
	v_cndmask_b32_e32 v183, v183, v181, vcc
	v_rsq_f32_e32 v183, v183
	s_nop 0
	v_mul_f32_e32 v181, 0x45800000, v183
	v_cndmask_b32_e32 v184, v183, v181, vcc
	v_mov_b32_e32 v185, v184
	v_pk_mul_f32 v[160:161], v[160:161], v[184:185]
	v_pk_mul_f32 v[162:163], v[162:163], v[184:185]
	v_pk_mul_f32 v[164:165], v[164:165], v[184:185]
	v_pk_mul_f32 v[166:167], v[166:167], v[184:185]
	v_pk_mul_f32 v[168:169], v[168:169], v[184:185]
	v_pk_mul_f32 v[170:171], v[170:171], v[184:185]
	v_pk_mul_f32 v[172:173], v[172:173], v[184:185]
	v_pk_mul_f32 v[174:175], v[174:175], v[184:185]
	v_pk_fma_f32 v[144:145], v[160:161], v[128:129], v[144:145]
	v_pk_fma_f32 v[146:147], v[162:163], v[130:131], v[146:147]
	v_pk_fma_f32 v[148:149], v[164:165], v[132:133], v[148:149]
	v_pk_fma_f32 v[150:151], v[166:167], v[134:135], v[150:151]
	v_pk_fma_f32 v[152:153], v[168:169], v[136:137], v[152:153]
	v_pk_fma_f32 v[154:155], v[170:171], v[138:139], v[154:155]
	v_pk_fma_f32 v[156:157], v[172:173], v[140:141], v[156:157]
	v_pk_fma_f32 v[158:159], v[174:175], v[142:143], v[158:159]
	v_pk_mul_f32 v[252:253], v[144:145], v[144:145]
	v_pk_mul_f32 v[254:255], v[146:147], v[146:147]
	v_pk_fma_f32 v[252:253], v[148:149], v[148:149], v[252:253]
	v_pk_fma_f32 v[254:255], v[150:151], v[150:151], v[254:255]
	v_pk_fma_f32 v[252:253], v[152:153], v[152:153], v[252:253]
	v_pk_fma_f32 v[254:255], v[154:155], v[154:155], v[254:255]
	v_pk_fma_f32 v[252:253], v[156:157], v[156:157], v[252:253]
	v_pk_fma_f32 v[254:255], v[158:159], v[158:159], v[254:255]
	v_pk_add_f32 v[252:253], v[252:253], v[254:255]
	s_nop 0
	v_add_f32_e32 v183, v252, v253
	s_nop 1
	v_add_f32_dpp v183, v183, v183 quad_perm:[1,0,3,2] row_mask:0xf bank_mask:0xf bound_ctrl:1
	s_nop 1
	v_add_f32_dpp v183, v183, v183 quad_perm:[2,3,0,1] row_mask:0xf bank_mask:0xf bound_ctrl:1
	s_nop 1
	v_add_f32_dpp v183, v183, v183 row_half_mirror row_mask:0xf bank_mask:0xf bound_ctrl:1
	s_nop 1
	v_add_f32_dpp v183, v183, v183 row_mirror row_mask:0xf bank_mask:0xf bound_ctrl:1
	s_nop 1
	v_readlane_b32 s98, v183, 0
	v_readlane_b32 s99, v183, 16
	v_readlane_b32 s100, v183, 32
	v_readlane_b32 s101, v183, 48
	s_nop 1
	v_mov_b32_e32 v183, s98
	v_add_f32_e32 v183, s99, v183
	v_add_f32_e32 v183, s100, v183
	v_add_f32_e32 v183, s101, v183
	v_fmamk_f32 v183, v183, 0x3a800000, v182
	v_cmp_gt_f32_e32 vcc, 0x800000, v183
	v_mul_f32_e32 v181, 0x4b800000, v183
	s_nop 1
	v_cndmask_b32_e32 v183, v183, v181, vcc
	v_rsq_f32_e32 v183, v183
	s_nop 0
	v_mul_f32_e32 v181, 0x45800000, v183
	v_cndmask_b32_e32 v184, v183, v181, vcc
	v_mov_b32_e32 v185, v184
	v_cvt_pk_bf16_f32 v112, v144, v145
	v_cvt_pk_bf16_f32 v113, v146, v147
	v_cvt_pk_bf16_f32 v114, v148, v149
	v_cvt_pk_bf16_f32 v115, v150, v151
	v_cvt_pk_bf16_f32 v116, v152, v153
	v_cvt_pk_bf16_f32 v117, v154, v155
	v_cvt_pk_bf16_f32 v118, v156, v157
	v_cvt_pk_bf16_f32 v119, v158, v159
	v_add_u32_e32 v181, 0x3400000, v177
	global_store_dwordx4 v181, v[112:115], s[78:79]
	global_store_dwordx4 v181, v[116:119], s[78:79] offset:1024
	v_add_u32_e32 v236, 0xe000, v237
	s_mov_b64 exec, 1
	global_store_dword v236, v184, s[78:79]
	s_mov_b64 exec, -1
	v_readfirstlane_b32 s98, v179
	s_nop 3
	s_and_b32 s99, s98, 3
	s_cmp_lg_u32 s99, 0
	s_cbranch_scc1 .Lmyxupd_done_0
	v_lshrrev_b32_e32 v179, 2, v179
	v_lshlrev_b32_e32 v177, 4, v176
	v_lshl_add_u32 v177, v179, 11, v177
	v_lshlrev_b32_e32 v237, 2, v179
	v_add_u32_e32 v237, 0x10000, v237
	v_add_u32_e32 v181, 0x3800000, v177
	global_load_dwordx4 v[240:243], v181, s[78:79]
	global_load_dwordx4 v[244:247], v181, s[78:79] offset:1024
	v_lshl_add_u32 v183, v179, 12, v180
	v_add_u32_e32 v183, 0xbf00000, v183
	v_add_u32_e32 v181, 0x0, v183
	global_load_dwordx4 v[0:3], v181, s[78:79]
	global_load_dwordx4 v[4:7], v181, s[78:79] offset:16
	global_load_dwordx4 v[8:11], v181, s[78:79] offset:2048
	global_load_dwordx4 v[12:15], v181, s[78:79] offset:2064
	v_add_u32_e32 v181, 0x200000, v183
	global_load_dwordx4 v[16:19], v181, s[78:79]
	global_load_dwordx4 v[20:23], v181, s[78:79] offset:16
	global_load_dwordx4 v[24:27], v181, s[78:79] offset:2048
	global_load_dwordx4 v[28:31], v181, s[78:79] offset:2064
	v_add_u32_e32 v181, 0x400000, v183
	global_load_dwordx4 v[32:35], v181, s[78:79]
	global_load_dwordx4 v[36:39], v181, s[78:79] offset:16
	global_load_dwordx4 v[40:43], v181, s[78:79] offset:2048
	global_load_dwordx4 v[44:47], v181, s[78:79] offset:2064
	v_add_u32_e32 v181, 0x600000, v183
	global_load_dwordx4 v[48:51], v181, s[78:79]
	global_load_dwordx4 v[52:55], v181, s[78:79] offset:16
	global_load_dwordx4 v[56:59], v181, s[78:79] offset:2048
	global_load_dwordx4 v[60:63], v181, s[78:79] offset:2064
	v_add_u32_e32 v181, 0x800000, v183
	global_load_dwordx4 v[64:67], v181, s[78:79]
	global_load_dwordx4 v[68:71], v181, s[78:79] offset:16
	global_load_dwordx4 v[72:75], v181, s[78:79] offset:2048
	global_load_dwordx4 v[76:79], v181, s[78:79] offset:2064
	v_add_u32_e32 v181, 0xa00000, v183
	global_load_dwordx4 v[80:83], v181, s[78:79]
	global_load_dwordx4 v[84:87], v181, s[78:79] offset:16
	global_load_dwordx4 v[88:91], v181, s[78:79] offset:2048
	global_load_dwordx4 v[92:95], v181, s[78:79] offset:2064
	v_add_u32_e32 v181, 0xc00000, v183
	global_load_dwordx4 v[96:99], v181, s[78:79]
	global_load_dwordx4 v[100:103], v181, s[78:79] offset:16
	global_load_dwordx4 v[104:107], v181, s[78:79] offset:2048
	global_load_dwordx4 v[108:111], v181, s[78:79] offset:2064
	v_add_u32_e32 v181, 0xe00000, v183
	global_load_dwordx4 v[112:115], v181, s[78:79]
	global_load_dwordx4 v[116:119], v181, s[78:79] offset:16
	global_load_dwordx4 v[120:123], v181, s[78:79] offset:2048
	global_load_dwordx4 v[124:127], v181, s[78:79] offset:2064
	s_waitcnt vmcnt(28)
	v_pk_add_f32 v[160:161], v[0:1], 0 op_sel_hi:[1,0]
	v_pk_add_f32 v[162:163], v[2:3], 0 op_sel_hi:[1,0]
	v_pk_add_f32 v[164:165], v[4:5], 0 op_sel_hi:[1,0]
	v_pk_add_f32 v[166:167], v[6:7], 0 op_sel_hi:[1,0]
	v_pk_add_f32 v[168:169], v[8:9], 0 op_sel_hi:[1,0]
	v_pk_add_f32 v[170:171], v[10:11], 0 op_sel_hi:[1,0]
	v_pk_add_f32 v[172:173], v[12:13], 0 op_sel_hi:[1,0]
	v_pk_add_f32 v[174:175], v[14:15], 0 op_sel_hi:[1,0]
	s_waitcnt vmcnt(24)
	v_pk_add_f32 v[160:161], v[160:161], v[16:17]
	v_pk_add_f32 v[162:163], v[162:163], v[18:19]
	v_pk_add_f32 v[164:165], v[164:165], v[20:21]
	v_pk_add_f32 v[166:167], v[166:167], v[22:23]
	v_pk_add_f32 v[168:169], v[168:169], v[24:25]
	v_pk_add_f32 v[170:171], v[170:171], v[26:27]
	v_pk_add_f32 v[172:173], v[172:173], v[28:29]
	v_pk_add_f32 v[174:175], v[174:175], v[30:31]
	s_waitcnt vmcnt(20)
	v_pk_add_f32 v[160:161], v[160:161], v[32:33]
	v_pk_add_f32 v[162:163], v[162:163], v[34:35]
	v_pk_add_f32 v[164:165], v[164:165], v[36:37]
	v_pk_add_f32 v[166:167], v[166:167], v[38:39]
	v_pk_add_f32 v[168:169], v[168:169], v[40:41]
	v_pk_add_f32 v[170:171], v[170:171], v[42:43]
	v_pk_add_f32 v[172:173], v[172:173], v[44:45]
	v_pk_add_f32 v[174:175], v[174:175], v[46:47]
	s_waitcnt vmcnt(16)
	v_pk_add_f32 v[160:161], v[160:161], v[48:49]
	v_pk_add_f32 v[162:163], v[162:163], v[50:51]
	v_pk_add_f32 v[164:165], v[164:165], v[52:53]
	v_pk_add_f32 v[166:167], v[166:167], v[54:55]
	v_pk_add_f32 v[168:169], v[168:169], v[56:57]
	v_pk_add_f32 v[170:171], v[170:171], v[58:59]
	v_pk_add_f32 v[172:173], v[172:173], v[60:61]
	v_pk_add_f32 v[174:175], v[174:175], v[62:63]
	s_waitcnt vmcnt(12)
	v_pk_add_f32 v[160:161], v[160:161], v[64:65]
	v_pk_add_f32 v[162:163], v[162:163], v[66:67]
	v_pk_add_f32 v[164:165], v[164:165], v[68:69]
	v_pk_add_f32 v[166:167], v[166:167], v[70:71]
	v_pk_add_f32 v[168:169], v[168:169], v[72:73]
	v_pk_add_f32 v[170:171], v[170:171], v[74:75]
	v_pk_add_f32 v[172:173], v[172:173], v[76:77]
	v_pk_add_f32 v[174:175], v[174:175], v[78:79]
	s_waitcnt vmcnt(8)
	v_pk_add_f32 v[160:161], v[160:161], v[80:81]
	v_pk_add_f32 v[162:163], v[162:163], v[82:83]
	v_pk_add_f32 v[164:165], v[164:165], v[84:85]
	v_pk_add_f32 v[166:167], v[166:167], v[86:87]
	v_pk_add_f32 v[168:169], v[168:169], v[88:89]
	v_pk_add_f32 v[170:171], v[170:171], v[90:91]
	v_pk_add_f32 v[172:173], v[172:173], v[92:93]
	v_pk_add_f32 v[174:175], v[174:175], v[94:95]
	s_waitcnt vmcnt(4)
	v_pk_add_f32 v[160:161], v[160:161], v[96:97]
	v_pk_add_f32 v[162:163], v[162:163], v[98:99]
	v_pk_add_f32 v[164:165], v[164:165], v[100:101]
	v_pk_add_f32 v[166:167], v[166:167], v[102:103]
	v_pk_add_f32 v[168:169], v[168:169], v[104:105]
	v_pk_add_f32 v[170:171], v[170:171], v[106:107]
	v_pk_add_f32 v[172:173], v[172:173], v[108:109]
	v_pk_add_f32 v[174:175], v[174:175], v[110:111]
	s_waitcnt vmcnt(0)
	v_pk_add_f32 v[160:161], v[160:161], v[112:113]
	v_pk_add_f32 v[162:163], v[162:163], v[114:115]
	v_pk_add_f32 v[164:165], v[164:165], v[116:117]
	v_pk_add_f32 v[166:167], v[166:167], v[118:119]
	v_pk_add_f32 v[168:169], v[168:169], v[120:121]
	v_pk_add_f32 v[170:171], v[170:171], v[122:123]
	v_pk_add_f32 v[172:173], v[172:173], v[124:125]
	v_pk_add_f32 v[174:175], v[174:175], v[126:127]
	v_lshlrev_b32_e32 v144, 16, v240
	v_and_b32_e32 v145, 0xffff0000, v240
	v_lshlrev_b32_e32 v146, 16, v241
	v_and_b32_e32 v147, 0xffff0000, v241
	v_lshlrev_b32_e32 v148, 16, v242
	v_and_b32_e32 v149, 0xffff0000, v242
	v_lshlrev_b32_e32 v150, 16, v243
	v_and_b32_e32 v151, 0xffff0000, v243
	v_lshlrev_b32_e32 v152, 16, v244
	v_and_b32_e32 v153, 0xffff0000, v244
	v_lshlrev_b32_e32 v154, 16, v245
	v_and_b32_e32 v155, 0xffff0000, v245
	v_lshlrev_b32_e32 v156, 16, v246
	v_and_b32_e32 v157, 0xffff0000, v246
	v_lshlrev_b32_e32 v158, 16, v247
	v_and_b32_e32 v159, 0xffff0000, v247
	v_pk_mul_f32 v[252:253], v[160:161], v[160:161]
	v_pk_mul_f32 v[254:255], v[162:163], v[162:163]
	v_pk_fma_f32 v[252:253], v[164:165], v[164:165], v[252:253]
	v_pk_fma_f32 v[254:255], v[166:167], v[166:167], v[254:255]
	v_pk_fma_f32 v[252:253], v[168:169], v[168:169], v[252:253]
	v_pk_fma_f32 v[254:255], v[170:171], v[170:171], v[254:255]
	v_pk_fma_f32 v[252:253], v[172:173], v[172:173], v[252:253]
	v_pk_fma_f32 v[254:255], v[174:175], v[174:175], v[254:255]
	v_pk_add_f32 v[252:253], v[252:253], v[254:255]
	s_nop 0
	v_add_f32_e32 v183, v252, v253
	s_nop 1
	v_add_f32_dpp v183, v183, v183 quad_perm:[1,0,3,2] row_mask:0xf bank_mask:0xf bound_ctrl:1
	s_nop 1
	v_add_f32_dpp v183, v183, v183 quad_perm:[2,3,0,1] row_mask:0xf bank_mask:0xf bound_ctrl:1
	s_nop 1
	v_add_f32_dpp v183, v183, v183 row_half_mirror row_mask:0xf bank_mask:0xf bound_ctrl:1
	s_nop 1
	v_add_f32_dpp v183, v183, v183 row_mirror row_mask:0xf bank_mask:0xf bound_ctrl:1
	s_nop 1
	v_readlane_b32 s98, v183, 0
	v_readlane_b32 s99, v183, 16
	v_readlane_b32 s100, v183, 32
	v_readlane_b32 s101, v183, 48
	s_nop 1
	v_mov_b32_e32 v183, s98
	v_add_f32_e32 v183, s99, v183
	v_add_f32_e32 v183, s100, v183
	v_add_f32_e32 v183, s101, v183
	v_fmamk_f32 v183, v183, 0x3a800000, v182
	v_cmp_gt_f32_e32 vcc, 0x800000, v183
	v_mul_f32_e32 v181, 0x4b800000, v183
	s_nop 1
	v_cndmask_b32_e32 v183, v183, v181, vcc
	v_rsq_f32_e32 v183, v183
	s_nop 0
	v_mul_f32_e32 v181, 0x45800000, v183
	v_cndmask_b32_e32 v184, v183, v181, vcc
	v_mov_b32_e32 v185, v184
	v_pk_mul_f32 v[160:161], v[160:161], v[184:185]
	v_pk_mul_f32 v[162:163], v[162:163], v[184:185]
	v_pk_mul_f32 v[164:165], v[164:165], v[184:185]
	v_pk_mul_f32 v[166:167], v[166:167], v[184:185]
	v_pk_mul_f32 v[168:169], v[168:169], v[184:185]
	v_pk_mul_f32 v[170:171], v[170:171], v[184:185]
	v_pk_mul_f32 v[172:173], v[172:173], v[184:185]
	v_pk_mul_f32 v[174:175], v[174:175], v[184:185]
	v_pk_fma_f32 v[144:145], v[160:161], v[128:129], v[144:145]
	v_pk_fma_f32 v[146:147], v[162:163], v[130:131], v[146:147]
	v_pk_fma_f32 v[148:149], v[164:165], v[132:133], v[148:149]
	v_pk_fma_f32 v[150:151], v[166:167], v[134:135], v[150:151]
	v_pk_fma_f32 v[152:153], v[168:169], v[136:137], v[152:153]
	v_pk_fma_f32 v[154:155], v[170:171], v[138:139], v[154:155]
	v_pk_fma_f32 v[156:157], v[172:173], v[140:141], v[156:157]
	v_pk_fma_f32 v[158:159], v[174:175], v[142:143], v[158:159]
	v_pk_mul_f32 v[252:253], v[144:145], v[144:145]
	v_pk_mul_f32 v[254:255], v[146:147], v[146:147]
	v_pk_fma_f32 v[252:253], v[148:149], v[148:149], v[252:253]
	v_pk_fma_f32 v[254:255], v[150:151], v[150:151], v[254:255]
	v_pk_fma_f32 v[252:253], v[152:153], v[152:153], v[252:253]
	v_pk_fma_f32 v[254:255], v[154:155], v[154:155], v[254:255]
	v_pk_fma_f32 v[252:253], v[156:157], v[156:157], v[252:253]
	v_pk_fma_f32 v[254:255], v[158:159], v[158:159], v[254:255]
	v_pk_add_f32 v[252:253], v[252:253], v[254:255]
	s_nop 0
	v_add_f32_e32 v183, v252, v253
	s_nop 1
	v_add_f32_dpp v183, v183, v183 quad_perm:[1,0,3,2] row_mask:0xf bank_mask:0xf bound_ctrl:1
	s_nop 1
	v_add_f32_dpp v183, v183, v183 quad_perm:[2,3,0,1] row_mask:0xf bank_mask:0xf bound_ctrl:1
	s_nop 1
	v_add_f32_dpp v183, v183, v183 row_half_mirror row_mask:0xf bank_mask:0xf bound_ctrl:1
	s_nop 1
	v_add_f32_dpp v183, v183, v183 row_mirror row_mask:0xf bank_mask:0xf bound_ctrl:1
	s_nop 1
	v_readlane_b32 s98, v183, 0
	v_readlane_b32 s99, v183, 16
	v_readlane_b32 s100, v183, 32
	v_readlane_b32 s101, v183, 48
	s_nop 1
	v_mov_b32_e32 v183, s98
	v_add_f32_e32 v183, s99, v183
	v_add_f32_e32 v183, s100, v183
	v_add_f32_e32 v183, s101, v183
	v_fmamk_f32 v183, v183, 0x3a800000, v182
	v_cmp_gt_f32_e32 vcc, 0x800000, v183
	v_mul_f32_e32 v181, 0x4b800000, v183
	s_nop 1
	v_cndmask_b32_e32 v183, v183, v181, vcc
	v_rsq_f32_e32 v183, v183
	s_nop 0
	v_mul_f32_e32 v181, 0x45800000, v183
	v_cndmask_b32_e32 v184, v183, v181, vcc
	v_mov_b32_e32 v185, v184
	v_cvt_pk_bf16_f32 v0, v144, v145
	v_cvt_pk_bf16_f32 v1, v146, v147
	v_cvt_pk_bf16_f32 v2, v148, v149
	v_cvt_pk_bf16_f32 v3, v150, v151
	v_cvt_pk_bf16_f32 v4, v152, v153
	v_cvt_pk_bf16_f32 v5, v154, v155
	v_cvt_pk_bf16_f32 v6, v156, v157
	v_cvt_pk_bf16_f32 v7, v158, v159
	v_add_u32_e32 v181, 0x3800000, v177
	global_store_dwordx4 v181, v[0:3], s[78:79]
	global_store_dwordx4 v181, v[4:7], s[78:79] offset:1024
	v_add_u32_e32 v236, 0x10000, v237
	s_mov_b64 exec, 1
	global_store_dword v236, v184, s[78:79]
	s_mov_b64 exec, -1

.LBB0_721:
	v_readlane_b32 s0, v235, 52
	v_readlane_b32 s1, v235, 53
	s_and_b64 vcc, exec, s[0:1]
	s_waitcnt lgkmcnt(0)
	s_barrier
	v_mbcnt_lo_u32_b32 v0, -1, 0
	v_mbcnt_hi_u32_b32 v0, -1, v0
	v_writelane_b32 v234, s93, 4
	s_cbranch_vccnz .LBB0_741
	v_readlane_b32 s4, v235, 4
	v_readlane_b32 s8, v235, 8
	v_readlane_b32 s9, v235, 9
	v_readlane_b32 s6, v235, 6
	v_readlane_b32 s7, v235, 7
	v_readlane_b32 s12, v235, 12
	v_readlane_b32 s13, v235, 13
	v_readlane_b32 s8, v235, 61
	v_readlane_b32 s10, v235, 10
	v_readlane_b32 s6, v235, 0
	v_readlane_b32 s9, v235, 62
	s_mov_b32 s12, s8
	s_ashr_i32 s13, s8, 31
	v_lshlrev_b32_e32 v2, 3, v0
	v_readlane_b32 s11, v235, 11
	s_lshl_b32 s6, s6, 4
	s_add_i32 s0, s8, 0xffffc000
	s_lshl_b64 s[8:9], s[12:13], 2
	s_mov_b32 s10, s12
	v_ashrrev_i32_e32 v3, 31, v2
	v_readlane_b32 s5, v235, 5
	v_readlane_b32 s14, v235, 14
	v_readlane_b32 s15, v235, 15
	v_readlane_b32 s16, v235, 16
	v_readlane_b32 s17, v235, 17
	v_readlane_b32 s18, v235, 18
	v_readlane_b32 s19, v235, 19
	v_readlane_b32 s7, v235, 1
	s_add_u32 s80, s8, 0x10000
	v_writelane_b32 v235, s10, 61
	v_lshlrev_b64 v[4:5], 1, v[2:3]
	v_lshlrev_b64 v[2:3], 2, v[2:3]
	s_addc_u32 s14, s9, 0
	s_ashr_i32 s7, s6, 31
	v_writelane_b32 v235, s11, 62
	s_lshl_b64 s[10:11], s[12:13], 11
	v_lshl_add_u64 v[152:153], s[86:87], 0, v[4:5]
	v_lshl_add_u64 v[154:155], s[90:91], 0, v[2:3]
	v_lshl_add_u64 v[156:157], s[54:55], 0, v[4:5]
	v_lshl_add_u64 v[158:159], s[18:19], 0, v[2:3]
	s_mov_b32 s1, 0
	v_cmp_eq_u32_e64 s[4:5], 0, v0
	s_lshl_b64 s[8:9], s[6:7], 2
	v_lshl_add_u64 v[160:161], s[10:11], 0, v[4:5]
	s_lshl_b64 s[10:11], s[6:7], 11
	s_mov_b64 s[24:25], 0x600000
	s_mov_b64 s[26:27], 0x600800
	s_mov_b64 s[28:29], 0x800000
	s_mov_b32 s7, 0x800000
	s_mov_b64 s[36:37], 0x800800
	s_mov_b64 s[38:39], 0xa00000
	s_mov_b64 s[40:41], 0xa00800
	s_mov_b64 s[42:43], 0xc00000
	s_mov_b64 s[44:45], 0xc00800
	s_mov_b64 s[46:47], 0xe00000
	s_mov_b64 s[48:49], 0xe00800
	s_mov_b64 s[50:51], 0x1000000
	s_mov_b32 s15, 0x1000000
	s_mov_b64 s[12:13], 0x1000800
	s_mov_b64 s[82:83], 0x1200000
	s_mov_b32 s16, 0x1200000
	s_mov_b64 s[90:91], 0x1200800
	s_mov_b64 s[20:21], 0x1400000
	s_mov_b32 s17, 0x1400000
	s_mov_b64 s[22:23], 0x1400800
	v_mov_b32_e32 v215, 0
	v_mov_b32_e32 v216, 0x358637bd
	v_mbcnt_lo_u32_b32 v176, -1, 0
	v_mbcnt_hi_u32_b32 v176, -1, v176
	v_readlane_b32 s98, v235, 49
	v_readlane_b32 s99, v235, 20
	v_readlane_b32 s100, v235, 18
	v_readlane_b32 s101, v235, 19
	s_nop 3
	s_lshr_b32 vcc_lo, s98, 3
	s_and_b32 vcc_hi, vcc_lo, 7
	s_lshr_b32 vcc_lo, vcc_lo, 3
	s_lshl_b32 vcc_lo, vcc_lo, 3
	s_add_i32 vcc_lo, vcc_lo, s99
	s_lshl_b32 s98, vcc_hi, 8
	s_add_i32 s98, s98, vcc_lo
	s_mov_b32 s99, s98
	v_mov_b32_e32 v183, s99
	v_lshlrev_b32_e32 v177, 4, v176
	s_lshl_b32 s99, s99, 11
	v_add_u32_e32 v177, s99, v177
	v_add_u32_e32 v178, 0x1800000, v177
	v_add_u32_e32 v179, 0x9e00000, v177
	v_lshlrev_b32_e32 v180, 5, v176
	global_load_dwordx4 v[128:131], v180, s[100:101]
	global_load_dwordx4 v[132:135], v180, s[100:101] offset:16
	global_load_dwordx4 v[136:139], v180, s[100:101] offset:2048
	global_load_dwordx4 v[140:143], v180, s[100:101] offset:2064
	v_mov_b32_e32 v182, 0x358637bd
	global_load_dwordx4 v[0:3], v178, s[78:79]
	global_load_dwordx4 v[4:7], v178, s[78:79] offset:1024
	global_load_dwordx4 v[8:11], v179, s[78:79]
	global_load_dwordx4 v[12:15], v179, s[78:79] offset:1024
	v_add_u32_e32 v178, 0x400000, v178
	v_add_u32_e32 v179, 0x400000, v179
	global_load_dwordx4 v[16:19], v178, s[78:79]
	global_load_dwordx4 v[20:23], v178, s[78:79] offset:1024
	global_load_dwordx4 v[24:27], v179, s[78:79]
	global_load_dwordx4 v[28:31], v179, s[78:79] offset:1024
	v_add_u32_e32 v178, 0x400000, v178
	v_add_u32_e32 v179, 0x400000, v179
	global_load_dwordx4 v[32:35], v178, s[78:79]
	global_load_dwordx4 v[36:39], v178, s[78:79] offset:1024
	global_load_dwordx4 v[40:43], v179, s[78:79]
	global_load_dwordx4 v[44:47], v179, s[78:79] offset:1024
	v_add_u32_e32 v178, 0x400000, v178
	v_add_u32_e32 v179, 0x400000, v179
	global_load_dwordx4 v[48:51], v178, s[78:79]
	global_load_dwordx4 v[52:55], v178, s[78:79] offset:1024
	global_load_dwordx4 v[56:59], v179, s[78:79]
	global_load_dwordx4 v[60:63], v179, s[78:79] offset:1024
	v_add_u32_e32 v178, 0x400000, v178
	v_add_u32_e32 v179, 0x400000, v179
	global_load_dwordx4 v[64:67], v178, s[78:79]
	global_load_dwordx4 v[68:71], v178, s[78:79] offset:1024
	global_load_dwordx4 v[72:75], v179, s[78:79]
	global_load_dwordx4 v[76:79], v179, s[78:79] offset:1024
	v_add_u32_e32 v178, 0x400000, v178
	v_add_u32_e32 v179, 0x400000, v179
	global_load_dwordx4 v[80:83], v178, s[78:79]
	global_load_dwordx4 v[84:87], v178, s[78:79] offset:1024
	global_load_dwordx4 v[88:91], v179, s[78:79]
	global_load_dwordx4 v[92:95], v179, s[78:79] offset:1024
	v_add_u32_e32 v178, 0x400000, v178
	v_add_u32_e32 v179, 0x400000, v179
	global_load_dwordx4 v[96:99], v178, s[78:79]
	global_load_dwordx4 v[100:103], v178, s[78:79] offset:1024
	global_load_dwordx4 v[104:107], v179, s[78:79]
	global_load_dwordx4 v[108:111], v179, s[78:79] offset:1024
	v_add_u32_e32 v178, 0x400000, v178
	v_add_u32_e32 v179, 0x400000, v179
	global_load_dwordx4 v[112:115], v178, s[78:79]
	global_load_dwordx4 v[116:119], v178, s[78:79] offset:1024
	global_load_dwordx4 v[120:123], v179, s[78:79]
	global_load_dwordx4 v[124:127], v179, s[78:79] offset:1024
	v_lshlrev_b32_e32 v237, 2, v183
	v_add_u32_e32 v237, 0x10000, v237
	v_mov_b32_e32 v179, s98
	s_waitcnt vmcnt(28)
	v_lshlrev_b32_e32 v144, 16, v0
	v_and_b32_e32 v145, 0xffff0000, v0
	v_lshlrev_b32_e32 v146, 16, v1
	v_and_b32_e32 v147, 0xffff0000, v1
	v_lshlrev_b32_e32 v148, 16, v2
	v_and_b32_e32 v149, 0xffff0000, v2
	v_lshlrev_b32_e32 v150, 16, v3
	v_and_b32_e32 v151, 0xffff0000, v3
	v_lshlrev_b32_e32 v152, 16, v4
	v_and_b32_e32 v153, 0xffff0000, v4
	v_lshlrev_b32_e32 v154, 16, v5
	v_and_b32_e32 v155, 0xffff0000, v5
	v_lshlrev_b32_e32 v156, 16, v6
	v_and_b32_e32 v157, 0xffff0000, v6
	v_lshlrev_b32_e32 v158, 16, v7
	v_and_b32_e32 v159, 0xffff0000, v7
	v_lshlrev_b32_e32 v160, 16, v8
	v_and_b32_e32 v161, 0xffff0000, v8
	v_lshlrev_b32_e32 v162, 16, v9
	v_and_b32_e32 v163, 0xffff0000, v9
	v_lshlrev_b32_e32 v164, 16, v10
	v_and_b32_e32 v165, 0xffff0000, v10
	v_lshlrev_b32_e32 v166, 16, v11
	v_and_b32_e32 v167, 0xffff0000, v11
	v_lshlrev_b32_e32 v168, 16, v12
	v_and_b32_e32 v169, 0xffff0000, v12
	v_lshlrev_b32_e32 v170, 16, v13
	v_and_b32_e32 v171, 0xffff0000, v13
	v_lshlrev_b32_e32 v172, 16, v14
	v_and_b32_e32 v173, 0xffff0000, v14
	v_lshlrev_b32_e32 v174, 16, v15
	v_and_b32_e32 v175, 0xffff0000, v15
	v_pk_mul_f32 v[252:253], v[160:161], v[160:161]
	v_pk_mul_f32 v[254:255], v[162:163], v[162:163]
	v_pk_fma_f32 v[252:253], v[164:165], v[164:165], v[252:253]
	v_pk_fma_f32 v[254:255], v[166:167], v[166:167], v[254:255]
	v_pk_fma_f32 v[252:253], v[168:169], v[168:169], v[252:253]
	v_pk_fma_f32 v[254:255], v[170:171], v[170:171], v[254:255]
	v_pk_fma_f32 v[252:253], v[172:173], v[172:173], v[252:253]
	v_pk_fma_f32 v[254:255], v[174:175], v[174:175], v[254:255]
	v_pk_add_f32 v[252:253], v[252:253], v[254:255]
	s_nop 0
	v_add_f32_e32 v183, v252, v253
	s_nop 1
	v_add_f32_dpp v183, v183, v183 quad_perm:[1,0,3,2] row_mask:0xf bank_mask:0xf bound_ctrl:1
	s_nop 1
	v_add_f32_dpp v183, v183, v183 quad_perm:[2,3,0,1] row_mask:0xf bank_mask:0xf bound_ctrl:1
	s_nop 1
	v_add_f32_dpp v183, v183, v183 row_half_mirror row_mask:0xf bank_mask:0xf bound_ctrl:1
	s_nop 1
	v_add_f32_dpp v183, v183, v183 row_mirror row_mask:0xf bank_mask:0xf bound_ctrl:1
	s_nop 1
	v_readlane_b32 s98, v183, 0
	v_readlane_b32 s99, v183, 16
	v_readlane_b32 s100, v183, 32
	v_readlane_b32 s101, v183, 48
	s_nop 1
	v_mov_b32_e32 v183, s98
	v_add_f32_e32 v183, s99, v183
	v_add_f32_e32 v183, s100, v183
	v_add_f32_e32 v183, s101, v183
	v_fmamk_f32 v183, v183, 0x3a800000, v182
	v_cmp_gt_f32_e32 vcc, 0x800000, v183
	v_mul_f32_e32 v181, 0x4b800000, v183
	s_nop 1
	v_cndmask_b32_e32 v183, v183, v181, vcc
	v_rsq_f32_e32 v183, v183
	s_nop 0
	v_mul_f32_e32 v181, 0x45800000, v183
	v_cndmask_b32_e32 v184, v183, v181, vcc
	v_mov_b32_e32 v185, v184
	v_pk_mul_f32 v[160:161], v[160:161], v[184:185]
	v_pk_mul_f32 v[162:163], v[162:163], v[184:185]
	v_pk_mul_f32 v[164:165], v[164:165], v[184:185]
	v_pk_mul_f32 v[166:167], v[166:167], v[184:185]
	v_pk_mul_f32 v[168:169], v[168:169], v[184:185]
	v_pk_mul_f32 v[170:171], v[170:171], v[184:185]
	v_pk_mul_f32 v[172:173], v[172:173], v[184:185]
	v_pk_mul_f32 v[174:175], v[174:175], v[184:185]
	v_pk_fma_f32 v[144:145], v[160:161], v[128:129], v[144:145]
	v_pk_fma_f32 v[146:147], v[162:163], v[130:131], v[146:147]
	v_pk_fma_f32 v[148:149], v[164:165], v[132:133], v[148:149]
	v_pk_fma_f32 v[150:151], v[166:167], v[134:135], v[150:151]
	v_pk_fma_f32 v[152:153], v[168:169], v[136:137], v[152:153]
	v_pk_fma_f32 v[154:155], v[170:171], v[138:139], v[154:155]
	v_pk_fma_f32 v[156:157], v[172:173], v[140:141], v[156:157]
	v_pk_fma_f32 v[158:159], v[174:175], v[142:143], v[158:159]
	v_pk_mul_f32 v[252:253], v[144:145], v[144:145]
	v_pk_mul_f32 v[254:255], v[146:147], v[146:147]
	v_pk_fma_f32 v[252:253], v[148:149], v[148:149], v[252:253]
	v_pk_fma_f32 v[254:255], v[150:151], v[150:151], v[254:255]
	v_pk_fma_f32 v[252:253], v[152:153], v[152:153], v[252:253]
	v_pk_fma_f32 v[254:255], v[154:155], v[154:155], v[254:255]
	v_pk_fma_f32 v[252:253], v[156:157], v[156:157], v[252:253]
	v_pk_fma_f32 v[254:255], v[158:159], v[158:159], v[254:255]
	v_pk_add_f32 v[252:253], v[252:253], v[254:255]
	s_nop 0
	v_add_f32_e32 v183, v252, v253
	s_nop 1
	v_add_f32_dpp v183, v183, v183 quad_perm:[1,0,3,2] row_mask:0xf bank_mask:0xf bound_ctrl:1
	s_nop 1
	v_add_f32_dpp v183, v183, v183 quad_perm:[2,3,0,1] row_mask:0xf bank_mask:0xf bound_ctrl:1
	s_nop 1
	v_add_f32_dpp v183, v183, v183 row_half_mirror row_mask:0xf bank_mask:0xf bound_ctrl:1
	s_nop 1
	v_add_f32_dpp v183, v183, v183 row_mirror row_mask:0xf bank_mask:0xf bound_ctrl:1
	s_nop 1
	v_readlane_b32 s98, v183, 0
	v_readlane_b32 s99, v183, 16
	v_readlane_b32 s100, v183, 32
	v_readlane_b32 s101, v183, 48
	s_nop 1
	v_mov_b32_e32 v183, s98
	v_add_f32_e32 v183, s99, v183
	v_add_f32_e32 v183, s100, v183
	v_add_f32_e32 v183, s101, v183
	v_fmamk_f32 v183, v183, 0x3a800000, v182
	v_cmp_gt_f32_e32 vcc, 0x800000, v183
	v_mul_f32_e32 v181, 0x4b800000, v183
	s_nop 1
	v_cndmask_b32_e32 v183, v183, v181, vcc
	v_rsq_f32_e32 v183, v183
	s_nop 0
	v_mul_f32_e32 v181, 0x45800000, v183
	v_cndmask_b32_e32 v184, v183, v181, vcc
	v_mov_b32_e32 v185, v184
	v_cvt_pk_bf16_f32 v0, v144, v145
	v_cvt_pk_bf16_f32 v1, v146, v147
	v_cvt_pk_bf16_f32 v2, v148, v149
	v_cvt_pk_bf16_f32 v3, v150, v151
	v_cvt_pk_bf16_f32 v4, v152, v153
	v_cvt_pk_bf16_f32 v5, v154, v155
	v_cvt_pk_bf16_f32 v6, v156, v157
	v_cvt_pk_bf16_f32 v7, v158, v159
	v_add_u32_e32 v181, 0x1800000, v177
	global_store_dwordx4 v181, v[0:3], s[78:79]
	global_store_dwordx4 v181, v[4:7], s[78:79] offset:1024
	v_add_u32_e32 v236, 0x0, v237
	s_mov_b64 exec, 1
	global_store_dword v236, v184, s[78:79]
	s_mov_b64 exec, -1
	s_waitcnt vmcnt(24)
	v_lshlrev_b32_e32 v144, 16, v16
	v_and_b32_e32 v145, 0xffff0000, v16
	v_lshlrev_b32_e32 v146, 16, v17
	v_and_b32_e32 v147, 0xffff0000, v17
	v_lshlrev_b32_e32 v148, 16, v18
	v_and_b32_e32 v149, 0xffff0000, v18
	v_lshlrev_b32_e32 v150, 16, v19
	v_and_b32_e32 v151, 0xffff0000, v19
	v_lshlrev_b32_e32 v152, 16, v20
	v_and_b32_e32 v153, 0xffff0000, v20
	v_lshlrev_b32_e32 v154, 16, v21
	v_and_b32_e32 v155, 0xffff0000, v21
	v_lshlrev_b32_e32 v156, 16, v22
	v_and_b32_e32 v157, 0xffff0000, v22
	v_lshlrev_b32_e32 v158, 16, v23
	v_and_b32_e32 v159, 0xffff0000, v23
	v_lshlrev_b32_e32 v160, 16, v24
	v_and_b32_e32 v161, 0xffff0000, v24
	v_lshlrev_b32_e32 v162, 16, v25
	v_and_b32_e32 v163, 0xffff0000, v25
	v_lshlrev_b32_e32 v164, 16, v26
	v_and_b32_e32 v165, 0xffff0000, v26
	v_lshlrev_b32_e32 v166, 16, v27
	v_and_b32_e32 v167, 0xffff0000, v27
	v_lshlrev_b32_e32 v168, 16, v28
	v_and_b32_e32 v169, 0xffff0000, v28
	v_lshlrev_b32_e32 v170, 16, v29
	v_and_b32_e32 v171, 0xffff0000, v29
	v_lshlrev_b32_e32 v172, 16, v30
	v_and_b32_e32 v173, 0xffff0000, v30
	v_lshlrev_b32_e32 v174, 16, v31
	v_and_b32_e32 v175, 0xffff0000, v31
	v_pk_mul_f32 v[252:253], v[160:161], v[160:161]
	v_pk_mul_f32 v[254:255], v[162:163], v[162:163]
	v_pk_fma_f32 v[252:253], v[164:165], v[164:165], v[252:253]
	v_pk_fma_f32 v[254:255], v[166:167], v[166:167], v[254:255]
	v_pk_fma_f32 v[252:253], v[168:169], v[168:169], v[252:253]
	v_pk_fma_f32 v[254:255], v[170:171], v[170:171], v[254:255]
	v_pk_fma_f32 v[252:253], v[172:173], v[172:173], v[252:253]
	v_pk_fma_f32 v[254:255], v[174:175], v[174:175], v[254:255]
	v_pk_add_f32 v[252:253], v[252:253], v[254:255]
	s_nop 0
	v_add_f32_e32 v183, v252, v253
	s_nop 1
	v_add_f32_dpp v183, v183, v183 quad_perm:[1,0,3,2] row_mask:0xf bank_mask:0xf bound_ctrl:1
	s_nop 1
	v_add_f32_dpp v183, v183, v183 quad_perm:[2,3,0,1] row_mask:0xf bank_mask:0xf bound_ctrl:1
	s_nop 1
	v_add_f32_dpp v183, v183, v183 row_half_mirror row_mask:0xf bank_mask:0xf bound_ctrl:1
	s_nop 1
	v_add_f32_dpp v183, v183, v183 row_mirror row_mask:0xf bank_mask:0xf bound_ctrl:1
	s_nop 1
	v_readlane_b32 s98, v183, 0
	v_readlane_b32 s99, v183, 16
	v_readlane_b32 s100, v183, 32
	v_readlane_b32 s101, v183, 48
	s_nop 1
	v_mov_b32_e32 v183, s98
	v_add_f32_e32 v183, s99, v183
	v_add_f32_e32 v183, s100, v183
	v_add_f32_e32 v183, s101, v183
	v_fmamk_f32 v183, v183, 0x3a800000, v182
	v_cmp_gt_f32_e32 vcc, 0x800000, v183
	v_mul_f32_e32 v181, 0x4b800000, v183
	s_nop 1
	v_cndmask_b32_e32 v183, v183, v181, vcc
	v_rsq_f32_e32 v183, v183
	s_nop 0
	v_mul_f32_e32 v181, 0x45800000, v183
	v_cndmask_b32_e32 v184, v183, v181, vcc
	v_mov_b32_e32 v185, v184
	v_pk_mul_f32 v[160:161], v[160:161], v[184:185]
	v_pk_mul_f32 v[162:163], v[162:163], v[184:185]
	v_pk_mul_f32 v[164:165], v[164:165], v[184:185]
	v_pk_mul_f32 v[166:167], v[166:167], v[184:185]
	v_pk_mul_f32 v[168:169], v[168:169], v[184:185]
	v_pk_mul_f32 v[170:171], v[170:171], v[184:185]
	v_pk_mul_f32 v[172:173], v[172:173], v[184:185]
	v_pk_mul_f32 v[174:175], v[174:175], v[184:185]
	v_pk_fma_f32 v[144:145], v[160:161], v[128:129], v[144:145]
	v_pk_fma_f32 v[146:147], v[162:163], v[130:131], v[146:147]
	v_pk_fma_f32 v[148:149], v[164:165], v[132:133], v[148:149]
	v_pk_fma_f32 v[150:151], v[166:167], v[134:135], v[150:151]
	v_pk_fma_f32 v[152:153], v[168:169], v[136:137], v[152:153]
	v_pk_fma_f32 v[154:155], v[170:171], v[138:139], v[154:155]
	v_pk_fma_f32 v[156:157], v[172:173], v[140:141], v[156:157]
	v_pk_fma_f32 v[158:159], v[174:175], v[142:143], v[158:159]
	v_pk_mul_f32 v[252:253], v[144:145], v[144:145]
	v_pk_mul_f32 v[254:255], v[146:147], v[146:147]
	v_pk_fma_f32 v[252:253], v[148:149], v[148:149], v[252:253]
	v_pk_fma_f32 v[254:255], v[150:151], v[150:151], v[254:255]
	v_pk_fma_f32 v[252:253], v[152:153], v[152:153], v[252:253]
	v_pk_fma_f32 v[254:255], v[154:155], v[154:155], v[254:255]
	v_pk_fma_f32 v[252:253], v[156:157], v[156:157], v[252:253]
	v_pk_fma_f32 v[254:255], v[158:159], v[158:159], v[254:255]
	v_pk_add_f32 v[252:253], v[252:253], v[254:255]
	s_nop 0
	v_add_f32_e32 v183, v252, v253
	s_nop 1
	v_add_f32_dpp v183, v183, v183 quad_perm:[1,0,3,2] row_mask:0xf bank_mask:0xf bound_ctrl:1
	s_nop 1
	v_add_f32_dpp v183, v183, v183 quad_perm:[2,3,0,1] row_mask:0xf bank_mask:0xf bound_ctrl:1
	s_nop 1
	v_add_f32_dpp v183, v183, v183 row_half_mirror row_mask:0xf bank_mask:0xf bound_ctrl:1
	s_nop 1
	v_add_f32_dpp v183, v183, v183 row_mirror row_mask:0xf bank_mask:0xf bound_ctrl:1
	s_nop 1
	v_readlane_b32 s98, v183, 0
	v_readlane_b32 s99, v183, 16
	v_readlane_b32 s100, v183, 32
	v_readlane_b32 s101, v183, 48
	s_nop 1
	v_mov_b32_e32 v183, s98
	v_add_f32_e32 v183, s99, v183
	v_add_f32_e32 v183, s100, v183
	v_add_f32_e32 v183, s101, v183
	v_fmamk_f32 v183, v183, 0x3a800000, v182
	v_cmp_gt_f32_e32 vcc, 0x800000, v183
	v_mul_f32_e32 v181, 0x4b800000, v183
	s_nop 1
	v_cndmask_b32_e32 v183, v183, v181, vcc
	v_rsq_f32_e32 v183, v183
	s_nop 0
	v_mul_f32_e32 v181, 0x45800000, v183
	v_cndmask_b32_e32 v184, v183, v181, vcc
	v_mov_b32_e32 v185, v184
	v_cvt_pk_bf16_f32 v16, v144, v145
	v_cvt_pk_bf16_f32 v17, v146, v147
	v_cvt_pk_bf16_f32 v18, v148, v149
	v_cvt_pk_bf16_f32 v19, v150, v151
	v_cvt_pk_bf16_f32 v20, v152, v153
	v_cvt_pk_bf16_f32 v21, v154, v155
	v_cvt_pk_bf16_f32 v22, v156, v157
	v_cvt_pk_bf16_f32 v23, v158, v159
	v_add_u32_e32 v181, 0x1c00000, v177
	global_store_dwordx4 v181, v[16:19], s[78:79]
	global_store_dwordx4 v181, v[20:23], s[78:79] offset:1024
	v_add_u32_e32 v236, 0x2000, v237
	s_mov_b64 exec, 1
	global_store_dword v236, v184, s[78:79]
	s_mov_b64 exec, -1
	s_waitcnt vmcnt(20)
	v_lshlrev_b32_e32 v144, 16, v32
	v_and_b32_e32 v145, 0xffff0000, v32
	v_lshlrev_b32_e32 v146, 16, v33
	v_and_b32_e32 v147, 0xffff0000, v33
	v_lshlrev_b32_e32 v148, 16, v34
	v_and_b32_e32 v149, 0xffff0000, v34
	v_lshlrev_b32_e32 v150, 16, v35
	v_and_b32_e32 v151, 0xffff0000, v35
	v_lshlrev_b32_e32 v152, 16, v36
	v_and_b32_e32 v153, 0xffff0000, v36
	v_lshlrev_b32_e32 v154, 16, v37
	v_and_b32_e32 v155, 0xffff0000, v37
	v_lshlrev_b32_e32 v156, 16, v38
	v_and_b32_e32 v157, 0xffff0000, v38
	v_lshlrev_b32_e32 v158, 16, v39
	v_and_b32_e32 v159, 0xffff0000, v39
	v_lshlrev_b32_e32 v160, 16, v40
	v_and_b32_e32 v161, 0xffff0000, v40
	v_lshlrev_b32_e32 v162, 16, v41
	v_and_b32_e32 v163, 0xffff0000, v41
	v_lshlrev_b32_e32 v164, 16, v42
	v_and_b32_e32 v165, 0xffff0000, v42
	v_lshlrev_b32_e32 v166, 16, v43
	v_and_b32_e32 v167, 0xffff0000, v43
	v_lshlrev_b32_e32 v168, 16, v44
	v_and_b32_e32 v169, 0xffff0000, v44
	v_lshlrev_b32_e32 v170, 16, v45
	v_and_b32_e32 v171, 0xffff0000, v45
	v_lshlrev_b32_e32 v172, 16, v46
	v_and_b32_e32 v173, 0xffff0000, v46
	v_lshlrev_b32_e32 v174, 16, v47
	v_and_b32_e32 v175, 0xffff0000, v47
	v_pk_mul_f32 v[252:253], v[160:161], v[160:161]
	v_pk_mul_f32 v[254:255], v[162:163], v[162:163]
	v_pk_fma_f32 v[252:253], v[164:165], v[164:165], v[252:253]
	v_pk_fma_f32 v[254:255], v[166:167], v[166:167], v[254:255]
	v_pk_fma_f32 v[252:253], v[168:169], v[168:169], v[252:253]
	v_pk_fma_f32 v[254:255], v[170:171], v[170:171], v[254:255]
	v_pk_fma_f32 v[252:253], v[172:173], v[172:173], v[252:253]
	v_pk_fma_f32 v[254:255], v[174:175], v[174:175], v[254:255]
	v_pk_add_f32 v[252:253], v[252:253], v[254:255]
	s_nop 0
	v_add_f32_e32 v183, v252, v253
	s_nop 1
	v_add_f32_dpp v183, v183, v183 quad_perm:[1,0,3,2] row_mask:0xf bank_mask:0xf bound_ctrl:1
	s_nop 1
	v_add_f32_dpp v183, v183, v183 quad_perm:[2,3,0,1] row_mask:0xf bank_mask:0xf bound_ctrl:1
	s_nop 1
	v_add_f32_dpp v183, v183, v183 row_half_mirror row_mask:0xf bank_mask:0xf bound_ctrl:1
	s_nop 1
	v_add_f32_dpp v183, v183, v183 row_mirror row_mask:0xf bank_mask:0xf bound_ctrl:1
	s_nop 1
	v_readlane_b32 s98, v183, 0
	v_readlane_b32 s99, v183, 16
	v_readlane_b32 s100, v183, 32
	v_readlane_b32 s101, v183, 48
	s_nop 1
	v_mov_b32_e32 v183, s98
	v_add_f32_e32 v183, s99, v183
	v_add_f32_e32 v183, s100, v183
	v_add_f32_e32 v183, s101, v183
	v_fmamk_f32 v183, v183, 0x3a800000, v182
	v_cmp_gt_f32_e32 vcc, 0x800000, v183
	v_mul_f32_e32 v181, 0x4b800000, v183
	s_nop 1
	v_cndmask_b32_e32 v183, v183, v181, vcc
	v_rsq_f32_e32 v183, v183
	s_nop 0
	v_mul_f32_e32 v181, 0x45800000, v183
	v_cndmask_b32_e32 v184, v183, v181, vcc
	v_mov_b32_e32 v185, v184
	v_pk_mul_f32 v[160:161], v[160:161], v[184:185]
	v_pk_mul_f32 v[162:163], v[162:163], v[184:185]
	v_pk_mul_f32 v[164:165], v[164:165], v[184:185]
	v_pk_mul_f32 v[166:167], v[166:167], v[184:185]
	v_pk_mul_f32 v[168:169], v[168:169], v[184:185]
	v_pk_mul_f32 v[170:171], v[170:171], v[184:185]
	v_pk_mul_f32 v[172:173], v[172:173], v[184:185]
	v_pk_mul_f32 v[174:175], v[174:175], v[184:185]
	v_pk_fma_f32 v[144:145], v[160:161], v[128:129], v[144:145]
	v_pk_fma_f32 v[146:147], v[162:163], v[130:131], v[146:147]
	v_pk_fma_f32 v[148:149], v[164:165], v[132:133], v[148:149]
	v_pk_fma_f32 v[150:151], v[166:167], v[134:135], v[150:151]
	v_pk_fma_f32 v[152:153], v[168:169], v[136:137], v[152:153]
	v_pk_fma_f32 v[154:155], v[170:171], v[138:139], v[154:155]
	v_pk_fma_f32 v[156:157], v[172:173], v[140:141], v[156:157]
	v_pk_fma_f32 v[158:159], v[174:175], v[142:143], v[158:159]
	v_pk_mul_f32 v[252:253], v[144:145], v[144:145]
	v_pk_mul_f32 v[254:255], v[146:147], v[146:147]
	v_pk_fma_f32 v[252:253], v[148:149], v[148:149], v[252:253]
	v_pk_fma_f32 v[254:255], v[150:151], v[150:151], v[254:255]
	v_pk_fma_f32 v[252:253], v[152:153], v[152:153], v[252:253]
	v_pk_fma_f32 v[254:255], v[154:155], v[154:155], v[254:255]
	v_pk_fma_f32 v[252:253], v[156:157], v[156:157], v[252:253]
	v_pk_fma_f32 v[254:255], v[158:159], v[158:159], v[254:255]
	v_pk_add_f32 v[252:253], v[252:253], v[254:255]
	s_nop 0
	v_add_f32_e32 v183, v252, v253
	s_nop 1
	v_add_f32_dpp v183, v183, v183 quad_perm:[1,0,3,2] row_mask:0xf bank_mask:0xf bound_ctrl:1
	s_nop 1
	v_add_f32_dpp v183, v183, v183 quad_perm:[2,3,0,1] row_mask:0xf bank_mask:0xf bound_ctrl:1
	s_nop 1
	v_add_f32_dpp v183, v183, v183 row_half_mirror row_mask:0xf bank_mask:0xf bound_ctrl:1
	s_nop 1
	v_add_f32_dpp v183, v183, v183 row_mirror row_mask:0xf bank_mask:0xf bound_ctrl:1
	s_nop 1
	v_readlane_b32 s98, v183, 0
	v_readlane_b32 s99, v183, 16
	v_readlane_b32 s100, v183, 32
	v_readlane_b32 s101, v183, 48
	s_nop 1
	v_mov_b32_e32 v183, s98
	v_add_f32_e32 v183, s99, v183
	v_add_f32_e32 v183, s100, v183
	v_add_f32_e32 v183, s101, v183
	v_fmamk_f32 v183, v183, 0x3a800000, v182
	v_cmp_gt_f32_e32 vcc, 0x800000, v183
	v_mul_f32_e32 v181, 0x4b800000, v183
	s_nop 1
	v_cndmask_b32_e32 v183, v183, v181, vcc
	v_rsq_f32_e32 v183, v183
	s_nop 0
	v_mul_f32_e32 v181, 0x45800000, v183
	v_cndmask_b32_e32 v184, v183, v181, vcc
	v_mov_b32_e32 v185, v184
	v_cvt_pk_bf16_f32 v32, v144, v145
	v_cvt_pk_bf16_f32 v33, v146, v147
	v_cvt_pk_bf16_f32 v34, v148, v149
	v_cvt_pk_bf16_f32 v35, v150, v151
	v_cvt_pk_bf16_f32 v36, v152, v153
	v_cvt_pk_bf16_f32 v37, v154, v155
	v_cvt_pk_bf16_f32 v38, v156, v157
	v_cvt_pk_bf16_f32 v39, v158, v159
	v_add_u32_e32 v181, 0x2000000, v177
	global_store_dwordx4 v181, v[32:35], s[78:79]
	global_store_dwordx4 v181, v[36:39], s[78:79] offset:1024
	v_add_u32_e32 v236, 0x4000, v237
	s_mov_b64 exec, 1
	global_store_dword v236, v184, s[78:79]
	s_mov_b64 exec, -1
	s_waitcnt vmcnt(16)
	v_lshlrev_b32_e32 v144, 16, v48
	v_and_b32_e32 v145, 0xffff0000, v48
	v_lshlrev_b32_e32 v146, 16, v49
	v_and_b32_e32 v147, 0xffff0000, v49
	v_lshlrev_b32_e32 v148, 16, v50
	v_and_b32_e32 v149, 0xffff0000, v50
	v_lshlrev_b32_e32 v150, 16, v51
	v_and_b32_e32 v151, 0xffff0000, v51
	v_lshlrev_b32_e32 v152, 16, v52
	v_and_b32_e32 v153, 0xffff0000, v52
	v_lshlrev_b32_e32 v154, 16, v53
	v_and_b32_e32 v155, 0xffff0000, v53
	v_lshlrev_b32_e32 v156, 16, v54
	v_and_b32_e32 v157, 0xffff0000, v54
	v_lshlrev_b32_e32 v158, 16, v55
	v_and_b32_e32 v159, 0xffff0000, v55
	v_lshlrev_b32_e32 v160, 16, v56
	v_and_b32_e32 v161, 0xffff0000, v56
	v_lshlrev_b32_e32 v162, 16, v57
	v_and_b32_e32 v163, 0xffff0000, v57
	v_lshlrev_b32_e32 v164, 16, v58
	v_and_b32_e32 v165, 0xffff0000, v58
	v_lshlrev_b32_e32 v166, 16, v59
	v_and_b32_e32 v167, 0xffff0000, v59
	v_lshlrev_b32_e32 v168, 16, v60
	v_and_b32_e32 v169, 0xffff0000, v60
	v_lshlrev_b32_e32 v170, 16, v61
	v_and_b32_e32 v171, 0xffff0000, v61
	v_lshlrev_b32_e32 v172, 16, v62
	v_and_b32_e32 v173, 0xffff0000, v62
	v_lshlrev_b32_e32 v174, 16, v63
	v_and_b32_e32 v175, 0xffff0000, v63
	v_pk_mul_f32 v[252:253], v[160:161], v[160:161]
	v_pk_mul_f32 v[254:255], v[162:163], v[162:163]
	v_pk_fma_f32 v[252:253], v[164:165], v[164:165], v[252:253]
	v_pk_fma_f32 v[254:255], v[166:167], v[166:167], v[254:255]
	v_pk_fma_f32 v[252:253], v[168:169], v[168:169], v[252:253]
	v_pk_fma_f32 v[254:255], v[170:171], v[170:171], v[254:255]
	v_pk_fma_f32 v[252:253], v[172:173], v[172:173], v[252:253]
	v_pk_fma_f32 v[254:255], v[174:175], v[174:175], v[254:255]
	v_pk_add_f32 v[252:253], v[252:253], v[254:255]
	s_nop 0
	v_add_f32_e32 v183, v252, v253
	s_nop 1
	v_add_f32_dpp v183, v183, v183 quad_perm:[1,0,3,2] row_mask:0xf bank_mask:0xf bound_ctrl:1
	s_nop 1
	v_add_f32_dpp v183, v183, v183 quad_perm:[2,3,0,1] row_mask:0xf bank_mask:0xf bound_ctrl:1
	s_nop 1
	v_add_f32_dpp v183, v183, v183 row_half_mirror row_mask:0xf bank_mask:0xf bound_ctrl:1
	s_nop 1
	v_add_f32_dpp v183, v183, v183 row_mirror row_mask:0xf bank_mask:0xf bound_ctrl:1
	s_nop 1
	v_readlane_b32 s98, v183, 0
	v_readlane_b32 s99, v183, 16
	v_readlane_b32 s100, v183, 32
	v_readlane_b32 s101, v183, 48
	s_nop 1
	v_mov_b32_e32 v183, s98
	v_add_f32_e32 v183, s99, v183
	v_add_f32_e32 v183, s100, v183
	v_add_f32_e32 v183, s101, v183
	v_fmamk_f32 v183, v183, 0x3a800000, v182
	v_cmp_gt_f32_e32 vcc, 0x800000, v183
	v_mul_f32_e32 v181, 0x4b800000, v183
	s_nop 1
	v_cndmask_b32_e32 v183, v183, v181, vcc
	v_rsq_f32_e32 v183, v183
	s_nop 0
	v_mul_f32_e32 v181, 0x45800000, v183
	v_cndmask_b32_e32 v184, v183, v181, vcc
	v_mov_b32_e32 v185, v184
	v_pk_mul_f32 v[160:161], v[160:161], v[184:185]
	v_pk_mul_f32 v[162:163], v[162:163], v[184:185]
	v_pk_mul_f32 v[164:165], v[164:165], v[184:185]
	v_pk_mul_f32 v[166:167], v[166:167], v[184:185]
	v_pk_mul_f32 v[168:169], v[168:169], v[184:185]
	v_pk_mul_f32 v[170:171], v[170:171], v[184:185]
	v_pk_mul_f32 v[172:173], v[172:173], v[184:185]
	v_pk_mul_f32 v[174:175], v[174:175], v[184:185]
	v_pk_fma_f32 v[144:145], v[160:161], v[128:129], v[144:145]
	v_pk_fma_f32 v[146:147], v[162:163], v[130:131], v[146:147]
	v_pk_fma_f32 v[148:149], v[164:165], v[132:133], v[148:149]
	v_pk_fma_f32 v[150:151], v[166:167], v[134:135], v[150:151]
	v_pk_fma_f32 v[152:153], v[168:169], v[136:137], v[152:153]
	v_pk_fma_f32 v[154:155], v[170:171], v[138:139], v[154:155]
	v_pk_fma_f32 v[156:157], v[172:173], v[140:141], v[156:157]
	v_pk_fma_f32 v[158:159], v[174:175], v[142:143], v[158:159]
	v_pk_mul_f32 v[252:253], v[144:145], v[144:145]
	v_pk_mul_f32 v[254:255], v[146:147], v[146:147]
	v_pk_fma_f32 v[252:253], v[148:149], v[148:149], v[252:253]
	v_pk_fma_f32 v[254:255], v[150:151], v[150:151], v[254:255]
	v_pk_fma_f32 v[252:253], v[152:153], v[152:153], v[252:253]
	v_pk_fma_f32 v[254:255], v[154:155], v[154:155], v[254:255]
	v_pk_fma_f32 v[252:253], v[156:157], v[156:157], v[252:253]
	v_pk_fma_f32 v[254:255], v[158:159], v[158:159], v[254:255]
	v_pk_add_f32 v[252:253], v[252:253], v[254:255]
	s_nop 0
	v_add_f32_e32 v183, v252, v253
	s_nop 1
	v_add_f32_dpp v183, v183, v183 quad_perm:[1,0,3,2] row_mask:0xf bank_mask:0xf bound_ctrl:1
	s_nop 1
	v_add_f32_dpp v183, v183, v183 quad_perm:[2,3,0,1] row_mask:0xf bank_mask:0xf bound_ctrl:1
	s_nop 1
	v_add_f32_dpp v183, v183, v183 row_half_mirror row_mask:0xf bank_mask:0xf bound_ctrl:1
	s_nop 1
	v_add_f32_dpp v183, v183, v183 row_mirror row_mask:0xf bank_mask:0xf bound_ctrl:1
	s_nop 1
	v_readlane_b32 s98, v183, 0
	v_readlane_b32 s99, v183, 16
	v_readlane_b32 s100, v183, 32
	v_readlane_b32 s101, v183, 48
	s_nop 1
	v_mov_b32_e32 v183, s98
	v_add_f32_e32 v183, s99, v183
	v_add_f32_e32 v183, s100, v183
	v_add_f32_e32 v183, s101, v183
	v_fmamk_f32 v183, v183, 0x3a800000, v182
	v_cmp_gt_f32_e32 vcc, 0x800000, v183
	v_mul_f32_e32 v181, 0x4b800000, v183
	s_nop 1
	v_cndmask_b32_e32 v183, v183, v181, vcc
	v_rsq_f32_e32 v183, v183
	s_nop 0
	v_mul_f32_e32 v181, 0x45800000, v183
	v_cndmask_b32_e32 v184, v183, v181, vcc
	v_mov_b32_e32 v185, v184
	v_cvt_pk_bf16_f32 v48, v144, v145
	v_cvt_pk_bf16_f32 v49, v146, v147
	v_cvt_pk_bf16_f32 v50, v148, v149
	v_cvt_pk_bf16_f32 v51, v150, v151
	v_cvt_pk_bf16_f32 v52, v152, v153
	v_cvt_pk_bf16_f32 v53, v154, v155
	v_cvt_pk_bf16_f32 v54, v156, v157
	v_cvt_pk_bf16_f32 v55, v158, v159
	v_add_u32_e32 v181, 0x2400000, v177
	global_store_dwordx4 v181, v[48:51], s[78:79]
	global_store_dwordx4 v181, v[52:55], s[78:79] offset:1024
	v_add_u32_e32 v236, 0x6000, v237
	s_mov_b64 exec, 1
	global_store_dword v236, v184, s[78:79]
	s_mov_b64 exec, -1
	s_waitcnt vmcnt(12)
	v_lshlrev_b32_e32 v144, 16, v64
	v_and_b32_e32 v145, 0xffff0000, v64
	v_lshlrev_b32_e32 v146, 16, v65
	v_and_b32_e32 v147, 0xffff0000, v65
	v_lshlrev_b32_e32 v148, 16, v66
	v_and_b32_e32 v149, 0xffff0000, v66
	v_lshlrev_b32_e32 v150, 16, v67
	v_and_b32_e32 v151, 0xffff0000, v67
	v_lshlrev_b32_e32 v152, 16, v68
	v_and_b32_e32 v153, 0xffff0000, v68
	v_lshlrev_b32_e32 v154, 16, v69
	v_and_b32_e32 v155, 0xffff0000, v69
	v_lshlrev_b32_e32 v156, 16, v70
	v_and_b32_e32 v157, 0xffff0000, v70
	v_lshlrev_b32_e32 v158, 16, v71
	v_and_b32_e32 v159, 0xffff0000, v71
	v_lshlrev_b32_e32 v160, 16, v72
	v_and_b32_e32 v161, 0xffff0000, v72
	v_lshlrev_b32_e32 v162, 16, v73
	v_and_b32_e32 v163, 0xffff0000, v73
	v_lshlrev_b32_e32 v164, 16, v74
	v_and_b32_e32 v165, 0xffff0000, v74
	v_lshlrev_b32_e32 v166, 16, v75
	v_and_b32_e32 v167, 0xffff0000, v75
	v_lshlrev_b32_e32 v168, 16, v76
	v_and_b32_e32 v169, 0xffff0000, v76
	v_lshlrev_b32_e32 v170, 16, v77
	v_and_b32_e32 v171, 0xffff0000, v77
	v_lshlrev_b32_e32 v172, 16, v78
	v_and_b32_e32 v173, 0xffff0000, v78
	v_lshlrev_b32_e32 v174, 16, v79
	v_and_b32_e32 v175, 0xffff0000, v79
	v_pk_mul_f32 v[252:253], v[160:161], v[160:161]
	v_pk_mul_f32 v[254:255], v[162:163], v[162:163]
	v_pk_fma_f32 v[252:253], v[164:165], v[164:165], v[252:253]
	v_pk_fma_f32 v[254:255], v[166:167], v[166:167], v[254:255]
	v_pk_fma_f32 v[252:253], v[168:169], v[168:169], v[252:253]
	v_pk_fma_f32 v[254:255], v[170:171], v[170:171], v[254:255]
	v_pk_fma_f32 v[252:253], v[172:173], v[172:173], v[252:253]
	v_pk_fma_f32 v[254:255], v[174:175], v[174:175], v[254:255]
	v_pk_add_f32 v[252:253], v[252:253], v[254:255]
	s_nop 0
	v_add_f32_e32 v183, v252, v253
	s_nop 1
	v_add_f32_dpp v183, v183, v183 quad_perm:[1,0,3,2] row_mask:0xf bank_mask:0xf bound_ctrl:1
	s_nop 1
	v_add_f32_dpp v183, v183, v183 quad_perm:[2,3,0,1] row_mask:0xf bank_mask:0xf bound_ctrl:1
	s_nop 1
	v_add_f32_dpp v183, v183, v183 row_half_mirror row_mask:0xf bank_mask:0xf bound_ctrl:1
	s_nop 1
	v_add_f32_dpp v183, v183, v183 row_mirror row_mask:0xf bank_mask:0xf bound_ctrl:1
	s_nop 1
	v_readlane_b32 s98, v183, 0
	v_readlane_b32 s99, v183, 16
	v_readlane_b32 s100, v183, 32
	v_readlane_b32 s101, v183, 48
	s_nop 1
	v_mov_b32_e32 v183, s98
	v_add_f32_e32 v183, s99, v183
	v_add_f32_e32 v183, s100, v183
	v_add_f32_e32 v183, s101, v183
	v_fmamk_f32 v183, v183, 0x3a800000, v182
	v_cmp_gt_f32_e32 vcc, 0x800000, v183
	v_mul_f32_e32 v181, 0x4b800000, v183
	s_nop 1
	v_cndmask_b32_e32 v183, v183, v181, vcc
	v_rsq_f32_e32 v183, v183
	s_nop 0
	v_mul_f32_e32 v181, 0x45800000, v183
	v_cndmask_b32_e32 v184, v183, v181, vcc
	v_mov_b32_e32 v185, v184
	v_pk_mul_f32 v[160:161], v[160:161], v[184:185]
	v_pk_mul_f32 v[162:163], v[162:163], v[184:185]
	v_pk_mul_f32 v[164:165], v[164:165], v[184:185]
	v_pk_mul_f32 v[166:167], v[166:167], v[184:185]
	v_pk_mul_f32 v[168:169], v[168:169], v[184:185]
	v_pk_mul_f32 v[170:171], v[170:171], v[184:185]
	v_pk_mul_f32 v[172:173], v[172:173], v[184:185]
	v_pk_mul_f32 v[174:175], v[174:175], v[184:185]
	v_pk_fma_f32 v[144:145], v[160:161], v[128:129], v[144:145]
	v_pk_fma_f32 v[146:147], v[162:163], v[130:131], v[146:147]
	v_pk_fma_f32 v[148:149], v[164:165], v[132:133], v[148:149]
	v_pk_fma_f32 v[150:151], v[166:167], v[134:135], v[150:151]
	v_pk_fma_f32 v[152:153], v[168:169], v[136:137], v[152:153]
	v_pk_fma_f32 v[154:155], v[170:171], v[138:139], v[154:155]
	v_pk_fma_f32 v[156:157], v[172:173], v[140:141], v[156:157]
	v_pk_fma_f32 v[158:159], v[174:175], v[142:143], v[158:159]
	v_pk_mul_f32 v[252:253], v[144:145], v[144:145]
	v_pk_mul_f32 v[254:255], v[146:147], v[146:147]
	v_pk_fma_f32 v[252:253], v[148:149], v[148:149], v[252:253]
	v_pk_fma_f32 v[254:255], v[150:151], v[150:151], v[254:255]
	v_pk_fma_f32 v[252:253], v[152:153], v[152:153], v[252:253]
	v_pk_fma_f32 v[254:255], v[154:155], v[154:155], v[254:255]
	v_pk_fma_f32 v[252:253], v[156:157], v[156:157], v[252:253]
	v_pk_fma_f32 v[254:255], v[158:159], v[158:159], v[254:255]
	v_pk_add_f32 v[252:253], v[252:253], v[254:255]
	s_nop 0
	v_add_f32_e32 v183, v252, v253
	s_nop 1
	v_add_f32_dpp v183, v183, v183 quad_perm:[1,0,3,2] row_mask:0xf bank_mask:0xf bound_ctrl:1
	s_nop 1
	v_add_f32_dpp v183, v183, v183 quad_perm:[2,3,0,1] row_mask:0xf bank_mask:0xf bound_ctrl:1
	s_nop 1
	v_add_f32_dpp v183, v183, v183 row_half_mirror row_mask:0xf bank_mask:0xf bound_ctrl:1
	s_nop 1
	v_add_f32_dpp v183, v183, v183 row_mirror row_mask:0xf bank_mask:0xf bound_ctrl:1
	s_nop 1
	v_readlane_b32 s98, v183, 0
	v_readlane_b32 s99, v183, 16
	v_readlane_b32 s100, v183, 32
	v_readlane_b32 s101, v183, 48
	s_nop 1
	v_mov_b32_e32 v183, s98
	v_add_f32_e32 v183, s99, v183
	v_add_f32_e32 v183, s100, v183
	v_add_f32_e32 v183, s101, v183
	v_fmamk_f32 v183, v183, 0x3a800000, v182
	v_cmp_gt_f32_e32 vcc, 0x800000, v183
	v_mul_f32_e32 v181, 0x4b800000, v183
	s_nop 1
	v_cndmask_b32_e32 v183, v183, v181, vcc
	v_rsq_f32_e32 v183, v183
	s_nop 0
	v_mul_f32_e32 v181, 0x45800000, v183
	v_cndmask_b32_e32 v184, v183, v181, vcc
	v_mov_b32_e32 v185, v184
	v_cvt_pk_bf16_f32 v64, v144, v145
	v_cvt_pk_bf16_f32 v65, v146, v147
	v_cvt_pk_bf16_f32 v66, v148, v149
	v_cvt_pk_bf16_f32 v67, v150, v151
	v_cvt_pk_bf16_f32 v68, v152, v153
	v_cvt_pk_bf16_f32 v69, v154, v155
	v_cvt_pk_bf16_f32 v70, v156, v157
	v_cvt_pk_bf16_f32 v71, v158, v159
	v_add_u32_e32 v181, 0x2800000, v177
	global_store_dwordx4 v181, v[64:67], s[78:79]
	global_store_dwordx4 v181, v[68:71], s[78:79] offset:1024
	v_add_u32_e32 v236, 0x8000, v237
	s_mov_b64 exec, 1
	global_store_dword v236, v184, s[78:79]
	s_mov_b64 exec, -1
	s_waitcnt vmcnt(8)
	v_lshlrev_b32_e32 v144, 16, v80
	v_and_b32_e32 v145, 0xffff0000, v80
	v_lshlrev_b32_e32 v146, 16, v81
	v_and_b32_e32 v147, 0xffff0000, v81
	v_lshlrev_b32_e32 v148, 16, v82
	v_and_b32_e32 v149, 0xffff0000, v82
	v_lshlrev_b32_e32 v150, 16, v83
	v_and_b32_e32 v151, 0xffff0000, v83
	v_lshlrev_b32_e32 v152, 16, v84
	v_and_b32_e32 v153, 0xffff0000, v84
	v_lshlrev_b32_e32 v154, 16, v85
	v_and_b32_e32 v155, 0xffff0000, v85
	v_lshlrev_b32_e32 v156, 16, v86
	v_and_b32_e32 v157, 0xffff0000, v86
	v_lshlrev_b32_e32 v158, 16, v87
	v_and_b32_e32 v159, 0xffff0000, v87
	v_lshlrev_b32_e32 v160, 16, v88
	v_and_b32_e32 v161, 0xffff0000, v88
	v_lshlrev_b32_e32 v162, 16, v89
	v_and_b32_e32 v163, 0xffff0000, v89
	v_lshlrev_b32_e32 v164, 16, v90
	v_and_b32_e32 v165, 0xffff0000, v90
	v_lshlrev_b32_e32 v166, 16, v91
	v_and_b32_e32 v167, 0xffff0000, v91
	v_lshlrev_b32_e32 v168, 16, v92
	v_and_b32_e32 v169, 0xffff0000, v92
	v_lshlrev_b32_e32 v170, 16, v93
	v_and_b32_e32 v171, 0xffff0000, v93
	v_lshlrev_b32_e32 v172, 16, v94
	v_and_b32_e32 v173, 0xffff0000, v94
	v_lshlrev_b32_e32 v174, 16, v95
	v_and_b32_e32 v175, 0xffff0000, v95
	v_pk_mul_f32 v[252:253], v[160:161], v[160:161]
	v_pk_mul_f32 v[254:255], v[162:163], v[162:163]
	v_pk_fma_f32 v[252:253], v[164:165], v[164:165], v[252:253]
	v_pk_fma_f32 v[254:255], v[166:167], v[166:167], v[254:255]
	v_pk_fma_f32 v[252:253], v[168:169], v[168:169], v[252:253]
	v_pk_fma_f32 v[254:255], v[170:171], v[170:171], v[254:255]
	v_pk_fma_f32 v[252:253], v[172:173], v[172:173], v[252:253]
	v_pk_fma_f32 v[254:255], v[174:175], v[174:175], v[254:255]
	v_pk_add_f32 v[252:253], v[252:253], v[254:255]
	s_nop 0
	v_add_f32_e32 v183, v252, v253
	s_nop 1
	v_add_f32_dpp v183, v183, v183 quad_perm:[1,0,3,2] row_mask:0xf bank_mask:0xf bound_ctrl:1
	s_nop 1
	v_add_f32_dpp v183, v183, v183 quad_perm:[2,3,0,1] row_mask:0xf bank_mask:0xf bound_ctrl:1
	s_nop 1
	v_add_f32_dpp v183, v183, v183 row_half_mirror row_mask:0xf bank_mask:0xf bound_ctrl:1
	s_nop 1
	v_add_f32_dpp v183, v183, v183 row_mirror row_mask:0xf bank_mask:0xf bound_ctrl:1
	s_nop 1
	v_readlane_b32 s98, v183, 0
	v_readlane_b32 s99, v183, 16
	v_readlane_b32 s100, v183, 32
	v_readlane_b32 s101, v183, 48
	s_nop 1
	v_mov_b32_e32 v183, s98
	v_add_f32_e32 v183, s99, v183
	v_add_f32_e32 v183, s100, v183
	v_add_f32_e32 v183, s101, v183
	v_fmamk_f32 v183, v183, 0x3a800000, v182
	v_cmp_gt_f32_e32 vcc, 0x800000, v183
	v_mul_f32_e32 v181, 0x4b800000, v183
	s_nop 1
	v_cndmask_b32_e32 v183, v183, v181, vcc
	v_rsq_f32_e32 v183, v183
	s_nop 0
	v_mul_f32_e32 v181, 0x45800000, v183
	v_cndmask_b32_e32 v184, v183, v181, vcc
	v_mov_b32_e32 v185, v184
	v_pk_mul_f32 v[160:161], v[160:161], v[184:185]
	v_pk_mul_f32 v[162:163], v[162:163], v[184:185]
	v_pk_mul_f32 v[164:165], v[164:165], v[184:185]
	v_pk_mul_f32 v[166:167], v[166:167], v[184:185]
	v_pk_mul_f32 v[168:169], v[168:169], v[184:185]
	v_pk_mul_f32 v[170:171], v[170:171], v[184:185]
	v_pk_mul_f32 v[172:173], v[172:173], v[184:185]
	v_pk_mul_f32 v[174:175], v[174:175], v[184:185]
	v_pk_fma_f32 v[144:145], v[160:161], v[128:129], v[144:145]
	v_pk_fma_f32 v[146:147], v[162:163], v[130:131], v[146:147]
	v_pk_fma_f32 v[148:149], v[164:165], v[132:133], v[148:149]
	v_pk_fma_f32 v[150:151], v[166:167], v[134:135], v[150:151]
	v_pk_fma_f32 v[152:153], v[168:169], v[136:137], v[152:153]
	v_pk_fma_f32 v[154:155], v[170:171], v[138:139], v[154:155]
	v_pk_fma_f32 v[156:157], v[172:173], v[140:141], v[156:157]
	v_pk_fma_f32 v[158:159], v[174:175], v[142:143], v[158:159]
	v_pk_mul_f32 v[252:253], v[144:145], v[144:145]
	v_pk_mul_f32 v[254:255], v[146:147], v[146:147]
	v_pk_fma_f32 v[252:253], v[148:149], v[148:149], v[252:253]
	v_pk_fma_f32 v[254:255], v[150:151], v[150:151], v[254:255]
	v_pk_fma_f32 v[252:253], v[152:153], v[152:153], v[252:253]
	v_pk_fma_f32 v[254:255], v[154:155], v[154:155], v[254:255]
	v_pk_fma_f32 v[252:253], v[156:157], v[156:157], v[252:253]
	v_pk_fma_f32 v[254:255], v[158:159], v[158:159], v[254:255]
	v_pk_add_f32 v[252:253], v[252:253], v[254:255]
	s_nop 0
	v_add_f32_e32 v183, v252, v253
	s_nop 1
	v_add_f32_dpp v183, v183, v183 quad_perm:[1,0,3,2] row_mask:0xf bank_mask:0xf bound_ctrl:1
	s_nop 1
	v_add_f32_dpp v183, v183, v183 quad_perm:[2,3,0,1] row_mask:0xf bank_mask:0xf bound_ctrl:1
	s_nop 1
	v_add_f32_dpp v183, v183, v183 row_half_mirror row_mask:0xf bank_mask:0xf bound_ctrl:1
	s_nop 1
	v_add_f32_dpp v183, v183, v183 row_mirror row_mask:0xf bank_mask:0xf bound_ctrl:1
	s_nop 1
	v_readlane_b32 s98, v183, 0
	v_readlane_b32 s99, v183, 16
	v_readlane_b32 s100, v183, 32
	v_readlane_b32 s101, v183, 48
	s_nop 1
	v_mov_b32_e32 v183, s98
	v_add_f32_e32 v183, s99, v183
	v_add_f32_e32 v183, s100, v183
	v_add_f32_e32 v183, s101, v183
	v_fmamk_f32 v183, v183, 0x3a800000, v182
	v_cmp_gt_f32_e32 vcc, 0x800000, v183
	v_mul_f32_e32 v181, 0x4b800000, v183
	s_nop 1
	v_cndmask_b32_e32 v183, v183, v181, vcc
	v_rsq_f32_e32 v183, v183
	s_nop 0
	v_mul_f32_e32 v181, 0x45800000, v183
	v_cndmask_b32_e32 v184, v183, v181, vcc
	v_mov_b32_e32 v185, v184
	v_cvt_pk_bf16_f32 v80, v144, v145
	v_cvt_pk_bf16_f32 v81, v146, v147
	v_cvt_pk_bf16_f32 v82, v148, v149
	v_cvt_pk_bf16_f32 v83, v150, v151
	v_cvt_pk_bf16_f32 v84, v152, v153
	v_cvt_pk_bf16_f32 v85, v154, v155
	v_cvt_pk_bf16_f32 v86, v156, v157
	v_cvt_pk_bf16_f32 v87, v158, v159
	v_add_u32_e32 v181, 0x2c00000, v177
	global_store_dwordx4 v181, v[80:83], s[78:79]
	global_store_dwordx4 v181, v[84:87], s[78:79] offset:1024
	v_add_u32_e32 v236, 0xa000, v237
	s_mov_b64 exec, 1
	global_store_dword v236, v184, s[78:79]
	s_mov_b64 exec, -1
	s_waitcnt vmcnt(4)
	v_lshlrev_b32_e32 v144, 16, v96
	v_and_b32_e32 v145, 0xffff0000, v96
	v_lshlrev_b32_e32 v146, 16, v97
	v_and_b32_e32 v147, 0xffff0000, v97
	v_lshlrev_b32_e32 v148, 16, v98
	v_and_b32_e32 v149, 0xffff0000, v98
	v_lshlrev_b32_e32 v150, 16, v99
	v_and_b32_e32 v151, 0xffff0000, v99
	v_lshlrev_b32_e32 v152, 16, v100
	v_and_b32_e32 v153, 0xffff0000, v100
	v_lshlrev_b32_e32 v154, 16, v101
	v_and_b32_e32 v155, 0xffff0000, v101
	v_lshlrev_b32_e32 v156, 16, v102
	v_and_b32_e32 v157, 0xffff0000, v102
	v_lshlrev_b32_e32 v158, 16, v103
	v_and_b32_e32 v159, 0xffff0000, v103
	v_lshlrev_b32_e32 v160, 16, v104
	v_and_b32_e32 v161, 0xffff0000, v104
	v_lshlrev_b32_e32 v162, 16, v105
	v_and_b32_e32 v163, 0xffff0000, v105
	v_lshlrev_b32_e32 v164, 16, v106
	v_and_b32_e32 v165, 0xffff0000, v106
	v_lshlrev_b32_e32 v166, 16, v107
	v_and_b32_e32 v167, 0xffff0000, v107
	v_lshlrev_b32_e32 v168, 16, v108
	v_and_b32_e32 v169, 0xffff0000, v108
	v_lshlrev_b32_e32 v170, 16, v109
	v_and_b32_e32 v171, 0xffff0000, v109
	v_lshlrev_b32_e32 v172, 16, v110
	v_and_b32_e32 v173, 0xffff0000, v110
	v_lshlrev_b32_e32 v174, 16, v111
	v_and_b32_e32 v175, 0xffff0000, v111
	v_pk_mul_f32 v[252:253], v[160:161], v[160:161]
	v_pk_mul_f32 v[254:255], v[162:163], v[162:163]
	v_pk_fma_f32 v[252:253], v[164:165], v[164:165], v[252:253]
	v_pk_fma_f32 v[254:255], v[166:167], v[166:167], v[254:255]
	v_pk_fma_f32 v[252:253], v[168:169], v[168:169], v[252:253]
	v_pk_fma_f32 v[254:255], v[170:171], v[170:171], v[254:255]
	v_pk_fma_f32 v[252:253], v[172:173], v[172:173], v[252:253]
	v_pk_fma_f32 v[254:255], v[174:175], v[174:175], v[254:255]
	v_pk_add_f32 v[252:253], v[252:253], v[254:255]
	s_nop 0
	v_add_f32_e32 v183, v252, v253
	s_nop 1
	v_add_f32_dpp v183, v183, v183 quad_perm:[1,0,3,2] row_mask:0xf bank_mask:0xf bound_ctrl:1
	s_nop 1
	v_add_f32_dpp v183, v183, v183 quad_perm:[2,3,0,1] row_mask:0xf bank_mask:0xf bound_ctrl:1
	s_nop 1
	v_add_f32_dpp v183, v183, v183 row_half_mirror row_mask:0xf bank_mask:0xf bound_ctrl:1
	s_nop 1
	v_add_f32_dpp v183, v183, v183 row_mirror row_mask:0xf bank_mask:0xf bound_ctrl:1
	s_nop 1
	v_readlane_b32 s98, v183, 0
	v_readlane_b32 s99, v183, 16
	v_readlane_b32 s100, v183, 32
	v_readlane_b32 s101, v183, 48
	s_nop 1
	v_mov_b32_e32 v183, s98
	v_add_f32_e32 v183, s99, v183
	v_add_f32_e32 v183, s100, v183
	v_add_f32_e32 v183, s101, v183
	v_fmamk_f32 v183, v183, 0x3a800000, v182
	v_cmp_gt_f32_e32 vcc, 0x800000, v183
	v_mul_f32_e32 v181, 0x4b800000, v183
	s_nop 1
	v_cndmask_b32_e32 v183, v183, v181, vcc
	v_rsq_f32_e32 v183, v183
	s_nop 0
	v_mul_f32_e32 v181, 0x45800000, v183
	v_cndmask_b32_e32 v184, v183, v181, vcc
	v_mov_b32_e32 v185, v184
	v_pk_mul_f32 v[160:161], v[160:161], v[184:185]
	v_pk_mul_f32 v[162:163], v[162:163], v[184:185]
	v_pk_mul_f32 v[164:165], v[164:165], v[184:185]
	v_pk_mul_f32 v[166:167], v[166:167], v[184:185]
	v_pk_mul_f32 v[168:169], v[168:169], v[184:185]
	v_pk_mul_f32 v[170:171], v[170:171], v[184:185]
	v_pk_mul_f32 v[172:173], v[172:173], v[184:185]
	v_pk_mul_f32 v[174:175], v[174:175], v[184:185]
	v_pk_fma_f32 v[144:145], v[160:161], v[128:129], v[144:145]
	v_pk_fma_f32 v[146:147], v[162:163], v[130:131], v[146:147]
	v_pk_fma_f32 v[148:149], v[164:165], v[132:133], v[148:149]
	v_pk_fma_f32 v[150:151], v[166:167], v[134:135], v[150:151]
	v_pk_fma_f32 v[152:153], v[168:169], v[136:137], v[152:153]
	v_pk_fma_f32 v[154:155], v[170:171], v[138:139], v[154:155]
	v_pk_fma_f32 v[156:157], v[172:173], v[140:141], v[156:157]
	v_pk_fma_f32 v[158:159], v[174:175], v[142:143], v[158:159]
	v_pk_mul_f32 v[252:253], v[144:145], v[144:145]
	v_pk_mul_f32 v[254:255], v[146:147], v[146:147]
	v_pk_fma_f32 v[252:253], v[148:149], v[148:149], v[252:253]
	v_pk_fma_f32 v[254:255], v[150:151], v[150:151], v[254:255]
	v_pk_fma_f32 v[252:253], v[152:153], v[152:153], v[252:253]
	v_pk_fma_f32 v[254:255], v[154:155], v[154:155], v[254:255]
	v_pk_fma_f32 v[252:253], v[156:157], v[156:157], v[252:253]
	v_pk_fma_f32 v[254:255], v[158:159], v[158:159], v[254:255]
	v_pk_add_f32 v[252:253], v[252:253], v[254:255]
	s_nop 0
	v_add_f32_e32 v183, v252, v253
	s_nop 1
	v_add_f32_dpp v183, v183, v183 quad_perm:[1,0,3,2] row_mask:0xf bank_mask:0xf bound_ctrl:1
	s_nop 1
	v_add_f32_dpp v183, v183, v183 quad_perm:[2,3,0,1] row_mask:0xf bank_mask:0xf bound_ctrl:1
	s_nop 1
	v_add_f32_dpp v183, v183, v183 row_half_mirror row_mask:0xf bank_mask:0xf bound_ctrl:1
	s_nop 1
	v_add_f32_dpp v183, v183, v183 row_mirror row_mask:0xf bank_mask:0xf bound_ctrl:1
	s_nop 1
	v_readlane_b32 s98, v183, 0
	v_readlane_b32 s99, v183, 16
	v_readlane_b32 s100, v183, 32
	v_readlane_b32 s101, v183, 48
	s_nop 1
	v_mov_b32_e32 v183, s98
	v_add_f32_e32 v183, s99, v183
	v_add_f32_e32 v183, s100, v183
	v_add_f32_e32 v183, s101, v183
	v_fmamk_f32 v183, v183, 0x3a800000, v182
	v_cmp_gt_f32_e32 vcc, 0x800000, v183
	v_mul_f32_e32 v181, 0x4b800000, v183
	s_nop 1
	v_cndmask_b32_e32 v183, v183, v181, vcc
	v_rsq_f32_e32 v183, v183
	s_nop 0
	v_mul_f32_e32 v181, 0x45800000, v183
	v_cndmask_b32_e32 v184, v183, v181, vcc
	v_mov_b32_e32 v185, v184
	v_cvt_pk_bf16_f32 v96, v144, v145
	v_cvt_pk_bf16_f32 v97, v146, v147
	v_cvt_pk_bf16_f32 v98, v148, v149
	v_cvt_pk_bf16_f32 v99, v150, v151
	v_cvt_pk_bf16_f32 v100, v152, v153
	v_cvt_pk_bf16_f32 v101, v154, v155
	v_cvt_pk_bf16_f32 v102, v156, v157
	v_cvt_pk_bf16_f32 v103, v158, v159
	v_add_u32_e32 v181, 0x3000000, v177
	global_store_dwordx4 v181, v[96:99], s[78:79]
	global_store_dwordx4 v181, v[100:103], s[78:79] offset:1024
	v_add_u32_e32 v236, 0xc000, v237
	s_mov_b64 exec, 1
	global_store_dword v236, v184, s[78:79]
	s_mov_b64 exec, -1
	s_waitcnt vmcnt(0)
	v_lshlrev_b32_e32 v144, 16, v112
	v_and_b32_e32 v145, 0xffff0000, v112
	v_lshlrev_b32_e32 v146, 16, v113
	v_and_b32_e32 v147, 0xffff0000, v113
	v_lshlrev_b32_e32 v148, 16, v114
	v_and_b32_e32 v149, 0xffff0000, v114
	v_lshlrev_b32_e32 v150, 16, v115
	v_and_b32_e32 v151, 0xffff0000, v115
	v_lshlrev_b32_e32 v152, 16, v116
	v_and_b32_e32 v153, 0xffff0000, v116
	v_lshlrev_b32_e32 v154, 16, v117
	v_and_b32_e32 v155, 0xffff0000, v117
	v_lshlrev_b32_e32 v156, 16, v118
	v_and_b32_e32 v157, 0xffff0000, v118
	v_lshlrev_b32_e32 v158, 16, v119
	v_and_b32_e32 v159, 0xffff0000, v119
	v_lshlrev_b32_e32 v160, 16, v120
	v_and_b32_e32 v161, 0xffff0000, v120
	v_lshlrev_b32_e32 v162, 16, v121
	v_and_b32_e32 v163, 0xffff0000, v121
	v_lshlrev_b32_e32 v164, 16, v122
	v_and_b32_e32 v165, 0xffff0000, v122
	v_lshlrev_b32_e32 v166, 16, v123
	v_and_b32_e32 v167, 0xffff0000, v123
	v_lshlrev_b32_e32 v168, 16, v124
	v_and_b32_e32 v169, 0xffff0000, v124
	v_lshlrev_b32_e32 v170, 16, v125
	v_and_b32_e32 v171, 0xffff0000, v125
	v_lshlrev_b32_e32 v172, 16, v126
	v_and_b32_e32 v173, 0xffff0000, v126
	v_lshlrev_b32_e32 v174, 16, v127
	v_and_b32_e32 v175, 0xffff0000, v127
	v_pk_mul_f32 v[252:253], v[160:161], v[160:161]
	v_pk_mul_f32 v[254:255], v[162:163], v[162:163]
	v_pk_fma_f32 v[252:253], v[164:165], v[164:165], v[252:253]
	v_pk_fma_f32 v[254:255], v[166:167], v[166:167], v[254:255]
	v_pk_fma_f32 v[252:253], v[168:169], v[168:169], v[252:253]
	v_pk_fma_f32 v[254:255], v[170:171], v[170:171], v[254:255]
	v_pk_fma_f32 v[252:253], v[172:173], v[172:173], v[252:253]
	v_pk_fma_f32 v[254:255], v[174:175], v[174:175], v[254:255]
	v_pk_add_f32 v[252:253], v[252:253], v[254:255]
	s_nop 0
	v_add_f32_e32 v183, v252, v253
	s_nop 1
	v_add_f32_dpp v183, v183, v183 quad_perm:[1,0,3,2] row_mask:0xf bank_mask:0xf bound_ctrl:1
	s_nop 1
	v_add_f32_dpp v183, v183, v183 quad_perm:[2,3,0,1] row_mask:0xf bank_mask:0xf bound_ctrl:1
	s_nop 1
	v_add_f32_dpp v183, v183, v183 row_half_mirror row_mask:0xf bank_mask:0xf bound_ctrl:1
	s_nop 1
	v_add_f32_dpp v183, v183, v183 row_mirror row_mask:0xf bank_mask:0xf bound_ctrl:1
	s_nop 1
	v_readlane_b32 s98, v183, 0
	v_readlane_b32 s99, v183, 16
	v_readlane_b32 s100, v183, 32
	v_readlane_b32 s101, v183, 48
	s_nop 1
	v_mov_b32_e32 v183, s98
	v_add_f32_e32 v183, s99, v183
	v_add_f32_e32 v183, s100, v183
	v_add_f32_e32 v183, s101, v183
	v_fmamk_f32 v183, v183, 0x3a800000, v182
	v_cmp_gt_f32_e32 vcc, 0x800000, v183
	v_mul_f32_e32 v181, 0x4b800000, v183
	s_nop 1
	v_cndmask_b32_e32 v183, v183, v181, vcc
	v_rsq_f32_e32 v183, v183
	s_nop 0
	v_mul_f32_e32 v181, 0x45800000, v183
	v_cndmask_b32_e32 v184, v183, v181, vcc
	v_mov_b32_e32 v185, v184
	v_pk_mul_f32 v[160:161], v[160:161], v[184:185]
	v_pk_mul_f32 v[162:163], v[162:163], v[184:185]
	v_pk_mul_f32 v[164:165], v[164:165], v[184:185]
	v_pk_mul_f32 v[166:167], v[166:167], v[184:185]
	v_pk_mul_f32 v[168:169], v[168:169], v[184:185]
	v_pk_mul_f32 v[170:171], v[170:171], v[184:185]
	v_pk_mul_f32 v[172:173], v[172:173], v[184:185]
	v_pk_mul_f32 v[174:175], v[174:175], v[184:185]
	v_pk_fma_f32 v[144:145], v[160:161], v[128:129], v[144:145]
	v_pk_fma_f32 v[146:147], v[162:163], v[130:131], v[146:147]
	v_pk_fma_f32 v[148:149], v[164:165], v[132:133], v[148:149]
	v_pk_fma_f32 v[150:151], v[166:167], v[134:135], v[150:151]
	v_pk_fma_f32 v[152:153], v[168:169], v[136:137], v[152:153]
	v_pk_fma_f32 v[154:155], v[170:171], v[138:139], v[154:155]
	v_pk_fma_f32 v[156:157], v[172:173], v[140:141], v[156:157]
	v_pk_fma_f32 v[158:159], v[174:175], v[142:143], v[158:159]
	v_pk_mul_f32 v[252:253], v[144:145], v[144:145]
	v_pk_mul_f32 v[254:255], v[146:147], v[146:147]
	v_pk_fma_f32 v[252:253], v[148:149], v[148:149], v[252:253]
	v_pk_fma_f32 v[254:255], v[150:151], v[150:151], v[254:255]
	v_pk_fma_f32 v[252:253], v[152:153], v[152:153], v[252:253]
	v_pk_fma_f32 v[254:255], v[154:155], v[154:155], v[254:255]
	v_pk_fma_f32 v[252:253], v[156:157], v[156:157], v[252:253]
	v_pk_fma_f32 v[254:255], v[158:159], v[158:159], v[254:255]
	v_pk_add_f32 v[252:253], v[252:253], v[254:255]
	s_nop 0
	v_add_f32_e32 v183, v252, v253
	s_nop 1
	v_add_f32_dpp v183, v183, v183 quad_perm:[1,0,3,2] row_mask:0xf bank_mask:0xf bound_ctrl:1
	s_nop 1
	v_add_f32_dpp v183, v183, v183 quad_perm:[2,3,0,1] row_mask:0xf bank_mask:0xf bound_ctrl:1
	s_nop 1
	v_add_f32_dpp v183, v183, v183 row_half_mirror row_mask:0xf bank_mask:0xf bound_ctrl:1
	s_nop 1
	v_add_f32_dpp v183, v183, v183 row_mirror row_mask:0xf bank_mask:0xf bound_ctrl:1
	s_nop 1
	v_readlane_b32 s98, v183, 0
	v_readlane_b32 s99, v183, 16
	v_readlane_b32 s100, v183, 32
	v_readlane_b32 s101, v183, 48
	s_nop 1
	v_mov_b32_e32 v183, s98
	v_add_f32_e32 v183, s99, v183
	v_add_f32_e32 v183, s100, v183
	v_add_f32_e32 v183, s101, v183
	v_fmamk_f32 v183, v183, 0x3a800000, v182
	v_cmp_gt_f32_e32 vcc, 0x800000, v183
	v_mul_f32_e32 v181, 0x4b800000, v183
	s_nop 1
	v_cndmask_b32_e32 v183, v183, v181, vcc
	v_rsq_f32_e32 v183, v183
	s_nop 0
	v_mul_f32_e32 v181, 0x45800000, v183
	v_cndmask_b32_e32 v184, v183, v181, vcc
	v_mov_b32_e32 v185, v184
	v_cvt_pk_bf16_f32 v112, v144, v145
	v_cvt_pk_bf16_f32 v113, v146, v147
	v_cvt_pk_bf16_f32 v114, v148, v149
	v_cvt_pk_bf16_f32 v115, v150, v151
	v_cvt_pk_bf16_f32 v116, v152, v153
	v_cvt_pk_bf16_f32 v117, v154, v155
	v_cvt_pk_bf16_f32 v118, v156, v157
	v_cvt_pk_bf16_f32 v119, v158, v159
	v_add_u32_e32 v181, 0x3400000, v177
	global_store_dwordx4 v181, v[112:115], s[78:79]
	global_store_dwordx4 v181, v[116:119], s[78:79] offset:1024
	v_add_u32_e32 v236, 0xe000, v237
	s_mov_b64 exec, 1
	global_store_dword v236, v184, s[78:79]
	s_mov_b64 exec, -1
	v_readfirstlane_b32 s98, v179
	s_nop 3
	s_and_b32 s99, s98, 3
	s_cmp_lg_u32 s99, 0
	s_cbranch_scc1 .Lmyxupd_done_1
	v_lshrrev_b32_e32 v179, 2, v179
	v_lshlrev_b32_e32 v177, 4, v176
	v_lshl_add_u32 v177, v179, 11, v177
	v_lshlrev_b32_e32 v237, 2, v179
	v_add_u32_e32 v237, 0x10000, v237
	v_add_u32_e32 v181, 0x3800000, v177
	global_load_dwordx4 v[240:243], v181, s[78:79]
	global_load_dwordx4 v[244:247], v181, s[78:79] offset:1024
	v_lshl_add_u32 v183, v179, 12, v180
	v_add_u32_e32 v183, 0xbf00000, v183
	v_add_u32_e32 v181, 0x0, v183
	global_load_dwordx4 v[0:3], v181, s[78:79]
	global_load_dwordx4 v[4:7], v181, s[78:79] offset:16
	global_load_dwordx4 v[8:11], v181, s[78:79] offset:2048
	global_load_dwordx4 v[12:15], v181, s[78:79] offset:2064
	v_add_u32_e32 v181, 0x200000, v183
	global_load_dwordx4 v[16:19], v181, s[78:79]
	global_load_dwordx4 v[20:23], v181, s[78:79] offset:16
	global_load_dwordx4 v[24:27], v181, s[78:79] offset:2048
	global_load_dwordx4 v[28:31], v181, s[78:79] offset:2064
	v_add_u32_e32 v181, 0x400000, v183
	global_load_dwordx4 v[32:35], v181, s[78:79]
	global_load_dwordx4 v[36:39], v181, s[78:79] offset:16
	global_load_dwordx4 v[40:43], v181, s[78:79] offset:2048
	global_load_dwordx4 v[44:47], v181, s[78:79] offset:2064
	v_add_u32_e32 v181, 0x600000, v183
	global_load_dwordx4 v[48:51], v181, s[78:79]
	global_load_dwordx4 v[52:55], v181, s[78:79] offset:16
	global_load_dwordx4 v[56:59], v181, s[78:79] offset:2048
	global_load_dwordx4 v[60:63], v181, s[78:79] offset:2064
	v_add_u32_e32 v181, 0x800000, v183
	global_load_dwordx4 v[64:67], v181, s[78:79]
	global_load_dwordx4 v[68:71], v181, s[78:79] offset:16
	global_load_dwordx4 v[72:75], v181, s[78:79] offset:2048
	global_load_dwordx4 v[76:79], v181, s[78:79] offset:2064
	v_add_u32_e32 v181, 0xa00000, v183
	global_load_dwordx4 v[80:83], v181, s[78:79]
	global_load_dwordx4 v[84:87], v181, s[78:79] offset:16
	global_load_dwordx4 v[88:91], v181, s[78:79] offset:2048
	global_load_dwordx4 v[92:95], v181, s[78:79] offset:2064
	v_add_u32_e32 v181, 0xc00000, v183
	global_load_dwordx4 v[96:99], v181, s[78:79]
	global_load_dwordx4 v[100:103], v181, s[78:79] offset:16
	global_load_dwordx4 v[104:107], v181, s[78:79] offset:2048
	global_load_dwordx4 v[108:111], v181, s[78:79] offset:2064
	v_add_u32_e32 v181, 0xe00000, v183
	global_load_dwordx4 v[112:115], v181, s[78:79]
	global_load_dwordx4 v[116:119], v181, s[78:79] offset:16
	global_load_dwordx4 v[120:123], v181, s[78:79] offset:2048
	global_load_dwordx4 v[124:127], v181, s[78:79] offset:2064
	s_waitcnt vmcnt(28)
	v_pk_add_f32 v[160:161], v[0:1], 0 op_sel_hi:[1,0]
	v_pk_add_f32 v[162:163], v[2:3], 0 op_sel_hi:[1,0]
	v_pk_add_f32 v[164:165], v[4:5], 0 op_sel_hi:[1,0]
	v_pk_add_f32 v[166:167], v[6:7], 0 op_sel_hi:[1,0]
	v_pk_add_f32 v[168:169], v[8:9], 0 op_sel_hi:[1,0]
	v_pk_add_f32 v[170:171], v[10:11], 0 op_sel_hi:[1,0]
	v_pk_add_f32 v[172:173], v[12:13], 0 op_sel_hi:[1,0]
	v_pk_add_f32 v[174:175], v[14:15], 0 op_sel_hi:[1,0]
	s_waitcnt vmcnt(24)
	v_pk_add_f32 v[160:161], v[160:161], v[16:17]
	v_pk_add_f32 v[162:163], v[162:163], v[18:19]
	v_pk_add_f32 v[164:165], v[164:165], v[20:21]
	v_pk_add_f32 v[166:167], v[166:167], v[22:23]
	v_pk_add_f32 v[168:169], v[168:169], v[24:25]
	v_pk_add_f32 v[170:171], v[170:171], v[26:27]
	v_pk_add_f32 v[172:173], v[172:173], v[28:29]
	v_pk_add_f32 v[174:175], v[174:175], v[30:31]
	s_waitcnt vmcnt(20)
	v_pk_add_f32 v[160:161], v[160:161], v[32:33]
	v_pk_add_f32 v[162:163], v[162:163], v[34:35]
	v_pk_add_f32 v[164:165], v[164:165], v[36:37]
	v_pk_add_f32 v[166:167], v[166:167], v[38:39]
	v_pk_add_f32 v[168:169], v[168:169], v[40:41]
	v_pk_add_f32 v[170:171], v[170:171], v[42:43]
	v_pk_add_f32 v[172:173], v[172:173], v[44:45]
	v_pk_add_f32 v[174:175], v[174:175], v[46:47]
	v_add_u32_e32 v181, 0x1000000, v183
	global_load_dwordx4 v[0:3], v181, s[78:79]
	global_load_dwordx4 v[4:7], v181, s[78:79] offset:16
	global_load_dwordx4 v[8:11], v181, s[78:79] offset:2048
	global_load_dwordx4 v[12:15], v181, s[78:79] offset:2064
	v_add_u32_e32 v181, 0x1200000, v183
	global_load_dwordx4 v[16:19], v181, s[78:79]
	global_load_dwordx4 v[20:23], v181, s[78:79] offset:16
	global_load_dwordx4 v[24:27], v181, s[78:79] offset:2048
	global_load_dwordx4 v[28:31], v181, s[78:79] offset:2064
	v_add_u32_e32 v181, 0x1400000, v183
	global_load_dwordx4 v[32:35], v181, s[78:79]
	global_load_dwordx4 v[36:39], v181, s[78:79] offset:16
	global_load_dwordx4 v[40:43], v181, s[78:79] offset:2048
	global_load_dwordx4 v[44:47], v181, s[78:79] offset:2064
	s_waitcnt vmcnt(28)
	v_pk_add_f32 v[160:161], v[160:161], v[48:49]
	v_pk_add_f32 v[162:163], v[162:163], v[50:51]
	v_pk_add_f32 v[164:165], v[164:165], v[52:53]
	v_pk_add_f32 v[166:167], v[166:167], v[54:55]
	v_pk_add_f32 v[168:169], v[168:169], v[56:57]
	v_pk_add_f32 v[170:171], v[170:171], v[58:59]
	v_pk_add_f32 v[172:173], v[172:173], v[60:61]
	v_pk_add_f32 v[174:175], v[174:175], v[62:63]
	s_waitcnt vmcnt(24)
	v_pk_add_f32 v[160:161], v[160:161], v[64:65]
	v_pk_add_f32 v[162:163], v[162:163], v[66:67]
	v_pk_add_f32 v[164:165], v[164:165], v[68:69]
	v_pk_add_f32 v[166:167], v[166:167], v[70:71]
	v_pk_add_f32 v[168:169], v[168:169], v[72:73]
	v_pk_add_f32 v[170:171], v[170:171], v[74:75]
	v_pk_add_f32 v[172:173], v[172:173], v[76:77]
	v_pk_add_f32 v[174:175], v[174:175], v[78:79]
	s_waitcnt vmcnt(20)
	v_pk_add_f32 v[160:161], v[160:161], v[80:81]
	v_pk_add_f32 v[162:163], v[162:163], v[82:83]
	v_pk_add_f32 v[164:165], v[164:165], v[84:85]
	v_pk_add_f32 v[166:167], v[166:167], v[86:87]
	v_pk_add_f32 v[168:169], v[168:169], v[88:89]
	v_pk_add_f32 v[170:171], v[170:171], v[90:91]
	v_pk_add_f32 v[172:173], v[172:173], v[92:93]
	v_pk_add_f32 v[174:175], v[174:175], v[94:95]
	s_waitcnt vmcnt(16)
	v_pk_add_f32 v[160:161], v[160:161], v[96:97]
	v_pk_add_f32 v[162:163], v[162:163], v[98:99]
	v_pk_add_f32 v[164:165], v[164:165], v[100:101]
	v_pk_add_f32 v[166:167], v[166:167], v[102:103]
	v_pk_add_f32 v[168:169], v[168:169], v[104:105]
	v_pk_add_f32 v[170:171], v[170:171], v[106:107]
	v_pk_add_f32 v[172:173], v[172:173], v[108:109]
	v_pk_add_f32 v[174:175], v[174:175], v[110:111]
	s_waitcnt vmcnt(12)
	v_pk_add_f32 v[160:161], v[160:161], v[112:113]
	v_pk_add_f32 v[162:163], v[162:163], v[114:115]
	v_pk_add_f32 v[164:165], v[164:165], v[116:117]
	v_pk_add_f32 v[166:167], v[166:167], v[118:119]
	v_pk_add_f32 v[168:169], v[168:169], v[120:121]
	v_pk_add_f32 v[170:171], v[170:171], v[122:123]
	v_pk_add_f32 v[172:173], v[172:173], v[124:125]
	v_pk_add_f32 v[174:175], v[174:175], v[126:127]
	v_lshlrev_b32_e32 v144, 16, v240
	v_and_b32_e32 v145, 0xffff0000, v240
	v_lshlrev_b32_e32 v146, 16, v241
	v_and_b32_e32 v147, 0xffff0000, v241
	v_lshlrev_b32_e32 v148, 16, v242
	v_and_b32_e32 v149, 0xffff0000, v242
	v_lshlrev_b32_e32 v150, 16, v243
	v_and_b32_e32 v151, 0xffff0000, v243
	v_lshlrev_b32_e32 v152, 16, v244
	v_and_b32_e32 v153, 0xffff0000, v244
	v_lshlrev_b32_e32 v154, 16, v245
	v_and_b32_e32 v155, 0xffff0000, v245
	v_lshlrev_b32_e32 v156, 16, v246
	v_and_b32_e32 v157, 0xffff0000, v246
	v_lshlrev_b32_e32 v158, 16, v247
	v_and_b32_e32 v159, 0xffff0000, v247
	s_waitcnt vmcnt(8)
	v_pk_add_f32 v[160:161], v[160:161], v[0:1]
	v_pk_add_f32 v[162:163], v[162:163], v[2:3]
	v_pk_add_f32 v[164:165], v[164:165], v[4:5]
	v_pk_add_f32 v[166:167], v[166:167], v[6:7]
	v_pk_add_f32 v[168:169], v[168:169], v[8:9]
	v_pk_add_f32 v[170:171], v[170:171], v[10:11]
	v_pk_add_f32 v[172:173], v[172:173], v[12:13]
	v_pk_add_f32 v[174:175], v[174:175], v[14:15]
	s_waitcnt vmcnt(4)
	v_pk_add_f32 v[160:161], v[160:161], v[16:17]
	v_pk_add_f32 v[162:163], v[162:163], v[18:19]
	v_pk_add_f32 v[164:165], v[164:165], v[20:21]
	v_pk_add_f32 v[166:167], v[166:167], v[22:23]
	v_pk_add_f32 v[168:169], v[168:169], v[24:25]
	v_pk_add_f32 v[170:171], v[170:171], v[26:27]
	v_pk_add_f32 v[172:173], v[172:173], v[28:29]
	v_pk_add_f32 v[174:175], v[174:175], v[30:31]
	s_waitcnt vmcnt(0)
	v_pk_add_f32 v[160:161], v[160:161], v[32:33]
	v_pk_add_f32 v[162:163], v[162:163], v[34:35]
	v_pk_add_f32 v[164:165], v[164:165], v[36:37]
	v_pk_add_f32 v[166:167], v[166:167], v[38:39]
	v_pk_add_f32 v[168:169], v[168:169], v[40:41]
	v_pk_add_f32 v[170:171], v[170:171], v[42:43]
	v_pk_add_f32 v[172:173], v[172:173], v[44:45]
	v_pk_add_f32 v[174:175], v[174:175], v[46:47]
	v_pk_mul_f32 v[252:253], v[160:161], v[160:161]
	v_pk_mul_f32 v[254:255], v[162:163], v[162:163]
	v_pk_fma_f32 v[252:253], v[164:165], v[164:165], v[252:253]
	v_pk_fma_f32 v[254:255], v[166:167], v[166:167], v[254:255]
	v_pk_fma_f32 v[252:253], v[168:169], v[168:169], v[252:253]
	v_pk_fma_f32 v[254:255], v[170:171], v[170:171], v[254:255]
	v_pk_fma_f32 v[252:253], v[172:173], v[172:173], v[252:253]
	v_pk_fma_f32 v[254:255], v[174:175], v[174:175], v[254:255]
	v_pk_add_f32 v[252:253], v[252:253], v[254:255]
	s_nop 0
	v_add_f32_e32 v183, v252, v253
	s_nop 1
	v_add_f32_dpp v183, v183, v183 quad_perm:[1,0,3,2] row_mask:0xf bank_mask:0xf bound_ctrl:1
	s_nop 1
	v_add_f32_dpp v183, v183, v183 quad_perm:[2,3,0,1] row_mask:0xf bank_mask:0xf bound_ctrl:1
	s_nop 1
	v_add_f32_dpp v183, v183, v183 row_half_mirror row_mask:0xf bank_mask:0xf bound_ctrl:1
	s_nop 1
	v_add_f32_dpp v183, v183, v183 row_mirror row_mask:0xf bank_mask:0xf bound_ctrl:1
	s_nop 1
	v_readlane_b32 s98, v183, 0
	v_readlane_b32 s99, v183, 16
	v_readlane_b32 s100, v183, 32
	v_readlane_b32 s101, v183, 48
	s_nop 1
	v_mov_b32_e32 v183, s98
	v_add_f32_e32 v183, s99, v183
	v_add_f32_e32 v183, s100, v183
	v_add_f32_e32 v183, s101, v183
	v_fmamk_f32 v183, v183, 0x3a800000, v182
	v_cmp_gt_f32_e32 vcc, 0x800000, v183
	v_mul_f32_e32 v181, 0x4b800000, v183
	s_nop 1
	v_cndmask_b32_e32 v183, v183, v181, vcc
	v_rsq_f32_e32 v183, v183
	s_nop 0
	v_mul_f32_e32 v181, 0x45800000, v183
	v_cndmask_b32_e32 v184, v183, v181, vcc
	v_mov_b32_e32 v185, v184
	v_pk_mul_f32 v[160:161], v[160:161], v[184:185]
	v_pk_mul_f32 v[162:163], v[162:163], v[184:185]
	v_pk_mul_f32 v[164:165], v[164:165], v[184:185]
	v_pk_mul_f32 v[166:167], v[166:167], v[184:185]
	v_pk_mul_f32 v[168:169], v[168:169], v[184:185]
	v_pk_mul_f32 v[170:171], v[170:171], v[184:185]
	v_pk_mul_f32 v[172:173], v[172:173], v[184:185]
	v_pk_mul_f32 v[174:175], v[174:175], v[184:185]
	v_pk_fma_f32 v[144:145], v[160:161], v[128:129], v[144:145]
	v_pk_fma_f32 v[146:147], v[162:163], v[130:131], v[146:147]
	v_pk_fma_f32 v[148:149], v[164:165], v[132:133], v[148:149]
	v_pk_fma_f32 v[150:151], v[166:167], v[134:135], v[150:151]
	v_pk_fma_f32 v[152:153], v[168:169], v[136:137], v[152:153]
	v_pk_fma_f32 v[154:155], v[170:171], v[138:139], v[154:155]
	v_pk_fma_f32 v[156:157], v[172:173], v[140:141], v[156:157]
	v_pk_fma_f32 v[158:159], v[174:175], v[142:143], v[158:159]
	v_pk_mul_f32 v[252:253], v[144:145], v[144:145]
	v_pk_mul_f32 v[254:255], v[146:147], v[146:147]
	v_pk_fma_f32 v[252:253], v[148:149], v[148:149], v[252:253]
	v_pk_fma_f32 v[254:255], v[150:151], v[150:151], v[254:255]
	v_pk_fma_f32 v[252:253], v[152:153], v[152:153], v[252:253]
	v_pk_fma_f32 v[254:255], v[154:155], v[154:155], v[254:255]
	v_pk_fma_f32 v[252:253], v[156:157], v[156:157], v[252:253]
	v_pk_fma_f32 v[254:255], v[158:159], v[158:159], v[254:255]
	v_pk_add_f32 v[252:253], v[252:253], v[254:255]
	s_nop 0
	v_add_f32_e32 v183, v252, v253
	s_nop 1
	v_add_f32_dpp v183, v183, v183 quad_perm:[1,0,3,2] row_mask:0xf bank_mask:0xf bound_ctrl:1
	s_nop 1
	v_add_f32_dpp v183, v183, v183 quad_perm:[2,3,0,1] row_mask:0xf bank_mask:0xf bound_ctrl:1
	s_nop 1
	v_add_f32_dpp v183, v183, v183 row_half_mirror row_mask:0xf bank_mask:0xf bound_ctrl:1
	s_nop 1
	v_add_f32_dpp v183, v183, v183 row_mirror row_mask:0xf bank_mask:0xf bound_ctrl:1
	s_nop 1
	v_readlane_b32 s98, v183, 0
	v_readlane_b32 s99, v183, 16
	v_readlane_b32 s100, v183, 32
	v_readlane_b32 s101, v183, 48
	s_nop 1
	v_mov_b32_e32 v183, s98
	v_add_f32_e32 v183, s99, v183
	v_add_f32_e32 v183, s100, v183
	v_add_f32_e32 v183, s101, v183
	v_fmamk_f32 v183, v183, 0x3a800000, v182
	v_cmp_gt_f32_e32 vcc, 0x800000, v183
	v_mul_f32_e32 v181, 0x4b800000, v183
	s_nop 1
	v_cndmask_b32_e32 v183, v183, v181, vcc
	v_rsq_f32_e32 v183, v183
	s_nop 0
	v_mul_f32_e32 v181, 0x45800000, v183
	v_cndmask_b32_e32 v184, v183, v181, vcc
	v_mov_b32_e32 v185, v184
	v_cvt_pk_bf16_f32 v0, v144, v145
	v_cvt_pk_bf16_f32 v1, v146, v147
	v_cvt_pk_bf16_f32 v2, v148, v149
	v_cvt_pk_bf16_f32 v3, v150, v151
	v_cvt_pk_bf16_f32 v4, v152, v153
	v_cvt_pk_bf16_f32 v5, v154, v155
	v_cvt_pk_bf16_f32 v6, v156, v157
	v_cvt_pk_bf16_f32 v7, v158, v159
	v_add_u32_e32 v181, 0x3800000, v177
	global_store_dwordx4 v181, v[0:3], s[78:79]
	global_store_dwordx4 v181, v[4:7], s[78:79] offset:1024
	v_add_u32_e32 v236, 0x10000, v237
	s_mov_b64 exec, 1
	global_store_dword v236, v184, s[78:79]
	s_mov_b64 exec, -1

.LBB0_1154:
	v_readlane_b32 s0, v235, 52
	v_readlane_b32 s1, v235, 53
	s_and_b64 vcc, exec, s[0:1]
	s_waitcnt lgkmcnt(0)
	s_barrier
	v_mbcnt_lo_u32_b32 v0, -1, 0
	v_mbcnt_hi_u32_b32 v0, -1, v0
	s_cbranch_vccnz .LBB0_1174
	v_lshlrev_b32_e32 v2, 3, v0
	v_ashrrev_i32_e32 v3, 31, v2
	v_readlane_b32 s4, v235, 4
	v_lshlrev_b64 v[4:5], 1, v[2:3]
	v_lshlrev_b64 v[2:3], 2, v[2:3]
	v_readlane_b32 s14, v235, 14
	v_readlane_b32 s15, v235, 15
	v_lshl_add_u64 v[62:63], s[90:91], 0, v[2:3]
	v_readlane_b32 s5, v235, 5
	v_readlane_b32 s6, v235, 6
	v_readlane_b32 s7, v235, 7
	v_readlane_b32 s8, v235, 8
	v_readlane_b32 s9, v235, 9
	v_readlane_b32 s10, v235, 10
	v_readlane_b32 s11, v235, 11
	v_readlane_b32 s12, v235, 12
	v_readlane_b32 s13, v235, 13
	v_readlane_b32 s16, v235, 16
	v_readlane_b32 s17, v235, 17
	v_readlane_b32 s18, v235, 18
	v_readlane_b32 s19, v235, 19
	v_lshl_add_u64 v[2:3], s[14:15], 0, v[2:3]
	s_mov_b64 s[0:1], 0x1000
	v_lshl_add_u64 v[60:61], s[86:87], 0, v[4:5]
	v_lshl_add_u64 v[64:65], s[54:55], 0, v[4:5]
	v_lshl_add_u64 v[66:67], v[2:3], 0, s[0:1]
	s_mov_b32 s1, 0
	v_cmp_eq_u32_e64 s[12:13], 0, v0
	s_mov_b64 s[4:5], 0x200000
	s_mov_b64 s[6:7], 0x200800
	s_mov_b64 s[8:9], 0x400000
	s_mov_b64 s[10:11], 0x400800
	s_mov_b64 s[14:15], 0x600000
	s_mov_b64 s[16:17], 0x600800
	s_mov_b64 s[18:19], 0x800000
	s_mov_b32 s48, 0x800000
	s_mov_b64 s[20:21], 0x800800
	s_mov_b64 s[22:23], 0xa00000
	s_mov_b64 s[24:25], 0xa00800
	s_mov_b64 s[26:27], 0xc00000
	s_mov_b64 s[28:29], 0xc00800
	s_mov_b64 s[36:37], 0xe00000
	s_mov_b64 s[38:39], 0xe00800
	v_mov_b32_e32 v104, 0
	v_mov_b32_e32 v105, 0x358637bd
	v_readlane_b32 s42, v235, 61
	v_readlane_b32 s43, v235, 62
	v_mbcnt_lo_u32_b32 v176, -1, 0
	v_mbcnt_hi_u32_b32 v176, -1, v176
	v_readlane_b32 s98, v235, 49
	v_readlane_b32 s99, v235, 20
	v_readlane_b32 s100, v235, 14
	v_readlane_b32 s101, v235, 15
	s_nop 3
	s_lshr_b32 vcc_lo, s98, 3
	s_and_b32 vcc_hi, vcc_lo, 7
	s_lshr_b32 vcc_lo, vcc_lo, 3
	s_lshl_b32 vcc_lo, vcc_lo, 3
	s_add_i32 vcc_lo, vcc_lo, s99
	s_lshl_b32 s98, vcc_hi, 8
	s_add_i32 s98, s98, vcc_lo
	s_mov_b32 s99, s98
	v_mov_b32_e32 v183, s99
	v_lshlrev_b32_e32 v177, 4, v176
	s_lshl_b32 s99, s99, 11
	v_add_u32_e32 v177, s99, v177
	v_add_u32_e32 v178, 0x1800000, v177
	v_add_u32_e32 v179, 0x9e00000, v177
	v_lshlrev_b32_e32 v180, 5, v176
	v_add_u32_e32 v181, 0x1000, v180
	global_load_dwordx4 v[128:131], v181, s[100:101]
	global_load_dwordx4 v[132:135], v181, s[100:101] offset:16
	global_load_dwordx4 v[136:139], v181, s[100:101] offset:2048
	global_load_dwordx4 v[140:143], v181, s[100:101] offset:2064
	v_mov_b32_e32 v182, 0x358637bd
	global_load_dwordx4 v[0:3], v178, s[78:79]
	global_load_dwordx4 v[4:7], v178, s[78:79] offset:1024
	global_load_dwordx4 v[8:11], v179, s[78:79]
	global_load_dwordx4 v[12:15], v179, s[78:79] offset:1024
	v_add_u32_e32 v178, 0x400000, v178
	v_add_u32_e32 v179, 0x400000, v179
	global_load_dwordx4 v[16:19], v178, s[78:79]
	global_load_dwordx4 v[20:23], v178, s[78:79] offset:1024
	global_load_dwordx4 v[24:27], v179, s[78:79]
	global_load_dwordx4 v[28:31], v179, s[78:79] offset:1024
	v_add_u32_e32 v178, 0x400000, v178
	v_add_u32_e32 v179, 0x400000, v179
	global_load_dwordx4 v[32:35], v178, s[78:79]
	global_load_dwordx4 v[36:39], v178, s[78:79] offset:1024
	global_load_dwordx4 v[40:43], v179, s[78:79]
	global_load_dwordx4 v[44:47], v179, s[78:79] offset:1024
	v_add_u32_e32 v178, 0x400000, v178
	v_add_u32_e32 v179, 0x400000, v179
	global_load_dwordx4 v[48:51], v178, s[78:79]
	global_load_dwordx4 v[52:55], v178, s[78:79] offset:1024
	global_load_dwordx4 v[56:59], v179, s[78:79]
	global_load_dwordx4 v[60:63], v179, s[78:79] offset:1024
	v_add_u32_e32 v178, 0x400000, v178
	v_add_u32_e32 v179, 0x400000, v179
	global_load_dwordx4 v[64:67], v178, s[78:79]
	global_load_dwordx4 v[68:71], v178, s[78:79] offset:1024
	global_load_dwordx4 v[72:75], v179, s[78:79]
	global_load_dwordx4 v[76:79], v179, s[78:79] offset:1024
	v_add_u32_e32 v178, 0x400000, v178
	v_add_u32_e32 v179, 0x400000, v179
	global_load_dwordx4 v[80:83], v178, s[78:79]
	global_load_dwordx4 v[84:87], v178, s[78:79] offset:1024
	global_load_dwordx4 v[88:91], v179, s[78:79]
	global_load_dwordx4 v[92:95], v179, s[78:79] offset:1024
	v_add_u32_e32 v178, 0x400000, v178
	v_add_u32_e32 v179, 0x400000, v179
	global_load_dwordx4 v[96:99], v178, s[78:79]
	global_load_dwordx4 v[100:103], v178, s[78:79] offset:1024
	global_load_dwordx4 v[104:107], v179, s[78:79]
	global_load_dwordx4 v[108:111], v179, s[78:79] offset:1024
	v_add_u32_e32 v178, 0x400000, v178
	v_add_u32_e32 v179, 0x400000, v179
	global_load_dwordx4 v[112:115], v178, s[78:79]
	global_load_dwordx4 v[116:119], v178, s[78:79] offset:1024
	global_load_dwordx4 v[120:123], v179, s[78:79]
	global_load_dwordx4 v[124:127], v179, s[78:79] offset:1024
	v_lshlrev_b32_e32 v237, 2, v183
	v_add_u32_e32 v237, 0x10000, v237
	v_mov_b32_e32 v179, s98
	s_waitcnt vmcnt(28)
	v_lshlrev_b32_e32 v144, 16, v0
	v_and_b32_e32 v145, 0xffff0000, v0
	v_lshlrev_b32_e32 v146, 16, v1
	v_and_b32_e32 v147, 0xffff0000, v1
	v_lshlrev_b32_e32 v148, 16, v2
	v_and_b32_e32 v149, 0xffff0000, v2
	v_lshlrev_b32_e32 v150, 16, v3
	v_and_b32_e32 v151, 0xffff0000, v3
	v_lshlrev_b32_e32 v152, 16, v4
	v_and_b32_e32 v153, 0xffff0000, v4
	v_lshlrev_b32_e32 v154, 16, v5
	v_and_b32_e32 v155, 0xffff0000, v5
	v_lshlrev_b32_e32 v156, 16, v6
	v_and_b32_e32 v157, 0xffff0000, v6
	v_lshlrev_b32_e32 v158, 16, v7
	v_and_b32_e32 v159, 0xffff0000, v7
	v_lshlrev_b32_e32 v160, 16, v8
	v_and_b32_e32 v161, 0xffff0000, v8
	v_lshlrev_b32_e32 v162, 16, v9
	v_and_b32_e32 v163, 0xffff0000, v9
	v_lshlrev_b32_e32 v164, 16, v10
	v_and_b32_e32 v165, 0xffff0000, v10
	v_lshlrev_b32_e32 v166, 16, v11
	v_and_b32_e32 v167, 0xffff0000, v11
	v_lshlrev_b32_e32 v168, 16, v12
	v_and_b32_e32 v169, 0xffff0000, v12
	v_lshlrev_b32_e32 v170, 16, v13
	v_and_b32_e32 v171, 0xffff0000, v13
	v_lshlrev_b32_e32 v172, 16, v14
	v_and_b32_e32 v173, 0xffff0000, v14
	v_lshlrev_b32_e32 v174, 16, v15
	v_and_b32_e32 v175, 0xffff0000, v15
	v_pk_mul_f32 v[252:253], v[160:161], v[160:161]
	v_pk_mul_f32 v[254:255], v[162:163], v[162:163]
	v_pk_fma_f32 v[252:253], v[164:165], v[164:165], v[252:253]
	v_pk_fma_f32 v[254:255], v[166:167], v[166:167], v[254:255]
	v_pk_fma_f32 v[252:253], v[168:169], v[168:169], v[252:253]
	v_pk_fma_f32 v[254:255], v[170:171], v[170:171], v[254:255]
	v_pk_fma_f32 v[252:253], v[172:173], v[172:173], v[252:253]
	v_pk_fma_f32 v[254:255], v[174:175], v[174:175], v[254:255]
	v_pk_add_f32 v[252:253], v[252:253], v[254:255]
	s_nop 0
	v_add_f32_e32 v183, v252, v253
	s_nop 1
	v_add_f32_dpp v183, v183, v183 quad_perm:[1,0,3,2] row_mask:0xf bank_mask:0xf bound_ctrl:1
	s_nop 1
	v_add_f32_dpp v183, v183, v183 quad_perm:[2,3,0,1] row_mask:0xf bank_mask:0xf bound_ctrl:1
	s_nop 1
	v_add_f32_dpp v183, v183, v183 row_half_mirror row_mask:0xf bank_mask:0xf bound_ctrl:1
	s_nop 1
	v_add_f32_dpp v183, v183, v183 row_mirror row_mask:0xf bank_mask:0xf bound_ctrl:1
	s_nop 1
	v_readlane_b32 s98, v183, 0
	v_readlane_b32 s99, v183, 16
	v_readlane_b32 s100, v183, 32
	v_readlane_b32 s101, v183, 48
	s_nop 1
	v_mov_b32_e32 v183, s98
	v_add_f32_e32 v183, s99, v183
	v_add_f32_e32 v183, s100, v183
	v_add_f32_e32 v183, s101, v183
	v_fmamk_f32 v183, v183, 0x3a800000, v182
	v_cmp_gt_f32_e32 vcc, 0x800000, v183
	v_mul_f32_e32 v181, 0x4b800000, v183
	s_nop 1
	v_cndmask_b32_e32 v183, v183, v181, vcc
	v_rsq_f32_e32 v183, v183
	s_nop 0
	v_mul_f32_e32 v181, 0x45800000, v183
	v_cndmask_b32_e32 v184, v183, v181, vcc
	v_mov_b32_e32 v185, v184
	v_pk_mul_f32 v[160:161], v[160:161], v[184:185]
	v_pk_mul_f32 v[162:163], v[162:163], v[184:185]
	v_pk_mul_f32 v[164:165], v[164:165], v[184:185]
	v_pk_mul_f32 v[166:167], v[166:167], v[184:185]
	v_pk_mul_f32 v[168:169], v[168:169], v[184:185]
	v_pk_mul_f32 v[170:171], v[170:171], v[184:185]
	v_pk_mul_f32 v[172:173], v[172:173], v[184:185]
	v_pk_mul_f32 v[174:175], v[174:175], v[184:185]
	v_pk_fma_f32 v[144:145], v[160:161], v[128:129], v[144:145]
	v_pk_fma_f32 v[146:147], v[162:163], v[130:131], v[146:147]
	v_pk_fma_f32 v[148:149], v[164:165], v[132:133], v[148:149]
	v_pk_fma_f32 v[150:151], v[166:167], v[134:135], v[150:151]
	v_pk_fma_f32 v[152:153], v[168:169], v[136:137], v[152:153]
	v_pk_fma_f32 v[154:155], v[170:171], v[138:139], v[154:155]
	v_pk_fma_f32 v[156:157], v[172:173], v[140:141], v[156:157]
	v_pk_fma_f32 v[158:159], v[174:175], v[142:143], v[158:159]
	v_pk_mul_f32 v[252:253], v[144:145], v[144:145]
	v_pk_mul_f32 v[254:255], v[146:147], v[146:147]
	v_pk_fma_f32 v[252:253], v[148:149], v[148:149], v[252:253]
	v_pk_fma_f32 v[254:255], v[150:151], v[150:151], v[254:255]
	v_pk_fma_f32 v[252:253], v[152:153], v[152:153], v[252:253]
	v_pk_fma_f32 v[254:255], v[154:155], v[154:155], v[254:255]
	v_pk_fma_f32 v[252:253], v[156:157], v[156:157], v[252:253]
	v_pk_fma_f32 v[254:255], v[158:159], v[158:159], v[254:255]
	v_pk_add_f32 v[252:253], v[252:253], v[254:255]
	s_nop 0
	v_add_f32_e32 v183, v252, v253
	s_nop 1
	v_add_f32_dpp v183, v183, v183 quad_perm:[1,0,3,2] row_mask:0xf bank_mask:0xf bound_ctrl:1
	s_nop 1
	v_add_f32_dpp v183, v183, v183 quad_perm:[2,3,0,1] row_mask:0xf bank_mask:0xf bound_ctrl:1
	s_nop 1
	v_add_f32_dpp v183, v183, v183 row_half_mirror row_mask:0xf bank_mask:0xf bound_ctrl:1
	s_nop 1
	v_add_f32_dpp v183, v183, v183 row_mirror row_mask:0xf bank_mask:0xf bound_ctrl:1
	s_nop 1
	v_readlane_b32 s98, v183, 0
	v_readlane_b32 s99, v183, 16
	v_readlane_b32 s100, v183, 32
	v_readlane_b32 s101, v183, 48
	s_nop 1
	v_mov_b32_e32 v183, s98
	v_add_f32_e32 v183, s99, v183
	v_add_f32_e32 v183, s100, v183
	v_add_f32_e32 v183, s101, v183
	v_fmamk_f32 v183, v183, 0x3a800000, v182
	v_cmp_gt_f32_e32 vcc, 0x800000, v183
	v_mul_f32_e32 v181, 0x4b800000, v183
	s_nop 1
	v_cndmask_b32_e32 v183, v183, v181, vcc
	v_rsq_f32_e32 v183, v183
	s_nop 0
	v_mul_f32_e32 v181, 0x45800000, v183
	v_cndmask_b32_e32 v184, v183, v181, vcc
	v_mov_b32_e32 v185, v184
	v_cvt_pk_bf16_f32 v0, v144, v145
	v_cvt_pk_bf16_f32 v1, v146, v147
	v_cvt_pk_bf16_f32 v2, v148, v149
	v_cvt_pk_bf16_f32 v3, v150, v151
	v_cvt_pk_bf16_f32 v4, v152, v153
	v_cvt_pk_bf16_f32 v5, v154, v155
	v_cvt_pk_bf16_f32 v6, v156, v157
	v_cvt_pk_bf16_f32 v7, v158, v159
	v_add_u32_e32 v181, 0x1800000, v177
	global_store_dwordx4 v181, v[0:3], s[78:79]
	global_store_dwordx4 v181, v[4:7], s[78:79] offset:1024
	v_add_u32_e32 v236, 0x0, v237
	s_mov_b64 exec, 1
	global_store_dword v236, v184, s[78:79]
	s_mov_b64 exec, -1
	s_waitcnt vmcnt(24)
	v_lshlrev_b32_e32 v144, 16, v16
	v_and_b32_e32 v145, 0xffff0000, v16
	v_lshlrev_b32_e32 v146, 16, v17
	v_and_b32_e32 v147, 0xffff0000, v17
	v_lshlrev_b32_e32 v148, 16, v18
	v_and_b32_e32 v149, 0xffff0000, v18
	v_lshlrev_b32_e32 v150, 16, v19
	v_and_b32_e32 v151, 0xffff0000, v19
	v_lshlrev_b32_e32 v152, 16, v20
	v_and_b32_e32 v153, 0xffff0000, v20
	v_lshlrev_b32_e32 v154, 16, v21
	v_and_b32_e32 v155, 0xffff0000, v21
	v_lshlrev_b32_e32 v156, 16, v22
	v_and_b32_e32 v157, 0xffff0000, v22
	v_lshlrev_b32_e32 v158, 16, v23
	v_and_b32_e32 v159, 0xffff0000, v23
	v_lshlrev_b32_e32 v160, 16, v24
	v_and_b32_e32 v161, 0xffff0000, v24
	v_lshlrev_b32_e32 v162, 16, v25
	v_and_b32_e32 v163, 0xffff0000, v25
	v_lshlrev_b32_e32 v164, 16, v26
	v_and_b32_e32 v165, 0xffff0000, v26
	v_lshlrev_b32_e32 v166, 16, v27
	v_and_b32_e32 v167, 0xffff0000, v27
	v_lshlrev_b32_e32 v168, 16, v28
	v_and_b32_e32 v169, 0xffff0000, v28
	v_lshlrev_b32_e32 v170, 16, v29
	v_and_b32_e32 v171, 0xffff0000, v29
	v_lshlrev_b32_e32 v172, 16, v30
	v_and_b32_e32 v173, 0xffff0000, v30
	v_lshlrev_b32_e32 v174, 16, v31
	v_and_b32_e32 v175, 0xffff0000, v31
	v_pk_mul_f32 v[252:253], v[160:161], v[160:161]
	v_pk_mul_f32 v[254:255], v[162:163], v[162:163]
	v_pk_fma_f32 v[252:253], v[164:165], v[164:165], v[252:253]
	v_pk_fma_f32 v[254:255], v[166:167], v[166:167], v[254:255]
	v_pk_fma_f32 v[252:253], v[168:169], v[168:169], v[252:253]
	v_pk_fma_f32 v[254:255], v[170:171], v[170:171], v[254:255]
	v_pk_fma_f32 v[252:253], v[172:173], v[172:173], v[252:253]
	v_pk_fma_f32 v[254:255], v[174:175], v[174:175], v[254:255]
	v_pk_add_f32 v[252:253], v[252:253], v[254:255]
	s_nop 0
	v_add_f32_e32 v183, v252, v253
	s_nop 1
	v_add_f32_dpp v183, v183, v183 quad_perm:[1,0,3,2] row_mask:0xf bank_mask:0xf bound_ctrl:1
	s_nop 1
	v_add_f32_dpp v183, v183, v183 quad_perm:[2,3,0,1] row_mask:0xf bank_mask:0xf bound_ctrl:1
	s_nop 1
	v_add_f32_dpp v183, v183, v183 row_half_mirror row_mask:0xf bank_mask:0xf bound_ctrl:1
	s_nop 1
	v_add_f32_dpp v183, v183, v183 row_mirror row_mask:0xf bank_mask:0xf bound_ctrl:1
	s_nop 1
	v_readlane_b32 s98, v183, 0
	v_readlane_b32 s99, v183, 16
	v_readlane_b32 s100, v183, 32
	v_readlane_b32 s101, v183, 48
	s_nop 1
	v_mov_b32_e32 v183, s98
	v_add_f32_e32 v183, s99, v183
	v_add_f32_e32 v183, s100, v183
	v_add_f32_e32 v183, s101, v183
	v_fmamk_f32 v183, v183, 0x3a800000, v182
	v_cmp_gt_f32_e32 vcc, 0x800000, v183
	v_mul_f32_e32 v181, 0x4b800000, v183
	s_nop 1
	v_cndmask_b32_e32 v183, v183, v181, vcc
	v_rsq_f32_e32 v183, v183
	s_nop 0
	v_mul_f32_e32 v181, 0x45800000, v183
	v_cndmask_b32_e32 v184, v183, v181, vcc
	v_mov_b32_e32 v185, v184
	v_pk_mul_f32 v[160:161], v[160:161], v[184:185]
	v_pk_mul_f32 v[162:163], v[162:163], v[184:185]
	v_pk_mul_f32 v[164:165], v[164:165], v[184:185]
	v_pk_mul_f32 v[166:167], v[166:167], v[184:185]
	v_pk_mul_f32 v[168:169], v[168:169], v[184:185]
	v_pk_mul_f32 v[170:171], v[170:171], v[184:185]
	v_pk_mul_f32 v[172:173], v[172:173], v[184:185]
	v_pk_mul_f32 v[174:175], v[174:175], v[184:185]
	v_pk_fma_f32 v[144:145], v[160:161], v[128:129], v[144:145]
	v_pk_fma_f32 v[146:147], v[162:163], v[130:131], v[146:147]
	v_pk_fma_f32 v[148:149], v[164:165], v[132:133], v[148:149]
	v_pk_fma_f32 v[150:151], v[166:167], v[134:135], v[150:151]
	v_pk_fma_f32 v[152:153], v[168:169], v[136:137], v[152:153]
	v_pk_fma_f32 v[154:155], v[170:171], v[138:139], v[154:155]
	v_pk_fma_f32 v[156:157], v[172:173], v[140:141], v[156:157]
	v_pk_fma_f32 v[158:159], v[174:175], v[142:143], v[158:159]
	v_pk_mul_f32 v[252:253], v[144:145], v[144:145]
	v_pk_mul_f32 v[254:255], v[146:147], v[146:147]
	v_pk_fma_f32 v[252:253], v[148:149], v[148:149], v[252:253]
	v_pk_fma_f32 v[254:255], v[150:151], v[150:151], v[254:255]
	v_pk_fma_f32 v[252:253], v[152:153], v[152:153], v[252:253]
	v_pk_fma_f32 v[254:255], v[154:155], v[154:155], v[254:255]
	v_pk_fma_f32 v[252:253], v[156:157], v[156:157], v[252:253]
	v_pk_fma_f32 v[254:255], v[158:159], v[158:159], v[254:255]
	v_pk_add_f32 v[252:253], v[252:253], v[254:255]
	s_nop 0
	v_add_f32_e32 v183, v252, v253
	s_nop 1
	v_add_f32_dpp v183, v183, v183 quad_perm:[1,0,3,2] row_mask:0xf bank_mask:0xf bound_ctrl:1
	s_nop 1
	v_add_f32_dpp v183, v183, v183 quad_perm:[2,3,0,1] row_mask:0xf bank_mask:0xf bound_ctrl:1
	s_nop 1
	v_add_f32_dpp v183, v183, v183 row_half_mirror row_mask:0xf bank_mask:0xf bound_ctrl:1
	s_nop 1
	v_add_f32_dpp v183, v183, v183 row_mirror row_mask:0xf bank_mask:0xf bound_ctrl:1
	s_nop 1
	v_readlane_b32 s98, v183, 0
	v_readlane_b32 s99, v183, 16
	v_readlane_b32 s100, v183, 32
	v_readlane_b32 s101, v183, 48
	s_nop 1
	v_mov_b32_e32 v183, s98
	v_add_f32_e32 v183, s99, v183
	v_add_f32_e32 v183, s100, v183
	v_add_f32_e32 v183, s101, v183
	v_fmamk_f32 v183, v183, 0x3a800000, v182
	v_cmp_gt_f32_e32 vcc, 0x800000, v183
	v_mul_f32_e32 v181, 0x4b800000, v183
	s_nop 1
	v_cndmask_b32_e32 v183, v183, v181, vcc
	v_rsq_f32_e32 v183, v183
	s_nop 0
	v_mul_f32_e32 v181, 0x45800000, v183
	v_cndmask_b32_e32 v184, v183, v181, vcc
	v_mov_b32_e32 v185, v184
	v_cvt_pk_bf16_f32 v16, v144, v145
	v_cvt_pk_bf16_f32 v17, v146, v147
	v_cvt_pk_bf16_f32 v18, v148, v149
	v_cvt_pk_bf16_f32 v19, v150, v151
	v_cvt_pk_bf16_f32 v20, v152, v153
	v_cvt_pk_bf16_f32 v21, v154, v155
	v_cvt_pk_bf16_f32 v22, v156, v157
	v_cvt_pk_bf16_f32 v23, v158, v159
	v_add_u32_e32 v181, 0x1c00000, v177
	global_store_dwordx4 v181, v[16:19], s[78:79]
	global_store_dwordx4 v181, v[20:23], s[78:79] offset:1024
	v_add_u32_e32 v236, 0x2000, v237
	s_mov_b64 exec, 1
	global_store_dword v236, v184, s[78:79]
	s_mov_b64 exec, -1
	s_waitcnt vmcnt(20)
	v_lshlrev_b32_e32 v144, 16, v32
	v_and_b32_e32 v145, 0xffff0000, v32
	v_lshlrev_b32_e32 v146, 16, v33
	v_and_b32_e32 v147, 0xffff0000, v33
	v_lshlrev_b32_e32 v148, 16, v34
	v_and_b32_e32 v149, 0xffff0000, v34
	v_lshlrev_b32_e32 v150, 16, v35
	v_and_b32_e32 v151, 0xffff0000, v35
	v_lshlrev_b32_e32 v152, 16, v36
	v_and_b32_e32 v153, 0xffff0000, v36
	v_lshlrev_b32_e32 v154, 16, v37
	v_and_b32_e32 v155, 0xffff0000, v37
	v_lshlrev_b32_e32 v156, 16, v38
	v_and_b32_e32 v157, 0xffff0000, v38
	v_lshlrev_b32_e32 v158, 16, v39
	v_and_b32_e32 v159, 0xffff0000, v39
	v_lshlrev_b32_e32 v160, 16, v40
	v_and_b32_e32 v161, 0xffff0000, v40
	v_lshlrev_b32_e32 v162, 16, v41
	v_and_b32_e32 v163, 0xffff0000, v41
	v_lshlrev_b32_e32 v164, 16, v42
	v_and_b32_e32 v165, 0xffff0000, v42
	v_lshlrev_b32_e32 v166, 16, v43
	v_and_b32_e32 v167, 0xffff0000, v43
	v_lshlrev_b32_e32 v168, 16, v44
	v_and_b32_e32 v169, 0xffff0000, v44
	v_lshlrev_b32_e32 v170, 16, v45
	v_and_b32_e32 v171, 0xffff0000, v45
	v_lshlrev_b32_e32 v172, 16, v46
	v_and_b32_e32 v173, 0xffff0000, v46
	v_lshlrev_b32_e32 v174, 16, v47
	v_and_b32_e32 v175, 0xffff0000, v47
	v_pk_mul_f32 v[252:253], v[160:161], v[160:161]
	v_pk_mul_f32 v[254:255], v[162:163], v[162:163]
	v_pk_fma_f32 v[252:253], v[164:165], v[164:165], v[252:253]
	v_pk_fma_f32 v[254:255], v[166:167], v[166:167], v[254:255]
	v_pk_fma_f32 v[252:253], v[168:169], v[168:169], v[252:253]
	v_pk_fma_f32 v[254:255], v[170:171], v[170:171], v[254:255]
	v_pk_fma_f32 v[252:253], v[172:173], v[172:173], v[252:253]
	v_pk_fma_f32 v[254:255], v[174:175], v[174:175], v[254:255]
	v_pk_add_f32 v[252:253], v[252:253], v[254:255]
	s_nop 0
	v_add_f32_e32 v183, v252, v253
	s_nop 1
	v_add_f32_dpp v183, v183, v183 quad_perm:[1,0,3,2] row_mask:0xf bank_mask:0xf bound_ctrl:1
	s_nop 1
	v_add_f32_dpp v183, v183, v183 quad_perm:[2,3,0,1] row_mask:0xf bank_mask:0xf bound_ctrl:1
	s_nop 1
	v_add_f32_dpp v183, v183, v183 row_half_mirror row_mask:0xf bank_mask:0xf bound_ctrl:1
	s_nop 1
	v_add_f32_dpp v183, v183, v183 row_mirror row_mask:0xf bank_mask:0xf bound_ctrl:1
	s_nop 1
	v_readlane_b32 s98, v183, 0
	v_readlane_b32 s99, v183, 16
	v_readlane_b32 s100, v183, 32
	v_readlane_b32 s101, v183, 48
	s_nop 1
	v_mov_b32_e32 v183, s98
	v_add_f32_e32 v183, s99, v183
	v_add_f32_e32 v183, s100, v183
	v_add_f32_e32 v183, s101, v183
	v_fmamk_f32 v183, v183, 0x3a800000, v182
	v_cmp_gt_f32_e32 vcc, 0x800000, v183
	v_mul_f32_e32 v181, 0x4b800000, v183
	s_nop 1
	v_cndmask_b32_e32 v183, v183, v181, vcc
	v_rsq_f32_e32 v183, v183
	s_nop 0
	v_mul_f32_e32 v181, 0x45800000, v183
	v_cndmask_b32_e32 v184, v183, v181, vcc
	v_mov_b32_e32 v185, v184
	v_pk_mul_f32 v[160:161], v[160:161], v[184:185]
	v_pk_mul_f32 v[162:163], v[162:163], v[184:185]
	v_pk_mul_f32 v[164:165], v[164:165], v[184:185]
	v_pk_mul_f32 v[166:167], v[166:167], v[184:185]
	v_pk_mul_f32 v[168:169], v[168:169], v[184:185]
	v_pk_mul_f32 v[170:171], v[170:171], v[184:185]
	v_pk_mul_f32 v[172:173], v[172:173], v[184:185]
	v_pk_mul_f32 v[174:175], v[174:175], v[184:185]
	v_pk_fma_f32 v[144:145], v[160:161], v[128:129], v[144:145]
	v_pk_fma_f32 v[146:147], v[162:163], v[130:131], v[146:147]
	v_pk_fma_f32 v[148:149], v[164:165], v[132:133], v[148:149]
	v_pk_fma_f32 v[150:151], v[166:167], v[134:135], v[150:151]
	v_pk_fma_f32 v[152:153], v[168:169], v[136:137], v[152:153]
	v_pk_fma_f32 v[154:155], v[170:171], v[138:139], v[154:155]
	v_pk_fma_f32 v[156:157], v[172:173], v[140:141], v[156:157]
	v_pk_fma_f32 v[158:159], v[174:175], v[142:143], v[158:159]
	v_pk_mul_f32 v[252:253], v[144:145], v[144:145]
	v_pk_mul_f32 v[254:255], v[146:147], v[146:147]
	v_pk_fma_f32 v[252:253], v[148:149], v[148:149], v[252:253]
	v_pk_fma_f32 v[254:255], v[150:151], v[150:151], v[254:255]
	v_pk_fma_f32 v[252:253], v[152:153], v[152:153], v[252:253]
	v_pk_fma_f32 v[254:255], v[154:155], v[154:155], v[254:255]
	v_pk_fma_f32 v[252:253], v[156:157], v[156:157], v[252:253]
	v_pk_fma_f32 v[254:255], v[158:159], v[158:159], v[254:255]
	v_pk_add_f32 v[252:253], v[252:253], v[254:255]
	s_nop 0
	v_add_f32_e32 v183, v252, v253
	s_nop 1
	v_add_f32_dpp v183, v183, v183 quad_perm:[1,0,3,2] row_mask:0xf bank_mask:0xf bound_ctrl:1
	s_nop 1
	v_add_f32_dpp v183, v183, v183 quad_perm:[2,3,0,1] row_mask:0xf bank_mask:0xf bound_ctrl:1
	s_nop 1
	v_add_f32_dpp v183, v183, v183 row_half_mirror row_mask:0xf bank_mask:0xf bound_ctrl:1
	s_nop 1
	v_add_f32_dpp v183, v183, v183 row_mirror row_mask:0xf bank_mask:0xf bound_ctrl:1
	s_nop 1
	v_readlane_b32 s98, v183, 0
	v_readlane_b32 s99, v183, 16
	v_readlane_b32 s100, v183, 32
	v_readlane_b32 s101, v183, 48
	s_nop 1
	v_mov_b32_e32 v183, s98
	v_add_f32_e32 v183, s99, v183
	v_add_f32_e32 v183, s100, v183
	v_add_f32_e32 v183, s101, v183
	v_fmamk_f32 v183, v183, 0x3a800000, v182
	v_cmp_gt_f32_e32 vcc, 0x800000, v183
	v_mul_f32_e32 v181, 0x4b800000, v183
	s_nop 1
	v_cndmask_b32_e32 v183, v183, v181, vcc
	v_rsq_f32_e32 v183, v183
	s_nop 0
	v_mul_f32_e32 v181, 0x45800000, v183
	v_cndmask_b32_e32 v184, v183, v181, vcc
	v_mov_b32_e32 v185, v184
	v_cvt_pk_bf16_f32 v32, v144, v145
	v_cvt_pk_bf16_f32 v33, v146, v147
	v_cvt_pk_bf16_f32 v34, v148, v149
	v_cvt_pk_bf16_f32 v35, v150, v151
	v_cvt_pk_bf16_f32 v36, v152, v153
	v_cvt_pk_bf16_f32 v37, v154, v155
	v_cvt_pk_bf16_f32 v38, v156, v157
	v_cvt_pk_bf16_f32 v39, v158, v159
	v_add_u32_e32 v181, 0x2000000, v177
	global_store_dwordx4 v181, v[32:35], s[78:79]
	global_store_dwordx4 v181, v[36:39], s[78:79] offset:1024
	v_add_u32_e32 v236, 0x4000, v237
	s_mov_b64 exec, 1
	global_store_dword v236, v184, s[78:79]
	s_mov_b64 exec, -1
	s_waitcnt vmcnt(16)
	v_lshlrev_b32_e32 v144, 16, v48
	v_and_b32_e32 v145, 0xffff0000, v48
	v_lshlrev_b32_e32 v146, 16, v49
	v_and_b32_e32 v147, 0xffff0000, v49
	v_lshlrev_b32_e32 v148, 16, v50
	v_and_b32_e32 v149, 0xffff0000, v50
	v_lshlrev_b32_e32 v150, 16, v51
	v_and_b32_e32 v151, 0xffff0000, v51
	v_lshlrev_b32_e32 v152, 16, v52
	v_and_b32_e32 v153, 0xffff0000, v52
	v_lshlrev_b32_e32 v154, 16, v53
	v_and_b32_e32 v155, 0xffff0000, v53
	v_lshlrev_b32_e32 v156, 16, v54
	v_and_b32_e32 v157, 0xffff0000, v54
	v_lshlrev_b32_e32 v158, 16, v55
	v_and_b32_e32 v159, 0xffff0000, v55
	v_lshlrev_b32_e32 v160, 16, v56
	v_and_b32_e32 v161, 0xffff0000, v56
	v_lshlrev_b32_e32 v162, 16, v57
	v_and_b32_e32 v163, 0xffff0000, v57
	v_lshlrev_b32_e32 v164, 16, v58
	v_and_b32_e32 v165, 0xffff0000, v58
	v_lshlrev_b32_e32 v166, 16, v59
	v_and_b32_e32 v167, 0xffff0000, v59
	v_lshlrev_b32_e32 v168, 16, v60
	v_and_b32_e32 v169, 0xffff0000, v60
	v_lshlrev_b32_e32 v170, 16, v61
	v_and_b32_e32 v171, 0xffff0000, v61
	v_lshlrev_b32_e32 v172, 16, v62
	v_and_b32_e32 v173, 0xffff0000, v62
	v_lshlrev_b32_e32 v174, 16, v63
	v_and_b32_e32 v175, 0xffff0000, v63
	v_pk_mul_f32 v[252:253], v[160:161], v[160:161]
	v_pk_mul_f32 v[254:255], v[162:163], v[162:163]
	v_pk_fma_f32 v[252:253], v[164:165], v[164:165], v[252:253]
	v_pk_fma_f32 v[254:255], v[166:167], v[166:167], v[254:255]
	v_pk_fma_f32 v[252:253], v[168:169], v[168:169], v[252:253]
	v_pk_fma_f32 v[254:255], v[170:171], v[170:171], v[254:255]
	v_pk_fma_f32 v[252:253], v[172:173], v[172:173], v[252:253]
	v_pk_fma_f32 v[254:255], v[174:175], v[174:175], v[254:255]
	v_pk_add_f32 v[252:253], v[252:253], v[254:255]
	s_nop 0
	v_add_f32_e32 v183, v252, v253
	s_nop 1
	v_add_f32_dpp v183, v183, v183 quad_perm:[1,0,3,2] row_mask:0xf bank_mask:0xf bound_ctrl:1
	s_nop 1
	v_add_f32_dpp v183, v183, v183 quad_perm:[2,3,0,1] row_mask:0xf bank_mask:0xf bound_ctrl:1
	s_nop 1
	v_add_f32_dpp v183, v183, v183 row_half_mirror row_mask:0xf bank_mask:0xf bound_ctrl:1
	s_nop 1
	v_add_f32_dpp v183, v183, v183 row_mirror row_mask:0xf bank_mask:0xf bound_ctrl:1
	s_nop 1
	v_readlane_b32 s98, v183, 0
	v_readlane_b32 s99, v183, 16
	v_readlane_b32 s100, v183, 32
	v_readlane_b32 s101, v183, 48
	s_nop 1
	v_mov_b32_e32 v183, s98
	v_add_f32_e32 v183, s99, v183
	v_add_f32_e32 v183, s100, v183
	v_add_f32_e32 v183, s101, v183
	v_fmamk_f32 v183, v183, 0x3a800000, v182
	v_cmp_gt_f32_e32 vcc, 0x800000, v183
	v_mul_f32_e32 v181, 0x4b800000, v183
	s_nop 1
	v_cndmask_b32_e32 v183, v183, v181, vcc
	v_rsq_f32_e32 v183, v183
	s_nop 0
	v_mul_f32_e32 v181, 0x45800000, v183
	v_cndmask_b32_e32 v184, v183, v181, vcc
	v_mov_b32_e32 v185, v184
	v_pk_mul_f32 v[160:161], v[160:161], v[184:185]
	v_pk_mul_f32 v[162:163], v[162:163], v[184:185]
	v_pk_mul_f32 v[164:165], v[164:165], v[184:185]
	v_pk_mul_f32 v[166:167], v[166:167], v[184:185]
	v_pk_mul_f32 v[168:169], v[168:169], v[184:185]
	v_pk_mul_f32 v[170:171], v[170:171], v[184:185]
	v_pk_mul_f32 v[172:173], v[172:173], v[184:185]
	v_pk_mul_f32 v[174:175], v[174:175], v[184:185]
	v_pk_fma_f32 v[144:145], v[160:161], v[128:129], v[144:145]
	v_pk_fma_f32 v[146:147], v[162:163], v[130:131], v[146:147]
	v_pk_fma_f32 v[148:149], v[164:165], v[132:133], v[148:149]
	v_pk_fma_f32 v[150:151], v[166:167], v[134:135], v[150:151]
	v_pk_fma_f32 v[152:153], v[168:169], v[136:137], v[152:153]
	v_pk_fma_f32 v[154:155], v[170:171], v[138:139], v[154:155]
	v_pk_fma_f32 v[156:157], v[172:173], v[140:141], v[156:157]
	v_pk_fma_f32 v[158:159], v[174:175], v[142:143], v[158:159]
	v_pk_mul_f32 v[252:253], v[144:145], v[144:145]
	v_pk_mul_f32 v[254:255], v[146:147], v[146:147]
	v_pk_fma_f32 v[252:253], v[148:149], v[148:149], v[252:253]
	v_pk_fma_f32 v[254:255], v[150:151], v[150:151], v[254:255]
	v_pk_fma_f32 v[252:253], v[152:153], v[152:153], v[252:253]
	v_pk_fma_f32 v[254:255], v[154:155], v[154:155], v[254:255]
	v_pk_fma_f32 v[252:253], v[156:157], v[156:157], v[252:253]
	v_pk_fma_f32 v[254:255], v[158:159], v[158:159], v[254:255]
	v_pk_add_f32 v[252:253], v[252:253], v[254:255]
	s_nop 0
	v_add_f32_e32 v183, v252, v253
	s_nop 1
	v_add_f32_dpp v183, v183, v183 quad_perm:[1,0,3,2] row_mask:0xf bank_mask:0xf bound_ctrl:1
	s_nop 1
	v_add_f32_dpp v183, v183, v183 quad_perm:[2,3,0,1] row_mask:0xf bank_mask:0xf bound_ctrl:1
	s_nop 1
	v_add_f32_dpp v183, v183, v183 row_half_mirror row_mask:0xf bank_mask:0xf bound_ctrl:1
	s_nop 1
	v_add_f32_dpp v183, v183, v183 row_mirror row_mask:0xf bank_mask:0xf bound_ctrl:1
	s_nop 1
	v_readlane_b32 s98, v183, 0
	v_readlane_b32 s99, v183, 16
	v_readlane_b32 s100, v183, 32
	v_readlane_b32 s101, v183, 48
	s_nop 1
	v_mov_b32_e32 v183, s98
	v_add_f32_e32 v183, s99, v183
	v_add_f32_e32 v183, s100, v183
	v_add_f32_e32 v183, s101, v183
	v_fmamk_f32 v183, v183, 0x3a800000, v182
	v_cmp_gt_f32_e32 vcc, 0x800000, v183
	v_mul_f32_e32 v181, 0x4b800000, v183
	s_nop 1
	v_cndmask_b32_e32 v183, v183, v181, vcc
	v_rsq_f32_e32 v183, v183
	s_nop 0
	v_mul_f32_e32 v181, 0x45800000, v183
	v_cndmask_b32_e32 v184, v183, v181, vcc
	v_mov_b32_e32 v185, v184
	v_cvt_pk_bf16_f32 v48, v144, v145
	v_cvt_pk_bf16_f32 v49, v146, v147
	v_cvt_pk_bf16_f32 v50, v148, v149
	v_cvt_pk_bf16_f32 v51, v150, v151
	v_cvt_pk_bf16_f32 v52, v152, v153
	v_cvt_pk_bf16_f32 v53, v154, v155
	v_cvt_pk_bf16_f32 v54, v156, v157
	v_cvt_pk_bf16_f32 v55, v158, v159
	v_add_u32_e32 v181, 0x2400000, v177
	global_store_dwordx4 v181, v[48:51], s[78:79]
	global_store_dwordx4 v181, v[52:55], s[78:79] offset:1024
	v_add_u32_e32 v236, 0x6000, v237
	s_mov_b64 exec, 1
	global_store_dword v236, v184, s[78:79]
	s_mov_b64 exec, -1
	s_waitcnt vmcnt(12)
	v_lshlrev_b32_e32 v144, 16, v64
	v_and_b32_e32 v145, 0xffff0000, v64
	v_lshlrev_b32_e32 v146, 16, v65
	v_and_b32_e32 v147, 0xffff0000, v65
	v_lshlrev_b32_e32 v148, 16, v66
	v_and_b32_e32 v149, 0xffff0000, v66
	v_lshlrev_b32_e32 v150, 16, v67
	v_and_b32_e32 v151, 0xffff0000, v67
	v_lshlrev_b32_e32 v152, 16, v68
	v_and_b32_e32 v153, 0xffff0000, v68
	v_lshlrev_b32_e32 v154, 16, v69
	v_and_b32_e32 v155, 0xffff0000, v69
	v_lshlrev_b32_e32 v156, 16, v70
	v_and_b32_e32 v157, 0xffff0000, v70
	v_lshlrev_b32_e32 v158, 16, v71
	v_and_b32_e32 v159, 0xffff0000, v71
	v_lshlrev_b32_e32 v160, 16, v72
	v_and_b32_e32 v161, 0xffff0000, v72
	v_lshlrev_b32_e32 v162, 16, v73
	v_and_b32_e32 v163, 0xffff0000, v73
	v_lshlrev_b32_e32 v164, 16, v74
	v_and_b32_e32 v165, 0xffff0000, v74
	v_lshlrev_b32_e32 v166, 16, v75
	v_and_b32_e32 v167, 0xffff0000, v75
	v_lshlrev_b32_e32 v168, 16, v76
	v_and_b32_e32 v169, 0xffff0000, v76
	v_lshlrev_b32_e32 v170, 16, v77
	v_and_b32_e32 v171, 0xffff0000, v77
	v_lshlrev_b32_e32 v172, 16, v78
	v_and_b32_e32 v173, 0xffff0000, v78
	v_lshlrev_b32_e32 v174, 16, v79
	v_and_b32_e32 v175, 0xffff0000, v79
	v_pk_mul_f32 v[252:253], v[160:161], v[160:161]
	v_pk_mul_f32 v[254:255], v[162:163], v[162:163]
	v_pk_fma_f32 v[252:253], v[164:165], v[164:165], v[252:253]
	v_pk_fma_f32 v[254:255], v[166:167], v[166:167], v[254:255]
	v_pk_fma_f32 v[252:253], v[168:169], v[168:169], v[252:253]
	v_pk_fma_f32 v[254:255], v[170:171], v[170:171], v[254:255]
	v_pk_fma_f32 v[252:253], v[172:173], v[172:173], v[252:253]
	v_pk_fma_f32 v[254:255], v[174:175], v[174:175], v[254:255]
	v_pk_add_f32 v[252:253], v[252:253], v[254:255]
	s_nop 0
	v_add_f32_e32 v183, v252, v253
	s_nop 1
	v_add_f32_dpp v183, v183, v183 quad_perm:[1,0,3,2] row_mask:0xf bank_mask:0xf bound_ctrl:1
	s_nop 1
	v_add_f32_dpp v183, v183, v183 quad_perm:[2,3,0,1] row_mask:0xf bank_mask:0xf bound_ctrl:1
	s_nop 1
	v_add_f32_dpp v183, v183, v183 row_half_mirror row_mask:0xf bank_mask:0xf bound_ctrl:1
	s_nop 1
	v_add_f32_dpp v183, v183, v183 row_mirror row_mask:0xf bank_mask:0xf bound_ctrl:1
	s_nop 1
	v_readlane_b32 s98, v183, 0
	v_readlane_b32 s99, v183, 16
	v_readlane_b32 s100, v183, 32
	v_readlane_b32 s101, v183, 48
	s_nop 1
	v_mov_b32_e32 v183, s98
	v_add_f32_e32 v183, s99, v183
	v_add_f32_e32 v183, s100, v183
	v_add_f32_e32 v183, s101, v183
	v_fmamk_f32 v183, v183, 0x3a800000, v182
	v_cmp_gt_f32_e32 vcc, 0x800000, v183
	v_mul_f32_e32 v181, 0x4b800000, v183
	s_nop 1
	v_cndmask_b32_e32 v183, v183, v181, vcc
	v_rsq_f32_e32 v183, v183
	s_nop 0
	v_mul_f32_e32 v181, 0x45800000, v183
	v_cndmask_b32_e32 v184, v183, v181, vcc
	v_mov_b32_e32 v185, v184
	v_pk_mul_f32 v[160:161], v[160:161], v[184:185]
	v_pk_mul_f32 v[162:163], v[162:163], v[184:185]
	v_pk_mul_f32 v[164:165], v[164:165], v[184:185]
	v_pk_mul_f32 v[166:167], v[166:167], v[184:185]
	v_pk_mul_f32 v[168:169], v[168:169], v[184:185]
	v_pk_mul_f32 v[170:171], v[170:171], v[184:185]
	v_pk_mul_f32 v[172:173], v[172:173], v[184:185]
	v_pk_mul_f32 v[174:175], v[174:175], v[184:185]
	v_pk_fma_f32 v[144:145], v[160:161], v[128:129], v[144:145]
	v_pk_fma_f32 v[146:147], v[162:163], v[130:131], v[146:147]
	v_pk_fma_f32 v[148:149], v[164:165], v[132:133], v[148:149]
	v_pk_fma_f32 v[150:151], v[166:167], v[134:135], v[150:151]
	v_pk_fma_f32 v[152:153], v[168:169], v[136:137], v[152:153]
	v_pk_fma_f32 v[154:155], v[170:171], v[138:139], v[154:155]
	v_pk_fma_f32 v[156:157], v[172:173], v[140:141], v[156:157]
	v_pk_fma_f32 v[158:159], v[174:175], v[142:143], v[158:159]
	v_pk_mul_f32 v[252:253], v[144:145], v[144:145]
	v_pk_mul_f32 v[254:255], v[146:147], v[146:147]
	v_pk_fma_f32 v[252:253], v[148:149], v[148:149], v[252:253]
	v_pk_fma_f32 v[254:255], v[150:151], v[150:151], v[254:255]
	v_pk_fma_f32 v[252:253], v[152:153], v[152:153], v[252:253]
	v_pk_fma_f32 v[254:255], v[154:155], v[154:155], v[254:255]
	v_pk_fma_f32 v[252:253], v[156:157], v[156:157], v[252:253]
	v_pk_fma_f32 v[254:255], v[158:159], v[158:159], v[254:255]
	v_pk_add_f32 v[252:253], v[252:253], v[254:255]
	s_nop 0
	v_add_f32_e32 v183, v252, v253
	s_nop 1
	v_add_f32_dpp v183, v183, v183 quad_perm:[1,0,3,2] row_mask:0xf bank_mask:0xf bound_ctrl:1
	s_nop 1
	v_add_f32_dpp v183, v183, v183 quad_perm:[2,3,0,1] row_mask:0xf bank_mask:0xf bound_ctrl:1
	s_nop 1
	v_add_f32_dpp v183, v183, v183 row_half_mirror row_mask:0xf bank_mask:0xf bound_ctrl:1
	s_nop 1
	v_add_f32_dpp v183, v183, v183 row_mirror row_mask:0xf bank_mask:0xf bound_ctrl:1
	s_nop 1
	v_readlane_b32 s98, v183, 0
	v_readlane_b32 s99, v183, 16
	v_readlane_b32 s100, v183, 32
	v_readlane_b32 s101, v183, 48
	s_nop 1
	v_mov_b32_e32 v183, s98
	v_add_f32_e32 v183, s99, v183
	v_add_f32_e32 v183, s100, v183
	v_add_f32_e32 v183, s101, v183
	v_fmamk_f32 v183, v183, 0x3a800000, v182
	v_cmp_gt_f32_e32 vcc, 0x800000, v183
	v_mul_f32_e32 v181, 0x4b800000, v183
	s_nop 1
	v_cndmask_b32_e32 v183, v183, v181, vcc
	v_rsq_f32_e32 v183, v183
	s_nop 0
	v_mul_f32_e32 v181, 0x45800000, v183
	v_cndmask_b32_e32 v184, v183, v181, vcc
	v_mov_b32_e32 v185, v184
	v_cvt_pk_bf16_f32 v64, v144, v145
	v_cvt_pk_bf16_f32 v65, v146, v147
	v_cvt_pk_bf16_f32 v66, v148, v149
	v_cvt_pk_bf16_f32 v67, v150, v151
	v_cvt_pk_bf16_f32 v68, v152, v153
	v_cvt_pk_bf16_f32 v69, v154, v155
	v_cvt_pk_bf16_f32 v70, v156, v157
	v_cvt_pk_bf16_f32 v71, v158, v159
	v_add_u32_e32 v181, 0x2800000, v177
	global_store_dwordx4 v181, v[64:67], s[78:79]
	global_store_dwordx4 v181, v[68:71], s[78:79] offset:1024
	v_add_u32_e32 v236, 0x8000, v237
	s_mov_b64 exec, 1
	global_store_dword v236, v184, s[78:79]
	s_mov_b64 exec, -1
	s_waitcnt vmcnt(8)
	v_lshlrev_b32_e32 v144, 16, v80
	v_and_b32_e32 v145, 0xffff0000, v80
	v_lshlrev_b32_e32 v146, 16, v81
	v_and_b32_e32 v147, 0xffff0000, v81
	v_lshlrev_b32_e32 v148, 16, v82
	v_and_b32_e32 v149, 0xffff0000, v82
	v_lshlrev_b32_e32 v150, 16, v83
	v_and_b32_e32 v151, 0xffff0000, v83
	v_lshlrev_b32_e32 v152, 16, v84
	v_and_b32_e32 v153, 0xffff0000, v84
	v_lshlrev_b32_e32 v154, 16, v85
	v_and_b32_e32 v155, 0xffff0000, v85
	v_lshlrev_b32_e32 v156, 16, v86
	v_and_b32_e32 v157, 0xffff0000, v86
	v_lshlrev_b32_e32 v158, 16, v87
	v_and_b32_e32 v159, 0xffff0000, v87
	v_lshlrev_b32_e32 v160, 16, v88
	v_and_b32_e32 v161, 0xffff0000, v88
	v_lshlrev_b32_e32 v162, 16, v89
	v_and_b32_e32 v163, 0xffff0000, v89
	v_lshlrev_b32_e32 v164, 16, v90
	v_and_b32_e32 v165, 0xffff0000, v90
	v_lshlrev_b32_e32 v166, 16, v91
	v_and_b32_e32 v167, 0xffff0000, v91
	v_lshlrev_b32_e32 v168, 16, v92
	v_and_b32_e32 v169, 0xffff0000, v92
	v_lshlrev_b32_e32 v170, 16, v93
	v_and_b32_e32 v171, 0xffff0000, v93
	v_lshlrev_b32_e32 v172, 16, v94
	v_and_b32_e32 v173, 0xffff0000, v94
	v_lshlrev_b32_e32 v174, 16, v95
	v_and_b32_e32 v175, 0xffff0000, v95
	v_pk_mul_f32 v[252:253], v[160:161], v[160:161]
	v_pk_mul_f32 v[254:255], v[162:163], v[162:163]
	v_pk_fma_f32 v[252:253], v[164:165], v[164:165], v[252:253]
	v_pk_fma_f32 v[254:255], v[166:167], v[166:167], v[254:255]
	v_pk_fma_f32 v[252:253], v[168:169], v[168:169], v[252:253]
	v_pk_fma_f32 v[254:255], v[170:171], v[170:171], v[254:255]
	v_pk_fma_f32 v[252:253], v[172:173], v[172:173], v[252:253]
	v_pk_fma_f32 v[254:255], v[174:175], v[174:175], v[254:255]
	v_pk_add_f32 v[252:253], v[252:253], v[254:255]
	s_nop 0
	v_add_f32_e32 v183, v252, v253
	s_nop 1
	v_add_f32_dpp v183, v183, v183 quad_perm:[1,0,3,2] row_mask:0xf bank_mask:0xf bound_ctrl:1
	s_nop 1
	v_add_f32_dpp v183, v183, v183 quad_perm:[2,3,0,1] row_mask:0xf bank_mask:0xf bound_ctrl:1
	s_nop 1
	v_add_f32_dpp v183, v183, v183 row_half_mirror row_mask:0xf bank_mask:0xf bound_ctrl:1
	s_nop 1
	v_add_f32_dpp v183, v183, v183 row_mirror row_mask:0xf bank_mask:0xf bound_ctrl:1
	s_nop 1
	v_readlane_b32 s98, v183, 0
	v_readlane_b32 s99, v183, 16
	v_readlane_b32 s100, v183, 32
	v_readlane_b32 s101, v183, 48
	s_nop 1
	v_mov_b32_e32 v183, s98
	v_add_f32_e32 v183, s99, v183
	v_add_f32_e32 v183, s100, v183
	v_add_f32_e32 v183, s101, v183
	v_fmamk_f32 v183, v183, 0x3a800000, v182
	v_cmp_gt_f32_e32 vcc, 0x800000, v183
	v_mul_f32_e32 v181, 0x4b800000, v183
	s_nop 1
	v_cndmask_b32_e32 v183, v183, v181, vcc
	v_rsq_f32_e32 v183, v183
	s_nop 0
	v_mul_f32_e32 v181, 0x45800000, v183
	v_cndmask_b32_e32 v184, v183, v181, vcc
	v_mov_b32_e32 v185, v184
	v_pk_mul_f32 v[160:161], v[160:161], v[184:185]
	v_pk_mul_f32 v[162:163], v[162:163], v[184:185]
	v_pk_mul_f32 v[164:165], v[164:165], v[184:185]
	v_pk_mul_f32 v[166:167], v[166:167], v[184:185]
	v_pk_mul_f32 v[168:169], v[168:169], v[184:185]
	v_pk_mul_f32 v[170:171], v[170:171], v[184:185]
	v_pk_mul_f32 v[172:173], v[172:173], v[184:185]
	v_pk_mul_f32 v[174:175], v[174:175], v[184:185]
	v_pk_fma_f32 v[144:145], v[160:161], v[128:129], v[144:145]
	v_pk_fma_f32 v[146:147], v[162:163], v[130:131], v[146:147]
	v_pk_fma_f32 v[148:149], v[164:165], v[132:133], v[148:149]
	v_pk_fma_f32 v[150:151], v[166:167], v[134:135], v[150:151]
	v_pk_fma_f32 v[152:153], v[168:169], v[136:137], v[152:153]
	v_pk_fma_f32 v[154:155], v[170:171], v[138:139], v[154:155]
	v_pk_fma_f32 v[156:157], v[172:173], v[140:141], v[156:157]
	v_pk_fma_f32 v[158:159], v[174:175], v[142:143], v[158:159]
	v_pk_mul_f32 v[252:253], v[144:145], v[144:145]
	v_pk_mul_f32 v[254:255], v[146:147], v[146:147]
	v_pk_fma_f32 v[252:253], v[148:149], v[148:149], v[252:253]
	v_pk_fma_f32 v[254:255], v[150:151], v[150:151], v[254:255]
	v_pk_fma_f32 v[252:253], v[152:153], v[152:153], v[252:253]
	v_pk_fma_f32 v[254:255], v[154:155], v[154:155], v[254:255]
	v_pk_fma_f32 v[252:253], v[156:157], v[156:157], v[252:253]
	v_pk_fma_f32 v[254:255], v[158:159], v[158:159], v[254:255]
	v_pk_add_f32 v[252:253], v[252:253], v[254:255]
	s_nop 0
	v_add_f32_e32 v183, v252, v253
	s_nop 1
	v_add_f32_dpp v183, v183, v183 quad_perm:[1,0,3,2] row_mask:0xf bank_mask:0xf bound_ctrl:1
	s_nop 1
	v_add_f32_dpp v183, v183, v183 quad_perm:[2,3,0,1] row_mask:0xf bank_mask:0xf bound_ctrl:1
	s_nop 1
	v_add_f32_dpp v183, v183, v183 row_half_mirror row_mask:0xf bank_mask:0xf bound_ctrl:1
	s_nop 1
	v_add_f32_dpp v183, v183, v183 row_mirror row_mask:0xf bank_mask:0xf bound_ctrl:1
	s_nop 1
	v_readlane_b32 s98, v183, 0
	v_readlane_b32 s99, v183, 16
	v_readlane_b32 s100, v183, 32
	v_readlane_b32 s101, v183, 48
	s_nop 1
	v_mov_b32_e32 v183, s98
	v_add_f32_e32 v183, s99, v183
	v_add_f32_e32 v183, s100, v183
	v_add_f32_e32 v183, s101, v183
	v_fmamk_f32 v183, v183, 0x3a800000, v182
	v_cmp_gt_f32_e32 vcc, 0x800000, v183
	v_mul_f32_e32 v181, 0x4b800000, v183
	s_nop 1
	v_cndmask_b32_e32 v183, v183, v181, vcc
	v_rsq_f32_e32 v183, v183
	s_nop 0
	v_mul_f32_e32 v181, 0x45800000, v183
	v_cndmask_b32_e32 v184, v183, v181, vcc
	v_mov_b32_e32 v185, v184
	v_cvt_pk_bf16_f32 v80, v144, v145
	v_cvt_pk_bf16_f32 v81, v146, v147
	v_cvt_pk_bf16_f32 v82, v148, v149
	v_cvt_pk_bf16_f32 v83, v150, v151
	v_cvt_pk_bf16_f32 v84, v152, v153
	v_cvt_pk_bf16_f32 v85, v154, v155
	v_cvt_pk_bf16_f32 v86, v156, v157
	v_cvt_pk_bf16_f32 v87, v158, v159
	v_add_u32_e32 v181, 0x2c00000, v177
	global_store_dwordx4 v181, v[80:83], s[78:79]
	global_store_dwordx4 v181, v[84:87], s[78:79] offset:1024
	v_add_u32_e32 v236, 0xa000, v237
	s_mov_b64 exec, 1
	global_store_dword v236, v184, s[78:79]
	s_mov_b64 exec, -1
	s_waitcnt vmcnt(4)
	v_lshlrev_b32_e32 v144, 16, v96
	v_and_b32_e32 v145, 0xffff0000, v96
	v_lshlrev_b32_e32 v146, 16, v97
	v_and_b32_e32 v147, 0xffff0000, v97
	v_lshlrev_b32_e32 v148, 16, v98
	v_and_b32_e32 v149, 0xffff0000, v98
	v_lshlrev_b32_e32 v150, 16, v99
	v_and_b32_e32 v151, 0xffff0000, v99
	v_lshlrev_b32_e32 v152, 16, v100
	v_and_b32_e32 v153, 0xffff0000, v100
	v_lshlrev_b32_e32 v154, 16, v101
	v_and_b32_e32 v155, 0xffff0000, v101
	v_lshlrev_b32_e32 v156, 16, v102
	v_and_b32_e32 v157, 0xffff0000, v102
	v_lshlrev_b32_e32 v158, 16, v103
	v_and_b32_e32 v159, 0xffff0000, v103
	v_lshlrev_b32_e32 v160, 16, v104
	v_and_b32_e32 v161, 0xffff0000, v104
	v_lshlrev_b32_e32 v162, 16, v105
	v_and_b32_e32 v163, 0xffff0000, v105
	v_lshlrev_b32_e32 v164, 16, v106
	v_and_b32_e32 v165, 0xffff0000, v106
	v_lshlrev_b32_e32 v166, 16, v107
	v_and_b32_e32 v167, 0xffff0000, v107
	v_lshlrev_b32_e32 v168, 16, v108
	v_and_b32_e32 v169, 0xffff0000, v108
	v_lshlrev_b32_e32 v170, 16, v109
	v_and_b32_e32 v171, 0xffff0000, v109
	v_lshlrev_b32_e32 v172, 16, v110
	v_and_b32_e32 v173, 0xffff0000, v110
	v_lshlrev_b32_e32 v174, 16, v111
	v_and_b32_e32 v175, 0xffff0000, v111
	v_pk_mul_f32 v[252:253], v[160:161], v[160:161]
	v_pk_mul_f32 v[254:255], v[162:163], v[162:163]
	v_pk_fma_f32 v[252:253], v[164:165], v[164:165], v[252:253]
	v_pk_fma_f32 v[254:255], v[166:167], v[166:167], v[254:255]
	v_pk_fma_f32 v[252:253], v[168:169], v[168:169], v[252:253]
	v_pk_fma_f32 v[254:255], v[170:171], v[170:171], v[254:255]
	v_pk_fma_f32 v[252:253], v[172:173], v[172:173], v[252:253]
	v_pk_fma_f32 v[254:255], v[174:175], v[174:175], v[254:255]
	v_pk_add_f32 v[252:253], v[252:253], v[254:255]
	s_nop 0
	v_add_f32_e32 v183, v252, v253
	s_nop 1
	v_add_f32_dpp v183, v183, v183 quad_perm:[1,0,3,2] row_mask:0xf bank_mask:0xf bound_ctrl:1
	s_nop 1
	v_add_f32_dpp v183, v183, v183 quad_perm:[2,3,0,1] row_mask:0xf bank_mask:0xf bound_ctrl:1
	s_nop 1
	v_add_f32_dpp v183, v183, v183 row_half_mirror row_mask:0xf bank_mask:0xf bound_ctrl:1
	s_nop 1
	v_add_f32_dpp v183, v183, v183 row_mirror row_mask:0xf bank_mask:0xf bound_ctrl:1
	s_nop 1
	v_readlane_b32 s98, v183, 0
	v_readlane_b32 s99, v183, 16
	v_readlane_b32 s100, v183, 32
	v_readlane_b32 s101, v183, 48
	s_nop 1
	v_mov_b32_e32 v183, s98
	v_add_f32_e32 v183, s99, v183
	v_add_f32_e32 v183, s100, v183
	v_add_f32_e32 v183, s101, v183
	v_fmamk_f32 v183, v183, 0x3a800000, v182
	v_cmp_gt_f32_e32 vcc, 0x800000, v183
	v_mul_f32_e32 v181, 0x4b800000, v183
	s_nop 1
	v_cndmask_b32_e32 v183, v183, v181, vcc
	v_rsq_f32_e32 v183, v183
	s_nop 0
	v_mul_f32_e32 v181, 0x45800000, v183
	v_cndmask_b32_e32 v184, v183, v181, vcc
	v_mov_b32_e32 v185, v184
	v_pk_mul_f32 v[160:161], v[160:161], v[184:185]
	v_pk_mul_f32 v[162:163], v[162:163], v[184:185]
	v_pk_mul_f32 v[164:165], v[164:165], v[184:185]
	v_pk_mul_f32 v[166:167], v[166:167], v[184:185]
	v_pk_mul_f32 v[168:169], v[168:169], v[184:185]
	v_pk_mul_f32 v[170:171], v[170:171], v[184:185]
	v_pk_mul_f32 v[172:173], v[172:173], v[184:185]
	v_pk_mul_f32 v[174:175], v[174:175], v[184:185]
	v_pk_fma_f32 v[144:145], v[160:161], v[128:129], v[144:145]
	v_pk_fma_f32 v[146:147], v[162:163], v[130:131], v[146:147]
	v_pk_fma_f32 v[148:149], v[164:165], v[132:133], v[148:149]
	v_pk_fma_f32 v[150:151], v[166:167], v[134:135], v[150:151]
	v_pk_fma_f32 v[152:153], v[168:169], v[136:137], v[152:153]
	v_pk_fma_f32 v[154:155], v[170:171], v[138:139], v[154:155]
	v_pk_fma_f32 v[156:157], v[172:173], v[140:141], v[156:157]
	v_pk_fma_f32 v[158:159], v[174:175], v[142:143], v[158:159]
	v_pk_mul_f32 v[252:253], v[144:145], v[144:145]
	v_pk_mul_f32 v[254:255], v[146:147], v[146:147]
	v_pk_fma_f32 v[252:253], v[148:149], v[148:149], v[252:253]
	v_pk_fma_f32 v[254:255], v[150:151], v[150:151], v[254:255]
	v_pk_fma_f32 v[252:253], v[152:153], v[152:153], v[252:253]
	v_pk_fma_f32 v[254:255], v[154:155], v[154:155], v[254:255]
	v_pk_fma_f32 v[252:253], v[156:157], v[156:157], v[252:253]
	v_pk_fma_f32 v[254:255], v[158:159], v[158:159], v[254:255]
	v_pk_add_f32 v[252:253], v[252:253], v[254:255]
	s_nop 0
	v_add_f32_e32 v183, v252, v253
	s_nop 1
	v_add_f32_dpp v183, v183, v183 quad_perm:[1,0,3,2] row_mask:0xf bank_mask:0xf bound_ctrl:1
	s_nop 1
	v_add_f32_dpp v183, v183, v183 quad_perm:[2,3,0,1] row_mask:0xf bank_mask:0xf bound_ctrl:1
	s_nop 1
	v_add_f32_dpp v183, v183, v183 row_half_mirror row_mask:0xf bank_mask:0xf bound_ctrl:1
	s_nop 1
	v_add_f32_dpp v183, v183, v183 row_mirror row_mask:0xf bank_mask:0xf bound_ctrl:1
	s_nop 1
	v_readlane_b32 s98, v183, 0
	v_readlane_b32 s99, v183, 16
	v_readlane_b32 s100, v183, 32
	v_readlane_b32 s101, v183, 48
	s_nop 1
	v_mov_b32_e32 v183, s98
	v_add_f32_e32 v183, s99, v183
	v_add_f32_e32 v183, s100, v183
	v_add_f32_e32 v183, s101, v183
	v_fmamk_f32 v183, v183, 0x3a800000, v182
	v_cmp_gt_f32_e32 vcc, 0x800000, v183
	v_mul_f32_e32 v181, 0x4b800000, v183
	s_nop 1
	v_cndmask_b32_e32 v183, v183, v181, vcc
	v_rsq_f32_e32 v183, v183
	s_nop 0
	v_mul_f32_e32 v181, 0x45800000, v183
	v_cndmask_b32_e32 v184, v183, v181, vcc
	v_mov_b32_e32 v185, v184
	v_cvt_pk_bf16_f32 v96, v144, v145
	v_cvt_pk_bf16_f32 v97, v146, v147
	v_cvt_pk_bf16_f32 v98, v148, v149
	v_cvt_pk_bf16_f32 v99, v150, v151
	v_cvt_pk_bf16_f32 v100, v152, v153
	v_cvt_pk_bf16_f32 v101, v154, v155
	v_cvt_pk_bf16_f32 v102, v156, v157
	v_cvt_pk_bf16_f32 v103, v158, v159
	v_add_u32_e32 v181, 0x3000000, v177
	global_store_dwordx4 v181, v[96:99], s[78:79]
	global_store_dwordx4 v181, v[100:103], s[78:79] offset:1024
	v_add_u32_e32 v236, 0xc000, v237
	s_mov_b64 exec, 1
	global_store_dword v236, v184, s[78:79]
	s_mov_b64 exec, -1
	s_waitcnt vmcnt(0)
	v_lshlrev_b32_e32 v144, 16, v112
	v_and_b32_e32 v145, 0xffff0000, v112
	v_lshlrev_b32_e32 v146, 16, v113
	v_and_b32_e32 v147, 0xffff0000, v113
	v_lshlrev_b32_e32 v148, 16, v114
	v_and_b32_e32 v149, 0xffff0000, v114
	v_lshlrev_b32_e32 v150, 16, v115
	v_and_b32_e32 v151, 0xffff0000, v115
	v_lshlrev_b32_e32 v152, 16, v116
	v_and_b32_e32 v153, 0xffff0000, v116
	v_lshlrev_b32_e32 v154, 16, v117
	v_and_b32_e32 v155, 0xffff0000, v117
	v_lshlrev_b32_e32 v156, 16, v118
	v_and_b32_e32 v157, 0xffff0000, v118
	v_lshlrev_b32_e32 v158, 16, v119
	v_and_b32_e32 v159, 0xffff0000, v119
	v_lshlrev_b32_e32 v160, 16, v120
	v_and_b32_e32 v161, 0xffff0000, v120
	v_lshlrev_b32_e32 v162, 16, v121
	v_and_b32_e32 v163, 0xffff0000, v121
	v_lshlrev_b32_e32 v164, 16, v122
	v_and_b32_e32 v165, 0xffff0000, v122
	v_lshlrev_b32_e32 v166, 16, v123
	v_and_b32_e32 v167, 0xffff0000, v123
	v_lshlrev_b32_e32 v168, 16, v124
	v_and_b32_e32 v169, 0xffff0000, v124
	v_lshlrev_b32_e32 v170, 16, v125
	v_and_b32_e32 v171, 0xffff0000, v125
	v_lshlrev_b32_e32 v172, 16, v126
	v_and_b32_e32 v173, 0xffff0000, v126
	v_lshlrev_b32_e32 v174, 16, v127
	v_and_b32_e32 v175, 0xffff0000, v127
	v_pk_mul_f32 v[252:253], v[160:161], v[160:161]
	v_pk_mul_f32 v[254:255], v[162:163], v[162:163]
	v_pk_fma_f32 v[252:253], v[164:165], v[164:165], v[252:253]
	v_pk_fma_f32 v[254:255], v[166:167], v[166:167], v[254:255]
	v_pk_fma_f32 v[252:253], v[168:169], v[168:169], v[252:253]
	v_pk_fma_f32 v[254:255], v[170:171], v[170:171], v[254:255]
	v_pk_fma_f32 v[252:253], v[172:173], v[172:173], v[252:253]
	v_pk_fma_f32 v[254:255], v[174:175], v[174:175], v[254:255]
	v_pk_add_f32 v[252:253], v[252:253], v[254:255]
	s_nop 0
	v_add_f32_e32 v183, v252, v253
	s_nop 1
	v_add_f32_dpp v183, v183, v183 quad_perm:[1,0,3,2] row_mask:0xf bank_mask:0xf bound_ctrl:1
	s_nop 1
	v_add_f32_dpp v183, v183, v183 quad_perm:[2,3,0,1] row_mask:0xf bank_mask:0xf bound_ctrl:1
	s_nop 1
	v_add_f32_dpp v183, v183, v183 row_half_mirror row_mask:0xf bank_mask:0xf bound_ctrl:1
	s_nop 1
	v_add_f32_dpp v183, v183, v183 row_mirror row_mask:0xf bank_mask:0xf bound_ctrl:1
	s_nop 1
	v_readlane_b32 s98, v183, 0
	v_readlane_b32 s99, v183, 16
	v_readlane_b32 s100, v183, 32
	v_readlane_b32 s101, v183, 48
	s_nop 1
	v_mov_b32_e32 v183, s98
	v_add_f32_e32 v183, s99, v183
	v_add_f32_e32 v183, s100, v183
	v_add_f32_e32 v183, s101, v183
	v_fmamk_f32 v183, v183, 0x3a800000, v182
	v_cmp_gt_f32_e32 vcc, 0x800000, v183
	v_mul_f32_e32 v181, 0x4b800000, v183
	s_nop 1
	v_cndmask_b32_e32 v183, v183, v181, vcc
	v_rsq_f32_e32 v183, v183
	s_nop 0
	v_mul_f32_e32 v181, 0x45800000, v183
	v_cndmask_b32_e32 v184, v183, v181, vcc
	v_mov_b32_e32 v185, v184
	v_pk_mul_f32 v[160:161], v[160:161], v[184:185]
	v_pk_mul_f32 v[162:163], v[162:163], v[184:185]
	v_pk_mul_f32 v[164:165], v[164:165], v[184:185]
	v_pk_mul_f32 v[166:167], v[166:167], v[184:185]
	v_pk_mul_f32 v[168:169], v[168:169], v[184:185]
	v_pk_mul_f32 v[170:171], v[170:171], v[184:185]
	v_pk_mul_f32 v[172:173], v[172:173], v[184:185]
	v_pk_mul_f32 v[174:175], v[174:175], v[184:185]
	v_pk_fma_f32 v[144:145], v[160:161], v[128:129], v[144:145]
	v_pk_fma_f32 v[146:147], v[162:163], v[130:131], v[146:147]
	v_pk_fma_f32 v[148:149], v[164:165], v[132:133], v[148:149]
	v_pk_fma_f32 v[150:151], v[166:167], v[134:135], v[150:151]
	v_pk_fma_f32 v[152:153], v[168:169], v[136:137], v[152:153]
	v_pk_fma_f32 v[154:155], v[170:171], v[138:139], v[154:155]
	v_pk_fma_f32 v[156:157], v[172:173], v[140:141], v[156:157]
	v_pk_fma_f32 v[158:159], v[174:175], v[142:143], v[158:159]
	v_pk_mul_f32 v[252:253], v[144:145], v[144:145]
	v_pk_mul_f32 v[254:255], v[146:147], v[146:147]
	v_pk_fma_f32 v[252:253], v[148:149], v[148:149], v[252:253]
	v_pk_fma_f32 v[254:255], v[150:151], v[150:151], v[254:255]
	v_pk_fma_f32 v[252:253], v[152:153], v[152:153], v[252:253]
	v_pk_fma_f32 v[254:255], v[154:155], v[154:155], v[254:255]
	v_pk_fma_f32 v[252:253], v[156:157], v[156:157], v[252:253]
	v_pk_fma_f32 v[254:255], v[158:159], v[158:159], v[254:255]
	v_pk_add_f32 v[252:253], v[252:253], v[254:255]
	s_nop 0
	v_add_f32_e32 v183, v252, v253
	s_nop 1
	v_add_f32_dpp v183, v183, v183 quad_perm:[1,0,3,2] row_mask:0xf bank_mask:0xf bound_ctrl:1
	s_nop 1
	v_add_f32_dpp v183, v183, v183 quad_perm:[2,3,0,1] row_mask:0xf bank_mask:0xf bound_ctrl:1
	s_nop 1
	v_add_f32_dpp v183, v183, v183 row_half_mirror row_mask:0xf bank_mask:0xf bound_ctrl:1
	s_nop 1
	v_add_f32_dpp v183, v183, v183 row_mirror row_mask:0xf bank_mask:0xf bound_ctrl:1
	s_nop 1
	v_readlane_b32 s98, v183, 0
	v_readlane_b32 s99, v183, 16
	v_readlane_b32 s100, v183, 32
	v_readlane_b32 s101, v183, 48
	s_nop 1
	v_mov_b32_e32 v183, s98
	v_add_f32_e32 v183, s99, v183
	v_add_f32_e32 v183, s100, v183
	v_add_f32_e32 v183, s101, v183
	v_fmamk_f32 v183, v183, 0x3a800000, v182
	v_cmp_gt_f32_e32 vcc, 0x800000, v183
	v_mul_f32_e32 v181, 0x4b800000, v183
	s_nop 1
	v_cndmask_b32_e32 v183, v183, v181, vcc
	v_rsq_f32_e32 v183, v183
	s_nop 0
	v_mul_f32_e32 v181, 0x45800000, v183
	v_cndmask_b32_e32 v184, v183, v181, vcc
	v_mov_b32_e32 v185, v184
	v_cvt_pk_bf16_f32 v112, v144, v145
	v_cvt_pk_bf16_f32 v113, v146, v147
	v_cvt_pk_bf16_f32 v114, v148, v149
	v_cvt_pk_bf16_f32 v115, v150, v151
	v_cvt_pk_bf16_f32 v116, v152, v153
	v_cvt_pk_bf16_f32 v117, v154, v155
	v_cvt_pk_bf16_f32 v118, v156, v157
	v_cvt_pk_bf16_f32 v119, v158, v159
	v_add_u32_e32 v181, 0x3400000, v177
	global_store_dwordx4 v181, v[112:115], s[78:79]
	global_store_dwordx4 v181, v[116:119], s[78:79] offset:1024
	v_add_u32_e32 v236, 0xe000, v237
	s_mov_b64 exec, 1
	global_store_dword v236, v184, s[78:79]
	s_mov_b64 exec, -1
	v_readfirstlane_b32 s98, v179
	s_nop 3
	s_and_b32 s99, s98, 3
	s_cmp_lg_u32 s99, 0
	s_cbranch_scc1 .Lmyxupd_done_2
	v_lshrrev_b32_e32 v179, 2, v179
	v_lshlrev_b32_e32 v177, 4, v176
	v_lshl_add_u32 v177, v179, 11, v177
	v_lshlrev_b32_e32 v237, 2, v179
	v_add_u32_e32 v237, 0x10000, v237
	v_add_u32_e32 v181, 0x3800000, v177
	global_load_dwordx4 v[240:243], v181, s[78:79]
	global_load_dwordx4 v[244:247], v181, s[78:79] offset:1024
	v_lshl_add_u32 v183, v179, 12, v180
	v_add_u32_e32 v183, 0xbf00000, v183
	v_add_u32_e32 v181, 0x0, v183
	global_load_dwordx4 v[0:3], v181, s[78:79]
	global_load_dwordx4 v[4:7], v181, s[78:79] offset:16
	global_load_dwordx4 v[8:11], v181, s[78:79] offset:2048
	global_load_dwordx4 v[12:15], v181, s[78:79] offset:2064
	v_add_u32_e32 v181, 0x200000, v183
	global_load_dwordx4 v[16:19], v181, s[78:79]
	global_load_dwordx4 v[20:23], v181, s[78:79] offset:16
	global_load_dwordx4 v[24:27], v181, s[78:79] offset:2048
	global_load_dwordx4 v[28:31], v181, s[78:79] offset:2064
	v_add_u32_e32 v181, 0x400000, v183
	global_load_dwordx4 v[32:35], v181, s[78:79]
	global_load_dwordx4 v[36:39], v181, s[78:79] offset:16
	global_load_dwordx4 v[40:43], v181, s[78:79] offset:2048
	global_load_dwordx4 v[44:47], v181, s[78:79] offset:2064
	v_add_u32_e32 v181, 0x600000, v183
	global_load_dwordx4 v[48:51], v181, s[78:79]
	global_load_dwordx4 v[52:55], v181, s[78:79] offset:16
	global_load_dwordx4 v[56:59], v181, s[78:79] offset:2048
	global_load_dwordx4 v[60:63], v181, s[78:79] offset:2064
	v_add_u32_e32 v181, 0x800000, v183
	global_load_dwordx4 v[64:67], v181, s[78:79]
	global_load_dwordx4 v[68:71], v181, s[78:79] offset:16
	global_load_dwordx4 v[72:75], v181, s[78:79] offset:2048
	global_load_dwordx4 v[76:79], v181, s[78:79] offset:2064
	v_add_u32_e32 v181, 0xa00000, v183
	global_load_dwordx4 v[80:83], v181, s[78:79]
	global_load_dwordx4 v[84:87], v181, s[78:79] offset:16
	global_load_dwordx4 v[88:91], v181, s[78:79] offset:2048
	global_load_dwordx4 v[92:95], v181, s[78:79] offset:2064
	v_add_u32_e32 v181, 0xc00000, v183
	global_load_dwordx4 v[96:99], v181, s[78:79]
	global_load_dwordx4 v[100:103], v181, s[78:79] offset:16
	global_load_dwordx4 v[104:107], v181, s[78:79] offset:2048
	global_load_dwordx4 v[108:111], v181, s[78:79] offset:2064
	v_add_u32_e32 v181, 0xe00000, v183
	global_load_dwordx4 v[112:115], v181, s[78:79]
	global_load_dwordx4 v[116:119], v181, s[78:79] offset:16
	global_load_dwordx4 v[120:123], v181, s[78:79] offset:2048
	global_load_dwordx4 v[124:127], v181, s[78:79] offset:2064
	s_waitcnt vmcnt(28)
	v_pk_add_f32 v[160:161], v[0:1], 0 op_sel_hi:[1,0]
	v_pk_add_f32 v[162:163], v[2:3], 0 op_sel_hi:[1,0]
	v_pk_add_f32 v[164:165], v[4:5], 0 op_sel_hi:[1,0]
	v_pk_add_f32 v[166:167], v[6:7], 0 op_sel_hi:[1,0]
	v_pk_add_f32 v[168:169], v[8:9], 0 op_sel_hi:[1,0]
	v_pk_add_f32 v[170:171], v[10:11], 0 op_sel_hi:[1,0]
	v_pk_add_f32 v[172:173], v[12:13], 0 op_sel_hi:[1,0]
	v_pk_add_f32 v[174:175], v[14:15], 0 op_sel_hi:[1,0]
	s_waitcnt vmcnt(24)
	v_pk_add_f32 v[160:161], v[160:161], v[16:17]
	v_pk_add_f32 v[162:163], v[162:163], v[18:19]
	v_pk_add_f32 v[164:165], v[164:165], v[20:21]
	v_pk_add_f32 v[166:167], v[166:167], v[22:23]
	v_pk_add_f32 v[168:169], v[168:169], v[24:25]
	v_pk_add_f32 v[170:171], v[170:171], v[26:27]
	v_pk_add_f32 v[172:173], v[172:173], v[28:29]
	v_pk_add_f32 v[174:175], v[174:175], v[30:31]
	s_waitcnt vmcnt(20)
	v_pk_add_f32 v[160:161], v[160:161], v[32:33]
	v_pk_add_f32 v[162:163], v[162:163], v[34:35]
	v_pk_add_f32 v[164:165], v[164:165], v[36:37]
	v_pk_add_f32 v[166:167], v[166:167], v[38:39]
	v_pk_add_f32 v[168:169], v[168:169], v[40:41]
	v_pk_add_f32 v[170:171], v[170:171], v[42:43]
	v_pk_add_f32 v[172:173], v[172:173], v[44:45]
	v_pk_add_f32 v[174:175], v[174:175], v[46:47]
	s_waitcnt vmcnt(16)
	v_pk_add_f32 v[160:161], v[160:161], v[48:49]
	v_pk_add_f32 v[162:163], v[162:163], v[50:51]
	v_pk_add_f32 v[164:165], v[164:165], v[52:53]
	v_pk_add_f32 v[166:167], v[166:167], v[54:55]
	v_pk_add_f32 v[168:169], v[168:169], v[56:57]
	v_pk_add_f32 v[170:171], v[170:171], v[58:59]
	v_pk_add_f32 v[172:173], v[172:173], v[60:61]
	v_pk_add_f32 v[174:175], v[174:175], v[62:63]
	s_waitcnt vmcnt(12)
	v_pk_add_f32 v[160:161], v[160:161], v[64:65]
	v_pk_add_f32 v[162:163], v[162:163], v[66:67]
	v_pk_add_f32 v[164:165], v[164:165], v[68:69]
	v_pk_add_f32 v[166:167], v[166:167], v[70:71]
	v_pk_add_f32 v[168:169], v[168:169], v[72:73]
	v_pk_add_f32 v[170:171], v[170:171], v[74:75]
	v_pk_add_f32 v[172:173], v[172:173], v[76:77]
	v_pk_add_f32 v[174:175], v[174:175], v[78:79]
	s_waitcnt vmcnt(8)
	v_pk_add_f32 v[160:161], v[160:161], v[80:81]
	v_pk_add_f32 v[162:163], v[162:163], v[82:83]
	v_pk_add_f32 v[164:165], v[164:165], v[84:85]
	v_pk_add_f32 v[166:167], v[166:167], v[86:87]
	v_pk_add_f32 v[168:169], v[168:169], v[88:89]
	v_pk_add_f32 v[170:171], v[170:171], v[90:91]
	v_pk_add_f32 v[172:173], v[172:173], v[92:93]
	v_pk_add_f32 v[174:175], v[174:175], v[94:95]
	s_waitcnt vmcnt(4)
	v_pk_add_f32 v[160:161], v[160:161], v[96:97]
	v_pk_add_f32 v[162:163], v[162:163], v[98:99]
	v_pk_add_f32 v[164:165], v[164:165], v[100:101]
	v_pk_add_f32 v[166:167], v[166:167], v[102:103]
	v_pk_add_f32 v[168:169], v[168:169], v[104:105]
	v_pk_add_f32 v[170:171], v[170:171], v[106:107]
	v_pk_add_f32 v[172:173], v[172:173], v[108:109]
	v_pk_add_f32 v[174:175], v[174:175], v[110:111]
	s_waitcnt vmcnt(0)
	v_pk_add_f32 v[160:161], v[160:161], v[112:113]
	v_pk_add_f32 v[162:163], v[162:163], v[114:115]
	v_pk_add_f32 v[164:165], v[164:165], v[116:117]
	v_pk_add_f32 v[166:167], v[166:167], v[118:119]
	v_pk_add_f32 v[168:169], v[168:169], v[120:121]
	v_pk_add_f32 v[170:171], v[170:171], v[122:123]
	v_pk_add_f32 v[172:173], v[172:173], v[124:125]
	v_pk_add_f32 v[174:175], v[174:175], v[126:127]
	v_lshlrev_b32_e32 v144, 16, v240
	v_and_b32_e32 v145, 0xffff0000, v240
	v_lshlrev_b32_e32 v146, 16, v241
	v_and_b32_e32 v147, 0xffff0000, v241
	v_lshlrev_b32_e32 v148, 16, v242
	v_and_b32_e32 v149, 0xffff0000, v242
	v_lshlrev_b32_e32 v150, 16, v243
	v_and_b32_e32 v151, 0xffff0000, v243
	v_lshlrev_b32_e32 v152, 16, v244
	v_and_b32_e32 v153, 0xffff0000, v244
	v_lshlrev_b32_e32 v154, 16, v245
	v_and_b32_e32 v155, 0xffff0000, v245
	v_lshlrev_b32_e32 v156, 16, v246
	v_and_b32_e32 v157, 0xffff0000, v246
	v_lshlrev_b32_e32 v158, 16, v247
	v_and_b32_e32 v159, 0xffff0000, v247
	v_pk_mul_f32 v[252:253], v[160:161], v[160:161]
	v_pk_mul_f32 v[254:255], v[162:163], v[162:163]
	v_pk_fma_f32 v[252:253], v[164:165], v[164:165], v[252:253]
	v_pk_fma_f32 v[254:255], v[166:167], v[166:167], v[254:255]
	v_pk_fma_f32 v[252:253], v[168:169], v[168:169], v[252:253]
	v_pk_fma_f32 v[254:255], v[170:171], v[170:171], v[254:255]
	v_pk_fma_f32 v[252:253], v[172:173], v[172:173], v[252:253]
	v_pk_fma_f32 v[254:255], v[174:175], v[174:175], v[254:255]
	v_pk_add_f32 v[252:253], v[252:253], v[254:255]
	s_nop 0
	v_add_f32_e32 v183, v252, v253
	s_nop 1
	v_add_f32_dpp v183, v183, v183 quad_perm:[1,0,3,2] row_mask:0xf bank_mask:0xf bound_ctrl:1
	s_nop 1
	v_add_f32_dpp v183, v183, v183 quad_perm:[2,3,0,1] row_mask:0xf bank_mask:0xf bound_ctrl:1
	s_nop 1
	v_add_f32_dpp v183, v183, v183 row_half_mirror row_mask:0xf bank_mask:0xf bound_ctrl:1
	s_nop 1
	v_add_f32_dpp v183, v183, v183 row_mirror row_mask:0xf bank_mask:0xf bound_ctrl:1
	s_nop 1
	v_readlane_b32 s98, v183, 0
	v_readlane_b32 s99, v183, 16
	v_readlane_b32 s100, v183, 32
	v_readlane_b32 s101, v183, 48
	s_nop 1
	v_mov_b32_e32 v183, s98
	v_add_f32_e32 v183, s99, v183
	v_add_f32_e32 v183, s100, v183
	v_add_f32_e32 v183, s101, v183
	v_fmamk_f32 v183, v183, 0x3a800000, v182
	v_cmp_gt_f32_e32 vcc, 0x800000, v183
	v_mul_f32_e32 v181, 0x4b800000, v183
	s_nop 1
	v_cndmask_b32_e32 v183, v183, v181, vcc
	v_rsq_f32_e32 v183, v183
	s_nop 0
	v_mul_f32_e32 v181, 0x45800000, v183
	v_cndmask_b32_e32 v184, v183, v181, vcc
	v_mov_b32_e32 v185, v184
	v_pk_mul_f32 v[160:161], v[160:161], v[184:185]
	v_pk_mul_f32 v[162:163], v[162:163], v[184:185]
	v_pk_mul_f32 v[164:165], v[164:165], v[184:185]
	v_pk_mul_f32 v[166:167], v[166:167], v[184:185]
	v_pk_mul_f32 v[168:169], v[168:169], v[184:185]
	v_pk_mul_f32 v[170:171], v[170:171], v[184:185]
	v_pk_mul_f32 v[172:173], v[172:173], v[184:185]
	v_pk_mul_f32 v[174:175], v[174:175], v[184:185]
	v_pk_fma_f32 v[144:145], v[160:161], v[128:129], v[144:145]
	v_pk_fma_f32 v[146:147], v[162:163], v[130:131], v[146:147]
	v_pk_fma_f32 v[148:149], v[164:165], v[132:133], v[148:149]
	v_pk_fma_f32 v[150:151], v[166:167], v[134:135], v[150:151]
	v_pk_fma_f32 v[152:153], v[168:169], v[136:137], v[152:153]
	v_pk_fma_f32 v[154:155], v[170:171], v[138:139], v[154:155]
	v_pk_fma_f32 v[156:157], v[172:173], v[140:141], v[156:157]
	v_pk_fma_f32 v[158:159], v[174:175], v[142:143], v[158:159]
	v_pk_mul_f32 v[252:253], v[144:145], v[144:145]
	v_pk_mul_f32 v[254:255], v[146:147], v[146:147]
	v_pk_fma_f32 v[252:253], v[148:149], v[148:149], v[252:253]
	v_pk_fma_f32 v[254:255], v[150:151], v[150:151], v[254:255]
	v_pk_fma_f32 v[252:253], v[152:153], v[152:153], v[252:253]
	v_pk_fma_f32 v[254:255], v[154:155], v[154:155], v[254:255]
	v_pk_fma_f32 v[252:253], v[156:157], v[156:157], v[252:253]
	v_pk_fma_f32 v[254:255], v[158:159], v[158:159], v[254:255]
	v_pk_add_f32 v[252:253], v[252:253], v[254:255]
	s_nop 0
	v_add_f32_e32 v183, v252, v253
	s_nop 1
	v_add_f32_dpp v183, v183, v183 quad_perm:[1,0,3,2] row_mask:0xf bank_mask:0xf bound_ctrl:1
	s_nop 1
	v_add_f32_dpp v183, v183, v183 quad_perm:[2,3,0,1] row_mask:0xf bank_mask:0xf bound_ctrl:1
	s_nop 1
	v_add_f32_dpp v183, v183, v183 row_half_mirror row_mask:0xf bank_mask:0xf bound_ctrl:1
	s_nop 1
	v_add_f32_dpp v183, v183, v183 row_mirror row_mask:0xf bank_mask:0xf bound_ctrl:1
	s_nop 1
	v_readlane_b32 s98, v183, 0
	v_readlane_b32 s99, v183, 16
	v_readlane_b32 s100, v183, 32
	v_readlane_b32 s101, v183, 48
	s_nop 1
	v_mov_b32_e32 v183, s98
	v_add_f32_e32 v183, s99, v183
	v_add_f32_e32 v183, s100, v183
	v_add_f32_e32 v183, s101, v183
	v_fmamk_f32 v183, v183, 0x3a800000, v182
	v_cmp_gt_f32_e32 vcc, 0x800000, v183
	v_mul_f32_e32 v181, 0x4b800000, v183
	s_nop 1
	v_cndmask_b32_e32 v183, v183, v181, vcc
	v_rsq_f32_e32 v183, v183
	s_nop 0
	v_mul_f32_e32 v181, 0x45800000, v183
	v_cndmask_b32_e32 v184, v183, v181, vcc
	v_mov_b32_e32 v185, v184
	v_cvt_pk_bf16_f32 v0, v144, v145
	v_cvt_pk_bf16_f32 v1, v146, v147
	v_cvt_pk_bf16_f32 v2, v148, v149
	v_cvt_pk_bf16_f32 v3, v150, v151
	v_cvt_pk_bf16_f32 v4, v152, v153
	v_cvt_pk_bf16_f32 v5, v154, v155
	v_cvt_pk_bf16_f32 v6, v156, v157
	v_cvt_pk_bf16_f32 v7, v158, v159
	v_add_u32_e32 v181, 0x3800000, v177
	global_store_dwordx4 v181, v[0:3], s[78:79]
	global_store_dwordx4 v181, v[4:7], s[78:79] offset:1024
	v_add_u32_e32 v236, 0x10000, v237
	s_mov_b64 exec, 1
	global_store_dword v236, v184, s[78:79]
	s_mov_b64 exec, -1

.LBB0_1430:
	v_readlane_b32 s0, v235, 52
	v_readlane_b32 s1, v235, 53
	s_and_b64 vcc, exec, s[0:1]
	s_waitcnt lgkmcnt(0)
	s_barrier
	v_mbcnt_lo_u32_b32 v0, -1, 0
	v_mbcnt_hi_u32_b32 v0, -1, v0
	s_cbranch_vccnz .LBB0_1450
	v_lshlrev_b32_e32 v2, 3, v0
	v_readlane_b32 s4, v235, 4
	v_ashrrev_i32_e32 v3, 31, v2
	v_readlane_b32 s6, v235, 6
	v_readlane_b32 s7, v235, 7
	v_lshlrev_b64 v[4:5], 1, v[2:3]
	v_lshlrev_b64 v[2:3], 2, v[2:3]
	v_readlane_b32 s5, v235, 5
	v_readlane_b32 s10, v235, 10
	v_readlane_b32 s11, v235, 11
	v_readlane_b32 s18, v235, 18
	v_readlane_b32 s19, v235, 19
	v_readlane_b32 s6, v235, 61
	v_lshl_add_u64 v[154:155], s[90:91], 0, v[2:3]
	v_readlane_b32 s8, v235, 8
	v_lshl_add_u64 v[2:3], s[18:19], 0, v[2:3]
	s_mov_b64 s[0:1], 0x1000
	v_readlane_b32 s4, v235, 0
	v_readlane_b32 s7, v235, 62
	s_mov_b32 s10, s6
	s_ashr_i32 s11, s6, 31
	v_readlane_b32 s9, v235, 9
	v_lshl_add_u64 v[158:159], v[2:3], 0, s[0:1]
	s_lshl_b32 s4, s4, 4
	s_add_i32 s0, s6, 0xffffc000
	s_lshl_b64 s[6:7], s[10:11], 2
	s_mov_b32 s8, s10
	v_readlane_b32 s12, v235, 12
	v_readlane_b32 s13, v235, 13
	v_readlane_b32 s14, v235, 14
	v_readlane_b32 s15, v235, 15
	v_readlane_b32 s16, v235, 16
	v_readlane_b32 s17, v235, 17
	v_readlane_b32 s5, v235, 1
	s_add_u32 s80, s6, 0x10000
	v_writelane_b32 v235, s8, 61
	s_addc_u32 s12, s7, 0
	s_ashr_i32 s5, s4, 31
	v_writelane_b32 v235, s9, 62
	s_lshl_b64 s[8:9], s[10:11], 11
	v_lshl_add_u64 v[152:153], s[86:87], 0, v[4:5]
	v_lshl_add_u64 v[156:157], s[54:55], 0, v[4:5]
	s_mov_b32 s1, 0
	v_cmp_eq_u32_e64 s[16:17], 0, v0
	s_lshl_b64 s[6:7], s[4:5], 2
	v_lshl_add_u64 v[160:161], s[8:9], 0, v[4:5]
	s_lshl_b64 s[8:9], s[4:5], 11
	s_mov_b64 s[20:21], 0x600000
	s_mov_b64 s[22:23], 0x600800
	s_mov_b64 s[24:25], 0x800000
	s_mov_b32 s5, 0x800000
	s_mov_b64 s[26:27], 0x800800
	s_mov_b64 s[28:29], 0xa00000
	s_mov_b64 s[36:37], 0xa00800
	s_mov_b64 s[38:39], 0xc00000
	s_mov_b64 s[40:41], 0xc00800
	s_mov_b64 s[42:43], 0xe00000
	s_mov_b64 s[44:45], 0xe00800
	s_mov_b64 s[46:47], 0x1000000
	s_mov_b32 s13, 0x1000000
	s_mov_b64 s[48:49], 0x1000800
	s_mov_b64 s[50:51], 0x1200000
	s_mov_b32 s14, 0x1200000
	s_mov_b64 s[10:11], 0x1200800
	s_mov_b64 s[82:83], 0x1400000
	s_mov_b32 s15, 0x1400000
	s_mov_b64 s[90:91], 0x1400800
	v_mov_b32_e32 v215, 0
	v_mov_b32_e32 v216, 0x358637bd
	v_mbcnt_lo_u32_b32 v176, -1, 0
	v_mbcnt_hi_u32_b32 v176, -1, v176
	v_readlane_b32 s98, v235, 49
	v_readlane_b32 s99, v235, 20
	v_readlane_b32 s100, v235, 18
	v_readlane_b32 s101, v235, 19
	s_nop 3
	s_lshr_b32 vcc_lo, s98, 3
	s_and_b32 vcc_hi, vcc_lo, 7
	s_lshr_b32 vcc_lo, vcc_lo, 3
	s_lshl_b32 vcc_lo, vcc_lo, 3
	s_add_i32 vcc_lo, vcc_lo, s99
	s_lshl_b32 s98, vcc_hi, 8
	s_add_i32 s98, s98, vcc_lo
	s_mov_b32 s99, s98
	v_mov_b32_e32 v183, s99
	v_lshlrev_b32_e32 v177, 4, v176
	s_lshl_b32 s99, s99, 11
	v_add_u32_e32 v177, s99, v177
	v_add_u32_e32 v178, 0x1800000, v177
	v_add_u32_e32 v179, 0x9e00000, v177
	v_lshlrev_b32_e32 v180, 5, v176
	v_add_u32_e32 v181, 0x1000, v180
	global_load_dwordx4 v[128:131], v181, s[100:101]
	global_load_dwordx4 v[132:135], v181, s[100:101] offset:16
	global_load_dwordx4 v[136:139], v181, s[100:101] offset:2048
	global_load_dwordx4 v[140:143], v181, s[100:101] offset:2064
	v_mov_b32_e32 v182, 0x358637bd
	global_load_dwordx4 v[0:3], v178, s[78:79]
	global_load_dwordx4 v[4:7], v178, s[78:79] offset:1024
	global_load_dwordx4 v[8:11], v179, s[78:79]
	global_load_dwordx4 v[12:15], v179, s[78:79] offset:1024
	v_add_u32_e32 v178, 0x400000, v178
	v_add_u32_e32 v179, 0x400000, v179
	global_load_dwordx4 v[16:19], v178, s[78:79]
	global_load_dwordx4 v[20:23], v178, s[78:79] offset:1024
	global_load_dwordx4 v[24:27], v179, s[78:79]
	global_load_dwordx4 v[28:31], v179, s[78:79] offset:1024
	v_add_u32_e32 v178, 0x400000, v178
	v_add_u32_e32 v179, 0x400000, v179
	global_load_dwordx4 v[32:35], v178, s[78:79]
	global_load_dwordx4 v[36:39], v178, s[78:79] offset:1024
	global_load_dwordx4 v[40:43], v179, s[78:79]
	global_load_dwordx4 v[44:47], v179, s[78:79] offset:1024
	v_add_u32_e32 v178, 0x400000, v178
	v_add_u32_e32 v179, 0x400000, v179
	global_load_dwordx4 v[48:51], v178, s[78:79]
	global_load_dwordx4 v[52:55], v178, s[78:79] offset:1024
	global_load_dwordx4 v[56:59], v179, s[78:79]
	global_load_dwordx4 v[60:63], v179, s[78:79] offset:1024
	v_add_u32_e32 v178, 0x400000, v178
	v_add_u32_e32 v179, 0x400000, v179
	global_load_dwordx4 v[64:67], v178, s[78:79]
	global_load_dwordx4 v[68:71], v178, s[78:79] offset:1024
	global_load_dwordx4 v[72:75], v179, s[78:79]
	global_load_dwordx4 v[76:79], v179, s[78:79] offset:1024
	v_add_u32_e32 v178, 0x400000, v178
	v_add_u32_e32 v179, 0x400000, v179
	global_load_dwordx4 v[80:83], v178, s[78:79]
	global_load_dwordx4 v[84:87], v178, s[78:79] offset:1024
	global_load_dwordx4 v[88:91], v179, s[78:79]
	global_load_dwordx4 v[92:95], v179, s[78:79] offset:1024
	v_add_u32_e32 v178, 0x400000, v178
	v_add_u32_e32 v179, 0x400000, v179
	global_load_dwordx4 v[96:99], v178, s[78:79]
	global_load_dwordx4 v[100:103], v178, s[78:79] offset:1024
	global_load_dwordx4 v[104:107], v179, s[78:79]
	global_load_dwordx4 v[108:111], v179, s[78:79] offset:1024
	v_add_u32_e32 v178, 0x400000, v178
	v_add_u32_e32 v179, 0x400000, v179
	global_load_dwordx4 v[112:115], v178, s[78:79]
	global_load_dwordx4 v[116:119], v178, s[78:79] offset:1024
	global_load_dwordx4 v[120:123], v179, s[78:79]
	global_load_dwordx4 v[124:127], v179, s[78:79] offset:1024
	v_lshlrev_b32_e32 v237, 2, v183
	v_add_u32_e32 v237, 0x10000, v237
	v_mov_b32_e32 v179, s98
	s_waitcnt vmcnt(28)
	v_lshlrev_b32_e32 v144, 16, v0
	v_and_b32_e32 v145, 0xffff0000, v0
	v_lshlrev_b32_e32 v146, 16, v1
	v_and_b32_e32 v147, 0xffff0000, v1
	v_lshlrev_b32_e32 v148, 16, v2
	v_and_b32_e32 v149, 0xffff0000, v2
	v_lshlrev_b32_e32 v150, 16, v3
	v_and_b32_e32 v151, 0xffff0000, v3
	v_lshlrev_b32_e32 v152, 16, v4
	v_and_b32_e32 v153, 0xffff0000, v4
	v_lshlrev_b32_e32 v154, 16, v5
	v_and_b32_e32 v155, 0xffff0000, v5
	v_lshlrev_b32_e32 v156, 16, v6
	v_and_b32_e32 v157, 0xffff0000, v6
	v_lshlrev_b32_e32 v158, 16, v7
	v_and_b32_e32 v159, 0xffff0000, v7
	v_lshlrev_b32_e32 v160, 16, v8
	v_and_b32_e32 v161, 0xffff0000, v8
	v_lshlrev_b32_e32 v162, 16, v9
	v_and_b32_e32 v163, 0xffff0000, v9
	v_lshlrev_b32_e32 v164, 16, v10
	v_and_b32_e32 v165, 0xffff0000, v10
	v_lshlrev_b32_e32 v166, 16, v11
	v_and_b32_e32 v167, 0xffff0000, v11
	v_lshlrev_b32_e32 v168, 16, v12
	v_and_b32_e32 v169, 0xffff0000, v12
	v_lshlrev_b32_e32 v170, 16, v13
	v_and_b32_e32 v171, 0xffff0000, v13
	v_lshlrev_b32_e32 v172, 16, v14
	v_and_b32_e32 v173, 0xffff0000, v14
	v_lshlrev_b32_e32 v174, 16, v15
	v_and_b32_e32 v175, 0xffff0000, v15
	v_pk_mul_f32 v[252:253], v[160:161], v[160:161]
	v_pk_mul_f32 v[254:255], v[162:163], v[162:163]
	v_pk_fma_f32 v[252:253], v[164:165], v[164:165], v[252:253]
	v_pk_fma_f32 v[254:255], v[166:167], v[166:167], v[254:255]
	v_pk_fma_f32 v[252:253], v[168:169], v[168:169], v[252:253]
	v_pk_fma_f32 v[254:255], v[170:171], v[170:171], v[254:255]
	v_pk_fma_f32 v[252:253], v[172:173], v[172:173], v[252:253]
	v_pk_fma_f32 v[254:255], v[174:175], v[174:175], v[254:255]
	v_pk_add_f32 v[252:253], v[252:253], v[254:255]
	s_nop 0
	v_add_f32_e32 v183, v252, v253
	s_nop 1
	v_add_f32_dpp v183, v183, v183 quad_perm:[1,0,3,2] row_mask:0xf bank_mask:0xf bound_ctrl:1
	s_nop 1
	v_add_f32_dpp v183, v183, v183 quad_perm:[2,3,0,1] row_mask:0xf bank_mask:0xf bound_ctrl:1
	s_nop 1
	v_add_f32_dpp v183, v183, v183 row_half_mirror row_mask:0xf bank_mask:0xf bound_ctrl:1
	s_nop 1
	v_add_f32_dpp v183, v183, v183 row_mirror row_mask:0xf bank_mask:0xf bound_ctrl:1
	s_nop 1
	v_readlane_b32 s98, v183, 0
	v_readlane_b32 s99, v183, 16
	v_readlane_b32 s100, v183, 32
	v_readlane_b32 s101, v183, 48
	s_nop 1
	v_mov_b32_e32 v183, s98
	v_add_f32_e32 v183, s99, v183
	v_add_f32_e32 v183, s100, v183
	v_add_f32_e32 v183, s101, v183
	v_fmamk_f32 v183, v183, 0x3a800000, v182
	v_cmp_gt_f32_e32 vcc, 0x800000, v183
	v_mul_f32_e32 v181, 0x4b800000, v183
	s_nop 1
	v_cndmask_b32_e32 v183, v183, v181, vcc
	v_rsq_f32_e32 v183, v183
	s_nop 0
	v_mul_f32_e32 v181, 0x45800000, v183
	v_cndmask_b32_e32 v184, v183, v181, vcc
	v_mov_b32_e32 v185, v184
	v_pk_mul_f32 v[160:161], v[160:161], v[184:185]
	v_pk_mul_f32 v[162:163], v[162:163], v[184:185]
	v_pk_mul_f32 v[164:165], v[164:165], v[184:185]
	v_pk_mul_f32 v[166:167], v[166:167], v[184:185]
	v_pk_mul_f32 v[168:169], v[168:169], v[184:185]
	v_pk_mul_f32 v[170:171], v[170:171], v[184:185]
	v_pk_mul_f32 v[172:173], v[172:173], v[184:185]
	v_pk_mul_f32 v[174:175], v[174:175], v[184:185]
	v_pk_fma_f32 v[144:145], v[160:161], v[128:129], v[144:145]
	v_pk_fma_f32 v[146:147], v[162:163], v[130:131], v[146:147]
	v_pk_fma_f32 v[148:149], v[164:165], v[132:133], v[148:149]
	v_pk_fma_f32 v[150:151], v[166:167], v[134:135], v[150:151]
	v_pk_fma_f32 v[152:153], v[168:169], v[136:137], v[152:153]
	v_pk_fma_f32 v[154:155], v[170:171], v[138:139], v[154:155]
	v_pk_fma_f32 v[156:157], v[172:173], v[140:141], v[156:157]
	v_pk_fma_f32 v[158:159], v[174:175], v[142:143], v[158:159]
	v_pk_mul_f32 v[252:253], v[144:145], v[144:145]
	v_pk_mul_f32 v[254:255], v[146:147], v[146:147]
	v_pk_fma_f32 v[252:253], v[148:149], v[148:149], v[252:253]
	v_pk_fma_f32 v[254:255], v[150:151], v[150:151], v[254:255]
	v_pk_fma_f32 v[252:253], v[152:153], v[152:153], v[252:253]
	v_pk_fma_f32 v[254:255], v[154:155], v[154:155], v[254:255]
	v_pk_fma_f32 v[252:253], v[156:157], v[156:157], v[252:253]
	v_pk_fma_f32 v[254:255], v[158:159], v[158:159], v[254:255]
	v_pk_add_f32 v[252:253], v[252:253], v[254:255]
	s_nop 0
	v_add_f32_e32 v183, v252, v253
	s_nop 1
	v_add_f32_dpp v183, v183, v183 quad_perm:[1,0,3,2] row_mask:0xf bank_mask:0xf bound_ctrl:1
	s_nop 1
	v_add_f32_dpp v183, v183, v183 quad_perm:[2,3,0,1] row_mask:0xf bank_mask:0xf bound_ctrl:1
	s_nop 1
	v_add_f32_dpp v183, v183, v183 row_half_mirror row_mask:0xf bank_mask:0xf bound_ctrl:1
	s_nop 1
	v_add_f32_dpp v183, v183, v183 row_mirror row_mask:0xf bank_mask:0xf bound_ctrl:1
	s_nop 1
	v_readlane_b32 s98, v183, 0
	v_readlane_b32 s99, v183, 16
	v_readlane_b32 s100, v183, 32
	v_readlane_b32 s101, v183, 48
	s_nop 1
	v_mov_b32_e32 v183, s98
	v_add_f32_e32 v183, s99, v183
	v_add_f32_e32 v183, s100, v183
	v_add_f32_e32 v183, s101, v183
	v_fmamk_f32 v183, v183, 0x3a800000, v182
	v_cmp_gt_f32_e32 vcc, 0x800000, v183
	v_mul_f32_e32 v181, 0x4b800000, v183
	s_nop 1
	v_cndmask_b32_e32 v183, v183, v181, vcc
	v_rsq_f32_e32 v183, v183
	s_nop 0
	v_mul_f32_e32 v181, 0x45800000, v183
	v_cndmask_b32_e32 v184, v183, v181, vcc
	v_mov_b32_e32 v185, v184
	v_cvt_pk_bf16_f32 v0, v144, v145
	v_cvt_pk_bf16_f32 v1, v146, v147
	v_cvt_pk_bf16_f32 v2, v148, v149
	v_cvt_pk_bf16_f32 v3, v150, v151
	v_cvt_pk_bf16_f32 v4, v152, v153
	v_cvt_pk_bf16_f32 v5, v154, v155
	v_cvt_pk_bf16_f32 v6, v156, v157
	v_cvt_pk_bf16_f32 v7, v158, v159
	v_add_u32_e32 v181, 0x1800000, v177
	global_store_dwordx4 v181, v[0:3], s[78:79]
	global_store_dwordx4 v181, v[4:7], s[78:79] offset:1024
	v_add_u32_e32 v236, 0x0, v237
	s_mov_b64 exec, 1
	global_store_dword v236, v184, s[78:79]
	s_mov_b64 exec, -1
	s_waitcnt vmcnt(24)
	v_lshlrev_b32_e32 v144, 16, v16
	v_and_b32_e32 v145, 0xffff0000, v16
	v_lshlrev_b32_e32 v146, 16, v17
	v_and_b32_e32 v147, 0xffff0000, v17
	v_lshlrev_b32_e32 v148, 16, v18
	v_and_b32_e32 v149, 0xffff0000, v18
	v_lshlrev_b32_e32 v150, 16, v19
	v_and_b32_e32 v151, 0xffff0000, v19
	v_lshlrev_b32_e32 v152, 16, v20
	v_and_b32_e32 v153, 0xffff0000, v20
	v_lshlrev_b32_e32 v154, 16, v21
	v_and_b32_e32 v155, 0xffff0000, v21
	v_lshlrev_b32_e32 v156, 16, v22
	v_and_b32_e32 v157, 0xffff0000, v22
	v_lshlrev_b32_e32 v158, 16, v23
	v_and_b32_e32 v159, 0xffff0000, v23
	v_lshlrev_b32_e32 v160, 16, v24
	v_and_b32_e32 v161, 0xffff0000, v24
	v_lshlrev_b32_e32 v162, 16, v25
	v_and_b32_e32 v163, 0xffff0000, v25
	v_lshlrev_b32_e32 v164, 16, v26
	v_and_b32_e32 v165, 0xffff0000, v26
	v_lshlrev_b32_e32 v166, 16, v27
	v_and_b32_e32 v167, 0xffff0000, v27
	v_lshlrev_b32_e32 v168, 16, v28
	v_and_b32_e32 v169, 0xffff0000, v28
	v_lshlrev_b32_e32 v170, 16, v29
	v_and_b32_e32 v171, 0xffff0000, v29
	v_lshlrev_b32_e32 v172, 16, v30
	v_and_b32_e32 v173, 0xffff0000, v30
	v_lshlrev_b32_e32 v174, 16, v31
	v_and_b32_e32 v175, 0xffff0000, v31
	v_pk_mul_f32 v[252:253], v[160:161], v[160:161]
	v_pk_mul_f32 v[254:255], v[162:163], v[162:163]
	v_pk_fma_f32 v[252:253], v[164:165], v[164:165], v[252:253]
	v_pk_fma_f32 v[254:255], v[166:167], v[166:167], v[254:255]
	v_pk_fma_f32 v[252:253], v[168:169], v[168:169], v[252:253]
	v_pk_fma_f32 v[254:255], v[170:171], v[170:171], v[254:255]
	v_pk_fma_f32 v[252:253], v[172:173], v[172:173], v[252:253]
	v_pk_fma_f32 v[254:255], v[174:175], v[174:175], v[254:255]
	v_pk_add_f32 v[252:253], v[252:253], v[254:255]
	s_nop 0
	v_add_f32_e32 v183, v252, v253
	s_nop 1
	v_add_f32_dpp v183, v183, v183 quad_perm:[1,0,3,2] row_mask:0xf bank_mask:0xf bound_ctrl:1
	s_nop 1
	v_add_f32_dpp v183, v183, v183 quad_perm:[2,3,0,1] row_mask:0xf bank_mask:0xf bound_ctrl:1
	s_nop 1
	v_add_f32_dpp v183, v183, v183 row_half_mirror row_mask:0xf bank_mask:0xf bound_ctrl:1
	s_nop 1
	v_add_f32_dpp v183, v183, v183 row_mirror row_mask:0xf bank_mask:0xf bound_ctrl:1
	s_nop 1
	v_readlane_b32 s98, v183, 0
	v_readlane_b32 s99, v183, 16
	v_readlane_b32 s100, v183, 32
	v_readlane_b32 s101, v183, 48
	s_nop 1
	v_mov_b32_e32 v183, s98
	v_add_f32_e32 v183, s99, v183
	v_add_f32_e32 v183, s100, v183
	v_add_f32_e32 v183, s101, v183
	v_fmamk_f32 v183, v183, 0x3a800000, v182
	v_cmp_gt_f32_e32 vcc, 0x800000, v183
	v_mul_f32_e32 v181, 0x4b800000, v183
	s_nop 1
	v_cndmask_b32_e32 v183, v183, v181, vcc
	v_rsq_f32_e32 v183, v183
	s_nop 0
	v_mul_f32_e32 v181, 0x45800000, v183
	v_cndmask_b32_e32 v184, v183, v181, vcc
	v_mov_b32_e32 v185, v184
	v_pk_mul_f32 v[160:161], v[160:161], v[184:185]
	v_pk_mul_f32 v[162:163], v[162:163], v[184:185]
	v_pk_mul_f32 v[164:165], v[164:165], v[184:185]
	v_pk_mul_f32 v[166:167], v[166:167], v[184:185]
	v_pk_mul_f32 v[168:169], v[168:169], v[184:185]
	v_pk_mul_f32 v[170:171], v[170:171], v[184:185]
	v_pk_mul_f32 v[172:173], v[172:173], v[184:185]
	v_pk_mul_f32 v[174:175], v[174:175], v[184:185]
	v_pk_fma_f32 v[144:145], v[160:161], v[128:129], v[144:145]
	v_pk_fma_f32 v[146:147], v[162:163], v[130:131], v[146:147]
	v_pk_fma_f32 v[148:149], v[164:165], v[132:133], v[148:149]
	v_pk_fma_f32 v[150:151], v[166:167], v[134:135], v[150:151]
	v_pk_fma_f32 v[152:153], v[168:169], v[136:137], v[152:153]
	v_pk_fma_f32 v[154:155], v[170:171], v[138:139], v[154:155]
	v_pk_fma_f32 v[156:157], v[172:173], v[140:141], v[156:157]
	v_pk_fma_f32 v[158:159], v[174:175], v[142:143], v[158:159]
	v_pk_mul_f32 v[252:253], v[144:145], v[144:145]
	v_pk_mul_f32 v[254:255], v[146:147], v[146:147]
	v_pk_fma_f32 v[252:253], v[148:149], v[148:149], v[252:253]
	v_pk_fma_f32 v[254:255], v[150:151], v[150:151], v[254:255]
	v_pk_fma_f32 v[252:253], v[152:153], v[152:153], v[252:253]
	v_pk_fma_f32 v[254:255], v[154:155], v[154:155], v[254:255]
	v_pk_fma_f32 v[252:253], v[156:157], v[156:157], v[252:253]
	v_pk_fma_f32 v[254:255], v[158:159], v[158:159], v[254:255]
	v_pk_add_f32 v[252:253], v[252:253], v[254:255]
	s_nop 0
	v_add_f32_e32 v183, v252, v253
	s_nop 1
	v_add_f32_dpp v183, v183, v183 quad_perm:[1,0,3,2] row_mask:0xf bank_mask:0xf bound_ctrl:1
	s_nop 1
	v_add_f32_dpp v183, v183, v183 quad_perm:[2,3,0,1] row_mask:0xf bank_mask:0xf bound_ctrl:1
	s_nop 1
	v_add_f32_dpp v183, v183, v183 row_half_mirror row_mask:0xf bank_mask:0xf bound_ctrl:1
	s_nop 1
	v_add_f32_dpp v183, v183, v183 row_mirror row_mask:0xf bank_mask:0xf bound_ctrl:1
	s_nop 1
	v_readlane_b32 s98, v183, 0
	v_readlane_b32 s99, v183, 16
	v_readlane_b32 s100, v183, 32
	v_readlane_b32 s101, v183, 48
	s_nop 1
	v_mov_b32_e32 v183, s98
	v_add_f32_e32 v183, s99, v183
	v_add_f32_e32 v183, s100, v183
	v_add_f32_e32 v183, s101, v183
	v_fmamk_f32 v183, v183, 0x3a800000, v182
	v_cmp_gt_f32_e32 vcc, 0x800000, v183
	v_mul_f32_e32 v181, 0x4b800000, v183
	s_nop 1
	v_cndmask_b32_e32 v183, v183, v181, vcc
	v_rsq_f32_e32 v183, v183
	s_nop 0
	v_mul_f32_e32 v181, 0x45800000, v183
	v_cndmask_b32_e32 v184, v183, v181, vcc
	v_mov_b32_e32 v185, v184
	v_cvt_pk_bf16_f32 v16, v144, v145
	v_cvt_pk_bf16_f32 v17, v146, v147
	v_cvt_pk_bf16_f32 v18, v148, v149
	v_cvt_pk_bf16_f32 v19, v150, v151
	v_cvt_pk_bf16_f32 v20, v152, v153
	v_cvt_pk_bf16_f32 v21, v154, v155
	v_cvt_pk_bf16_f32 v22, v156, v157
	v_cvt_pk_bf16_f32 v23, v158, v159
	v_add_u32_e32 v181, 0x1c00000, v177
	global_store_dwordx4 v181, v[16:19], s[78:79]
	global_store_dwordx4 v181, v[20:23], s[78:79] offset:1024
	v_add_u32_e32 v236, 0x2000, v237
	s_mov_b64 exec, 1
	global_store_dword v236, v184, s[78:79]
	s_mov_b64 exec, -1
	s_waitcnt vmcnt(20)
	v_lshlrev_b32_e32 v144, 16, v32
	v_and_b32_e32 v145, 0xffff0000, v32
	v_lshlrev_b32_e32 v146, 16, v33
	v_and_b32_e32 v147, 0xffff0000, v33
	v_lshlrev_b32_e32 v148, 16, v34
	v_and_b32_e32 v149, 0xffff0000, v34
	v_lshlrev_b32_e32 v150, 16, v35
	v_and_b32_e32 v151, 0xffff0000, v35
	v_lshlrev_b32_e32 v152, 16, v36
	v_and_b32_e32 v153, 0xffff0000, v36
	v_lshlrev_b32_e32 v154, 16, v37
	v_and_b32_e32 v155, 0xffff0000, v37
	v_lshlrev_b32_e32 v156, 16, v38
	v_and_b32_e32 v157, 0xffff0000, v38
	v_lshlrev_b32_e32 v158, 16, v39
	v_and_b32_e32 v159, 0xffff0000, v39
	v_lshlrev_b32_e32 v160, 16, v40
	v_and_b32_e32 v161, 0xffff0000, v40
	v_lshlrev_b32_e32 v162, 16, v41
	v_and_b32_e32 v163, 0xffff0000, v41
	v_lshlrev_b32_e32 v164, 16, v42
	v_and_b32_e32 v165, 0xffff0000, v42
	v_lshlrev_b32_e32 v166, 16, v43
	v_and_b32_e32 v167, 0xffff0000, v43
	v_lshlrev_b32_e32 v168, 16, v44
	v_and_b32_e32 v169, 0xffff0000, v44
	v_lshlrev_b32_e32 v170, 16, v45
	v_and_b32_e32 v171, 0xffff0000, v45
	v_lshlrev_b32_e32 v172, 16, v46
	v_and_b32_e32 v173, 0xffff0000, v46
	v_lshlrev_b32_e32 v174, 16, v47
	v_and_b32_e32 v175, 0xffff0000, v47
	v_pk_mul_f32 v[252:253], v[160:161], v[160:161]
	v_pk_mul_f32 v[254:255], v[162:163], v[162:163]
	v_pk_fma_f32 v[252:253], v[164:165], v[164:165], v[252:253]
	v_pk_fma_f32 v[254:255], v[166:167], v[166:167], v[254:255]
	v_pk_fma_f32 v[252:253], v[168:169], v[168:169], v[252:253]
	v_pk_fma_f32 v[254:255], v[170:171], v[170:171], v[254:255]
	v_pk_fma_f32 v[252:253], v[172:173], v[172:173], v[252:253]
	v_pk_fma_f32 v[254:255], v[174:175], v[174:175], v[254:255]
	v_pk_add_f32 v[252:253], v[252:253], v[254:255]
	s_nop 0
	v_add_f32_e32 v183, v252, v253
	s_nop 1
	v_add_f32_dpp v183, v183, v183 quad_perm:[1,0,3,2] row_mask:0xf bank_mask:0xf bound_ctrl:1
	s_nop 1
	v_add_f32_dpp v183, v183, v183 quad_perm:[2,3,0,1] row_mask:0xf bank_mask:0xf bound_ctrl:1
	s_nop 1
	v_add_f32_dpp v183, v183, v183 row_half_mirror row_mask:0xf bank_mask:0xf bound_ctrl:1
	s_nop 1
	v_add_f32_dpp v183, v183, v183 row_mirror row_mask:0xf bank_mask:0xf bound_ctrl:1
	s_nop 1
	v_readlane_b32 s98, v183, 0
	v_readlane_b32 s99, v183, 16
	v_readlane_b32 s100, v183, 32
	v_readlane_b32 s101, v183, 48
	s_nop 1
	v_mov_b32_e32 v183, s98
	v_add_f32_e32 v183, s99, v183
	v_add_f32_e32 v183, s100, v183
	v_add_f32_e32 v183, s101, v183
	v_fmamk_f32 v183, v183, 0x3a800000, v182
	v_cmp_gt_f32_e32 vcc, 0x800000, v183
	v_mul_f32_e32 v181, 0x4b800000, v183
	s_nop 1
	v_cndmask_b32_e32 v183, v183, v181, vcc
	v_rsq_f32_e32 v183, v183
	s_nop 0
	v_mul_f32_e32 v181, 0x45800000, v183
	v_cndmask_b32_e32 v184, v183, v181, vcc
	v_mov_b32_e32 v185, v184
	v_pk_mul_f32 v[160:161], v[160:161], v[184:185]
	v_pk_mul_f32 v[162:163], v[162:163], v[184:185]
	v_pk_mul_f32 v[164:165], v[164:165], v[184:185]
	v_pk_mul_f32 v[166:167], v[166:167], v[184:185]
	v_pk_mul_f32 v[168:169], v[168:169], v[184:185]
	v_pk_mul_f32 v[170:171], v[170:171], v[184:185]
	v_pk_mul_f32 v[172:173], v[172:173], v[184:185]
	v_pk_mul_f32 v[174:175], v[174:175], v[184:185]
	v_pk_fma_f32 v[144:145], v[160:161], v[128:129], v[144:145]
	v_pk_fma_f32 v[146:147], v[162:163], v[130:131], v[146:147]
	v_pk_fma_f32 v[148:149], v[164:165], v[132:133], v[148:149]
	v_pk_fma_f32 v[150:151], v[166:167], v[134:135], v[150:151]
	v_pk_fma_f32 v[152:153], v[168:169], v[136:137], v[152:153]
	v_pk_fma_f32 v[154:155], v[170:171], v[138:139], v[154:155]
	v_pk_fma_f32 v[156:157], v[172:173], v[140:141], v[156:157]
	v_pk_fma_f32 v[158:159], v[174:175], v[142:143], v[158:159]
	v_pk_mul_f32 v[252:253], v[144:145], v[144:145]
	v_pk_mul_f32 v[254:255], v[146:147], v[146:147]
	v_pk_fma_f32 v[252:253], v[148:149], v[148:149], v[252:253]
	v_pk_fma_f32 v[254:255], v[150:151], v[150:151], v[254:255]
	v_pk_fma_f32 v[252:253], v[152:153], v[152:153], v[252:253]
	v_pk_fma_f32 v[254:255], v[154:155], v[154:155], v[254:255]
	v_pk_fma_f32 v[252:253], v[156:157], v[156:157], v[252:253]
	v_pk_fma_f32 v[254:255], v[158:159], v[158:159], v[254:255]
	v_pk_add_f32 v[252:253], v[252:253], v[254:255]
	s_nop 0
	v_add_f32_e32 v183, v252, v253
	s_nop 1
	v_add_f32_dpp v183, v183, v183 quad_perm:[1,0,3,2] row_mask:0xf bank_mask:0xf bound_ctrl:1
	s_nop 1
	v_add_f32_dpp v183, v183, v183 quad_perm:[2,3,0,1] row_mask:0xf bank_mask:0xf bound_ctrl:1
	s_nop 1
	v_add_f32_dpp v183, v183, v183 row_half_mirror row_mask:0xf bank_mask:0xf bound_ctrl:1
	s_nop 1
	v_add_f32_dpp v183, v183, v183 row_mirror row_mask:0xf bank_mask:0xf bound_ctrl:1
	s_nop 1
	v_readlane_b32 s98, v183, 0
	v_readlane_b32 s99, v183, 16
	v_readlane_b32 s100, v183, 32
	v_readlane_b32 s101, v183, 48
	s_nop 1
	v_mov_b32_e32 v183, s98
	v_add_f32_e32 v183, s99, v183
	v_add_f32_e32 v183, s100, v183
	v_add_f32_e32 v183, s101, v183
	v_fmamk_f32 v183, v183, 0x3a800000, v182
	v_cmp_gt_f32_e32 vcc, 0x800000, v183
	v_mul_f32_e32 v181, 0x4b800000, v183
	s_nop 1
	v_cndmask_b32_e32 v183, v183, v181, vcc
	v_rsq_f32_e32 v183, v183
	s_nop 0
	v_mul_f32_e32 v181, 0x45800000, v183
	v_cndmask_b32_e32 v184, v183, v181, vcc
	v_mov_b32_e32 v185, v184
	v_cvt_pk_bf16_f32 v32, v144, v145
	v_cvt_pk_bf16_f32 v33, v146, v147
	v_cvt_pk_bf16_f32 v34, v148, v149
	v_cvt_pk_bf16_f32 v35, v150, v151
	v_cvt_pk_bf16_f32 v36, v152, v153
	v_cvt_pk_bf16_f32 v37, v154, v155
	v_cvt_pk_bf16_f32 v38, v156, v157
	v_cvt_pk_bf16_f32 v39, v158, v159
	v_add_u32_e32 v181, 0x2000000, v177
	global_store_dwordx4 v181, v[32:35], s[78:79]
	global_store_dwordx4 v181, v[36:39], s[78:79] offset:1024
	v_add_u32_e32 v236, 0x4000, v237
	s_mov_b64 exec, 1
	global_store_dword v236, v184, s[78:79]
	s_mov_b64 exec, -1
	s_waitcnt vmcnt(16)
	v_lshlrev_b32_e32 v144, 16, v48
	v_and_b32_e32 v145, 0xffff0000, v48
	v_lshlrev_b32_e32 v146, 16, v49
	v_and_b32_e32 v147, 0xffff0000, v49
	v_lshlrev_b32_e32 v148, 16, v50
	v_and_b32_e32 v149, 0xffff0000, v50
	v_lshlrev_b32_e32 v150, 16, v51
	v_and_b32_e32 v151, 0xffff0000, v51
	v_lshlrev_b32_e32 v152, 16, v52
	v_and_b32_e32 v153, 0xffff0000, v52
	v_lshlrev_b32_e32 v154, 16, v53
	v_and_b32_e32 v155, 0xffff0000, v53
	v_lshlrev_b32_e32 v156, 16, v54
	v_and_b32_e32 v157, 0xffff0000, v54
	v_lshlrev_b32_e32 v158, 16, v55
	v_and_b32_e32 v159, 0xffff0000, v55
	v_lshlrev_b32_e32 v160, 16, v56
	v_and_b32_e32 v161, 0xffff0000, v56
	v_lshlrev_b32_e32 v162, 16, v57
	v_and_b32_e32 v163, 0xffff0000, v57
	v_lshlrev_b32_e32 v164, 16, v58
	v_and_b32_e32 v165, 0xffff0000, v58
	v_lshlrev_b32_e32 v166, 16, v59
	v_and_b32_e32 v167, 0xffff0000, v59
	v_lshlrev_b32_e32 v168, 16, v60
	v_and_b32_e32 v169, 0xffff0000, v60
	v_lshlrev_b32_e32 v170, 16, v61
	v_and_b32_e32 v171, 0xffff0000, v61
	v_lshlrev_b32_e32 v172, 16, v62
	v_and_b32_e32 v173, 0xffff0000, v62
	v_lshlrev_b32_e32 v174, 16, v63
	v_and_b32_e32 v175, 0xffff0000, v63
	v_pk_mul_f32 v[252:253], v[160:161], v[160:161]
	v_pk_mul_f32 v[254:255], v[162:163], v[162:163]
	v_pk_fma_f32 v[252:253], v[164:165], v[164:165], v[252:253]
	v_pk_fma_f32 v[254:255], v[166:167], v[166:167], v[254:255]
	v_pk_fma_f32 v[252:253], v[168:169], v[168:169], v[252:253]
	v_pk_fma_f32 v[254:255], v[170:171], v[170:171], v[254:255]
	v_pk_fma_f32 v[252:253], v[172:173], v[172:173], v[252:253]
	v_pk_fma_f32 v[254:255], v[174:175], v[174:175], v[254:255]
	v_pk_add_f32 v[252:253], v[252:253], v[254:255]
	s_nop 0
	v_add_f32_e32 v183, v252, v253
	s_nop 1
	v_add_f32_dpp v183, v183, v183 quad_perm:[1,0,3,2] row_mask:0xf bank_mask:0xf bound_ctrl:1
	s_nop 1
	v_add_f32_dpp v183, v183, v183 quad_perm:[2,3,0,1] row_mask:0xf bank_mask:0xf bound_ctrl:1
	s_nop 1
	v_add_f32_dpp v183, v183, v183 row_half_mirror row_mask:0xf bank_mask:0xf bound_ctrl:1
	s_nop 1
	v_add_f32_dpp v183, v183, v183 row_mirror row_mask:0xf bank_mask:0xf bound_ctrl:1
	s_nop 1
	v_readlane_b32 s98, v183, 0
	v_readlane_b32 s99, v183, 16
	v_readlane_b32 s100, v183, 32
	v_readlane_b32 s101, v183, 48
	s_nop 1
	v_mov_b32_e32 v183, s98
	v_add_f32_e32 v183, s99, v183
	v_add_f32_e32 v183, s100, v183
	v_add_f32_e32 v183, s101, v183
	v_fmamk_f32 v183, v183, 0x3a800000, v182
	v_cmp_gt_f32_e32 vcc, 0x800000, v183
	v_mul_f32_e32 v181, 0x4b800000, v183
	s_nop 1
	v_cndmask_b32_e32 v183, v183, v181, vcc
	v_rsq_f32_e32 v183, v183
	s_nop 0
	v_mul_f32_e32 v181, 0x45800000, v183
	v_cndmask_b32_e32 v184, v183, v181, vcc
	v_mov_b32_e32 v185, v184
	v_pk_mul_f32 v[160:161], v[160:161], v[184:185]
	v_pk_mul_f32 v[162:163], v[162:163], v[184:185]
	v_pk_mul_f32 v[164:165], v[164:165], v[184:185]
	v_pk_mul_f32 v[166:167], v[166:167], v[184:185]
	v_pk_mul_f32 v[168:169], v[168:169], v[184:185]
	v_pk_mul_f32 v[170:171], v[170:171], v[184:185]
	v_pk_mul_f32 v[172:173], v[172:173], v[184:185]
	v_pk_mul_f32 v[174:175], v[174:175], v[184:185]
	v_pk_fma_f32 v[144:145], v[160:161], v[128:129], v[144:145]
	v_pk_fma_f32 v[146:147], v[162:163], v[130:131], v[146:147]
	v_pk_fma_f32 v[148:149], v[164:165], v[132:133], v[148:149]
	v_pk_fma_f32 v[150:151], v[166:167], v[134:135], v[150:151]
	v_pk_fma_f32 v[152:153], v[168:169], v[136:137], v[152:153]
	v_pk_fma_f32 v[154:155], v[170:171], v[138:139], v[154:155]
	v_pk_fma_f32 v[156:157], v[172:173], v[140:141], v[156:157]
	v_pk_fma_f32 v[158:159], v[174:175], v[142:143], v[158:159]
	v_pk_mul_f32 v[252:253], v[144:145], v[144:145]
	v_pk_mul_f32 v[254:255], v[146:147], v[146:147]
	v_pk_fma_f32 v[252:253], v[148:149], v[148:149], v[252:253]
	v_pk_fma_f32 v[254:255], v[150:151], v[150:151], v[254:255]
	v_pk_fma_f32 v[252:253], v[152:153], v[152:153], v[252:253]
	v_pk_fma_f32 v[254:255], v[154:155], v[154:155], v[254:255]
	v_pk_fma_f32 v[252:253], v[156:157], v[156:157], v[252:253]
	v_pk_fma_f32 v[254:255], v[158:159], v[158:159], v[254:255]
	v_pk_add_f32 v[252:253], v[252:253], v[254:255]
	s_nop 0
	v_add_f32_e32 v183, v252, v253
	s_nop 1
	v_add_f32_dpp v183, v183, v183 quad_perm:[1,0,3,2] row_mask:0xf bank_mask:0xf bound_ctrl:1
	s_nop 1
	v_add_f32_dpp v183, v183, v183 quad_perm:[2,3,0,1] row_mask:0xf bank_mask:0xf bound_ctrl:1
	s_nop 1
	v_add_f32_dpp v183, v183, v183 row_half_mirror row_mask:0xf bank_mask:0xf bound_ctrl:1
	s_nop 1
	v_add_f32_dpp v183, v183, v183 row_mirror row_mask:0xf bank_mask:0xf bound_ctrl:1
	s_nop 1
	v_readlane_b32 s98, v183, 0
	v_readlane_b32 s99, v183, 16
	v_readlane_b32 s100, v183, 32
	v_readlane_b32 s101, v183, 48
	s_nop 1
	v_mov_b32_e32 v183, s98
	v_add_f32_e32 v183, s99, v183
	v_add_f32_e32 v183, s100, v183
	v_add_f32_e32 v183, s101, v183
	v_fmamk_f32 v183, v183, 0x3a800000, v182
	v_cmp_gt_f32_e32 vcc, 0x800000, v183
	v_mul_f32_e32 v181, 0x4b800000, v183
	s_nop 1
	v_cndmask_b32_e32 v183, v183, v181, vcc
	v_rsq_f32_e32 v183, v183
	s_nop 0
	v_mul_f32_e32 v181, 0x45800000, v183
	v_cndmask_b32_e32 v184, v183, v181, vcc
	v_mov_b32_e32 v185, v184
	v_cvt_pk_bf16_f32 v48, v144, v145
	v_cvt_pk_bf16_f32 v49, v146, v147
	v_cvt_pk_bf16_f32 v50, v148, v149
	v_cvt_pk_bf16_f32 v51, v150, v151
	v_cvt_pk_bf16_f32 v52, v152, v153
	v_cvt_pk_bf16_f32 v53, v154, v155
	v_cvt_pk_bf16_f32 v54, v156, v157
	v_cvt_pk_bf16_f32 v55, v158, v159
	v_add_u32_e32 v181, 0x2400000, v177
	global_store_dwordx4 v181, v[48:51], s[78:79]
	global_store_dwordx4 v181, v[52:55], s[78:79] offset:1024
	v_add_u32_e32 v236, 0x6000, v237
	s_mov_b64 exec, 1
	global_store_dword v236, v184, s[78:79]
	s_mov_b64 exec, -1
	s_waitcnt vmcnt(12)
	v_lshlrev_b32_e32 v144, 16, v64
	v_and_b32_e32 v145, 0xffff0000, v64
	v_lshlrev_b32_e32 v146, 16, v65
	v_and_b32_e32 v147, 0xffff0000, v65
	v_lshlrev_b32_e32 v148, 16, v66
	v_and_b32_e32 v149, 0xffff0000, v66
	v_lshlrev_b32_e32 v150, 16, v67
	v_and_b32_e32 v151, 0xffff0000, v67
	v_lshlrev_b32_e32 v152, 16, v68
	v_and_b32_e32 v153, 0xffff0000, v68
	v_lshlrev_b32_e32 v154, 16, v69
	v_and_b32_e32 v155, 0xffff0000, v69
	v_lshlrev_b32_e32 v156, 16, v70
	v_and_b32_e32 v157, 0xffff0000, v70
	v_lshlrev_b32_e32 v158, 16, v71
	v_and_b32_e32 v159, 0xffff0000, v71
	v_lshlrev_b32_e32 v160, 16, v72
	v_and_b32_e32 v161, 0xffff0000, v72
	v_lshlrev_b32_e32 v162, 16, v73
	v_and_b32_e32 v163, 0xffff0000, v73
	v_lshlrev_b32_e32 v164, 16, v74
	v_and_b32_e32 v165, 0xffff0000, v74
	v_lshlrev_b32_e32 v166, 16, v75
	v_and_b32_e32 v167, 0xffff0000, v75
	v_lshlrev_b32_e32 v168, 16, v76
	v_and_b32_e32 v169, 0xffff0000, v76
	v_lshlrev_b32_e32 v170, 16, v77
	v_and_b32_e32 v171, 0xffff0000, v77
	v_lshlrev_b32_e32 v172, 16, v78
	v_and_b32_e32 v173, 0xffff0000, v78
	v_lshlrev_b32_e32 v174, 16, v79
	v_and_b32_e32 v175, 0xffff0000, v79
	v_pk_mul_f32 v[252:253], v[160:161], v[160:161]
	v_pk_mul_f32 v[254:255], v[162:163], v[162:163]
	v_pk_fma_f32 v[252:253], v[164:165], v[164:165], v[252:253]
	v_pk_fma_f32 v[254:255], v[166:167], v[166:167], v[254:255]
	v_pk_fma_f32 v[252:253], v[168:169], v[168:169], v[252:253]
	v_pk_fma_f32 v[254:255], v[170:171], v[170:171], v[254:255]
	v_pk_fma_f32 v[252:253], v[172:173], v[172:173], v[252:253]
	v_pk_fma_f32 v[254:255], v[174:175], v[174:175], v[254:255]
	v_pk_add_f32 v[252:253], v[252:253], v[254:255]
	s_nop 0
	v_add_f32_e32 v183, v252, v253
	s_nop 1
	v_add_f32_dpp v183, v183, v183 quad_perm:[1,0,3,2] row_mask:0xf bank_mask:0xf bound_ctrl:1
	s_nop 1
	v_add_f32_dpp v183, v183, v183 quad_perm:[2,3,0,1] row_mask:0xf bank_mask:0xf bound_ctrl:1
	s_nop 1
	v_add_f32_dpp v183, v183, v183 row_half_mirror row_mask:0xf bank_mask:0xf bound_ctrl:1
	s_nop 1
	v_add_f32_dpp v183, v183, v183 row_mirror row_mask:0xf bank_mask:0xf bound_ctrl:1
	s_nop 1
	v_readlane_b32 s98, v183, 0
	v_readlane_b32 s99, v183, 16
	v_readlane_b32 s100, v183, 32
	v_readlane_b32 s101, v183, 48
	s_nop 1
	v_mov_b32_e32 v183, s98
	v_add_f32_e32 v183, s99, v183
	v_add_f32_e32 v183, s100, v183
	v_add_f32_e32 v183, s101, v183
	v_fmamk_f32 v183, v183, 0x3a800000, v182
	v_cmp_gt_f32_e32 vcc, 0x800000, v183
	v_mul_f32_e32 v181, 0x4b800000, v183
	s_nop 1
	v_cndmask_b32_e32 v183, v183, v181, vcc
	v_rsq_f32_e32 v183, v183
	s_nop 0
	v_mul_f32_e32 v181, 0x45800000, v183
	v_cndmask_b32_e32 v184, v183, v181, vcc
	v_mov_b32_e32 v185, v184
	v_pk_mul_f32 v[160:161], v[160:161], v[184:185]
	v_pk_mul_f32 v[162:163], v[162:163], v[184:185]
	v_pk_mul_f32 v[164:165], v[164:165], v[184:185]
	v_pk_mul_f32 v[166:167], v[166:167], v[184:185]
	v_pk_mul_f32 v[168:169], v[168:169], v[184:185]
	v_pk_mul_f32 v[170:171], v[170:171], v[184:185]
	v_pk_mul_f32 v[172:173], v[172:173], v[184:185]
	v_pk_mul_f32 v[174:175], v[174:175], v[184:185]
	v_pk_fma_f32 v[144:145], v[160:161], v[128:129], v[144:145]
	v_pk_fma_f32 v[146:147], v[162:163], v[130:131], v[146:147]
	v_pk_fma_f32 v[148:149], v[164:165], v[132:133], v[148:149]
	v_pk_fma_f32 v[150:151], v[166:167], v[134:135], v[150:151]
	v_pk_fma_f32 v[152:153], v[168:169], v[136:137], v[152:153]
	v_pk_fma_f32 v[154:155], v[170:171], v[138:139], v[154:155]
	v_pk_fma_f32 v[156:157], v[172:173], v[140:141], v[156:157]
	v_pk_fma_f32 v[158:159], v[174:175], v[142:143], v[158:159]
	v_pk_mul_f32 v[252:253], v[144:145], v[144:145]
	v_pk_mul_f32 v[254:255], v[146:147], v[146:147]
	v_pk_fma_f32 v[252:253], v[148:149], v[148:149], v[252:253]
	v_pk_fma_f32 v[254:255], v[150:151], v[150:151], v[254:255]
	v_pk_fma_f32 v[252:253], v[152:153], v[152:153], v[252:253]
	v_pk_fma_f32 v[254:255], v[154:155], v[154:155], v[254:255]
	v_pk_fma_f32 v[252:253], v[156:157], v[156:157], v[252:253]
	v_pk_fma_f32 v[254:255], v[158:159], v[158:159], v[254:255]
	v_pk_add_f32 v[252:253], v[252:253], v[254:255]
	s_nop 0
	v_add_f32_e32 v183, v252, v253
	s_nop 1
	v_add_f32_dpp v183, v183, v183 quad_perm:[1,0,3,2] row_mask:0xf bank_mask:0xf bound_ctrl:1
	s_nop 1
	v_add_f32_dpp v183, v183, v183 quad_perm:[2,3,0,1] row_mask:0xf bank_mask:0xf bound_ctrl:1
	s_nop 1
	v_add_f32_dpp v183, v183, v183 row_half_mirror row_mask:0xf bank_mask:0xf bound_ctrl:1
	s_nop 1
	v_add_f32_dpp v183, v183, v183 row_mirror row_mask:0xf bank_mask:0xf bound_ctrl:1
	s_nop 1
	v_readlane_b32 s98, v183, 0
	v_readlane_b32 s99, v183, 16
	v_readlane_b32 s100, v183, 32
	v_readlane_b32 s101, v183, 48
	s_nop 1
	v_mov_b32_e32 v183, s98
	v_add_f32_e32 v183, s99, v183
	v_add_f32_e32 v183, s100, v183
	v_add_f32_e32 v183, s101, v183
	v_fmamk_f32 v183, v183, 0x3a800000, v182
	v_cmp_gt_f32_e32 vcc, 0x800000, v183
	v_mul_f32_e32 v181, 0x4b800000, v183
	s_nop 1
	v_cndmask_b32_e32 v183, v183, v181, vcc
	v_rsq_f32_e32 v183, v183
	s_nop 0
	v_mul_f32_e32 v181, 0x45800000, v183
	v_cndmask_b32_e32 v184, v183, v181, vcc
	v_mov_b32_e32 v185, v184
	v_cvt_pk_bf16_f32 v64, v144, v145
	v_cvt_pk_bf16_f32 v65, v146, v147
	v_cvt_pk_bf16_f32 v66, v148, v149
	v_cvt_pk_bf16_f32 v67, v150, v151
	v_cvt_pk_bf16_f32 v68, v152, v153
	v_cvt_pk_bf16_f32 v69, v154, v155
	v_cvt_pk_bf16_f32 v70, v156, v157
	v_cvt_pk_bf16_f32 v71, v158, v159
	v_add_u32_e32 v181, 0x2800000, v177
	global_store_dwordx4 v181, v[64:67], s[78:79]
	global_store_dwordx4 v181, v[68:71], s[78:79] offset:1024
	v_add_u32_e32 v236, 0x8000, v237
	s_mov_b64 exec, 1
	global_store_dword v236, v184, s[78:79]
	s_mov_b64 exec, -1
	s_waitcnt vmcnt(8)
	v_lshlrev_b32_e32 v144, 16, v80
	v_and_b32_e32 v145, 0xffff0000, v80
	v_lshlrev_b32_e32 v146, 16, v81
	v_and_b32_e32 v147, 0xffff0000, v81
	v_lshlrev_b32_e32 v148, 16, v82
	v_and_b32_e32 v149, 0xffff0000, v82
	v_lshlrev_b32_e32 v150, 16, v83
	v_and_b32_e32 v151, 0xffff0000, v83
	v_lshlrev_b32_e32 v152, 16, v84
	v_and_b32_e32 v153, 0xffff0000, v84
	v_lshlrev_b32_e32 v154, 16, v85
	v_and_b32_e32 v155, 0xffff0000, v85
	v_lshlrev_b32_e32 v156, 16, v86
	v_and_b32_e32 v157, 0xffff0000, v86
	v_lshlrev_b32_e32 v158, 16, v87
	v_and_b32_e32 v159, 0xffff0000, v87
	v_lshlrev_b32_e32 v160, 16, v88
	v_and_b32_e32 v161, 0xffff0000, v88
	v_lshlrev_b32_e32 v162, 16, v89
	v_and_b32_e32 v163, 0xffff0000, v89
	v_lshlrev_b32_e32 v164, 16, v90
	v_and_b32_e32 v165, 0xffff0000, v90
	v_lshlrev_b32_e32 v166, 16, v91
	v_and_b32_e32 v167, 0xffff0000, v91
	v_lshlrev_b32_e32 v168, 16, v92
	v_and_b32_e32 v169, 0xffff0000, v92
	v_lshlrev_b32_e32 v170, 16, v93
	v_and_b32_e32 v171, 0xffff0000, v93
	v_lshlrev_b32_e32 v172, 16, v94
	v_and_b32_e32 v173, 0xffff0000, v94
	v_lshlrev_b32_e32 v174, 16, v95
	v_and_b32_e32 v175, 0xffff0000, v95
	v_pk_mul_f32 v[252:253], v[160:161], v[160:161]
	v_pk_mul_f32 v[254:255], v[162:163], v[162:163]
	v_pk_fma_f32 v[252:253], v[164:165], v[164:165], v[252:253]
	v_pk_fma_f32 v[254:255], v[166:167], v[166:167], v[254:255]
	v_pk_fma_f32 v[252:253], v[168:169], v[168:169], v[252:253]
	v_pk_fma_f32 v[254:255], v[170:171], v[170:171], v[254:255]
	v_pk_fma_f32 v[252:253], v[172:173], v[172:173], v[252:253]
	v_pk_fma_f32 v[254:255], v[174:175], v[174:175], v[254:255]
	v_pk_add_f32 v[252:253], v[252:253], v[254:255]
	s_nop 0
	v_add_f32_e32 v183, v252, v253
	s_nop 1
	v_add_f32_dpp v183, v183, v183 quad_perm:[1,0,3,2] row_mask:0xf bank_mask:0xf bound_ctrl:1
	s_nop 1
	v_add_f32_dpp v183, v183, v183 quad_perm:[2,3,0,1] row_mask:0xf bank_mask:0xf bound_ctrl:1
	s_nop 1
	v_add_f32_dpp v183, v183, v183 row_half_mirror row_mask:0xf bank_mask:0xf bound_ctrl:1
	s_nop 1
	v_add_f32_dpp v183, v183, v183 row_mirror row_mask:0xf bank_mask:0xf bound_ctrl:1
	s_nop 1
	v_readlane_b32 s98, v183, 0
	v_readlane_b32 s99, v183, 16
	v_readlane_b32 s100, v183, 32
	v_readlane_b32 s101, v183, 48
	s_nop 1
	v_mov_b32_e32 v183, s98
	v_add_f32_e32 v183, s99, v183
	v_add_f32_e32 v183, s100, v183
	v_add_f32_e32 v183, s101, v183
	v_fmamk_f32 v183, v183, 0x3a800000, v182
	v_cmp_gt_f32_e32 vcc, 0x800000, v183
	v_mul_f32_e32 v181, 0x4b800000, v183
	s_nop 1
	v_cndmask_b32_e32 v183, v183, v181, vcc
	v_rsq_f32_e32 v183, v183
	s_nop 0
	v_mul_f32_e32 v181, 0x45800000, v183
	v_cndmask_b32_e32 v184, v183, v181, vcc
	v_mov_b32_e32 v185, v184
	v_pk_mul_f32 v[160:161], v[160:161], v[184:185]
	v_pk_mul_f32 v[162:163], v[162:163], v[184:185]
	v_pk_mul_f32 v[164:165], v[164:165], v[184:185]
	v_pk_mul_f32 v[166:167], v[166:167], v[184:185]
	v_pk_mul_f32 v[168:169], v[168:169], v[184:185]
	v_pk_mul_f32 v[170:171], v[170:171], v[184:185]
	v_pk_mul_f32 v[172:173], v[172:173], v[184:185]
	v_pk_mul_f32 v[174:175], v[174:175], v[184:185]
	v_pk_fma_f32 v[144:145], v[160:161], v[128:129], v[144:145]
	v_pk_fma_f32 v[146:147], v[162:163], v[130:131], v[146:147]
	v_pk_fma_f32 v[148:149], v[164:165], v[132:133], v[148:149]
	v_pk_fma_f32 v[150:151], v[166:167], v[134:135], v[150:151]
	v_pk_fma_f32 v[152:153], v[168:169], v[136:137], v[152:153]
	v_pk_fma_f32 v[154:155], v[170:171], v[138:139], v[154:155]
	v_pk_fma_f32 v[156:157], v[172:173], v[140:141], v[156:157]
	v_pk_fma_f32 v[158:159], v[174:175], v[142:143], v[158:159]
	v_pk_mul_f32 v[252:253], v[144:145], v[144:145]
	v_pk_mul_f32 v[254:255], v[146:147], v[146:147]
	v_pk_fma_f32 v[252:253], v[148:149], v[148:149], v[252:253]
	v_pk_fma_f32 v[254:255], v[150:151], v[150:151], v[254:255]
	v_pk_fma_f32 v[252:253], v[152:153], v[152:153], v[252:253]
	v_pk_fma_f32 v[254:255], v[154:155], v[154:155], v[254:255]
	v_pk_fma_f32 v[252:253], v[156:157], v[156:157], v[252:253]
	v_pk_fma_f32 v[254:255], v[158:159], v[158:159], v[254:255]
	v_pk_add_f32 v[252:253], v[252:253], v[254:255]
	s_nop 0
	v_add_f32_e32 v183, v252, v253
	s_nop 1
	v_add_f32_dpp v183, v183, v183 quad_perm:[1,0,3,2] row_mask:0xf bank_mask:0xf bound_ctrl:1
	s_nop 1
	v_add_f32_dpp v183, v183, v183 quad_perm:[2,3,0,1] row_mask:0xf bank_mask:0xf bound_ctrl:1
	s_nop 1
	v_add_f32_dpp v183, v183, v183 row_half_mirror row_mask:0xf bank_mask:0xf bound_ctrl:1
	s_nop 1
	v_add_f32_dpp v183, v183, v183 row_mirror row_mask:0xf bank_mask:0xf bound_ctrl:1
	s_nop 1
	v_readlane_b32 s98, v183, 0
	v_readlane_b32 s99, v183, 16
	v_readlane_b32 s100, v183, 32
	v_readlane_b32 s101, v183, 48
	s_nop 1
	v_mov_b32_e32 v183, s98
	v_add_f32_e32 v183, s99, v183
	v_add_f32_e32 v183, s100, v183
	v_add_f32_e32 v183, s101, v183
	v_fmamk_f32 v183, v183, 0x3a800000, v182
	v_cmp_gt_f32_e32 vcc, 0x800000, v183
	v_mul_f32_e32 v181, 0x4b800000, v183
	s_nop 1
	v_cndmask_b32_e32 v183, v183, v181, vcc
	v_rsq_f32_e32 v183, v183
	s_nop 0
	v_mul_f32_e32 v181, 0x45800000, v183
	v_cndmask_b32_e32 v184, v183, v181, vcc
	v_mov_b32_e32 v185, v184
	v_cvt_pk_bf16_f32 v80, v144, v145
	v_cvt_pk_bf16_f32 v81, v146, v147
	v_cvt_pk_bf16_f32 v82, v148, v149
	v_cvt_pk_bf16_f32 v83, v150, v151
	v_cvt_pk_bf16_f32 v84, v152, v153
	v_cvt_pk_bf16_f32 v85, v154, v155
	v_cvt_pk_bf16_f32 v86, v156, v157
	v_cvt_pk_bf16_f32 v87, v158, v159
	v_add_u32_e32 v181, 0x2c00000, v177
	global_store_dwordx4 v181, v[80:83], s[78:79]
	global_store_dwordx4 v181, v[84:87], s[78:79] offset:1024
	v_add_u32_e32 v236, 0xa000, v237
	s_mov_b64 exec, 1
	global_store_dword v236, v184, s[78:79]
	s_mov_b64 exec, -1
	s_waitcnt vmcnt(4)
	v_lshlrev_b32_e32 v144, 16, v96
	v_and_b32_e32 v145, 0xffff0000, v96
	v_lshlrev_b32_e32 v146, 16, v97
	v_and_b32_e32 v147, 0xffff0000, v97
	v_lshlrev_b32_e32 v148, 16, v98
	v_and_b32_e32 v149, 0xffff0000, v98
	v_lshlrev_b32_e32 v150, 16, v99
	v_and_b32_e32 v151, 0xffff0000, v99
	v_lshlrev_b32_e32 v152, 16, v100
	v_and_b32_e32 v153, 0xffff0000, v100
	v_lshlrev_b32_e32 v154, 16, v101
	v_and_b32_e32 v155, 0xffff0000, v101
	v_lshlrev_b32_e32 v156, 16, v102
	v_and_b32_e32 v157, 0xffff0000, v102
	v_lshlrev_b32_e32 v158, 16, v103
	v_and_b32_e32 v159, 0xffff0000, v103
	v_lshlrev_b32_e32 v160, 16, v104
	v_and_b32_e32 v161, 0xffff0000, v104
	v_lshlrev_b32_e32 v162, 16, v105
	v_and_b32_e32 v163, 0xffff0000, v105
	v_lshlrev_b32_e32 v164, 16, v106
	v_and_b32_e32 v165, 0xffff0000, v106
	v_lshlrev_b32_e32 v166, 16, v107
	v_and_b32_e32 v167, 0xffff0000, v107
	v_lshlrev_b32_e32 v168, 16, v108
	v_and_b32_e32 v169, 0xffff0000, v108
	v_lshlrev_b32_e32 v170, 16, v109
	v_and_b32_e32 v171, 0xffff0000, v109
	v_lshlrev_b32_e32 v172, 16, v110
	v_and_b32_e32 v173, 0xffff0000, v110
	v_lshlrev_b32_e32 v174, 16, v111
	v_and_b32_e32 v175, 0xffff0000, v111
	v_pk_mul_f32 v[252:253], v[160:161], v[160:161]
	v_pk_mul_f32 v[254:255], v[162:163], v[162:163]
	v_pk_fma_f32 v[252:253], v[164:165], v[164:165], v[252:253]
	v_pk_fma_f32 v[254:255], v[166:167], v[166:167], v[254:255]
	v_pk_fma_f32 v[252:253], v[168:169], v[168:169], v[252:253]
	v_pk_fma_f32 v[254:255], v[170:171], v[170:171], v[254:255]
	v_pk_fma_f32 v[252:253], v[172:173], v[172:173], v[252:253]
	v_pk_fma_f32 v[254:255], v[174:175], v[174:175], v[254:255]
	v_pk_add_f32 v[252:253], v[252:253], v[254:255]
	s_nop 0
	v_add_f32_e32 v183, v252, v253
	s_nop 1
	v_add_f32_dpp v183, v183, v183 quad_perm:[1,0,3,2] row_mask:0xf bank_mask:0xf bound_ctrl:1
	s_nop 1
	v_add_f32_dpp v183, v183, v183 quad_perm:[2,3,0,1] row_mask:0xf bank_mask:0xf bound_ctrl:1
	s_nop 1
	v_add_f32_dpp v183, v183, v183 row_half_mirror row_mask:0xf bank_mask:0xf bound_ctrl:1
	s_nop 1
	v_add_f32_dpp v183, v183, v183 row_mirror row_mask:0xf bank_mask:0xf bound_ctrl:1
	s_nop 1
	v_readlane_b32 s98, v183, 0
	v_readlane_b32 s99, v183, 16
	v_readlane_b32 s100, v183, 32
	v_readlane_b32 s101, v183, 48
	s_nop 1
	v_mov_b32_e32 v183, s98
	v_add_f32_e32 v183, s99, v183
	v_add_f32_e32 v183, s100, v183
	v_add_f32_e32 v183, s101, v183
	v_fmamk_f32 v183, v183, 0x3a800000, v182
	v_cmp_gt_f32_e32 vcc, 0x800000, v183
	v_mul_f32_e32 v181, 0x4b800000, v183
	s_nop 1
	v_cndmask_b32_e32 v183, v183, v181, vcc
	v_rsq_f32_e32 v183, v183
	s_nop 0
	v_mul_f32_e32 v181, 0x45800000, v183
	v_cndmask_b32_e32 v184, v183, v181, vcc
	v_mov_b32_e32 v185, v184
	v_pk_mul_f32 v[160:161], v[160:161], v[184:185]
	v_pk_mul_f32 v[162:163], v[162:163], v[184:185]
	v_pk_mul_f32 v[164:165], v[164:165], v[184:185]
	v_pk_mul_f32 v[166:167], v[166:167], v[184:185]
	v_pk_mul_f32 v[168:169], v[168:169], v[184:185]
	v_pk_mul_f32 v[170:171], v[170:171], v[184:185]
	v_pk_mul_f32 v[172:173], v[172:173], v[184:185]
	v_pk_mul_f32 v[174:175], v[174:175], v[184:185]
	v_pk_fma_f32 v[144:145], v[160:161], v[128:129], v[144:145]
	v_pk_fma_f32 v[146:147], v[162:163], v[130:131], v[146:147]
	v_pk_fma_f32 v[148:149], v[164:165], v[132:133], v[148:149]
	v_pk_fma_f32 v[150:151], v[166:167], v[134:135], v[150:151]
	v_pk_fma_f32 v[152:153], v[168:169], v[136:137], v[152:153]
	v_pk_fma_f32 v[154:155], v[170:171], v[138:139], v[154:155]
	v_pk_fma_f32 v[156:157], v[172:173], v[140:141], v[156:157]
	v_pk_fma_f32 v[158:159], v[174:175], v[142:143], v[158:159]
	v_pk_mul_f32 v[252:253], v[144:145], v[144:145]
	v_pk_mul_f32 v[254:255], v[146:147], v[146:147]
	v_pk_fma_f32 v[252:253], v[148:149], v[148:149], v[252:253]
	v_pk_fma_f32 v[254:255], v[150:151], v[150:151], v[254:255]
	v_pk_fma_f32 v[252:253], v[152:153], v[152:153], v[252:253]
	v_pk_fma_f32 v[254:255], v[154:155], v[154:155], v[254:255]
	v_pk_fma_f32 v[252:253], v[156:157], v[156:157], v[252:253]
	v_pk_fma_f32 v[254:255], v[158:159], v[158:159], v[254:255]
	v_pk_add_f32 v[252:253], v[252:253], v[254:255]
	s_nop 0
	v_add_f32_e32 v183, v252, v253
	s_nop 1
	v_add_f32_dpp v183, v183, v183 quad_perm:[1,0,3,2] row_mask:0xf bank_mask:0xf bound_ctrl:1
	s_nop 1
	v_add_f32_dpp v183, v183, v183 quad_perm:[2,3,0,1] row_mask:0xf bank_mask:0xf bound_ctrl:1
	s_nop 1
	v_add_f32_dpp v183, v183, v183 row_half_mirror row_mask:0xf bank_mask:0xf bound_ctrl:1
	s_nop 1
	v_add_f32_dpp v183, v183, v183 row_mirror row_mask:0xf bank_mask:0xf bound_ctrl:1
	s_nop 1
	v_readlane_b32 s98, v183, 0
	v_readlane_b32 s99, v183, 16
	v_readlane_b32 s100, v183, 32
	v_readlane_b32 s101, v183, 48
	s_nop 1
	v_mov_b32_e32 v183, s98
	v_add_f32_e32 v183, s99, v183
	v_add_f32_e32 v183, s100, v183
	v_add_f32_e32 v183, s101, v183
	v_fmamk_f32 v183, v183, 0x3a800000, v182
	v_cmp_gt_f32_e32 vcc, 0x800000, v183
	v_mul_f32_e32 v181, 0x4b800000, v183
	s_nop 1
	v_cndmask_b32_e32 v183, v183, v181, vcc
	v_rsq_f32_e32 v183, v183
	s_nop 0
	v_mul_f32_e32 v181, 0x45800000, v183
	v_cndmask_b32_e32 v184, v183, v181, vcc
	v_mov_b32_e32 v185, v184
	v_cvt_pk_bf16_f32 v96, v144, v145
	v_cvt_pk_bf16_f32 v97, v146, v147
	v_cvt_pk_bf16_f32 v98, v148, v149
	v_cvt_pk_bf16_f32 v99, v150, v151
	v_cvt_pk_bf16_f32 v100, v152, v153
	v_cvt_pk_bf16_f32 v101, v154, v155
	v_cvt_pk_bf16_f32 v102, v156, v157
	v_cvt_pk_bf16_f32 v103, v158, v159
	v_add_u32_e32 v181, 0x3000000, v177
	global_store_dwordx4 v181, v[96:99], s[78:79]
	global_store_dwordx4 v181, v[100:103], s[78:79] offset:1024
	v_add_u32_e32 v236, 0xc000, v237
	s_mov_b64 exec, 1
	global_store_dword v236, v184, s[78:79]
	s_mov_b64 exec, -1
	s_waitcnt vmcnt(0)
	v_lshlrev_b32_e32 v144, 16, v112
	v_and_b32_e32 v145, 0xffff0000, v112
	v_lshlrev_b32_e32 v146, 16, v113
	v_and_b32_e32 v147, 0xffff0000, v113
	v_lshlrev_b32_e32 v148, 16, v114
	v_and_b32_e32 v149, 0xffff0000, v114
	v_lshlrev_b32_e32 v150, 16, v115
	v_and_b32_e32 v151, 0xffff0000, v115
	v_lshlrev_b32_e32 v152, 16, v116
	v_and_b32_e32 v153, 0xffff0000, v116
	v_lshlrev_b32_e32 v154, 16, v117
	v_and_b32_e32 v155, 0xffff0000, v117
	v_lshlrev_b32_e32 v156, 16, v118
	v_and_b32_e32 v157, 0xffff0000, v118
	v_lshlrev_b32_e32 v158, 16, v119
	v_and_b32_e32 v159, 0xffff0000, v119
	v_lshlrev_b32_e32 v160, 16, v120
	v_and_b32_e32 v161, 0xffff0000, v120
	v_lshlrev_b32_e32 v162, 16, v121
	v_and_b32_e32 v163, 0xffff0000, v121
	v_lshlrev_b32_e32 v164, 16, v122
	v_and_b32_e32 v165, 0xffff0000, v122
	v_lshlrev_b32_e32 v166, 16, v123
	v_and_b32_e32 v167, 0xffff0000, v123
	v_lshlrev_b32_e32 v168, 16, v124
	v_and_b32_e32 v169, 0xffff0000, v124
	v_lshlrev_b32_e32 v170, 16, v125
	v_and_b32_e32 v171, 0xffff0000, v125
	v_lshlrev_b32_e32 v172, 16, v126
	v_and_b32_e32 v173, 0xffff0000, v126
	v_lshlrev_b32_e32 v174, 16, v127
	v_and_b32_e32 v175, 0xffff0000, v127
	v_pk_mul_f32 v[252:253], v[160:161], v[160:161]
	v_pk_mul_f32 v[254:255], v[162:163], v[162:163]
	v_pk_fma_f32 v[252:253], v[164:165], v[164:165], v[252:253]
	v_pk_fma_f32 v[254:255], v[166:167], v[166:167], v[254:255]
	v_pk_fma_f32 v[252:253], v[168:169], v[168:169], v[252:253]
	v_pk_fma_f32 v[254:255], v[170:171], v[170:171], v[254:255]
	v_pk_fma_f32 v[252:253], v[172:173], v[172:173], v[252:253]
	v_pk_fma_f32 v[254:255], v[174:175], v[174:175], v[254:255]
	v_pk_add_f32 v[252:253], v[252:253], v[254:255]
	s_nop 0
	v_add_f32_e32 v183, v252, v253
	s_nop 1
	v_add_f32_dpp v183, v183, v183 quad_perm:[1,0,3,2] row_mask:0xf bank_mask:0xf bound_ctrl:1
	s_nop 1
	v_add_f32_dpp v183, v183, v183 quad_perm:[2,3,0,1] row_mask:0xf bank_mask:0xf bound_ctrl:1
	s_nop 1
	v_add_f32_dpp v183, v183, v183 row_half_mirror row_mask:0xf bank_mask:0xf bound_ctrl:1
	s_nop 1
	v_add_f32_dpp v183, v183, v183 row_mirror row_mask:0xf bank_mask:0xf bound_ctrl:1
	s_nop 1
	v_readlane_b32 s98, v183, 0
	v_readlane_b32 s99, v183, 16
	v_readlane_b32 s100, v183, 32
	v_readlane_b32 s101, v183, 48
	s_nop 1
	v_mov_b32_e32 v183, s98
	v_add_f32_e32 v183, s99, v183
	v_add_f32_e32 v183, s100, v183
	v_add_f32_e32 v183, s101, v183
	v_fmamk_f32 v183, v183, 0x3a800000, v182
	v_cmp_gt_f32_e32 vcc, 0x800000, v183
	v_mul_f32_e32 v181, 0x4b800000, v183
	s_nop 1
	v_cndmask_b32_e32 v183, v183, v181, vcc
	v_rsq_f32_e32 v183, v183
	s_nop 0
	v_mul_f32_e32 v181, 0x45800000, v183
	v_cndmask_b32_e32 v184, v183, v181, vcc
	v_mov_b32_e32 v185, v184
	v_pk_mul_f32 v[160:161], v[160:161], v[184:185]
	v_pk_mul_f32 v[162:163], v[162:163], v[184:185]
	v_pk_mul_f32 v[164:165], v[164:165], v[184:185]
	v_pk_mul_f32 v[166:167], v[166:167], v[184:185]
	v_pk_mul_f32 v[168:169], v[168:169], v[184:185]
	v_pk_mul_f32 v[170:171], v[170:171], v[184:185]
	v_pk_mul_f32 v[172:173], v[172:173], v[184:185]
	v_pk_mul_f32 v[174:175], v[174:175], v[184:185]
	v_pk_fma_f32 v[144:145], v[160:161], v[128:129], v[144:145]
	v_pk_fma_f32 v[146:147], v[162:163], v[130:131], v[146:147]
	v_pk_fma_f32 v[148:149], v[164:165], v[132:133], v[148:149]
	v_pk_fma_f32 v[150:151], v[166:167], v[134:135], v[150:151]
	v_pk_fma_f32 v[152:153], v[168:169], v[136:137], v[152:153]
	v_pk_fma_f32 v[154:155], v[170:171], v[138:139], v[154:155]
	v_pk_fma_f32 v[156:157], v[172:173], v[140:141], v[156:157]
	v_pk_fma_f32 v[158:159], v[174:175], v[142:143], v[158:159]
	v_pk_mul_f32 v[252:253], v[144:145], v[144:145]
	v_pk_mul_f32 v[254:255], v[146:147], v[146:147]
	v_pk_fma_f32 v[252:253], v[148:149], v[148:149], v[252:253]
	v_pk_fma_f32 v[254:255], v[150:151], v[150:151], v[254:255]
	v_pk_fma_f32 v[252:253], v[152:153], v[152:153], v[252:253]
	v_pk_fma_f32 v[254:255], v[154:155], v[154:155], v[254:255]
	v_pk_fma_f32 v[252:253], v[156:157], v[156:157], v[252:253]
	v_pk_fma_f32 v[254:255], v[158:159], v[158:159], v[254:255]
	v_pk_add_f32 v[252:253], v[252:253], v[254:255]
	s_nop 0
	v_add_f32_e32 v183, v252, v253
	s_nop 1
	v_add_f32_dpp v183, v183, v183 quad_perm:[1,0,3,2] row_mask:0xf bank_mask:0xf bound_ctrl:1
	s_nop 1
	v_add_f32_dpp v183, v183, v183 quad_perm:[2,3,0,1] row_mask:0xf bank_mask:0xf bound_ctrl:1
	s_nop 1
	v_add_f32_dpp v183, v183, v183 row_half_mirror row_mask:0xf bank_mask:0xf bound_ctrl:1
	s_nop 1
	v_add_f32_dpp v183, v183, v183 row_mirror row_mask:0xf bank_mask:0xf bound_ctrl:1
	s_nop 1
	v_readlane_b32 s98, v183, 0
	v_readlane_b32 s99, v183, 16
	v_readlane_b32 s100, v183, 32
	v_readlane_b32 s101, v183, 48
	s_nop 1
	v_mov_b32_e32 v183, s98
	v_add_f32_e32 v183, s99, v183
	v_add_f32_e32 v183, s100, v183
	v_add_f32_e32 v183, s101, v183
	v_fmamk_f32 v183, v183, 0x3a800000, v182
	v_cmp_gt_f32_e32 vcc, 0x800000, v183
	v_mul_f32_e32 v181, 0x4b800000, v183
	s_nop 1
	v_cndmask_b32_e32 v183, v183, v181, vcc
	v_rsq_f32_e32 v183, v183
	s_nop 0
	v_mul_f32_e32 v181, 0x45800000, v183
	v_cndmask_b32_e32 v184, v183, v181, vcc
	v_mov_b32_e32 v185, v184
	v_cvt_pk_bf16_f32 v112, v144, v145
	v_cvt_pk_bf16_f32 v113, v146, v147
	v_cvt_pk_bf16_f32 v114, v148, v149
	v_cvt_pk_bf16_f32 v115, v150, v151
	v_cvt_pk_bf16_f32 v116, v152, v153
	v_cvt_pk_bf16_f32 v117, v154, v155
	v_cvt_pk_bf16_f32 v118, v156, v157
	v_cvt_pk_bf16_f32 v119, v158, v159
	v_add_u32_e32 v181, 0x3400000, v177
	global_store_dwordx4 v181, v[112:115], s[78:79]
	global_store_dwordx4 v181, v[116:119], s[78:79] offset:1024
	v_add_u32_e32 v236, 0xe000, v237
	s_mov_b64 exec, 1
	global_store_dword v236, v184, s[78:79]
	s_mov_b64 exec, -1
	v_readfirstlane_b32 s98, v179
	s_nop 3
	s_and_b32 s99, s98, 3
	s_cmp_lg_u32 s99, 0
	s_cbranch_scc1 .Lmyxupd_done_3
	v_lshrrev_b32_e32 v179, 2, v179
	v_lshlrev_b32_e32 v177, 4, v176
	v_lshl_add_u32 v177, v179, 11, v177
	v_lshlrev_b32_e32 v237, 2, v179
	v_add_u32_e32 v237, 0x10000, v237
	v_add_u32_e32 v181, 0x3800000, v177
	global_load_dwordx4 v[240:243], v181, s[78:79]
	global_load_dwordx4 v[244:247], v181, s[78:79] offset:1024
	v_lshl_add_u32 v183, v179, 12, v180
	v_add_u32_e32 v183, 0xbf00000, v183
	v_add_u32_e32 v181, 0x0, v183
	global_load_dwordx4 v[0:3], v181, s[78:79]
	global_load_dwordx4 v[4:7], v181, s[78:79] offset:16
	global_load_dwordx4 v[8:11], v181, s[78:79] offset:2048
	global_load_dwordx4 v[12:15], v181, s[78:79] offset:2064
	v_add_u32_e32 v181, 0x200000, v183
	global_load_dwordx4 v[16:19], v181, s[78:79]
	global_load_dwordx4 v[20:23], v181, s[78:79] offset:16
	global_load_dwordx4 v[24:27], v181, s[78:79] offset:2048
	global_load_dwordx4 v[28:31], v181, s[78:79] offset:2064
	v_add_u32_e32 v181, 0x400000, v183
	global_load_dwordx4 v[32:35], v181, s[78:79]
	global_load_dwordx4 v[36:39], v181, s[78:79] offset:16
	global_load_dwordx4 v[40:43], v181, s[78:79] offset:2048
	global_load_dwordx4 v[44:47], v181, s[78:79] offset:2064
	v_add_u32_e32 v181, 0x600000, v183
	global_load_dwordx4 v[48:51], v181, s[78:79]
	global_load_dwordx4 v[52:55], v181, s[78:79] offset:16
	global_load_dwordx4 v[56:59], v181, s[78:79] offset:2048
	global_load_dwordx4 v[60:63], v181, s[78:79] offset:2064
	v_add_u32_e32 v181, 0x800000, v183
	global_load_dwordx4 v[64:67], v181, s[78:79]
	global_load_dwordx4 v[68:71], v181, s[78:79] offset:16
	global_load_dwordx4 v[72:75], v181, s[78:79] offset:2048
	global_load_dwordx4 v[76:79], v181, s[78:79] offset:2064
	v_add_u32_e32 v181, 0xa00000, v183
	global_load_dwordx4 v[80:83], v181, s[78:79]
	global_load_dwordx4 v[84:87], v181, s[78:79] offset:16
	global_load_dwordx4 v[88:91], v181, s[78:79] offset:2048
	global_load_dwordx4 v[92:95], v181, s[78:79] offset:2064
	v_add_u32_e32 v181, 0xc00000, v183
	global_load_dwordx4 v[96:99], v181, s[78:79]
	global_load_dwordx4 v[100:103], v181, s[78:79] offset:16
	global_load_dwordx4 v[104:107], v181, s[78:79] offset:2048
	global_load_dwordx4 v[108:111], v181, s[78:79] offset:2064
	v_add_u32_e32 v181, 0xe00000, v183
	global_load_dwordx4 v[112:115], v181, s[78:79]
	global_load_dwordx4 v[116:119], v181, s[78:79] offset:16
	global_load_dwordx4 v[120:123], v181, s[78:79] offset:2048
	global_load_dwordx4 v[124:127], v181, s[78:79] offset:2064
	s_waitcnt vmcnt(28)
	v_pk_add_f32 v[160:161], v[0:1], 0 op_sel_hi:[1,0]
	v_pk_add_f32 v[162:163], v[2:3], 0 op_sel_hi:[1,0]
	v_pk_add_f32 v[164:165], v[4:5], 0 op_sel_hi:[1,0]
	v_pk_add_f32 v[166:167], v[6:7], 0 op_sel_hi:[1,0]
	v_pk_add_f32 v[168:169], v[8:9], 0 op_sel_hi:[1,0]
	v_pk_add_f32 v[170:171], v[10:11], 0 op_sel_hi:[1,0]
	v_pk_add_f32 v[172:173], v[12:13], 0 op_sel_hi:[1,0]
	v_pk_add_f32 v[174:175], v[14:15], 0 op_sel_hi:[1,0]
	s_waitcnt vmcnt(24)
	v_pk_add_f32 v[160:161], v[160:161], v[16:17]
	v_pk_add_f32 v[162:163], v[162:163], v[18:19]
	v_pk_add_f32 v[164:165], v[164:165], v[20:21]
	v_pk_add_f32 v[166:167], v[166:167], v[22:23]
	v_pk_add_f32 v[168:169], v[168:169], v[24:25]
	v_pk_add_f32 v[170:171], v[170:171], v[26:27]
	v_pk_add_f32 v[172:173], v[172:173], v[28:29]
	v_pk_add_f32 v[174:175], v[174:175], v[30:31]
	s_waitcnt vmcnt(20)
	v_pk_add_f32 v[160:161], v[160:161], v[32:33]
	v_pk_add_f32 v[162:163], v[162:163], v[34:35]
	v_pk_add_f32 v[164:165], v[164:165], v[36:37]
	v_pk_add_f32 v[166:167], v[166:167], v[38:39]
	v_pk_add_f32 v[168:169], v[168:169], v[40:41]
	v_pk_add_f32 v[170:171], v[170:171], v[42:43]
	v_pk_add_f32 v[172:173], v[172:173], v[44:45]
	v_pk_add_f32 v[174:175], v[174:175], v[46:47]
	v_add_u32_e32 v181, 0x1000000, v183
	global_load_dwordx4 v[0:3], v181, s[78:79]
	global_load_dwordx4 v[4:7], v181, s[78:79] offset:16
	global_load_dwordx4 v[8:11], v181, s[78:79] offset:2048
	global_load_dwordx4 v[12:15], v181, s[78:79] offset:2064
	v_add_u32_e32 v181, 0x1200000, v183
	global_load_dwordx4 v[16:19], v181, s[78:79]
	global_load_dwordx4 v[20:23], v181, s[78:79] offset:16
	global_load_dwordx4 v[24:27], v181, s[78:79] offset:2048
	global_load_dwordx4 v[28:31], v181, s[78:79] offset:2064
	v_add_u32_e32 v181, 0x1400000, v183
	global_load_dwordx4 v[32:35], v181, s[78:79]
	global_load_dwordx4 v[36:39], v181, s[78:79] offset:16
	global_load_dwordx4 v[40:43], v181, s[78:79] offset:2048
	global_load_dwordx4 v[44:47], v181, s[78:79] offset:2064
	s_waitcnt vmcnt(28)
	v_pk_add_f32 v[160:161], v[160:161], v[48:49]
	v_pk_add_f32 v[162:163], v[162:163], v[50:51]
	v_pk_add_f32 v[164:165], v[164:165], v[52:53]
	v_pk_add_f32 v[166:167], v[166:167], v[54:55]
	v_pk_add_f32 v[168:169], v[168:169], v[56:57]
	v_pk_add_f32 v[170:171], v[170:171], v[58:59]
	v_pk_add_f32 v[172:173], v[172:173], v[60:61]
	v_pk_add_f32 v[174:175], v[174:175], v[62:63]
	s_waitcnt vmcnt(24)
	v_pk_add_f32 v[160:161], v[160:161], v[64:65]
	v_pk_add_f32 v[162:163], v[162:163], v[66:67]
	v_pk_add_f32 v[164:165], v[164:165], v[68:69]
	v_pk_add_f32 v[166:167], v[166:167], v[70:71]
	v_pk_add_f32 v[168:169], v[168:169], v[72:73]
	v_pk_add_f32 v[170:171], v[170:171], v[74:75]
	v_pk_add_f32 v[172:173], v[172:173], v[76:77]
	v_pk_add_f32 v[174:175], v[174:175], v[78:79]
	s_waitcnt vmcnt(20)
	v_pk_add_f32 v[160:161], v[160:161], v[80:81]
	v_pk_add_f32 v[162:163], v[162:163], v[82:83]
	v_pk_add_f32 v[164:165], v[164:165], v[84:85]
	v_pk_add_f32 v[166:167], v[166:167], v[86:87]
	v_pk_add_f32 v[168:169], v[168:169], v[88:89]
	v_pk_add_f32 v[170:171], v[170:171], v[90:91]
	v_pk_add_f32 v[172:173], v[172:173], v[92:93]
	v_pk_add_f32 v[174:175], v[174:175], v[94:95]
	s_waitcnt vmcnt(16)
	v_pk_add_f32 v[160:161], v[160:161], v[96:97]
	v_pk_add_f32 v[162:163], v[162:163], v[98:99]
	v_pk_add_f32 v[164:165], v[164:165], v[100:101]
	v_pk_add_f32 v[166:167], v[166:167], v[102:103]
	v_pk_add_f32 v[168:169], v[168:169], v[104:105]
	v_pk_add_f32 v[170:171], v[170:171], v[106:107]
	v_pk_add_f32 v[172:173], v[172:173], v[108:109]
	v_pk_add_f32 v[174:175], v[174:175], v[110:111]
	s_waitcnt vmcnt(12)
	v_pk_add_f32 v[160:161], v[160:161], v[112:113]
	v_pk_add_f32 v[162:163], v[162:163], v[114:115]
	v_pk_add_f32 v[164:165], v[164:165], v[116:117]
	v_pk_add_f32 v[166:167], v[166:167], v[118:119]
	v_pk_add_f32 v[168:169], v[168:169], v[120:121]
	v_pk_add_f32 v[170:171], v[170:171], v[122:123]
	v_pk_add_f32 v[172:173], v[172:173], v[124:125]
	v_pk_add_f32 v[174:175], v[174:175], v[126:127]
	v_lshlrev_b32_e32 v144, 16, v240
	v_and_b32_e32 v145, 0xffff0000, v240
	v_lshlrev_b32_e32 v146, 16, v241
	v_and_b32_e32 v147, 0xffff0000, v241
	v_lshlrev_b32_e32 v148, 16, v242
	v_and_b32_e32 v149, 0xffff0000, v242
	v_lshlrev_b32_e32 v150, 16, v243
	v_and_b32_e32 v151, 0xffff0000, v243
	v_lshlrev_b32_e32 v152, 16, v244
	v_and_b32_e32 v153, 0xffff0000, v244
	v_lshlrev_b32_e32 v154, 16, v245
	v_and_b32_e32 v155, 0xffff0000, v245
	v_lshlrev_b32_e32 v156, 16, v246
	v_and_b32_e32 v157, 0xffff0000, v246
	v_lshlrev_b32_e32 v158, 16, v247
	v_and_b32_e32 v159, 0xffff0000, v247
	s_waitcnt vmcnt(8)
	v_pk_add_f32 v[160:161], v[160:161], v[0:1]
	v_pk_add_f32 v[162:163], v[162:163], v[2:3]
	v_pk_add_f32 v[164:165], v[164:165], v[4:5]
	v_pk_add_f32 v[166:167], v[166:167], v[6:7]
	v_pk_add_f32 v[168:169], v[168:169], v[8:9]
	v_pk_add_f32 v[170:171], v[170:171], v[10:11]
	v_pk_add_f32 v[172:173], v[172:173], v[12:13]
	v_pk_add_f32 v[174:175], v[174:175], v[14:15]
	s_waitcnt vmcnt(4)
	v_pk_add_f32 v[160:161], v[160:161], v[16:17]
	v_pk_add_f32 v[162:163], v[162:163], v[18:19]
	v_pk_add_f32 v[164:165], v[164:165], v[20:21]
	v_pk_add_f32 v[166:167], v[166:167], v[22:23]
	v_pk_add_f32 v[168:169], v[168:169], v[24:25]
	v_pk_add_f32 v[170:171], v[170:171], v[26:27]
	v_pk_add_f32 v[172:173], v[172:173], v[28:29]
	v_pk_add_f32 v[174:175], v[174:175], v[30:31]
	s_waitcnt vmcnt(0)
	v_pk_add_f32 v[160:161], v[160:161], v[32:33]
	v_pk_add_f32 v[162:163], v[162:163], v[34:35]
	v_pk_add_f32 v[164:165], v[164:165], v[36:37]
	v_pk_add_f32 v[166:167], v[166:167], v[38:39]
	v_pk_add_f32 v[168:169], v[168:169], v[40:41]
	v_pk_add_f32 v[170:171], v[170:171], v[42:43]
	v_pk_add_f32 v[172:173], v[172:173], v[44:45]
	v_pk_add_f32 v[174:175], v[174:175], v[46:47]
	v_pk_mul_f32 v[252:253], v[160:161], v[160:161]
	v_pk_mul_f32 v[254:255], v[162:163], v[162:163]
	v_pk_fma_f32 v[252:253], v[164:165], v[164:165], v[252:253]
	v_pk_fma_f32 v[254:255], v[166:167], v[166:167], v[254:255]
	v_pk_fma_f32 v[252:253], v[168:169], v[168:169], v[252:253]
	v_pk_fma_f32 v[254:255], v[170:171], v[170:171], v[254:255]
	v_pk_fma_f32 v[252:253], v[172:173], v[172:173], v[252:253]
	v_pk_fma_f32 v[254:255], v[174:175], v[174:175], v[254:255]
	v_pk_add_f32 v[252:253], v[252:253], v[254:255]
	s_nop 0
	v_add_f32_e32 v183, v252, v253
	s_nop 1
	v_add_f32_dpp v183, v183, v183 quad_perm:[1,0,3,2] row_mask:0xf bank_mask:0xf bound_ctrl:1
	s_nop 1
	v_add_f32_dpp v183, v183, v183 quad_perm:[2,3,0,1] row_mask:0xf bank_mask:0xf bound_ctrl:1
	s_nop 1
	v_add_f32_dpp v183, v183, v183 row_half_mirror row_mask:0xf bank_mask:0xf bound_ctrl:1
	s_nop 1
	v_add_f32_dpp v183, v183, v183 row_mirror row_mask:0xf bank_mask:0xf bound_ctrl:1
	s_nop 1
	v_readlane_b32 s98, v183, 0
	v_readlane_b32 s99, v183, 16
	v_readlane_b32 s100, v183, 32
	v_readlane_b32 s101, v183, 48
	s_nop 1
	v_mov_b32_e32 v183, s98
	v_add_f32_e32 v183, s99, v183
	v_add_f32_e32 v183, s100, v183
	v_add_f32_e32 v183, s101, v183
	v_fmamk_f32 v183, v183, 0x3a800000, v182
	v_cmp_gt_f32_e32 vcc, 0x800000, v183
	v_mul_f32_e32 v181, 0x4b800000, v183
	s_nop 1
	v_cndmask_b32_e32 v183, v183, v181, vcc
	v_rsq_f32_e32 v183, v183
	s_nop 0
	v_mul_f32_e32 v181, 0x45800000, v183
	v_cndmask_b32_e32 v184, v183, v181, vcc
	v_mov_b32_e32 v185, v184
	v_pk_mul_f32 v[160:161], v[160:161], v[184:185]
	v_pk_mul_f32 v[162:163], v[162:163], v[184:185]
	v_pk_mul_f32 v[164:165], v[164:165], v[184:185]
	v_pk_mul_f32 v[166:167], v[166:167], v[184:185]
	v_pk_mul_f32 v[168:169], v[168:169], v[184:185]
	v_pk_mul_f32 v[170:171], v[170:171], v[184:185]
	v_pk_mul_f32 v[172:173], v[172:173], v[184:185]
	v_pk_mul_f32 v[174:175], v[174:175], v[184:185]
	v_pk_fma_f32 v[144:145], v[160:161], v[128:129], v[144:145]
	v_pk_fma_f32 v[146:147], v[162:163], v[130:131], v[146:147]
	v_pk_fma_f32 v[148:149], v[164:165], v[132:133], v[148:149]
	v_pk_fma_f32 v[150:151], v[166:167], v[134:135], v[150:151]
	v_pk_fma_f32 v[152:153], v[168:169], v[136:137], v[152:153]
	v_pk_fma_f32 v[154:155], v[170:171], v[138:139], v[154:155]
	v_pk_fma_f32 v[156:157], v[172:173], v[140:141], v[156:157]
	v_pk_fma_f32 v[158:159], v[174:175], v[142:143], v[158:159]
	v_pk_mul_f32 v[252:253], v[144:145], v[144:145]
	v_pk_mul_f32 v[254:255], v[146:147], v[146:147]
	v_pk_fma_f32 v[252:253], v[148:149], v[148:149], v[252:253]
	v_pk_fma_f32 v[254:255], v[150:151], v[150:151], v[254:255]
	v_pk_fma_f32 v[252:253], v[152:153], v[152:153], v[252:253]
	v_pk_fma_f32 v[254:255], v[154:155], v[154:155], v[254:255]
	v_pk_fma_f32 v[252:253], v[156:157], v[156:157], v[252:253]
	v_pk_fma_f32 v[254:255], v[158:159], v[158:159], v[254:255]
	v_pk_add_f32 v[252:253], v[252:253], v[254:255]
	s_nop 0
	v_add_f32_e32 v183, v252, v253
	s_nop 1
	v_add_f32_dpp v183, v183, v183 quad_perm:[1,0,3,2] row_mask:0xf bank_mask:0xf bound_ctrl:1
	s_nop 1
	v_add_f32_dpp v183, v183, v183 quad_perm:[2,3,0,1] row_mask:0xf bank_mask:0xf bound_ctrl:1
	s_nop 1
	v_add_f32_dpp v183, v183, v183 row_half_mirror row_mask:0xf bank_mask:0xf bound_ctrl:1
	s_nop 1
	v_add_f32_dpp v183, v183, v183 row_mirror row_mask:0xf bank_mask:0xf bound_ctrl:1
	s_nop 1
	v_readlane_b32 s98, v183, 0
	v_readlane_b32 s99, v183, 16
	v_readlane_b32 s100, v183, 32
	v_readlane_b32 s101, v183, 48
	s_nop 1
	v_mov_b32_e32 v183, s98
	v_add_f32_e32 v183, s99, v183
	v_add_f32_e32 v183, s100, v183
	v_add_f32_e32 v183, s101, v183
	v_fmamk_f32 v183, v183, 0x3a800000, v182
	v_cmp_gt_f32_e32 vcc, 0x800000, v183
	v_mul_f32_e32 v181, 0x4b800000, v183
	s_nop 1
	v_cndmask_b32_e32 v183, v183, v181, vcc
	v_rsq_f32_e32 v183, v183
	s_nop 0
	v_mul_f32_e32 v181, 0x45800000, v183
	v_cndmask_b32_e32 v184, v183, v181, vcc
	v_mov_b32_e32 v185, v184
	v_cvt_pk_bf16_f32 v0, v144, v145
	v_cvt_pk_bf16_f32 v1, v146, v147
	v_cvt_pk_bf16_f32 v2, v148, v149
	v_cvt_pk_bf16_f32 v3, v150, v151
	v_cvt_pk_bf16_f32 v4, v152, v153
	v_cvt_pk_bf16_f32 v5, v154, v155
	v_cvt_pk_bf16_f32 v6, v156, v157
	v_cvt_pk_bf16_f32 v7, v158, v159
	v_add_u32_e32 v181, 0x3800000, v177
	global_store_dwordx4 v181, v[0:3], s[78:79]
	global_store_dwordx4 v181, v[4:7], s[78:79] offset:1024
	v_add_u32_e32 v236, 0x10000, v237
	s_mov_b64 exec, 1
	global_store_dword v236, v184, s[78:79]
	s_mov_b64 exec, -1

.LBB0_1863:
	v_readlane_b32 s0, v235, 52
	v_readlane_b32 s1, v235, 53
	s_and_b64 vcc, exec, s[0:1]
	s_waitcnt lgkmcnt(0)
	s_barrier
	v_mbcnt_lo_u32_b32 v0, -1, 0
	v_mbcnt_hi_u32_b32 v0, -1, v0
	s_cbranch_vccnz .LBB0_1883
	v_lshlrev_b32_e32 v2, 3, v0
	v_ashrrev_i32_e32 v3, 31, v2
	v_readlane_b32 s4, v235, 4
	v_lshlrev_b64 v[4:5], 1, v[2:3]
	v_lshlrev_b64 v[2:3], 2, v[2:3]
	v_readlane_b32 s14, v235, 14
	v_readlane_b32 s15, v235, 15
	v_lshl_add_u64 v[62:63], s[90:91], 0, v[2:3]
	v_readlane_b32 s5, v235, 5
	v_readlane_b32 s6, v235, 6
	v_readlane_b32 s7, v235, 7
	v_readlane_b32 s8, v235, 8
	v_readlane_b32 s9, v235, 9
	v_readlane_b32 s10, v235, 10
	v_readlane_b32 s11, v235, 11
	v_readlane_b32 s12, v235, 12
	v_readlane_b32 s13, v235, 13
	v_readlane_b32 s16, v235, 16
	v_readlane_b32 s17, v235, 17
	v_readlane_b32 s18, v235, 18
	v_readlane_b32 s19, v235, 19
	v_lshl_add_u64 v[2:3], s[14:15], 0, v[2:3]
	s_mov_b64 s[0:1], 0x2000
	v_lshl_add_u64 v[60:61], s[86:87], 0, v[4:5]
	v_lshl_add_u64 v[64:65], s[54:55], 0, v[4:5]
	v_lshl_add_u64 v[66:67], v[2:3], 0, s[0:1]
	s_mov_b32 s1, 0
	v_cmp_eq_u32_e64 s[16:17], 0, v0
	s_mov_b64 s[4:5], 0x200000
	s_mov_b64 s[6:7], 0x200800
	s_mov_b64 s[8:9], 0x400000
	s_mov_b64 s[10:11], 0x400800
	s_mov_b64 s[12:13], 0x600000
	s_mov_b64 s[14:15], 0x600800
	s_mov_b64 s[18:19], 0x800000
	s_mov_b32 s48, 0x800000
	s_mov_b64 s[20:21], 0x800800
	s_mov_b64 s[22:23], 0xa00000
	s_mov_b64 s[24:25], 0xa00800
	s_mov_b64 s[26:27], 0xc00000
	s_mov_b64 s[28:29], 0xc00800
	s_mov_b64 s[36:37], 0xe00000
	s_mov_b64 s[38:39], 0xe00800
	v_mov_b32_e32 v104, 0
	v_mov_b32_e32 v105, 0x358637bd
	v_readlane_b32 s42, v235, 61
	v_readlane_b32 s43, v235, 62
	v_mbcnt_lo_u32_b32 v176, -1, 0
	v_mbcnt_hi_u32_b32 v176, -1, v176
	v_readlane_b32 s98, v235, 49
	v_readlane_b32 s99, v235, 20
	v_readlane_b32 s100, v235, 14
	v_readlane_b32 s101, v235, 15
	s_nop 3
	s_lshr_b32 vcc_lo, s98, 3
	s_and_b32 vcc_hi, vcc_lo, 7
	s_lshr_b32 vcc_lo, vcc_lo, 3
	s_lshl_b32 vcc_lo, vcc_lo, 3
	s_add_i32 vcc_lo, vcc_lo, s99
	s_lshl_b32 s98, vcc_hi, 8
	s_add_i32 s98, s98, vcc_lo
	s_mov_b32 s99, s98
	v_mov_b32_e32 v183, s99
	v_lshlrev_b32_e32 v177, 4, v176
	s_lshl_b32 s99, s99, 11
	v_add_u32_e32 v177, s99, v177
	v_add_u32_e32 v178, 0x1800000, v177
	v_add_u32_e32 v179, 0x9e00000, v177
	v_lshlrev_b32_e32 v180, 5, v176
	v_add_u32_e32 v181, 0x2000, v180
	global_load_dwordx4 v[128:131], v181, s[100:101]
	global_load_dwordx4 v[132:135], v181, s[100:101] offset:16
	global_load_dwordx4 v[136:139], v181, s[100:101] offset:2048
	global_load_dwordx4 v[140:143], v181, s[100:101] offset:2064
	v_mov_b32_e32 v182, 0x358637bd
	global_load_dwordx4 v[0:3], v178, s[78:79]
	global_load_dwordx4 v[4:7], v178, s[78:79] offset:1024
	global_load_dwordx4 v[8:11], v179, s[78:79]
	global_load_dwordx4 v[12:15], v179, s[78:79] offset:1024
	v_add_u32_e32 v178, 0x400000, v178
	v_add_u32_e32 v179, 0x400000, v179
	global_load_dwordx4 v[16:19], v178, s[78:79]
	global_load_dwordx4 v[20:23], v178, s[78:79] offset:1024
	global_load_dwordx4 v[24:27], v179, s[78:79]
	global_load_dwordx4 v[28:31], v179, s[78:79] offset:1024
	v_add_u32_e32 v178, 0x400000, v178
	v_add_u32_e32 v179, 0x400000, v179
	global_load_dwordx4 v[32:35], v178, s[78:79]
	global_load_dwordx4 v[36:39], v178, s[78:79] offset:1024
	global_load_dwordx4 v[40:43], v179, s[78:79]
	global_load_dwordx4 v[44:47], v179, s[78:79] offset:1024
	v_add_u32_e32 v178, 0x400000, v178
	v_add_u32_e32 v179, 0x400000, v179
	global_load_dwordx4 v[48:51], v178, s[78:79]
	global_load_dwordx4 v[52:55], v178, s[78:79] offset:1024
	global_load_dwordx4 v[56:59], v179, s[78:79]
	global_load_dwordx4 v[60:63], v179, s[78:79] offset:1024
	v_add_u32_e32 v178, 0x400000, v178
	v_add_u32_e32 v179, 0x400000, v179
	global_load_dwordx4 v[64:67], v178, s[78:79]
	global_load_dwordx4 v[68:71], v178, s[78:79] offset:1024
	global_load_dwordx4 v[72:75], v179, s[78:79]
	global_load_dwordx4 v[76:79], v179, s[78:79] offset:1024
	v_add_u32_e32 v178, 0x400000, v178
	v_add_u32_e32 v179, 0x400000, v179
	global_load_dwordx4 v[80:83], v178, s[78:79]
	global_load_dwordx4 v[84:87], v178, s[78:79] offset:1024
	global_load_dwordx4 v[88:91], v179, s[78:79]
	global_load_dwordx4 v[92:95], v179, s[78:79] offset:1024
	v_add_u32_e32 v178, 0x400000, v178
	v_add_u32_e32 v179, 0x400000, v179
	global_load_dwordx4 v[96:99], v178, s[78:79]
	global_load_dwordx4 v[100:103], v178, s[78:79] offset:1024
	global_load_dwordx4 v[104:107], v179, s[78:79]
	global_load_dwordx4 v[108:111], v179, s[78:79] offset:1024
	v_add_u32_e32 v178, 0x400000, v178
	v_add_u32_e32 v179, 0x400000, v179
	global_load_dwordx4 v[112:115], v178, s[78:79]
	global_load_dwordx4 v[116:119], v178, s[78:79] offset:1024
	global_load_dwordx4 v[120:123], v179, s[78:79]
	global_load_dwordx4 v[124:127], v179, s[78:79] offset:1024
	v_lshlrev_b32_e32 v237, 2, v183
	v_add_u32_e32 v237, 0x10000, v237
	v_mov_b32_e32 v179, s98
	s_waitcnt vmcnt(28)
	v_lshlrev_b32_e32 v144, 16, v0
	v_and_b32_e32 v145, 0xffff0000, v0
	v_lshlrev_b32_e32 v146, 16, v1
	v_and_b32_e32 v147, 0xffff0000, v1
	v_lshlrev_b32_e32 v148, 16, v2
	v_and_b32_e32 v149, 0xffff0000, v2
	v_lshlrev_b32_e32 v150, 16, v3
	v_and_b32_e32 v151, 0xffff0000, v3
	v_lshlrev_b32_e32 v152, 16, v4
	v_and_b32_e32 v153, 0xffff0000, v4
	v_lshlrev_b32_e32 v154, 16, v5
	v_and_b32_e32 v155, 0xffff0000, v5
	v_lshlrev_b32_e32 v156, 16, v6
	v_and_b32_e32 v157, 0xffff0000, v6
	v_lshlrev_b32_e32 v158, 16, v7
	v_and_b32_e32 v159, 0xffff0000, v7
	v_lshlrev_b32_e32 v160, 16, v8
	v_and_b32_e32 v161, 0xffff0000, v8
	v_lshlrev_b32_e32 v162, 16, v9
	v_and_b32_e32 v163, 0xffff0000, v9
	v_lshlrev_b32_e32 v164, 16, v10
	v_and_b32_e32 v165, 0xffff0000, v10
	v_lshlrev_b32_e32 v166, 16, v11
	v_and_b32_e32 v167, 0xffff0000, v11
	v_lshlrev_b32_e32 v168, 16, v12
	v_and_b32_e32 v169, 0xffff0000, v12
	v_lshlrev_b32_e32 v170, 16, v13
	v_and_b32_e32 v171, 0xffff0000, v13
	v_lshlrev_b32_e32 v172, 16, v14
	v_and_b32_e32 v173, 0xffff0000, v14
	v_lshlrev_b32_e32 v174, 16, v15
	v_and_b32_e32 v175, 0xffff0000, v15
	v_pk_mul_f32 v[252:253], v[160:161], v[160:161]
	v_pk_mul_f32 v[254:255], v[162:163], v[162:163]
	v_pk_fma_f32 v[252:253], v[164:165], v[164:165], v[252:253]
	v_pk_fma_f32 v[254:255], v[166:167], v[166:167], v[254:255]
	v_pk_fma_f32 v[252:253], v[168:169], v[168:169], v[252:253]
	v_pk_fma_f32 v[254:255], v[170:171], v[170:171], v[254:255]
	v_pk_fma_f32 v[252:253], v[172:173], v[172:173], v[252:253]
	v_pk_fma_f32 v[254:255], v[174:175], v[174:175], v[254:255]
	v_pk_add_f32 v[252:253], v[252:253], v[254:255]
	s_nop 0
	v_add_f32_e32 v183, v252, v253
	s_nop 1
	v_add_f32_dpp v183, v183, v183 quad_perm:[1,0,3,2] row_mask:0xf bank_mask:0xf bound_ctrl:1
	s_nop 1
	v_add_f32_dpp v183, v183, v183 quad_perm:[2,3,0,1] row_mask:0xf bank_mask:0xf bound_ctrl:1
	s_nop 1
	v_add_f32_dpp v183, v183, v183 row_half_mirror row_mask:0xf bank_mask:0xf bound_ctrl:1
	s_nop 1
	v_add_f32_dpp v183, v183, v183 row_mirror row_mask:0xf bank_mask:0xf bound_ctrl:1
	s_nop 1
	v_readlane_b32 s98, v183, 0
	v_readlane_b32 s99, v183, 16
	v_readlane_b32 s100, v183, 32
	v_readlane_b32 s101, v183, 48
	s_nop 1
	v_mov_b32_e32 v183, s98
	v_add_f32_e32 v183, s99, v183
	v_add_f32_e32 v183, s100, v183
	v_add_f32_e32 v183, s101, v183
	v_fmamk_f32 v183, v183, 0x3a800000, v182
	v_cmp_gt_f32_e32 vcc, 0x800000, v183
	v_mul_f32_e32 v181, 0x4b800000, v183
	s_nop 1
	v_cndmask_b32_e32 v183, v183, v181, vcc
	v_rsq_f32_e32 v183, v183
	s_nop 0
	v_mul_f32_e32 v181, 0x45800000, v183
	v_cndmask_b32_e32 v184, v183, v181, vcc
	v_mov_b32_e32 v185, v184
	v_pk_mul_f32 v[160:161], v[160:161], v[184:185]
	v_pk_mul_f32 v[162:163], v[162:163], v[184:185]
	v_pk_mul_f32 v[164:165], v[164:165], v[184:185]
	v_pk_mul_f32 v[166:167], v[166:167], v[184:185]
	v_pk_mul_f32 v[168:169], v[168:169], v[184:185]
	v_pk_mul_f32 v[170:171], v[170:171], v[184:185]
	v_pk_mul_f32 v[172:173], v[172:173], v[184:185]
	v_pk_mul_f32 v[174:175], v[174:175], v[184:185]
	v_pk_fma_f32 v[144:145], v[160:161], v[128:129], v[144:145]
	v_pk_fma_f32 v[146:147], v[162:163], v[130:131], v[146:147]
	v_pk_fma_f32 v[148:149], v[164:165], v[132:133], v[148:149]
	v_pk_fma_f32 v[150:151], v[166:167], v[134:135], v[150:151]
	v_pk_fma_f32 v[152:153], v[168:169], v[136:137], v[152:153]
	v_pk_fma_f32 v[154:155], v[170:171], v[138:139], v[154:155]
	v_pk_fma_f32 v[156:157], v[172:173], v[140:141], v[156:157]
	v_pk_fma_f32 v[158:159], v[174:175], v[142:143], v[158:159]
	v_pk_mul_f32 v[252:253], v[144:145], v[144:145]
	v_pk_mul_f32 v[254:255], v[146:147], v[146:147]
	v_pk_fma_f32 v[252:253], v[148:149], v[148:149], v[252:253]
	v_pk_fma_f32 v[254:255], v[150:151], v[150:151], v[254:255]
	v_pk_fma_f32 v[252:253], v[152:153], v[152:153], v[252:253]
	v_pk_fma_f32 v[254:255], v[154:155], v[154:155], v[254:255]
	v_pk_fma_f32 v[252:253], v[156:157], v[156:157], v[252:253]
	v_pk_fma_f32 v[254:255], v[158:159], v[158:159], v[254:255]
	v_pk_add_f32 v[252:253], v[252:253], v[254:255]
	s_nop 0
	v_add_f32_e32 v183, v252, v253
	s_nop 1
	v_add_f32_dpp v183, v183, v183 quad_perm:[1,0,3,2] row_mask:0xf bank_mask:0xf bound_ctrl:1
	s_nop 1
	v_add_f32_dpp v183, v183, v183 quad_perm:[2,3,0,1] row_mask:0xf bank_mask:0xf bound_ctrl:1
	s_nop 1
	v_add_f32_dpp v183, v183, v183 row_half_mirror row_mask:0xf bank_mask:0xf bound_ctrl:1
	s_nop 1
	v_add_f32_dpp v183, v183, v183 row_mirror row_mask:0xf bank_mask:0xf bound_ctrl:1
	s_nop 1
	v_readlane_b32 s98, v183, 0
	v_readlane_b32 s99, v183, 16
	v_readlane_b32 s100, v183, 32
	v_readlane_b32 s101, v183, 48
	s_nop 1
	v_mov_b32_e32 v183, s98
	v_add_f32_e32 v183, s99, v183
	v_add_f32_e32 v183, s100, v183
	v_add_f32_e32 v183, s101, v183
	v_fmamk_f32 v183, v183, 0x3a800000, v182
	v_cmp_gt_f32_e32 vcc, 0x800000, v183
	v_mul_f32_e32 v181, 0x4b800000, v183
	s_nop 1
	v_cndmask_b32_e32 v183, v183, v181, vcc
	v_rsq_f32_e32 v183, v183
	s_nop 0
	v_mul_f32_e32 v181, 0x45800000, v183
	v_cndmask_b32_e32 v184, v183, v181, vcc
	v_mov_b32_e32 v185, v184
	v_cvt_pk_bf16_f32 v0, v144, v145
	v_cvt_pk_bf16_f32 v1, v146, v147
	v_cvt_pk_bf16_f32 v2, v148, v149
	v_cvt_pk_bf16_f32 v3, v150, v151
	v_cvt_pk_bf16_f32 v4, v152, v153
	v_cvt_pk_bf16_f32 v5, v154, v155
	v_cvt_pk_bf16_f32 v6, v156, v157
	v_cvt_pk_bf16_f32 v7, v158, v159
	v_add_u32_e32 v181, 0x1800000, v177
	global_store_dwordx4 v181, v[0:3], s[78:79]
	global_store_dwordx4 v181, v[4:7], s[78:79] offset:1024
	v_add_u32_e32 v236, 0x0, v237
	s_mov_b64 exec, 1
	global_store_dword v236, v184, s[78:79]
	s_mov_b64 exec, -1
	s_waitcnt vmcnt(24)
	v_lshlrev_b32_e32 v144, 16, v16
	v_and_b32_e32 v145, 0xffff0000, v16
	v_lshlrev_b32_e32 v146, 16, v17
	v_and_b32_e32 v147, 0xffff0000, v17
	v_lshlrev_b32_e32 v148, 16, v18
	v_and_b32_e32 v149, 0xffff0000, v18
	v_lshlrev_b32_e32 v150, 16, v19
	v_and_b32_e32 v151, 0xffff0000, v19
	v_lshlrev_b32_e32 v152, 16, v20
	v_and_b32_e32 v153, 0xffff0000, v20
	v_lshlrev_b32_e32 v154, 16, v21
	v_and_b32_e32 v155, 0xffff0000, v21
	v_lshlrev_b32_e32 v156, 16, v22
	v_and_b32_e32 v157, 0xffff0000, v22
	v_lshlrev_b32_e32 v158, 16, v23
	v_and_b32_e32 v159, 0xffff0000, v23
	v_lshlrev_b32_e32 v160, 16, v24
	v_and_b32_e32 v161, 0xffff0000, v24
	v_lshlrev_b32_e32 v162, 16, v25
	v_and_b32_e32 v163, 0xffff0000, v25
	v_lshlrev_b32_e32 v164, 16, v26
	v_and_b32_e32 v165, 0xffff0000, v26
	v_lshlrev_b32_e32 v166, 16, v27
	v_and_b32_e32 v167, 0xffff0000, v27
	v_lshlrev_b32_e32 v168, 16, v28
	v_and_b32_e32 v169, 0xffff0000, v28
	v_lshlrev_b32_e32 v170, 16, v29
	v_and_b32_e32 v171, 0xffff0000, v29
	v_lshlrev_b32_e32 v172, 16, v30
	v_and_b32_e32 v173, 0xffff0000, v30
	v_lshlrev_b32_e32 v174, 16, v31
	v_and_b32_e32 v175, 0xffff0000, v31
	v_pk_mul_f32 v[252:253], v[160:161], v[160:161]
	v_pk_mul_f32 v[254:255], v[162:163], v[162:163]
	v_pk_fma_f32 v[252:253], v[164:165], v[164:165], v[252:253]
	v_pk_fma_f32 v[254:255], v[166:167], v[166:167], v[254:255]
	v_pk_fma_f32 v[252:253], v[168:169], v[168:169], v[252:253]
	v_pk_fma_f32 v[254:255], v[170:171], v[170:171], v[254:255]
	v_pk_fma_f32 v[252:253], v[172:173], v[172:173], v[252:253]
	v_pk_fma_f32 v[254:255], v[174:175], v[174:175], v[254:255]
	v_pk_add_f32 v[252:253], v[252:253], v[254:255]
	s_nop 0
	v_add_f32_e32 v183, v252, v253
	s_nop 1
	v_add_f32_dpp v183, v183, v183 quad_perm:[1,0,3,2] row_mask:0xf bank_mask:0xf bound_ctrl:1
	s_nop 1
	v_add_f32_dpp v183, v183, v183 quad_perm:[2,3,0,1] row_mask:0xf bank_mask:0xf bound_ctrl:1
	s_nop 1
	v_add_f32_dpp v183, v183, v183 row_half_mirror row_mask:0xf bank_mask:0xf bound_ctrl:1
	s_nop 1
	v_add_f32_dpp v183, v183, v183 row_mirror row_mask:0xf bank_mask:0xf bound_ctrl:1
	s_nop 1
	v_readlane_b32 s98, v183, 0
	v_readlane_b32 s99, v183, 16
	v_readlane_b32 s100, v183, 32
	v_readlane_b32 s101, v183, 48
	s_nop 1
	v_mov_b32_e32 v183, s98
	v_add_f32_e32 v183, s99, v183
	v_add_f32_e32 v183, s100, v183
	v_add_f32_e32 v183, s101, v183
	v_fmamk_f32 v183, v183, 0x3a800000, v182
	v_cmp_gt_f32_e32 vcc, 0x800000, v183
	v_mul_f32_e32 v181, 0x4b800000, v183
	s_nop 1
	v_cndmask_b32_e32 v183, v183, v181, vcc
	v_rsq_f32_e32 v183, v183
	s_nop 0
	v_mul_f32_e32 v181, 0x45800000, v183
	v_cndmask_b32_e32 v184, v183, v181, vcc
	v_mov_b32_e32 v185, v184
	v_pk_mul_f32 v[160:161], v[160:161], v[184:185]
	v_pk_mul_f32 v[162:163], v[162:163], v[184:185]
	v_pk_mul_f32 v[164:165], v[164:165], v[184:185]
	v_pk_mul_f32 v[166:167], v[166:167], v[184:185]
	v_pk_mul_f32 v[168:169], v[168:169], v[184:185]
	v_pk_mul_f32 v[170:171], v[170:171], v[184:185]
	v_pk_mul_f32 v[172:173], v[172:173], v[184:185]
	v_pk_mul_f32 v[174:175], v[174:175], v[184:185]
	v_pk_fma_f32 v[144:145], v[160:161], v[128:129], v[144:145]
	v_pk_fma_f32 v[146:147], v[162:163], v[130:131], v[146:147]
	v_pk_fma_f32 v[148:149], v[164:165], v[132:133], v[148:149]
	v_pk_fma_f32 v[150:151], v[166:167], v[134:135], v[150:151]
	v_pk_fma_f32 v[152:153], v[168:169], v[136:137], v[152:153]
	v_pk_fma_f32 v[154:155], v[170:171], v[138:139], v[154:155]
	v_pk_fma_f32 v[156:157], v[172:173], v[140:141], v[156:157]
	v_pk_fma_f32 v[158:159], v[174:175], v[142:143], v[158:159]
	v_pk_mul_f32 v[252:253], v[144:145], v[144:145]
	v_pk_mul_f32 v[254:255], v[146:147], v[146:147]
	v_pk_fma_f32 v[252:253], v[148:149], v[148:149], v[252:253]
	v_pk_fma_f32 v[254:255], v[150:151], v[150:151], v[254:255]
	v_pk_fma_f32 v[252:253], v[152:153], v[152:153], v[252:253]
	v_pk_fma_f32 v[254:255], v[154:155], v[154:155], v[254:255]
	v_pk_fma_f32 v[252:253], v[156:157], v[156:157], v[252:253]
	v_pk_fma_f32 v[254:255], v[158:159], v[158:159], v[254:255]
	v_pk_add_f32 v[252:253], v[252:253], v[254:255]
	s_nop 0
	v_add_f32_e32 v183, v252, v253
	s_nop 1
	v_add_f32_dpp v183, v183, v183 quad_perm:[1,0,3,2] row_mask:0xf bank_mask:0xf bound_ctrl:1
	s_nop 1
	v_add_f32_dpp v183, v183, v183 quad_perm:[2,3,0,1] row_mask:0xf bank_mask:0xf bound_ctrl:1
	s_nop 1
	v_add_f32_dpp v183, v183, v183 row_half_mirror row_mask:0xf bank_mask:0xf bound_ctrl:1
	s_nop 1
	v_add_f32_dpp v183, v183, v183 row_mirror row_mask:0xf bank_mask:0xf bound_ctrl:1
	s_nop 1
	v_readlane_b32 s98, v183, 0
	v_readlane_b32 s99, v183, 16
	v_readlane_b32 s100, v183, 32
	v_readlane_b32 s101, v183, 48
	s_nop 1
	v_mov_b32_e32 v183, s98
	v_add_f32_e32 v183, s99, v183
	v_add_f32_e32 v183, s100, v183
	v_add_f32_e32 v183, s101, v183
	v_fmamk_f32 v183, v183, 0x3a800000, v182
	v_cmp_gt_f32_e32 vcc, 0x800000, v183
	v_mul_f32_e32 v181, 0x4b800000, v183
	s_nop 1
	v_cndmask_b32_e32 v183, v183, v181, vcc
	v_rsq_f32_e32 v183, v183
	s_nop 0
	v_mul_f32_e32 v181, 0x45800000, v183
	v_cndmask_b32_e32 v184, v183, v181, vcc
	v_mov_b32_e32 v185, v184
	v_cvt_pk_bf16_f32 v16, v144, v145
	v_cvt_pk_bf16_f32 v17, v146, v147
	v_cvt_pk_bf16_f32 v18, v148, v149
	v_cvt_pk_bf16_f32 v19, v150, v151
	v_cvt_pk_bf16_f32 v20, v152, v153
	v_cvt_pk_bf16_f32 v21, v154, v155
	v_cvt_pk_bf16_f32 v22, v156, v157
	v_cvt_pk_bf16_f32 v23, v158, v159
	v_add_u32_e32 v181, 0x1c00000, v177
	global_store_dwordx4 v181, v[16:19], s[78:79]
	global_store_dwordx4 v181, v[20:23], s[78:79] offset:1024
	v_add_u32_e32 v236, 0x2000, v237
	s_mov_b64 exec, 1
	global_store_dword v236, v184, s[78:79]
	s_mov_b64 exec, -1
	s_waitcnt vmcnt(20)
	v_lshlrev_b32_e32 v144, 16, v32
	v_and_b32_e32 v145, 0xffff0000, v32
	v_lshlrev_b32_e32 v146, 16, v33
	v_and_b32_e32 v147, 0xffff0000, v33
	v_lshlrev_b32_e32 v148, 16, v34
	v_and_b32_e32 v149, 0xffff0000, v34
	v_lshlrev_b32_e32 v150, 16, v35
	v_and_b32_e32 v151, 0xffff0000, v35
	v_lshlrev_b32_e32 v152, 16, v36
	v_and_b32_e32 v153, 0xffff0000, v36
	v_lshlrev_b32_e32 v154, 16, v37
	v_and_b32_e32 v155, 0xffff0000, v37
	v_lshlrev_b32_e32 v156, 16, v38
	v_and_b32_e32 v157, 0xffff0000, v38
	v_lshlrev_b32_e32 v158, 16, v39
	v_and_b32_e32 v159, 0xffff0000, v39
	v_lshlrev_b32_e32 v160, 16, v40
	v_and_b32_e32 v161, 0xffff0000, v40
	v_lshlrev_b32_e32 v162, 16, v41
	v_and_b32_e32 v163, 0xffff0000, v41
	v_lshlrev_b32_e32 v164, 16, v42
	v_and_b32_e32 v165, 0xffff0000, v42
	v_lshlrev_b32_e32 v166, 16, v43
	v_and_b32_e32 v167, 0xffff0000, v43
	v_lshlrev_b32_e32 v168, 16, v44
	v_and_b32_e32 v169, 0xffff0000, v44
	v_lshlrev_b32_e32 v170, 16, v45
	v_and_b32_e32 v171, 0xffff0000, v45
	v_lshlrev_b32_e32 v172, 16, v46
	v_and_b32_e32 v173, 0xffff0000, v46
	v_lshlrev_b32_e32 v174, 16, v47
	v_and_b32_e32 v175, 0xffff0000, v47
	v_pk_mul_f32 v[252:253], v[160:161], v[160:161]
	v_pk_mul_f32 v[254:255], v[162:163], v[162:163]
	v_pk_fma_f32 v[252:253], v[164:165], v[164:165], v[252:253]
	v_pk_fma_f32 v[254:255], v[166:167], v[166:167], v[254:255]
	v_pk_fma_f32 v[252:253], v[168:169], v[168:169], v[252:253]
	v_pk_fma_f32 v[254:255], v[170:171], v[170:171], v[254:255]
	v_pk_fma_f32 v[252:253], v[172:173], v[172:173], v[252:253]
	v_pk_fma_f32 v[254:255], v[174:175], v[174:175], v[254:255]
	v_pk_add_f32 v[252:253], v[252:253], v[254:255]
	s_nop 0
	v_add_f32_e32 v183, v252, v253
	s_nop 1
	v_add_f32_dpp v183, v183, v183 quad_perm:[1,0,3,2] row_mask:0xf bank_mask:0xf bound_ctrl:1
	s_nop 1
	v_add_f32_dpp v183, v183, v183 quad_perm:[2,3,0,1] row_mask:0xf bank_mask:0xf bound_ctrl:1
	s_nop 1
	v_add_f32_dpp v183, v183, v183 row_half_mirror row_mask:0xf bank_mask:0xf bound_ctrl:1
	s_nop 1
	v_add_f32_dpp v183, v183, v183 row_mirror row_mask:0xf bank_mask:0xf bound_ctrl:1
	s_nop 1
	v_readlane_b32 s98, v183, 0
	v_readlane_b32 s99, v183, 16
	v_readlane_b32 s100, v183, 32
	v_readlane_b32 s101, v183, 48
	s_nop 1
	v_mov_b32_e32 v183, s98
	v_add_f32_e32 v183, s99, v183
	v_add_f32_e32 v183, s100, v183
	v_add_f32_e32 v183, s101, v183
	v_fmamk_f32 v183, v183, 0x3a800000, v182
	v_cmp_gt_f32_e32 vcc, 0x800000, v183
	v_mul_f32_e32 v181, 0x4b800000, v183
	s_nop 1
	v_cndmask_b32_e32 v183, v183, v181, vcc
	v_rsq_f32_e32 v183, v183
	s_nop 0
	v_mul_f32_e32 v181, 0x45800000, v183
	v_cndmask_b32_e32 v184, v183, v181, vcc
	v_mov_b32_e32 v185, v184
	v_pk_mul_f32 v[160:161], v[160:161], v[184:185]
	v_pk_mul_f32 v[162:163], v[162:163], v[184:185]
	v_pk_mul_f32 v[164:165], v[164:165], v[184:185]
	v_pk_mul_f32 v[166:167], v[166:167], v[184:185]
	v_pk_mul_f32 v[168:169], v[168:169], v[184:185]
	v_pk_mul_f32 v[170:171], v[170:171], v[184:185]
	v_pk_mul_f32 v[172:173], v[172:173], v[184:185]
	v_pk_mul_f32 v[174:175], v[174:175], v[184:185]
	v_pk_fma_f32 v[144:145], v[160:161], v[128:129], v[144:145]
	v_pk_fma_f32 v[146:147], v[162:163], v[130:131], v[146:147]
	v_pk_fma_f32 v[148:149], v[164:165], v[132:133], v[148:149]
	v_pk_fma_f32 v[150:151], v[166:167], v[134:135], v[150:151]
	v_pk_fma_f32 v[152:153], v[168:169], v[136:137], v[152:153]
	v_pk_fma_f32 v[154:155], v[170:171], v[138:139], v[154:155]
	v_pk_fma_f32 v[156:157], v[172:173], v[140:141], v[156:157]
	v_pk_fma_f32 v[158:159], v[174:175], v[142:143], v[158:159]
	v_pk_mul_f32 v[252:253], v[144:145], v[144:145]
	v_pk_mul_f32 v[254:255], v[146:147], v[146:147]
	v_pk_fma_f32 v[252:253], v[148:149], v[148:149], v[252:253]
	v_pk_fma_f32 v[254:255], v[150:151], v[150:151], v[254:255]
	v_pk_fma_f32 v[252:253], v[152:153], v[152:153], v[252:253]
	v_pk_fma_f32 v[254:255], v[154:155], v[154:155], v[254:255]
	v_pk_fma_f32 v[252:253], v[156:157], v[156:157], v[252:253]
	v_pk_fma_f32 v[254:255], v[158:159], v[158:159], v[254:255]
	v_pk_add_f32 v[252:253], v[252:253], v[254:255]
	s_nop 0
	v_add_f32_e32 v183, v252, v253
	s_nop 1
	v_add_f32_dpp v183, v183, v183 quad_perm:[1,0,3,2] row_mask:0xf bank_mask:0xf bound_ctrl:1
	s_nop 1
	v_add_f32_dpp v183, v183, v183 quad_perm:[2,3,0,1] row_mask:0xf bank_mask:0xf bound_ctrl:1
	s_nop 1
	v_add_f32_dpp v183, v183, v183 row_half_mirror row_mask:0xf bank_mask:0xf bound_ctrl:1
	s_nop 1
	v_add_f32_dpp v183, v183, v183 row_mirror row_mask:0xf bank_mask:0xf bound_ctrl:1
	s_nop 1
	v_readlane_b32 s98, v183, 0
	v_readlane_b32 s99, v183, 16
	v_readlane_b32 s100, v183, 32
	v_readlane_b32 s101, v183, 48
	s_nop 1
	v_mov_b32_e32 v183, s98
	v_add_f32_e32 v183, s99, v183
	v_add_f32_e32 v183, s100, v183
	v_add_f32_e32 v183, s101, v183
	v_fmamk_f32 v183, v183, 0x3a800000, v182
	v_cmp_gt_f32_e32 vcc, 0x800000, v183
	v_mul_f32_e32 v181, 0x4b800000, v183
	s_nop 1
	v_cndmask_b32_e32 v183, v183, v181, vcc
	v_rsq_f32_e32 v183, v183
	s_nop 0
	v_mul_f32_e32 v181, 0x45800000, v183
	v_cndmask_b32_e32 v184, v183, v181, vcc
	v_mov_b32_e32 v185, v184
	v_cvt_pk_bf16_f32 v32, v144, v145
	v_cvt_pk_bf16_f32 v33, v146, v147
	v_cvt_pk_bf16_f32 v34, v148, v149
	v_cvt_pk_bf16_f32 v35, v150, v151
	v_cvt_pk_bf16_f32 v36, v152, v153
	v_cvt_pk_bf16_f32 v37, v154, v155
	v_cvt_pk_bf16_f32 v38, v156, v157
	v_cvt_pk_bf16_f32 v39, v158, v159
	v_add_u32_e32 v181, 0x2000000, v177
	global_store_dwordx4 v181, v[32:35], s[78:79]
	global_store_dwordx4 v181, v[36:39], s[78:79] offset:1024
	v_add_u32_e32 v236, 0x4000, v237
	s_mov_b64 exec, 1
	global_store_dword v236, v184, s[78:79]
	s_mov_b64 exec, -1
	s_waitcnt vmcnt(16)
	v_lshlrev_b32_e32 v144, 16, v48
	v_and_b32_e32 v145, 0xffff0000, v48
	v_lshlrev_b32_e32 v146, 16, v49
	v_and_b32_e32 v147, 0xffff0000, v49
	v_lshlrev_b32_e32 v148, 16, v50
	v_and_b32_e32 v149, 0xffff0000, v50
	v_lshlrev_b32_e32 v150, 16, v51
	v_and_b32_e32 v151, 0xffff0000, v51
	v_lshlrev_b32_e32 v152, 16, v52
	v_and_b32_e32 v153, 0xffff0000, v52
	v_lshlrev_b32_e32 v154, 16, v53
	v_and_b32_e32 v155, 0xffff0000, v53
	v_lshlrev_b32_e32 v156, 16, v54
	v_and_b32_e32 v157, 0xffff0000, v54
	v_lshlrev_b32_e32 v158, 16, v55
	v_and_b32_e32 v159, 0xffff0000, v55
	v_lshlrev_b32_e32 v160, 16, v56
	v_and_b32_e32 v161, 0xffff0000, v56
	v_lshlrev_b32_e32 v162, 16, v57
	v_and_b32_e32 v163, 0xffff0000, v57
	v_lshlrev_b32_e32 v164, 16, v58
	v_and_b32_e32 v165, 0xffff0000, v58
	v_lshlrev_b32_e32 v166, 16, v59
	v_and_b32_e32 v167, 0xffff0000, v59
	v_lshlrev_b32_e32 v168, 16, v60
	v_and_b32_e32 v169, 0xffff0000, v60
	v_lshlrev_b32_e32 v170, 16, v61
	v_and_b32_e32 v171, 0xffff0000, v61
	v_lshlrev_b32_e32 v172, 16, v62
	v_and_b32_e32 v173, 0xffff0000, v62
	v_lshlrev_b32_e32 v174, 16, v63
	v_and_b32_e32 v175, 0xffff0000, v63
	v_pk_mul_f32 v[252:253], v[160:161], v[160:161]
	v_pk_mul_f32 v[254:255], v[162:163], v[162:163]
	v_pk_fma_f32 v[252:253], v[164:165], v[164:165], v[252:253]
	v_pk_fma_f32 v[254:255], v[166:167], v[166:167], v[254:255]
	v_pk_fma_f32 v[252:253], v[168:169], v[168:169], v[252:253]
	v_pk_fma_f32 v[254:255], v[170:171], v[170:171], v[254:255]
	v_pk_fma_f32 v[252:253], v[172:173], v[172:173], v[252:253]
	v_pk_fma_f32 v[254:255], v[174:175], v[174:175], v[254:255]
	v_pk_add_f32 v[252:253], v[252:253], v[254:255]
	s_nop 0
	v_add_f32_e32 v183, v252, v253
	s_nop 1
	v_add_f32_dpp v183, v183, v183 quad_perm:[1,0,3,2] row_mask:0xf bank_mask:0xf bound_ctrl:1
	s_nop 1
	v_add_f32_dpp v183, v183, v183 quad_perm:[2,3,0,1] row_mask:0xf bank_mask:0xf bound_ctrl:1
	s_nop 1
	v_add_f32_dpp v183, v183, v183 row_half_mirror row_mask:0xf bank_mask:0xf bound_ctrl:1
	s_nop 1
	v_add_f32_dpp v183, v183, v183 row_mirror row_mask:0xf bank_mask:0xf bound_ctrl:1
	s_nop 1
	v_readlane_b32 s98, v183, 0
	v_readlane_b32 s99, v183, 16
	v_readlane_b32 s100, v183, 32
	v_readlane_b32 s101, v183, 48
	s_nop 1
	v_mov_b32_e32 v183, s98
	v_add_f32_e32 v183, s99, v183
	v_add_f32_e32 v183, s100, v183
	v_add_f32_e32 v183, s101, v183
	v_fmamk_f32 v183, v183, 0x3a800000, v182
	v_cmp_gt_f32_e32 vcc, 0x800000, v183
	v_mul_f32_e32 v181, 0x4b800000, v183
	s_nop 1
	v_cndmask_b32_e32 v183, v183, v181, vcc
	v_rsq_f32_e32 v183, v183
	s_nop 0
	v_mul_f32_e32 v181, 0x45800000, v183
	v_cndmask_b32_e32 v184, v183, v181, vcc
	v_mov_b32_e32 v185, v184
	v_pk_mul_f32 v[160:161], v[160:161], v[184:185]
	v_pk_mul_f32 v[162:163], v[162:163], v[184:185]
	v_pk_mul_f32 v[164:165], v[164:165], v[184:185]
	v_pk_mul_f32 v[166:167], v[166:167], v[184:185]
	v_pk_mul_f32 v[168:169], v[168:169], v[184:185]
	v_pk_mul_f32 v[170:171], v[170:171], v[184:185]
	v_pk_mul_f32 v[172:173], v[172:173], v[184:185]
	v_pk_mul_f32 v[174:175], v[174:175], v[184:185]
	v_pk_fma_f32 v[144:145], v[160:161], v[128:129], v[144:145]
	v_pk_fma_f32 v[146:147], v[162:163], v[130:131], v[146:147]
	v_pk_fma_f32 v[148:149], v[164:165], v[132:133], v[148:149]
	v_pk_fma_f32 v[150:151], v[166:167], v[134:135], v[150:151]
	v_pk_fma_f32 v[152:153], v[168:169], v[136:137], v[152:153]
	v_pk_fma_f32 v[154:155], v[170:171], v[138:139], v[154:155]
	v_pk_fma_f32 v[156:157], v[172:173], v[140:141], v[156:157]
	v_pk_fma_f32 v[158:159], v[174:175], v[142:143], v[158:159]
	v_pk_mul_f32 v[252:253], v[144:145], v[144:145]
	v_pk_mul_f32 v[254:255], v[146:147], v[146:147]
	v_pk_fma_f32 v[252:253], v[148:149], v[148:149], v[252:253]
	v_pk_fma_f32 v[254:255], v[150:151], v[150:151], v[254:255]
	v_pk_fma_f32 v[252:253], v[152:153], v[152:153], v[252:253]
	v_pk_fma_f32 v[254:255], v[154:155], v[154:155], v[254:255]
	v_pk_fma_f32 v[252:253], v[156:157], v[156:157], v[252:253]
	v_pk_fma_f32 v[254:255], v[158:159], v[158:159], v[254:255]
	v_pk_add_f32 v[252:253], v[252:253], v[254:255]
	s_nop 0
	v_add_f32_e32 v183, v252, v253
	s_nop 1
	v_add_f32_dpp v183, v183, v183 quad_perm:[1,0,3,2] row_mask:0xf bank_mask:0xf bound_ctrl:1
	s_nop 1
	v_add_f32_dpp v183, v183, v183 quad_perm:[2,3,0,1] row_mask:0xf bank_mask:0xf bound_ctrl:1
	s_nop 1
	v_add_f32_dpp v183, v183, v183 row_half_mirror row_mask:0xf bank_mask:0xf bound_ctrl:1
	s_nop 1
	v_add_f32_dpp v183, v183, v183 row_mirror row_mask:0xf bank_mask:0xf bound_ctrl:1
	s_nop 1
	v_readlane_b32 s98, v183, 0
	v_readlane_b32 s99, v183, 16
	v_readlane_b32 s100, v183, 32
	v_readlane_b32 s101, v183, 48
	s_nop 1
	v_mov_b32_e32 v183, s98
	v_add_f32_e32 v183, s99, v183
	v_add_f32_e32 v183, s100, v183
	v_add_f32_e32 v183, s101, v183
	v_fmamk_f32 v183, v183, 0x3a800000, v182
	v_cmp_gt_f32_e32 vcc, 0x800000, v183
	v_mul_f32_e32 v181, 0x4b800000, v183
	s_nop 1
	v_cndmask_b32_e32 v183, v183, v181, vcc
	v_rsq_f32_e32 v183, v183
	s_nop 0
	v_mul_f32_e32 v181, 0x45800000, v183
	v_cndmask_b32_e32 v184, v183, v181, vcc
	v_mov_b32_e32 v185, v184
	v_cvt_pk_bf16_f32 v48, v144, v145
	v_cvt_pk_bf16_f32 v49, v146, v147
	v_cvt_pk_bf16_f32 v50, v148, v149
	v_cvt_pk_bf16_f32 v51, v150, v151
	v_cvt_pk_bf16_f32 v52, v152, v153
	v_cvt_pk_bf16_f32 v53, v154, v155
	v_cvt_pk_bf16_f32 v54, v156, v157
	v_cvt_pk_bf16_f32 v55, v158, v159
	v_add_u32_e32 v181, 0x2400000, v177
	global_store_dwordx4 v181, v[48:51], s[78:79]
	global_store_dwordx4 v181, v[52:55], s[78:79] offset:1024
	v_add_u32_e32 v236, 0x6000, v237
	s_mov_b64 exec, 1
	global_store_dword v236, v184, s[78:79]
	s_mov_b64 exec, -1
	s_waitcnt vmcnt(12)
	v_lshlrev_b32_e32 v144, 16, v64
	v_and_b32_e32 v145, 0xffff0000, v64
	v_lshlrev_b32_e32 v146, 16, v65
	v_and_b32_e32 v147, 0xffff0000, v65
	v_lshlrev_b32_e32 v148, 16, v66
	v_and_b32_e32 v149, 0xffff0000, v66
	v_lshlrev_b32_e32 v150, 16, v67
	v_and_b32_e32 v151, 0xffff0000, v67
	v_lshlrev_b32_e32 v152, 16, v68
	v_and_b32_e32 v153, 0xffff0000, v68
	v_lshlrev_b32_e32 v154, 16, v69
	v_and_b32_e32 v155, 0xffff0000, v69
	v_lshlrev_b32_e32 v156, 16, v70
	v_and_b32_e32 v157, 0xffff0000, v70
	v_lshlrev_b32_e32 v158, 16, v71
	v_and_b32_e32 v159, 0xffff0000, v71
	v_lshlrev_b32_e32 v160, 16, v72
	v_and_b32_e32 v161, 0xffff0000, v72
	v_lshlrev_b32_e32 v162, 16, v73
	v_and_b32_e32 v163, 0xffff0000, v73
	v_lshlrev_b32_e32 v164, 16, v74
	v_and_b32_e32 v165, 0xffff0000, v74
	v_lshlrev_b32_e32 v166, 16, v75
	v_and_b32_e32 v167, 0xffff0000, v75
	v_lshlrev_b32_e32 v168, 16, v76
	v_and_b32_e32 v169, 0xffff0000, v76
	v_lshlrev_b32_e32 v170, 16, v77
	v_and_b32_e32 v171, 0xffff0000, v77
	v_lshlrev_b32_e32 v172, 16, v78
	v_and_b32_e32 v173, 0xffff0000, v78
	v_lshlrev_b32_e32 v174, 16, v79
	v_and_b32_e32 v175, 0xffff0000, v79
	v_pk_mul_f32 v[252:253], v[160:161], v[160:161]
	v_pk_mul_f32 v[254:255], v[162:163], v[162:163]
	v_pk_fma_f32 v[252:253], v[164:165], v[164:165], v[252:253]
	v_pk_fma_f32 v[254:255], v[166:167], v[166:167], v[254:255]
	v_pk_fma_f32 v[252:253], v[168:169], v[168:169], v[252:253]
	v_pk_fma_f32 v[254:255], v[170:171], v[170:171], v[254:255]
	v_pk_fma_f32 v[252:253], v[172:173], v[172:173], v[252:253]
	v_pk_fma_f32 v[254:255], v[174:175], v[174:175], v[254:255]
	v_pk_add_f32 v[252:253], v[252:253], v[254:255]
	s_nop 0
	v_add_f32_e32 v183, v252, v253
	s_nop 1
	v_add_f32_dpp v183, v183, v183 quad_perm:[1,0,3,2] row_mask:0xf bank_mask:0xf bound_ctrl:1
	s_nop 1
	v_add_f32_dpp v183, v183, v183 quad_perm:[2,3,0,1] row_mask:0xf bank_mask:0xf bound_ctrl:1
	s_nop 1
	v_add_f32_dpp v183, v183, v183 row_half_mirror row_mask:0xf bank_mask:0xf bound_ctrl:1
	s_nop 1
	v_add_f32_dpp v183, v183, v183 row_mirror row_mask:0xf bank_mask:0xf bound_ctrl:1
	s_nop 1
	v_readlane_b32 s98, v183, 0
	v_readlane_b32 s99, v183, 16
	v_readlane_b32 s100, v183, 32
	v_readlane_b32 s101, v183, 48
	s_nop 1
	v_mov_b32_e32 v183, s98
	v_add_f32_e32 v183, s99, v183
	v_add_f32_e32 v183, s100, v183
	v_add_f32_e32 v183, s101, v183
	v_fmamk_f32 v183, v183, 0x3a800000, v182
	v_cmp_gt_f32_e32 vcc, 0x800000, v183
	v_mul_f32_e32 v181, 0x4b800000, v183
	s_nop 1
	v_cndmask_b32_e32 v183, v183, v181, vcc
	v_rsq_f32_e32 v183, v183
	s_nop 0
	v_mul_f32_e32 v181, 0x45800000, v183
	v_cndmask_b32_e32 v184, v183, v181, vcc
	v_mov_b32_e32 v185, v184
	v_pk_mul_f32 v[160:161], v[160:161], v[184:185]
	v_pk_mul_f32 v[162:163], v[162:163], v[184:185]
	v_pk_mul_f32 v[164:165], v[164:165], v[184:185]
	v_pk_mul_f32 v[166:167], v[166:167], v[184:185]
	v_pk_mul_f32 v[168:169], v[168:169], v[184:185]
	v_pk_mul_f32 v[170:171], v[170:171], v[184:185]
	v_pk_mul_f32 v[172:173], v[172:173], v[184:185]
	v_pk_mul_f32 v[174:175], v[174:175], v[184:185]
	v_pk_fma_f32 v[144:145], v[160:161], v[128:129], v[144:145]
	v_pk_fma_f32 v[146:147], v[162:163], v[130:131], v[146:147]
	v_pk_fma_f32 v[148:149], v[164:165], v[132:133], v[148:149]
	v_pk_fma_f32 v[150:151], v[166:167], v[134:135], v[150:151]
	v_pk_fma_f32 v[152:153], v[168:169], v[136:137], v[152:153]
	v_pk_fma_f32 v[154:155], v[170:171], v[138:139], v[154:155]
	v_pk_fma_f32 v[156:157], v[172:173], v[140:141], v[156:157]
	v_pk_fma_f32 v[158:159], v[174:175], v[142:143], v[158:159]
	v_pk_mul_f32 v[252:253], v[144:145], v[144:145]
	v_pk_mul_f32 v[254:255], v[146:147], v[146:147]
	v_pk_fma_f32 v[252:253], v[148:149], v[148:149], v[252:253]
	v_pk_fma_f32 v[254:255], v[150:151], v[150:151], v[254:255]
	v_pk_fma_f32 v[252:253], v[152:153], v[152:153], v[252:253]
	v_pk_fma_f32 v[254:255], v[154:155], v[154:155], v[254:255]
	v_pk_fma_f32 v[252:253], v[156:157], v[156:157], v[252:253]
	v_pk_fma_f32 v[254:255], v[158:159], v[158:159], v[254:255]
	v_pk_add_f32 v[252:253], v[252:253], v[254:255]
	s_nop 0
	v_add_f32_e32 v183, v252, v253
	s_nop 1
	v_add_f32_dpp v183, v183, v183 quad_perm:[1,0,3,2] row_mask:0xf bank_mask:0xf bound_ctrl:1
	s_nop 1
	v_add_f32_dpp v183, v183, v183 quad_perm:[2,3,0,1] row_mask:0xf bank_mask:0xf bound_ctrl:1
	s_nop 1
	v_add_f32_dpp v183, v183, v183 row_half_mirror row_mask:0xf bank_mask:0xf bound_ctrl:1
	s_nop 1
	v_add_f32_dpp v183, v183, v183 row_mirror row_mask:0xf bank_mask:0xf bound_ctrl:1
	s_nop 1
	v_readlane_b32 s98, v183, 0
	v_readlane_b32 s99, v183, 16
	v_readlane_b32 s100, v183, 32
	v_readlane_b32 s101, v183, 48
	s_nop 1
	v_mov_b32_e32 v183, s98
	v_add_f32_e32 v183, s99, v183
	v_add_f32_e32 v183, s100, v183
	v_add_f32_e32 v183, s101, v183
	v_fmamk_f32 v183, v183, 0x3a800000, v182
	v_cmp_gt_f32_e32 vcc, 0x800000, v183
	v_mul_f32_e32 v181, 0x4b800000, v183
	s_nop 1
	v_cndmask_b32_e32 v183, v183, v181, vcc
	v_rsq_f32_e32 v183, v183
	s_nop 0
	v_mul_f32_e32 v181, 0x45800000, v183
	v_cndmask_b32_e32 v184, v183, v181, vcc
	v_mov_b32_e32 v185, v184
	v_cvt_pk_bf16_f32 v64, v144, v145
	v_cvt_pk_bf16_f32 v65, v146, v147
	v_cvt_pk_bf16_f32 v66, v148, v149
	v_cvt_pk_bf16_f32 v67, v150, v151
	v_cvt_pk_bf16_f32 v68, v152, v153
	v_cvt_pk_bf16_f32 v69, v154, v155
	v_cvt_pk_bf16_f32 v70, v156, v157
	v_cvt_pk_bf16_f32 v71, v158, v159
	v_add_u32_e32 v181, 0x2800000, v177
	global_store_dwordx4 v181, v[64:67], s[78:79]
	global_store_dwordx4 v181, v[68:71], s[78:79] offset:1024
	v_add_u32_e32 v236, 0x8000, v237
	s_mov_b64 exec, 1
	global_store_dword v236, v184, s[78:79]
	s_mov_b64 exec, -1
	s_waitcnt vmcnt(8)
	v_lshlrev_b32_e32 v144, 16, v80
	v_and_b32_e32 v145, 0xffff0000, v80
	v_lshlrev_b32_e32 v146, 16, v81
	v_and_b32_e32 v147, 0xffff0000, v81
	v_lshlrev_b32_e32 v148, 16, v82
	v_and_b32_e32 v149, 0xffff0000, v82
	v_lshlrev_b32_e32 v150, 16, v83
	v_and_b32_e32 v151, 0xffff0000, v83
	v_lshlrev_b32_e32 v152, 16, v84
	v_and_b32_e32 v153, 0xffff0000, v84
	v_lshlrev_b32_e32 v154, 16, v85
	v_and_b32_e32 v155, 0xffff0000, v85
	v_lshlrev_b32_e32 v156, 16, v86
	v_and_b32_e32 v157, 0xffff0000, v86
	v_lshlrev_b32_e32 v158, 16, v87
	v_and_b32_e32 v159, 0xffff0000, v87
	v_lshlrev_b32_e32 v160, 16, v88
	v_and_b32_e32 v161, 0xffff0000, v88
	v_lshlrev_b32_e32 v162, 16, v89
	v_and_b32_e32 v163, 0xffff0000, v89
	v_lshlrev_b32_e32 v164, 16, v90
	v_and_b32_e32 v165, 0xffff0000, v90
	v_lshlrev_b32_e32 v166, 16, v91
	v_and_b32_e32 v167, 0xffff0000, v91
	v_lshlrev_b32_e32 v168, 16, v92
	v_and_b32_e32 v169, 0xffff0000, v92
	v_lshlrev_b32_e32 v170, 16, v93
	v_and_b32_e32 v171, 0xffff0000, v93
	v_lshlrev_b32_e32 v172, 16, v94
	v_and_b32_e32 v173, 0xffff0000, v94
	v_lshlrev_b32_e32 v174, 16, v95
	v_and_b32_e32 v175, 0xffff0000, v95
	v_pk_mul_f32 v[252:253], v[160:161], v[160:161]
	v_pk_mul_f32 v[254:255], v[162:163], v[162:163]
	v_pk_fma_f32 v[252:253], v[164:165], v[164:165], v[252:253]
	v_pk_fma_f32 v[254:255], v[166:167], v[166:167], v[254:255]
	v_pk_fma_f32 v[252:253], v[168:169], v[168:169], v[252:253]
	v_pk_fma_f32 v[254:255], v[170:171], v[170:171], v[254:255]
	v_pk_fma_f32 v[252:253], v[172:173], v[172:173], v[252:253]
	v_pk_fma_f32 v[254:255], v[174:175], v[174:175], v[254:255]
	v_pk_add_f32 v[252:253], v[252:253], v[254:255]
	s_nop 0
	v_add_f32_e32 v183, v252, v253
	s_nop 1
	v_add_f32_dpp v183, v183, v183 quad_perm:[1,0,3,2] row_mask:0xf bank_mask:0xf bound_ctrl:1
	s_nop 1
	v_add_f32_dpp v183, v183, v183 quad_perm:[2,3,0,1] row_mask:0xf bank_mask:0xf bound_ctrl:1
	s_nop 1
	v_add_f32_dpp v183, v183, v183 row_half_mirror row_mask:0xf bank_mask:0xf bound_ctrl:1
	s_nop 1
	v_add_f32_dpp v183, v183, v183 row_mirror row_mask:0xf bank_mask:0xf bound_ctrl:1
	s_nop 1
	v_readlane_b32 s98, v183, 0
	v_readlane_b32 s99, v183, 16
	v_readlane_b32 s100, v183, 32
	v_readlane_b32 s101, v183, 48
	s_nop 1
	v_mov_b32_e32 v183, s98
	v_add_f32_e32 v183, s99, v183
	v_add_f32_e32 v183, s100, v183
	v_add_f32_e32 v183, s101, v183
	v_fmamk_f32 v183, v183, 0x3a800000, v182
	v_cmp_gt_f32_e32 vcc, 0x800000, v183
	v_mul_f32_e32 v181, 0x4b800000, v183
	s_nop 1
	v_cndmask_b32_e32 v183, v183, v181, vcc
	v_rsq_f32_e32 v183, v183
	s_nop 0
	v_mul_f32_e32 v181, 0x45800000, v183
	v_cndmask_b32_e32 v184, v183, v181, vcc
	v_mov_b32_e32 v185, v184
	v_pk_mul_f32 v[160:161], v[160:161], v[184:185]
	v_pk_mul_f32 v[162:163], v[162:163], v[184:185]
	v_pk_mul_f32 v[164:165], v[164:165], v[184:185]
	v_pk_mul_f32 v[166:167], v[166:167], v[184:185]
	v_pk_mul_f32 v[168:169], v[168:169], v[184:185]
	v_pk_mul_f32 v[170:171], v[170:171], v[184:185]
	v_pk_mul_f32 v[172:173], v[172:173], v[184:185]
	v_pk_mul_f32 v[174:175], v[174:175], v[184:185]
	v_pk_fma_f32 v[144:145], v[160:161], v[128:129], v[144:145]
	v_pk_fma_f32 v[146:147], v[162:163], v[130:131], v[146:147]
	v_pk_fma_f32 v[148:149], v[164:165], v[132:133], v[148:149]
	v_pk_fma_f32 v[150:151], v[166:167], v[134:135], v[150:151]
	v_pk_fma_f32 v[152:153], v[168:169], v[136:137], v[152:153]
	v_pk_fma_f32 v[154:155], v[170:171], v[138:139], v[154:155]
	v_pk_fma_f32 v[156:157], v[172:173], v[140:141], v[156:157]
	v_pk_fma_f32 v[158:159], v[174:175], v[142:143], v[158:159]
	v_pk_mul_f32 v[252:253], v[144:145], v[144:145]
	v_pk_mul_f32 v[254:255], v[146:147], v[146:147]
	v_pk_fma_f32 v[252:253], v[148:149], v[148:149], v[252:253]
	v_pk_fma_f32 v[254:255], v[150:151], v[150:151], v[254:255]
	v_pk_fma_f32 v[252:253], v[152:153], v[152:153], v[252:253]
	v_pk_fma_f32 v[254:255], v[154:155], v[154:155], v[254:255]
	v_pk_fma_f32 v[252:253], v[156:157], v[156:157], v[252:253]
	v_pk_fma_f32 v[254:255], v[158:159], v[158:159], v[254:255]
	v_pk_add_f32 v[252:253], v[252:253], v[254:255]
	s_nop 0
	v_add_f32_e32 v183, v252, v253
	s_nop 1
	v_add_f32_dpp v183, v183, v183 quad_perm:[1,0,3,2] row_mask:0xf bank_mask:0xf bound_ctrl:1
	s_nop 1
	v_add_f32_dpp v183, v183, v183 quad_perm:[2,3,0,1] row_mask:0xf bank_mask:0xf bound_ctrl:1
	s_nop 1
	v_add_f32_dpp v183, v183, v183 row_half_mirror row_mask:0xf bank_mask:0xf bound_ctrl:1
	s_nop 1
	v_add_f32_dpp v183, v183, v183 row_mirror row_mask:0xf bank_mask:0xf bound_ctrl:1
	s_nop 1
	v_readlane_b32 s98, v183, 0
	v_readlane_b32 s99, v183, 16
	v_readlane_b32 s100, v183, 32
	v_readlane_b32 s101, v183, 48
	s_nop 1
	v_mov_b32_e32 v183, s98
	v_add_f32_e32 v183, s99, v183
	v_add_f32_e32 v183, s100, v183
	v_add_f32_e32 v183, s101, v183
	v_fmamk_f32 v183, v183, 0x3a800000, v182
	v_cmp_gt_f32_e32 vcc, 0x800000, v183
	v_mul_f32_e32 v181, 0x4b800000, v183
	s_nop 1
	v_cndmask_b32_e32 v183, v183, v181, vcc
	v_rsq_f32_e32 v183, v183
	s_nop 0
	v_mul_f32_e32 v181, 0x45800000, v183
	v_cndmask_b32_e32 v184, v183, v181, vcc
	v_mov_b32_e32 v185, v184
	v_cvt_pk_bf16_f32 v80, v144, v145
	v_cvt_pk_bf16_f32 v81, v146, v147
	v_cvt_pk_bf16_f32 v82, v148, v149
	v_cvt_pk_bf16_f32 v83, v150, v151
	v_cvt_pk_bf16_f32 v84, v152, v153
	v_cvt_pk_bf16_f32 v85, v154, v155
	v_cvt_pk_bf16_f32 v86, v156, v157
	v_cvt_pk_bf16_f32 v87, v158, v159
	v_add_u32_e32 v181, 0x2c00000, v177
	global_store_dwordx4 v181, v[80:83], s[78:79]
	global_store_dwordx4 v181, v[84:87], s[78:79] offset:1024
	v_add_u32_e32 v236, 0xa000, v237
	s_mov_b64 exec, 1
	global_store_dword v236, v184, s[78:79]
	s_mov_b64 exec, -1
	s_waitcnt vmcnt(4)
	v_lshlrev_b32_e32 v144, 16, v96
	v_and_b32_e32 v145, 0xffff0000, v96
	v_lshlrev_b32_e32 v146, 16, v97
	v_and_b32_e32 v147, 0xffff0000, v97
	v_lshlrev_b32_e32 v148, 16, v98
	v_and_b32_e32 v149, 0xffff0000, v98
	v_lshlrev_b32_e32 v150, 16, v99
	v_and_b32_e32 v151, 0xffff0000, v99
	v_lshlrev_b32_e32 v152, 16, v100
	v_and_b32_e32 v153, 0xffff0000, v100
	v_lshlrev_b32_e32 v154, 16, v101
	v_and_b32_e32 v155, 0xffff0000, v101
	v_lshlrev_b32_e32 v156, 16, v102
	v_and_b32_e32 v157, 0xffff0000, v102
	v_lshlrev_b32_e32 v158, 16, v103
	v_and_b32_e32 v159, 0xffff0000, v103
	v_lshlrev_b32_e32 v160, 16, v104
	v_and_b32_e32 v161, 0xffff0000, v104
	v_lshlrev_b32_e32 v162, 16, v105
	v_and_b32_e32 v163, 0xffff0000, v105
	v_lshlrev_b32_e32 v164, 16, v106
	v_and_b32_e32 v165, 0xffff0000, v106
	v_lshlrev_b32_e32 v166, 16, v107
	v_and_b32_e32 v167, 0xffff0000, v107
	v_lshlrev_b32_e32 v168, 16, v108
	v_and_b32_e32 v169, 0xffff0000, v108
	v_lshlrev_b32_e32 v170, 16, v109
	v_and_b32_e32 v171, 0xffff0000, v109
	v_lshlrev_b32_e32 v172, 16, v110
	v_and_b32_e32 v173, 0xffff0000, v110
	v_lshlrev_b32_e32 v174, 16, v111
	v_and_b32_e32 v175, 0xffff0000, v111
	v_pk_mul_f32 v[252:253], v[160:161], v[160:161]
	v_pk_mul_f32 v[254:255], v[162:163], v[162:163]
	v_pk_fma_f32 v[252:253], v[164:165], v[164:165], v[252:253]
	v_pk_fma_f32 v[254:255], v[166:167], v[166:167], v[254:255]
	v_pk_fma_f32 v[252:253], v[168:169], v[168:169], v[252:253]
	v_pk_fma_f32 v[254:255], v[170:171], v[170:171], v[254:255]
	v_pk_fma_f32 v[252:253], v[172:173], v[172:173], v[252:253]
	v_pk_fma_f32 v[254:255], v[174:175], v[174:175], v[254:255]
	v_pk_add_f32 v[252:253], v[252:253], v[254:255]
	s_nop 0
	v_add_f32_e32 v183, v252, v253
	s_nop 1
	v_add_f32_dpp v183, v183, v183 quad_perm:[1,0,3,2] row_mask:0xf bank_mask:0xf bound_ctrl:1
	s_nop 1
	v_add_f32_dpp v183, v183, v183 quad_perm:[2,3,0,1] row_mask:0xf bank_mask:0xf bound_ctrl:1
	s_nop 1
	v_add_f32_dpp v183, v183, v183 row_half_mirror row_mask:0xf bank_mask:0xf bound_ctrl:1
	s_nop 1
	v_add_f32_dpp v183, v183, v183 row_mirror row_mask:0xf bank_mask:0xf bound_ctrl:1
	s_nop 1
	v_readlane_b32 s98, v183, 0
	v_readlane_b32 s99, v183, 16
	v_readlane_b32 s100, v183, 32
	v_readlane_b32 s101, v183, 48
	s_nop 1
	v_mov_b32_e32 v183, s98
	v_add_f32_e32 v183, s99, v183
	v_add_f32_e32 v183, s100, v183
	v_add_f32_e32 v183, s101, v183
	v_fmamk_f32 v183, v183, 0x3a800000, v182
	v_cmp_gt_f32_e32 vcc, 0x800000, v183
	v_mul_f32_e32 v181, 0x4b800000, v183
	s_nop 1
	v_cndmask_b32_e32 v183, v183, v181, vcc
	v_rsq_f32_e32 v183, v183
	s_nop 0
	v_mul_f32_e32 v181, 0x45800000, v183
	v_cndmask_b32_e32 v184, v183, v181, vcc
	v_mov_b32_e32 v185, v184
	v_pk_mul_f32 v[160:161], v[160:161], v[184:185]
	v_pk_mul_f32 v[162:163], v[162:163], v[184:185]
	v_pk_mul_f32 v[164:165], v[164:165], v[184:185]
	v_pk_mul_f32 v[166:167], v[166:167], v[184:185]
	v_pk_mul_f32 v[168:169], v[168:169], v[184:185]
	v_pk_mul_f32 v[170:171], v[170:171], v[184:185]
	v_pk_mul_f32 v[172:173], v[172:173], v[184:185]
	v_pk_mul_f32 v[174:175], v[174:175], v[184:185]
	v_pk_fma_f32 v[144:145], v[160:161], v[128:129], v[144:145]
	v_pk_fma_f32 v[146:147], v[162:163], v[130:131], v[146:147]
	v_pk_fma_f32 v[148:149], v[164:165], v[132:133], v[148:149]
	v_pk_fma_f32 v[150:151], v[166:167], v[134:135], v[150:151]
	v_pk_fma_f32 v[152:153], v[168:169], v[136:137], v[152:153]
	v_pk_fma_f32 v[154:155], v[170:171], v[138:139], v[154:155]
	v_pk_fma_f32 v[156:157], v[172:173], v[140:141], v[156:157]
	v_pk_fma_f32 v[158:159], v[174:175], v[142:143], v[158:159]
	v_pk_mul_f32 v[252:253], v[144:145], v[144:145]
	v_pk_mul_f32 v[254:255], v[146:147], v[146:147]
	v_pk_fma_f32 v[252:253], v[148:149], v[148:149], v[252:253]
	v_pk_fma_f32 v[254:255], v[150:151], v[150:151], v[254:255]
	v_pk_fma_f32 v[252:253], v[152:153], v[152:153], v[252:253]
	v_pk_fma_f32 v[254:255], v[154:155], v[154:155], v[254:255]
	v_pk_fma_f32 v[252:253], v[156:157], v[156:157], v[252:253]
	v_pk_fma_f32 v[254:255], v[158:159], v[158:159], v[254:255]
	v_pk_add_f32 v[252:253], v[252:253], v[254:255]
	s_nop 0
	v_add_f32_e32 v183, v252, v253
	s_nop 1
	v_add_f32_dpp v183, v183, v183 quad_perm:[1,0,3,2] row_mask:0xf bank_mask:0xf bound_ctrl:1
	s_nop 1
	v_add_f32_dpp v183, v183, v183 quad_perm:[2,3,0,1] row_mask:0xf bank_mask:0xf bound_ctrl:1
	s_nop 1
	v_add_f32_dpp v183, v183, v183 row_half_mirror row_mask:0xf bank_mask:0xf bound_ctrl:1
	s_nop 1
	v_add_f32_dpp v183, v183, v183 row_mirror row_mask:0xf bank_mask:0xf bound_ctrl:1
	s_nop 1
	v_readlane_b32 s98, v183, 0
	v_readlane_b32 s99, v183, 16
	v_readlane_b32 s100, v183, 32
	v_readlane_b32 s101, v183, 48
	s_nop 1
	v_mov_b32_e32 v183, s98
	v_add_f32_e32 v183, s99, v183
	v_add_f32_e32 v183, s100, v183
	v_add_f32_e32 v183, s101, v183
	v_fmamk_f32 v183, v183, 0x3a800000, v182
	v_cmp_gt_f32_e32 vcc, 0x800000, v183
	v_mul_f32_e32 v181, 0x4b800000, v183
	s_nop 1
	v_cndmask_b32_e32 v183, v183, v181, vcc
	v_rsq_f32_e32 v183, v183
	s_nop 0
	v_mul_f32_e32 v181, 0x45800000, v183
	v_cndmask_b32_e32 v184, v183, v181, vcc
	v_mov_b32_e32 v185, v184
	v_cvt_pk_bf16_f32 v96, v144, v145
	v_cvt_pk_bf16_f32 v97, v146, v147
	v_cvt_pk_bf16_f32 v98, v148, v149
	v_cvt_pk_bf16_f32 v99, v150, v151
	v_cvt_pk_bf16_f32 v100, v152, v153
	v_cvt_pk_bf16_f32 v101, v154, v155
	v_cvt_pk_bf16_f32 v102, v156, v157
	v_cvt_pk_bf16_f32 v103, v158, v159
	v_add_u32_e32 v181, 0x3000000, v177
	global_store_dwordx4 v181, v[96:99], s[78:79]
	global_store_dwordx4 v181, v[100:103], s[78:79] offset:1024
	v_add_u32_e32 v236, 0xc000, v237
	s_mov_b64 exec, 1
	global_store_dword v236, v184, s[78:79]
	s_mov_b64 exec, -1
	s_waitcnt vmcnt(0)
	v_lshlrev_b32_e32 v144, 16, v112
	v_and_b32_e32 v145, 0xffff0000, v112
	v_lshlrev_b32_e32 v146, 16, v113
	v_and_b32_e32 v147, 0xffff0000, v113
	v_lshlrev_b32_e32 v148, 16, v114
	v_and_b32_e32 v149, 0xffff0000, v114
	v_lshlrev_b32_e32 v150, 16, v115
	v_and_b32_e32 v151, 0xffff0000, v115
	v_lshlrev_b32_e32 v152, 16, v116
	v_and_b32_e32 v153, 0xffff0000, v116
	v_lshlrev_b32_e32 v154, 16, v117
	v_and_b32_e32 v155, 0xffff0000, v117
	v_lshlrev_b32_e32 v156, 16, v118
	v_and_b32_e32 v157, 0xffff0000, v118
	v_lshlrev_b32_e32 v158, 16, v119
	v_and_b32_e32 v159, 0xffff0000, v119
	v_lshlrev_b32_e32 v160, 16, v120
	v_and_b32_e32 v161, 0xffff0000, v120
	v_lshlrev_b32_e32 v162, 16, v121
	v_and_b32_e32 v163, 0xffff0000, v121
	v_lshlrev_b32_e32 v164, 16, v122
	v_and_b32_e32 v165, 0xffff0000, v122
	v_lshlrev_b32_e32 v166, 16, v123
	v_and_b32_e32 v167, 0xffff0000, v123
	v_lshlrev_b32_e32 v168, 16, v124
	v_and_b32_e32 v169, 0xffff0000, v124
	v_lshlrev_b32_e32 v170, 16, v125
	v_and_b32_e32 v171, 0xffff0000, v125
	v_lshlrev_b32_e32 v172, 16, v126
	v_and_b32_e32 v173, 0xffff0000, v126
	v_lshlrev_b32_e32 v174, 16, v127
	v_and_b32_e32 v175, 0xffff0000, v127
	v_pk_mul_f32 v[252:253], v[160:161], v[160:161]
	v_pk_mul_f32 v[254:255], v[162:163], v[162:163]
	v_pk_fma_f32 v[252:253], v[164:165], v[164:165], v[252:253]
	v_pk_fma_f32 v[254:255], v[166:167], v[166:167], v[254:255]
	v_pk_fma_f32 v[252:253], v[168:169], v[168:169], v[252:253]
	v_pk_fma_f32 v[254:255], v[170:171], v[170:171], v[254:255]
	v_pk_fma_f32 v[252:253], v[172:173], v[172:173], v[252:253]
	v_pk_fma_f32 v[254:255], v[174:175], v[174:175], v[254:255]
	v_pk_add_f32 v[252:253], v[252:253], v[254:255]
	s_nop 0
	v_add_f32_e32 v183, v252, v253
	s_nop 1
	v_add_f32_dpp v183, v183, v183 quad_perm:[1,0,3,2] row_mask:0xf bank_mask:0xf bound_ctrl:1
	s_nop 1
	v_add_f32_dpp v183, v183, v183 quad_perm:[2,3,0,1] row_mask:0xf bank_mask:0xf bound_ctrl:1
	s_nop 1
	v_add_f32_dpp v183, v183, v183 row_half_mirror row_mask:0xf bank_mask:0xf bound_ctrl:1
	s_nop 1
	v_add_f32_dpp v183, v183, v183 row_mirror row_mask:0xf bank_mask:0xf bound_ctrl:1
	s_nop 1
	v_readlane_b32 s98, v183, 0
	v_readlane_b32 s99, v183, 16
	v_readlane_b32 s100, v183, 32
	v_readlane_b32 s101, v183, 48
	s_nop 1
	v_mov_b32_e32 v183, s98
	v_add_f32_e32 v183, s99, v183
	v_add_f32_e32 v183, s100, v183
	v_add_f32_e32 v183, s101, v183
	v_fmamk_f32 v183, v183, 0x3a800000, v182
	v_cmp_gt_f32_e32 vcc, 0x800000, v183
	v_mul_f32_e32 v181, 0x4b800000, v183
	s_nop 1
	v_cndmask_b32_e32 v183, v183, v181, vcc
	v_rsq_f32_e32 v183, v183
	s_nop 0
	v_mul_f32_e32 v181, 0x45800000, v183
	v_cndmask_b32_e32 v184, v183, v181, vcc
	v_mov_b32_e32 v185, v184
	v_pk_mul_f32 v[160:161], v[160:161], v[184:185]
	v_pk_mul_f32 v[162:163], v[162:163], v[184:185]
	v_pk_mul_f32 v[164:165], v[164:165], v[184:185]
	v_pk_mul_f32 v[166:167], v[166:167], v[184:185]
	v_pk_mul_f32 v[168:169], v[168:169], v[184:185]
	v_pk_mul_f32 v[170:171], v[170:171], v[184:185]
	v_pk_mul_f32 v[172:173], v[172:173], v[184:185]
	v_pk_mul_f32 v[174:175], v[174:175], v[184:185]
	v_pk_fma_f32 v[144:145], v[160:161], v[128:129], v[144:145]
	v_pk_fma_f32 v[146:147], v[162:163], v[130:131], v[146:147]
	v_pk_fma_f32 v[148:149], v[164:165], v[132:133], v[148:149]
	v_pk_fma_f32 v[150:151], v[166:167], v[134:135], v[150:151]
	v_pk_fma_f32 v[152:153], v[168:169], v[136:137], v[152:153]
	v_pk_fma_f32 v[154:155], v[170:171], v[138:139], v[154:155]
	v_pk_fma_f32 v[156:157], v[172:173], v[140:141], v[156:157]
	v_pk_fma_f32 v[158:159], v[174:175], v[142:143], v[158:159]
	v_pk_mul_f32 v[252:253], v[144:145], v[144:145]
	v_pk_mul_f32 v[254:255], v[146:147], v[146:147]
	v_pk_fma_f32 v[252:253], v[148:149], v[148:149], v[252:253]
	v_pk_fma_f32 v[254:255], v[150:151], v[150:151], v[254:255]
	v_pk_fma_f32 v[252:253], v[152:153], v[152:153], v[252:253]
	v_pk_fma_f32 v[254:255], v[154:155], v[154:155], v[254:255]
	v_pk_fma_f32 v[252:253], v[156:157], v[156:157], v[252:253]
	v_pk_fma_f32 v[254:255], v[158:159], v[158:159], v[254:255]
	v_pk_add_f32 v[252:253], v[252:253], v[254:255]
	s_nop 0
	v_add_f32_e32 v183, v252, v253
	s_nop 1
	v_add_f32_dpp v183, v183, v183 quad_perm:[1,0,3,2] row_mask:0xf bank_mask:0xf bound_ctrl:1
	s_nop 1
	v_add_f32_dpp v183, v183, v183 quad_perm:[2,3,0,1] row_mask:0xf bank_mask:0xf bound_ctrl:1
	s_nop 1
	v_add_f32_dpp v183, v183, v183 row_half_mirror row_mask:0xf bank_mask:0xf bound_ctrl:1
	s_nop 1
	v_add_f32_dpp v183, v183, v183 row_mirror row_mask:0xf bank_mask:0xf bound_ctrl:1
	s_nop 1
	v_readlane_b32 s98, v183, 0
	v_readlane_b32 s99, v183, 16
	v_readlane_b32 s100, v183, 32
	v_readlane_b32 s101, v183, 48
	s_nop 1
	v_mov_b32_e32 v183, s98
	v_add_f32_e32 v183, s99, v183
	v_add_f32_e32 v183, s100, v183
	v_add_f32_e32 v183, s101, v183
	v_fmamk_f32 v183, v183, 0x3a800000, v182
	v_cmp_gt_f32_e32 vcc, 0x800000, v183
	v_mul_f32_e32 v181, 0x4b800000, v183
	s_nop 1
	v_cndmask_b32_e32 v183, v183, v181, vcc
	v_rsq_f32_e32 v183, v183
	s_nop 0
	v_mul_f32_e32 v181, 0x45800000, v183
	v_cndmask_b32_e32 v184, v183, v181, vcc
	v_mov_b32_e32 v185, v184
	v_cvt_pk_bf16_f32 v112, v144, v145
	v_cvt_pk_bf16_f32 v113, v146, v147
	v_cvt_pk_bf16_f32 v114, v148, v149
	v_cvt_pk_bf16_f32 v115, v150, v151
	v_cvt_pk_bf16_f32 v116, v152, v153
	v_cvt_pk_bf16_f32 v117, v154, v155
	v_cvt_pk_bf16_f32 v118, v156, v157
	v_cvt_pk_bf16_f32 v119, v158, v159
	v_add_u32_e32 v181, 0x3400000, v177
	global_store_dwordx4 v181, v[112:115], s[78:79]
	global_store_dwordx4 v181, v[116:119], s[78:79] offset:1024
	v_add_u32_e32 v236, 0xe000, v237
	s_mov_b64 exec, 1
	global_store_dword v236, v184, s[78:79]
	s_mov_b64 exec, -1
	v_readfirstlane_b32 s98, v179
	s_nop 3
	s_and_b32 s99, s98, 3
	s_cmp_lg_u32 s99, 0
	s_cbranch_scc1 .Lmyxupd_done_4
	v_lshrrev_b32_e32 v179, 2, v179
	v_lshlrev_b32_e32 v177, 4, v176
	v_lshl_add_u32 v177, v179, 11, v177
	v_lshlrev_b32_e32 v237, 2, v179
	v_add_u32_e32 v237, 0x10000, v237
	v_add_u32_e32 v181, 0x3800000, v177
	global_load_dwordx4 v[240:243], v181, s[78:79]
	global_load_dwordx4 v[244:247], v181, s[78:79] offset:1024
	v_lshl_add_u32 v183, v179, 12, v180
	v_add_u32_e32 v183, 0xbf00000, v183
	v_add_u32_e32 v181, 0x0, v183
	global_load_dwordx4 v[0:3], v181, s[78:79]
	global_load_dwordx4 v[4:7], v181, s[78:79] offset:16
	global_load_dwordx4 v[8:11], v181, s[78:79] offset:2048
	global_load_dwordx4 v[12:15], v181, s[78:79] offset:2064
	v_add_u32_e32 v181, 0x200000, v183
	global_load_dwordx4 v[16:19], v181, s[78:79]
	global_load_dwordx4 v[20:23], v181, s[78:79] offset:16
	global_load_dwordx4 v[24:27], v181, s[78:79] offset:2048
	global_load_dwordx4 v[28:31], v181, s[78:79] offset:2064
	v_add_u32_e32 v181, 0x400000, v183
	global_load_dwordx4 v[32:35], v181, s[78:79]
	global_load_dwordx4 v[36:39], v181, s[78:79] offset:16
	global_load_dwordx4 v[40:43], v181, s[78:79] offset:2048
	global_load_dwordx4 v[44:47], v181, s[78:79] offset:2064
	v_add_u32_e32 v181, 0x600000, v183
	global_load_dwordx4 v[48:51], v181, s[78:79]
	global_load_dwordx4 v[52:55], v181, s[78:79] offset:16
	global_load_dwordx4 v[56:59], v181, s[78:79] offset:2048
	global_load_dwordx4 v[60:63], v181, s[78:79] offset:2064
	v_add_u32_e32 v181, 0x800000, v183
	global_load_dwordx4 v[64:67], v181, s[78:79]
	global_load_dwordx4 v[68:71], v181, s[78:79] offset:16
	global_load_dwordx4 v[72:75], v181, s[78:79] offset:2048
	global_load_dwordx4 v[76:79], v181, s[78:79] offset:2064
	v_add_u32_e32 v181, 0xa00000, v183
	global_load_dwordx4 v[80:83], v181, s[78:79]
	global_load_dwordx4 v[84:87], v181, s[78:79] offset:16
	global_load_dwordx4 v[88:91], v181, s[78:79] offset:2048
	global_load_dwordx4 v[92:95], v181, s[78:79] offset:2064
	v_add_u32_e32 v181, 0xc00000, v183
	global_load_dwordx4 v[96:99], v181, s[78:79]
	global_load_dwordx4 v[100:103], v181, s[78:79] offset:16
	global_load_dwordx4 v[104:107], v181, s[78:79] offset:2048
	global_load_dwordx4 v[108:111], v181, s[78:79] offset:2064
	v_add_u32_e32 v181, 0xe00000, v183
	global_load_dwordx4 v[112:115], v181, s[78:79]
	global_load_dwordx4 v[116:119], v181, s[78:79] offset:16
	global_load_dwordx4 v[120:123], v181, s[78:79] offset:2048
	global_load_dwordx4 v[124:127], v181, s[78:79] offset:2064
	s_waitcnt vmcnt(28)
	v_pk_add_f32 v[160:161], v[0:1], 0 op_sel_hi:[1,0]
	v_pk_add_f32 v[162:163], v[2:3], 0 op_sel_hi:[1,0]
	v_pk_add_f32 v[164:165], v[4:5], 0 op_sel_hi:[1,0]
	v_pk_add_f32 v[166:167], v[6:7], 0 op_sel_hi:[1,0]
	v_pk_add_f32 v[168:169], v[8:9], 0 op_sel_hi:[1,0]
	v_pk_add_f32 v[170:171], v[10:11], 0 op_sel_hi:[1,0]
	v_pk_add_f32 v[172:173], v[12:13], 0 op_sel_hi:[1,0]
	v_pk_add_f32 v[174:175], v[14:15], 0 op_sel_hi:[1,0]
	s_waitcnt vmcnt(24)
	v_pk_add_f32 v[160:161], v[160:161], v[16:17]
	v_pk_add_f32 v[162:163], v[162:163], v[18:19]
	v_pk_add_f32 v[164:165], v[164:165], v[20:21]
	v_pk_add_f32 v[166:167], v[166:167], v[22:23]
	v_pk_add_f32 v[168:169], v[168:169], v[24:25]
	v_pk_add_f32 v[170:171], v[170:171], v[26:27]
	v_pk_add_f32 v[172:173], v[172:173], v[28:29]
	v_pk_add_f32 v[174:175], v[174:175], v[30:31]
	s_waitcnt vmcnt(20)
	v_pk_add_f32 v[160:161], v[160:161], v[32:33]
	v_pk_add_f32 v[162:163], v[162:163], v[34:35]
	v_pk_add_f32 v[164:165], v[164:165], v[36:37]
	v_pk_add_f32 v[166:167], v[166:167], v[38:39]
	v_pk_add_f32 v[168:169], v[168:169], v[40:41]
	v_pk_add_f32 v[170:171], v[170:171], v[42:43]
	v_pk_add_f32 v[172:173], v[172:173], v[44:45]
	v_pk_add_f32 v[174:175], v[174:175], v[46:47]
	s_waitcnt vmcnt(16)
	v_pk_add_f32 v[160:161], v[160:161], v[48:49]
	v_pk_add_f32 v[162:163], v[162:163], v[50:51]
	v_pk_add_f32 v[164:165], v[164:165], v[52:53]
	v_pk_add_f32 v[166:167], v[166:167], v[54:55]
	v_pk_add_f32 v[168:169], v[168:169], v[56:57]
	v_pk_add_f32 v[170:171], v[170:171], v[58:59]
	v_pk_add_f32 v[172:173], v[172:173], v[60:61]
	v_pk_add_f32 v[174:175], v[174:175], v[62:63]
	s_waitcnt vmcnt(12)
	v_pk_add_f32 v[160:161], v[160:161], v[64:65]
	v_pk_add_f32 v[162:163], v[162:163], v[66:67]
	v_pk_add_f32 v[164:165], v[164:165], v[68:69]
	v_pk_add_f32 v[166:167], v[166:167], v[70:71]
	v_pk_add_f32 v[168:169], v[168:169], v[72:73]
	v_pk_add_f32 v[170:171], v[170:171], v[74:75]
	v_pk_add_f32 v[172:173], v[172:173], v[76:77]
	v_pk_add_f32 v[174:175], v[174:175], v[78:79]
	s_waitcnt vmcnt(8)
	v_pk_add_f32 v[160:161], v[160:161], v[80:81]
	v_pk_add_f32 v[162:163], v[162:163], v[82:83]
	v_pk_add_f32 v[164:165], v[164:165], v[84:85]
	v_pk_add_f32 v[166:167], v[166:167], v[86:87]
	v_pk_add_f32 v[168:169], v[168:169], v[88:89]
	v_pk_add_f32 v[170:171], v[170:171], v[90:91]
	v_pk_add_f32 v[172:173], v[172:173], v[92:93]
	v_pk_add_f32 v[174:175], v[174:175], v[94:95]
	s_waitcnt vmcnt(4)
	v_pk_add_f32 v[160:161], v[160:161], v[96:97]
	v_pk_add_f32 v[162:163], v[162:163], v[98:99]
	v_pk_add_f32 v[164:165], v[164:165], v[100:101]
	v_pk_add_f32 v[166:167], v[166:167], v[102:103]
	v_pk_add_f32 v[168:169], v[168:169], v[104:105]
	v_pk_add_f32 v[170:171], v[170:171], v[106:107]
	v_pk_add_f32 v[172:173], v[172:173], v[108:109]
	v_pk_add_f32 v[174:175], v[174:175], v[110:111]
	s_waitcnt vmcnt(0)
	v_pk_add_f32 v[160:161], v[160:161], v[112:113]
	v_pk_add_f32 v[162:163], v[162:163], v[114:115]
	v_pk_add_f32 v[164:165], v[164:165], v[116:117]
	v_pk_add_f32 v[166:167], v[166:167], v[118:119]
	v_pk_add_f32 v[168:169], v[168:169], v[120:121]
	v_pk_add_f32 v[170:171], v[170:171], v[122:123]
	v_pk_add_f32 v[172:173], v[172:173], v[124:125]
	v_pk_add_f32 v[174:175], v[174:175], v[126:127]
	v_lshlrev_b32_e32 v144, 16, v240
	v_and_b32_e32 v145, 0xffff0000, v240
	v_lshlrev_b32_e32 v146, 16, v241
	v_and_b32_e32 v147, 0xffff0000, v241
	v_lshlrev_b32_e32 v148, 16, v242
	v_and_b32_e32 v149, 0xffff0000, v242
	v_lshlrev_b32_e32 v150, 16, v243
	v_and_b32_e32 v151, 0xffff0000, v243
	v_lshlrev_b32_e32 v152, 16, v244
	v_and_b32_e32 v153, 0xffff0000, v244
	v_lshlrev_b32_e32 v154, 16, v245
	v_and_b32_e32 v155, 0xffff0000, v245
	v_lshlrev_b32_e32 v156, 16, v246
	v_and_b32_e32 v157, 0xffff0000, v246
	v_lshlrev_b32_e32 v158, 16, v247
	v_and_b32_e32 v159, 0xffff0000, v247
	v_pk_mul_f32 v[252:253], v[160:161], v[160:161]
	v_pk_mul_f32 v[254:255], v[162:163], v[162:163]
	v_pk_fma_f32 v[252:253], v[164:165], v[164:165], v[252:253]
	v_pk_fma_f32 v[254:255], v[166:167], v[166:167], v[254:255]
	v_pk_fma_f32 v[252:253], v[168:169], v[168:169], v[252:253]
	v_pk_fma_f32 v[254:255], v[170:171], v[170:171], v[254:255]
	v_pk_fma_f32 v[252:253], v[172:173], v[172:173], v[252:253]
	v_pk_fma_f32 v[254:255], v[174:175], v[174:175], v[254:255]
	v_pk_add_f32 v[252:253], v[252:253], v[254:255]
	s_nop 0
	v_add_f32_e32 v183, v252, v253
	s_nop 1
	v_add_f32_dpp v183, v183, v183 quad_perm:[1,0,3,2] row_mask:0xf bank_mask:0xf bound_ctrl:1
	s_nop 1
	v_add_f32_dpp v183, v183, v183 quad_perm:[2,3,0,1] row_mask:0xf bank_mask:0xf bound_ctrl:1
	s_nop 1
	v_add_f32_dpp v183, v183, v183 row_half_mirror row_mask:0xf bank_mask:0xf bound_ctrl:1
	s_nop 1
	v_add_f32_dpp v183, v183, v183 row_mirror row_mask:0xf bank_mask:0xf bound_ctrl:1
	s_nop 1
	v_readlane_b32 s98, v183, 0
	v_readlane_b32 s99, v183, 16
	v_readlane_b32 s100, v183, 32
	v_readlane_b32 s101, v183, 48
	s_nop 1
	v_mov_b32_e32 v183, s98
	v_add_f32_e32 v183, s99, v183
	v_add_f32_e32 v183, s100, v183
	v_add_f32_e32 v183, s101, v183
	v_fmamk_f32 v183, v183, 0x3a800000, v182
	v_cmp_gt_f32_e32 vcc, 0x800000, v183
	v_mul_f32_e32 v181, 0x4b800000, v183
	s_nop 1
	v_cndmask_b32_e32 v183, v183, v181, vcc
	v_rsq_f32_e32 v183, v183
	s_nop 0
	v_mul_f32_e32 v181, 0x45800000, v183
	v_cndmask_b32_e32 v184, v183, v181, vcc
	v_mov_b32_e32 v185, v184
	v_pk_mul_f32 v[160:161], v[160:161], v[184:185]
	v_pk_mul_f32 v[162:163], v[162:163], v[184:185]
	v_pk_mul_f32 v[164:165], v[164:165], v[184:185]
	v_pk_mul_f32 v[166:167], v[166:167], v[184:185]
	v_pk_mul_f32 v[168:169], v[168:169], v[184:185]
	v_pk_mul_f32 v[170:171], v[170:171], v[184:185]
	v_pk_mul_f32 v[172:173], v[172:173], v[184:185]
	v_pk_mul_f32 v[174:175], v[174:175], v[184:185]
	v_pk_fma_f32 v[144:145], v[160:161], v[128:129], v[144:145]
	v_pk_fma_f32 v[146:147], v[162:163], v[130:131], v[146:147]
	v_pk_fma_f32 v[148:149], v[164:165], v[132:133], v[148:149]
	v_pk_fma_f32 v[150:151], v[166:167], v[134:135], v[150:151]
	v_pk_fma_f32 v[152:153], v[168:169], v[136:137], v[152:153]
	v_pk_fma_f32 v[154:155], v[170:171], v[138:139], v[154:155]
	v_pk_fma_f32 v[156:157], v[172:173], v[140:141], v[156:157]
	v_pk_fma_f32 v[158:159], v[174:175], v[142:143], v[158:159]
	v_pk_mul_f32 v[252:253], v[144:145], v[144:145]
	v_pk_mul_f32 v[254:255], v[146:147], v[146:147]
	v_pk_fma_f32 v[252:253], v[148:149], v[148:149], v[252:253]
	v_pk_fma_f32 v[254:255], v[150:151], v[150:151], v[254:255]
	v_pk_fma_f32 v[252:253], v[152:153], v[152:153], v[252:253]
	v_pk_fma_f32 v[254:255], v[154:155], v[154:155], v[254:255]
	v_pk_fma_f32 v[252:253], v[156:157], v[156:157], v[252:253]
	v_pk_fma_f32 v[254:255], v[158:159], v[158:159], v[254:255]
	v_pk_add_f32 v[252:253], v[252:253], v[254:255]
	s_nop 0
	v_add_f32_e32 v183, v252, v253
	s_nop 1
	v_add_f32_dpp v183, v183, v183 quad_perm:[1,0,3,2] row_mask:0xf bank_mask:0xf bound_ctrl:1
	s_nop 1
	v_add_f32_dpp v183, v183, v183 quad_perm:[2,3,0,1] row_mask:0xf bank_mask:0xf bound_ctrl:1
	s_nop 1
	v_add_f32_dpp v183, v183, v183 row_half_mirror row_mask:0xf bank_mask:0xf bound_ctrl:1
	s_nop 1
	v_add_f32_dpp v183, v183, v183 row_mirror row_mask:0xf bank_mask:0xf bound_ctrl:1
	s_nop 1
	v_readlane_b32 s98, v183, 0
	v_readlane_b32 s99, v183, 16
	v_readlane_b32 s100, v183, 32
	v_readlane_b32 s101, v183, 48
	s_nop 1
	v_mov_b32_e32 v183, s98
	v_add_f32_e32 v183, s99, v183
	v_add_f32_e32 v183, s100, v183
	v_add_f32_e32 v183, s101, v183
	v_fmamk_f32 v183, v183, 0x3a800000, v182
	v_cmp_gt_f32_e32 vcc, 0x800000, v183
	v_mul_f32_e32 v181, 0x4b800000, v183
	s_nop 1
	v_cndmask_b32_e32 v183, v183, v181, vcc
	v_rsq_f32_e32 v183, v183
	s_nop 0
	v_mul_f32_e32 v181, 0x45800000, v183
	v_cndmask_b32_e32 v184, v183, v181, vcc
	v_mov_b32_e32 v185, v184
	v_cvt_pk_bf16_f32 v0, v144, v145
	v_cvt_pk_bf16_f32 v1, v146, v147
	v_cvt_pk_bf16_f32 v2, v148, v149
	v_cvt_pk_bf16_f32 v3, v150, v151
	v_cvt_pk_bf16_f32 v4, v152, v153
	v_cvt_pk_bf16_f32 v5, v154, v155
	v_cvt_pk_bf16_f32 v6, v156, v157
	v_cvt_pk_bf16_f32 v7, v158, v159
	v_add_u32_e32 v181, 0x3800000, v177
	global_store_dwordx4 v181, v[0:3], s[78:79]
	global_store_dwordx4 v181, v[4:7], s[78:79] offset:1024
	v_add_u32_e32 v236, 0x10000, v237
	s_mov_b64 exec, 1
	global_store_dword v236, v184, s[78:79]
	s_mov_b64 exec, -1

.LBB0_2139:
	v_readlane_b32 s0, v235, 52
	v_readlane_b32 s1, v235, 53
	s_and_b64 vcc, exec, s[0:1]
	s_waitcnt lgkmcnt(0)
	s_barrier
	v_mbcnt_lo_u32_b32 v0, -1, 0
	v_mbcnt_hi_u32_b32 v0, -1, v0
	s_cbranch_vccnz .LBB0_2159
	v_lshlrev_b32_e32 v2, 3, v0
	v_readlane_b32 s4, v235, 4
	v_ashrrev_i32_e32 v3, 31, v2
	v_readlane_b32 s6, v235, 6
	v_readlane_b32 s7, v235, 7
	v_lshlrev_b64 v[4:5], 1, v[2:3]
	v_lshlrev_b64 v[2:3], 2, v[2:3]
	v_readlane_b32 s5, v235, 5
	v_readlane_b32 s10, v235, 10
	v_readlane_b32 s11, v235, 11
	v_readlane_b32 s18, v235, 18
	v_readlane_b32 s19, v235, 19
	v_readlane_b32 s6, v235, 61
	v_lshl_add_u64 v[154:155], s[90:91], 0, v[2:3]
	v_readlane_b32 s8, v235, 8
	v_lshl_add_u64 v[2:3], s[18:19], 0, v[2:3]
	s_mov_b64 s[0:1], 0x2000
	v_readlane_b32 s4, v235, 0
	v_readlane_b32 s7, v235, 62
	s_mov_b32 s10, s6
	s_ashr_i32 s11, s6, 31
	v_readlane_b32 s9, v235, 9
	v_lshl_add_u64 v[158:159], v[2:3], 0, s[0:1]
	s_lshl_b32 s4, s4, 4
	s_add_i32 s0, s6, 0xffffc000
	s_lshl_b64 s[6:7], s[10:11], 2
	s_mov_b32 s8, s10
	v_readlane_b32 s12, v235, 12
	v_readlane_b32 s13, v235, 13
	v_readlane_b32 s14, v235, 14
	v_readlane_b32 s15, v235, 15
	v_readlane_b32 s16, v235, 16
	v_readlane_b32 s17, v235, 17
	v_readlane_b32 s5, v235, 1
	s_add_u32 s80, s6, 0x10000
	v_writelane_b32 v235, s8, 61
	s_addc_u32 s12, s7, 0
	s_ashr_i32 s5, s4, 31
	v_writelane_b32 v235, s9, 62
	s_lshl_b64 s[8:9], s[10:11], 11
	v_lshl_add_u64 v[152:153], s[86:87], 0, v[4:5]
	v_lshl_add_u64 v[156:157], s[54:55], 0, v[4:5]
	s_mov_b32 s1, 0
	v_cmp_eq_u32_e64 s[16:17], 0, v0
	s_lshl_b64 s[6:7], s[4:5], 2
	v_lshl_add_u64 v[160:161], s[8:9], 0, v[4:5]
	s_lshl_b64 s[8:9], s[4:5], 11
	s_mov_b64 s[20:21], 0x600000
	s_mov_b64 s[22:23], 0x600800
	s_mov_b64 s[24:25], 0x800000
	s_mov_b32 s5, 0x800000
	s_mov_b64 s[26:27], 0x800800
	s_mov_b64 s[28:29], 0xa00000
	s_mov_b64 s[36:37], 0xa00800
	s_mov_b64 s[38:39], 0xc00000
	s_mov_b64 s[40:41], 0xc00800
	s_mov_b64 s[42:43], 0xe00000
	s_mov_b64 s[44:45], 0xe00800
	s_mov_b64 s[46:47], 0x1000000
	s_mov_b32 s13, 0x1000000
	s_mov_b64 s[48:49], 0x1000800
	s_mov_b64 s[50:51], 0x1200000
	s_mov_b32 s14, 0x1200000
	s_mov_b64 s[10:11], 0x1200800
	s_mov_b64 s[82:83], 0x1400000
	s_mov_b32 s15, 0x1400000
	s_mov_b64 s[90:91], 0x1400800
	v_mov_b32_e32 v215, 0
	v_mov_b32_e32 v216, 0x358637bd
	v_mbcnt_lo_u32_b32 v176, -1, 0
	v_mbcnt_hi_u32_b32 v176, -1, v176
	v_readlane_b32 s98, v235, 49
	v_readlane_b32 s99, v235, 20
	v_readlane_b32 s100, v235, 18
	v_readlane_b32 s101, v235, 19
	s_nop 3
	s_lshr_b32 vcc_lo, s98, 3
	s_and_b32 vcc_hi, vcc_lo, 7
	s_lshr_b32 vcc_lo, vcc_lo, 3
	s_lshl_b32 vcc_lo, vcc_lo, 3
	s_add_i32 vcc_lo, vcc_lo, s99
	s_lshl_b32 s98, vcc_hi, 8
	s_add_i32 s98, s98, vcc_lo
	s_mov_b32 s99, s98
	v_mov_b32_e32 v183, s99
	v_lshlrev_b32_e32 v177, 4, v176
	s_lshl_b32 s99, s99, 11
	v_add_u32_e32 v177, s99, v177
	v_add_u32_e32 v178, 0x1800000, v177
	v_add_u32_e32 v179, 0x9e00000, v177
	v_lshlrev_b32_e32 v180, 5, v176
	v_add_u32_e32 v181, 0x2000, v180
	global_load_dwordx4 v[128:131], v181, s[100:101]
	global_load_dwordx4 v[132:135], v181, s[100:101] offset:16
	global_load_dwordx4 v[136:139], v181, s[100:101] offset:2048
	global_load_dwordx4 v[140:143], v181, s[100:101] offset:2064
	v_mov_b32_e32 v182, 0x358637bd
	global_load_dwordx4 v[0:3], v178, s[78:79]
	global_load_dwordx4 v[4:7], v178, s[78:79] offset:1024
	global_load_dwordx4 v[8:11], v179, s[78:79]
	global_load_dwordx4 v[12:15], v179, s[78:79] offset:1024
	v_add_u32_e32 v178, 0x400000, v178
	v_add_u32_e32 v179, 0x400000, v179
	global_load_dwordx4 v[16:19], v178, s[78:79]
	global_load_dwordx4 v[20:23], v178, s[78:79] offset:1024
	global_load_dwordx4 v[24:27], v179, s[78:79]
	global_load_dwordx4 v[28:31], v179, s[78:79] offset:1024
	v_add_u32_e32 v178, 0x400000, v178
	v_add_u32_e32 v179, 0x400000, v179
	global_load_dwordx4 v[32:35], v178, s[78:79]
	global_load_dwordx4 v[36:39], v178, s[78:79] offset:1024
	global_load_dwordx4 v[40:43], v179, s[78:79]
	global_load_dwordx4 v[44:47], v179, s[78:79] offset:1024
	v_add_u32_e32 v178, 0x400000, v178
	v_add_u32_e32 v179, 0x400000, v179
	global_load_dwordx4 v[48:51], v178, s[78:79]
	global_load_dwordx4 v[52:55], v178, s[78:79] offset:1024
	global_load_dwordx4 v[56:59], v179, s[78:79]
	global_load_dwordx4 v[60:63], v179, s[78:79] offset:1024
	v_add_u32_e32 v178, 0x400000, v178
	v_add_u32_e32 v179, 0x400000, v179
	global_load_dwordx4 v[64:67], v178, s[78:79]
	global_load_dwordx4 v[68:71], v178, s[78:79] offset:1024
	global_load_dwordx4 v[72:75], v179, s[78:79]
	global_load_dwordx4 v[76:79], v179, s[78:79] offset:1024
	v_add_u32_e32 v178, 0x400000, v178
	v_add_u32_e32 v179, 0x400000, v179
	global_load_dwordx4 v[80:83], v178, s[78:79]
	global_load_dwordx4 v[84:87], v178, s[78:79] offset:1024
	global_load_dwordx4 v[88:91], v179, s[78:79]
	global_load_dwordx4 v[92:95], v179, s[78:79] offset:1024
	v_add_u32_e32 v178, 0x400000, v178
	v_add_u32_e32 v179, 0x400000, v179
	global_load_dwordx4 v[96:99], v178, s[78:79]
	global_load_dwordx4 v[100:103], v178, s[78:79] offset:1024
	global_load_dwordx4 v[104:107], v179, s[78:79]
	global_load_dwordx4 v[108:111], v179, s[78:79] offset:1024
	v_add_u32_e32 v178, 0x400000, v178
	v_add_u32_e32 v179, 0x400000, v179
	global_load_dwordx4 v[112:115], v178, s[78:79]
	global_load_dwordx4 v[116:119], v178, s[78:79] offset:1024
	global_load_dwordx4 v[120:123], v179, s[78:79]
	global_load_dwordx4 v[124:127], v179, s[78:79] offset:1024
	v_lshlrev_b32_e32 v237, 2, v183
	v_add_u32_e32 v237, 0x10000, v237
	v_mov_b32_e32 v179, s98
	s_waitcnt vmcnt(28)
	v_lshlrev_b32_e32 v144, 16, v0
	v_and_b32_e32 v145, 0xffff0000, v0
	v_lshlrev_b32_e32 v146, 16, v1
	v_and_b32_e32 v147, 0xffff0000, v1
	v_lshlrev_b32_e32 v148, 16, v2
	v_and_b32_e32 v149, 0xffff0000, v2
	v_lshlrev_b32_e32 v150, 16, v3
	v_and_b32_e32 v151, 0xffff0000, v3
	v_lshlrev_b32_e32 v152, 16, v4
	v_and_b32_e32 v153, 0xffff0000, v4
	v_lshlrev_b32_e32 v154, 16, v5
	v_and_b32_e32 v155, 0xffff0000, v5
	v_lshlrev_b32_e32 v156, 16, v6
	v_and_b32_e32 v157, 0xffff0000, v6
	v_lshlrev_b32_e32 v158, 16, v7
	v_and_b32_e32 v159, 0xffff0000, v7
	v_lshlrev_b32_e32 v160, 16, v8
	v_and_b32_e32 v161, 0xffff0000, v8
	v_lshlrev_b32_e32 v162, 16, v9
	v_and_b32_e32 v163, 0xffff0000, v9
	v_lshlrev_b32_e32 v164, 16, v10
	v_and_b32_e32 v165, 0xffff0000, v10
	v_lshlrev_b32_e32 v166, 16, v11
	v_and_b32_e32 v167, 0xffff0000, v11
	v_lshlrev_b32_e32 v168, 16, v12
	v_and_b32_e32 v169, 0xffff0000, v12
	v_lshlrev_b32_e32 v170, 16, v13
	v_and_b32_e32 v171, 0xffff0000, v13
	v_lshlrev_b32_e32 v172, 16, v14
	v_and_b32_e32 v173, 0xffff0000, v14
	v_lshlrev_b32_e32 v174, 16, v15
	v_and_b32_e32 v175, 0xffff0000, v15
	v_pk_mul_f32 v[252:253], v[160:161], v[160:161]
	v_pk_mul_f32 v[254:255], v[162:163], v[162:163]
	v_pk_fma_f32 v[252:253], v[164:165], v[164:165], v[252:253]
	v_pk_fma_f32 v[254:255], v[166:167], v[166:167], v[254:255]
	v_pk_fma_f32 v[252:253], v[168:169], v[168:169], v[252:253]
	v_pk_fma_f32 v[254:255], v[170:171], v[170:171], v[254:255]
	v_pk_fma_f32 v[252:253], v[172:173], v[172:173], v[252:253]
	v_pk_fma_f32 v[254:255], v[174:175], v[174:175], v[254:255]
	v_pk_add_f32 v[252:253], v[252:253], v[254:255]
	s_nop 0
	v_add_f32_e32 v183, v252, v253
	s_nop 1
	v_add_f32_dpp v183, v183, v183 quad_perm:[1,0,3,2] row_mask:0xf bank_mask:0xf bound_ctrl:1
	s_nop 1
	v_add_f32_dpp v183, v183, v183 quad_perm:[2,3,0,1] row_mask:0xf bank_mask:0xf bound_ctrl:1
	s_nop 1
	v_add_f32_dpp v183, v183, v183 row_half_mirror row_mask:0xf bank_mask:0xf bound_ctrl:1
	s_nop 1
	v_add_f32_dpp v183, v183, v183 row_mirror row_mask:0xf bank_mask:0xf bound_ctrl:1
	s_nop 1
	v_readlane_b32 s98, v183, 0
	v_readlane_b32 s99, v183, 16
	v_readlane_b32 s100, v183, 32
	v_readlane_b32 s101, v183, 48
	s_nop 1
	v_mov_b32_e32 v183, s98
	v_add_f32_e32 v183, s99, v183
	v_add_f32_e32 v183, s100, v183
	v_add_f32_e32 v183, s101, v183
	v_fmamk_f32 v183, v183, 0x3a800000, v182
	v_cmp_gt_f32_e32 vcc, 0x800000, v183
	v_mul_f32_e32 v181, 0x4b800000, v183
	s_nop 1
	v_cndmask_b32_e32 v183, v183, v181, vcc
	v_rsq_f32_e32 v183, v183
	s_nop 0
	v_mul_f32_e32 v181, 0x45800000, v183
	v_cndmask_b32_e32 v184, v183, v181, vcc
	v_mov_b32_e32 v185, v184
	v_pk_mul_f32 v[160:161], v[160:161], v[184:185]
	v_pk_mul_f32 v[162:163], v[162:163], v[184:185]
	v_pk_mul_f32 v[164:165], v[164:165], v[184:185]
	v_pk_mul_f32 v[166:167], v[166:167], v[184:185]
	v_pk_mul_f32 v[168:169], v[168:169], v[184:185]
	v_pk_mul_f32 v[170:171], v[170:171], v[184:185]
	v_pk_mul_f32 v[172:173], v[172:173], v[184:185]
	v_pk_mul_f32 v[174:175], v[174:175], v[184:185]
	v_pk_fma_f32 v[144:145], v[160:161], v[128:129], v[144:145]
	v_pk_fma_f32 v[146:147], v[162:163], v[130:131], v[146:147]
	v_pk_fma_f32 v[148:149], v[164:165], v[132:133], v[148:149]
	v_pk_fma_f32 v[150:151], v[166:167], v[134:135], v[150:151]
	v_pk_fma_f32 v[152:153], v[168:169], v[136:137], v[152:153]
	v_pk_fma_f32 v[154:155], v[170:171], v[138:139], v[154:155]
	v_pk_fma_f32 v[156:157], v[172:173], v[140:141], v[156:157]
	v_pk_fma_f32 v[158:159], v[174:175], v[142:143], v[158:159]
	v_pk_mul_f32 v[252:253], v[144:145], v[144:145]
	v_pk_mul_f32 v[254:255], v[146:147], v[146:147]
	v_pk_fma_f32 v[252:253], v[148:149], v[148:149], v[252:253]
	v_pk_fma_f32 v[254:255], v[150:151], v[150:151], v[254:255]
	v_pk_fma_f32 v[252:253], v[152:153], v[152:153], v[252:253]
	v_pk_fma_f32 v[254:255], v[154:155], v[154:155], v[254:255]
	v_pk_fma_f32 v[252:253], v[156:157], v[156:157], v[252:253]
	v_pk_fma_f32 v[254:255], v[158:159], v[158:159], v[254:255]
	v_pk_add_f32 v[252:253], v[252:253], v[254:255]
	s_nop 0
	v_add_f32_e32 v183, v252, v253
	s_nop 1
	v_add_f32_dpp v183, v183, v183 quad_perm:[1,0,3,2] row_mask:0xf bank_mask:0xf bound_ctrl:1
	s_nop 1
	v_add_f32_dpp v183, v183, v183 quad_perm:[2,3,0,1] row_mask:0xf bank_mask:0xf bound_ctrl:1
	s_nop 1
	v_add_f32_dpp v183, v183, v183 row_half_mirror row_mask:0xf bank_mask:0xf bound_ctrl:1
	s_nop 1
	v_add_f32_dpp v183, v183, v183 row_mirror row_mask:0xf bank_mask:0xf bound_ctrl:1
	s_nop 1
	v_readlane_b32 s98, v183, 0
	v_readlane_b32 s99, v183, 16
	v_readlane_b32 s100, v183, 32
	v_readlane_b32 s101, v183, 48
	s_nop 1
	v_mov_b32_e32 v183, s98
	v_add_f32_e32 v183, s99, v183
	v_add_f32_e32 v183, s100, v183
	v_add_f32_e32 v183, s101, v183
	v_fmamk_f32 v183, v183, 0x3a800000, v182
	v_cmp_gt_f32_e32 vcc, 0x800000, v183
	v_mul_f32_e32 v181, 0x4b800000, v183
	s_nop 1
	v_cndmask_b32_e32 v183, v183, v181, vcc
	v_rsq_f32_e32 v183, v183
	s_nop 0
	v_mul_f32_e32 v181, 0x45800000, v183
	v_cndmask_b32_e32 v184, v183, v181, vcc
	v_mov_b32_e32 v185, v184
	v_cvt_pk_bf16_f32 v0, v144, v145
	v_cvt_pk_bf16_f32 v1, v146, v147
	v_cvt_pk_bf16_f32 v2, v148, v149
	v_cvt_pk_bf16_f32 v3, v150, v151
	v_cvt_pk_bf16_f32 v4, v152, v153
	v_cvt_pk_bf16_f32 v5, v154, v155
	v_cvt_pk_bf16_f32 v6, v156, v157
	v_cvt_pk_bf16_f32 v7, v158, v159
	v_add_u32_e32 v181, 0x1800000, v177
	global_store_dwordx4 v181, v[0:3], s[78:79]
	global_store_dwordx4 v181, v[4:7], s[78:79] offset:1024
	v_add_u32_e32 v236, 0x0, v237
	s_mov_b64 exec, 1
	global_store_dword v236, v184, s[78:79]
	s_mov_b64 exec, -1
	s_waitcnt vmcnt(24)
	v_lshlrev_b32_e32 v144, 16, v16
	v_and_b32_e32 v145, 0xffff0000, v16
	v_lshlrev_b32_e32 v146, 16, v17
	v_and_b32_e32 v147, 0xffff0000, v17
	v_lshlrev_b32_e32 v148, 16, v18
	v_and_b32_e32 v149, 0xffff0000, v18
	v_lshlrev_b32_e32 v150, 16, v19
	v_and_b32_e32 v151, 0xffff0000, v19
	v_lshlrev_b32_e32 v152, 16, v20
	v_and_b32_e32 v153, 0xffff0000, v20
	v_lshlrev_b32_e32 v154, 16, v21
	v_and_b32_e32 v155, 0xffff0000, v21
	v_lshlrev_b32_e32 v156, 16, v22
	v_and_b32_e32 v157, 0xffff0000, v22
	v_lshlrev_b32_e32 v158, 16, v23
	v_and_b32_e32 v159, 0xffff0000, v23
	v_lshlrev_b32_e32 v160, 16, v24
	v_and_b32_e32 v161, 0xffff0000, v24
	v_lshlrev_b32_e32 v162, 16, v25
	v_and_b32_e32 v163, 0xffff0000, v25
	v_lshlrev_b32_e32 v164, 16, v26
	v_and_b32_e32 v165, 0xffff0000, v26
	v_lshlrev_b32_e32 v166, 16, v27
	v_and_b32_e32 v167, 0xffff0000, v27
	v_lshlrev_b32_e32 v168, 16, v28
	v_and_b32_e32 v169, 0xffff0000, v28
	v_lshlrev_b32_e32 v170, 16, v29
	v_and_b32_e32 v171, 0xffff0000, v29
	v_lshlrev_b32_e32 v172, 16, v30
	v_and_b32_e32 v173, 0xffff0000, v30
	v_lshlrev_b32_e32 v174, 16, v31
	v_and_b32_e32 v175, 0xffff0000, v31
	v_pk_mul_f32 v[252:253], v[160:161], v[160:161]
	v_pk_mul_f32 v[254:255], v[162:163], v[162:163]
	v_pk_fma_f32 v[252:253], v[164:165], v[164:165], v[252:253]
	v_pk_fma_f32 v[254:255], v[166:167], v[166:167], v[254:255]
	v_pk_fma_f32 v[252:253], v[168:169], v[168:169], v[252:253]
	v_pk_fma_f32 v[254:255], v[170:171], v[170:171], v[254:255]
	v_pk_fma_f32 v[252:253], v[172:173], v[172:173], v[252:253]
	v_pk_fma_f32 v[254:255], v[174:175], v[174:175], v[254:255]
	v_pk_add_f32 v[252:253], v[252:253], v[254:255]
	s_nop 0
	v_add_f32_e32 v183, v252, v253
	s_nop 1
	v_add_f32_dpp v183, v183, v183 quad_perm:[1,0,3,2] row_mask:0xf bank_mask:0xf bound_ctrl:1
	s_nop 1
	v_add_f32_dpp v183, v183, v183 quad_perm:[2,3,0,1] row_mask:0xf bank_mask:0xf bound_ctrl:1
	s_nop 1
	v_add_f32_dpp v183, v183, v183 row_half_mirror row_mask:0xf bank_mask:0xf bound_ctrl:1
	s_nop 1
	v_add_f32_dpp v183, v183, v183 row_mirror row_mask:0xf bank_mask:0xf bound_ctrl:1
	s_nop 1
	v_readlane_b32 s98, v183, 0
	v_readlane_b32 s99, v183, 16
	v_readlane_b32 s100, v183, 32
	v_readlane_b32 s101, v183, 48
	s_nop 1
	v_mov_b32_e32 v183, s98
	v_add_f32_e32 v183, s99, v183
	v_add_f32_e32 v183, s100, v183
	v_add_f32_e32 v183, s101, v183
	v_fmamk_f32 v183, v183, 0x3a800000, v182
	v_cmp_gt_f32_e32 vcc, 0x800000, v183
	v_mul_f32_e32 v181, 0x4b800000, v183
	s_nop 1
	v_cndmask_b32_e32 v183, v183, v181, vcc
	v_rsq_f32_e32 v183, v183
	s_nop 0
	v_mul_f32_e32 v181, 0x45800000, v183
	v_cndmask_b32_e32 v184, v183, v181, vcc
	v_mov_b32_e32 v185, v184
	v_pk_mul_f32 v[160:161], v[160:161], v[184:185]
	v_pk_mul_f32 v[162:163], v[162:163], v[184:185]
	v_pk_mul_f32 v[164:165], v[164:165], v[184:185]
	v_pk_mul_f32 v[166:167], v[166:167], v[184:185]
	v_pk_mul_f32 v[168:169], v[168:169], v[184:185]
	v_pk_mul_f32 v[170:171], v[170:171], v[184:185]
	v_pk_mul_f32 v[172:173], v[172:173], v[184:185]
	v_pk_mul_f32 v[174:175], v[174:175], v[184:185]
	v_pk_fma_f32 v[144:145], v[160:161], v[128:129], v[144:145]
	v_pk_fma_f32 v[146:147], v[162:163], v[130:131], v[146:147]
	v_pk_fma_f32 v[148:149], v[164:165], v[132:133], v[148:149]
	v_pk_fma_f32 v[150:151], v[166:167], v[134:135], v[150:151]
	v_pk_fma_f32 v[152:153], v[168:169], v[136:137], v[152:153]
	v_pk_fma_f32 v[154:155], v[170:171], v[138:139], v[154:155]
	v_pk_fma_f32 v[156:157], v[172:173], v[140:141], v[156:157]
	v_pk_fma_f32 v[158:159], v[174:175], v[142:143], v[158:159]
	v_pk_mul_f32 v[252:253], v[144:145], v[144:145]
	v_pk_mul_f32 v[254:255], v[146:147], v[146:147]
	v_pk_fma_f32 v[252:253], v[148:149], v[148:149], v[252:253]
	v_pk_fma_f32 v[254:255], v[150:151], v[150:151], v[254:255]
	v_pk_fma_f32 v[252:253], v[152:153], v[152:153], v[252:253]
	v_pk_fma_f32 v[254:255], v[154:155], v[154:155], v[254:255]
	v_pk_fma_f32 v[252:253], v[156:157], v[156:157], v[252:253]
	v_pk_fma_f32 v[254:255], v[158:159], v[158:159], v[254:255]
	v_pk_add_f32 v[252:253], v[252:253], v[254:255]
	s_nop 0
	v_add_f32_e32 v183, v252, v253
	s_nop 1
	v_add_f32_dpp v183, v183, v183 quad_perm:[1,0,3,2] row_mask:0xf bank_mask:0xf bound_ctrl:1
	s_nop 1
	v_add_f32_dpp v183, v183, v183 quad_perm:[2,3,0,1] row_mask:0xf bank_mask:0xf bound_ctrl:1
	s_nop 1
	v_add_f32_dpp v183, v183, v183 row_half_mirror row_mask:0xf bank_mask:0xf bound_ctrl:1
	s_nop 1
	v_add_f32_dpp v183, v183, v183 row_mirror row_mask:0xf bank_mask:0xf bound_ctrl:1
	s_nop 1
	v_readlane_b32 s98, v183, 0
	v_readlane_b32 s99, v183, 16
	v_readlane_b32 s100, v183, 32
	v_readlane_b32 s101, v183, 48
	s_nop 1
	v_mov_b32_e32 v183, s98
	v_add_f32_e32 v183, s99, v183
	v_add_f32_e32 v183, s100, v183
	v_add_f32_e32 v183, s101, v183
	v_fmamk_f32 v183, v183, 0x3a800000, v182
	v_cmp_gt_f32_e32 vcc, 0x800000, v183
	v_mul_f32_e32 v181, 0x4b800000, v183
	s_nop 1
	v_cndmask_b32_e32 v183, v183, v181, vcc
	v_rsq_f32_e32 v183, v183
	s_nop 0
	v_mul_f32_e32 v181, 0x45800000, v183
	v_cndmask_b32_e32 v184, v183, v181, vcc
	v_mov_b32_e32 v185, v184
	v_cvt_pk_bf16_f32 v16, v144, v145
	v_cvt_pk_bf16_f32 v17, v146, v147
	v_cvt_pk_bf16_f32 v18, v148, v149
	v_cvt_pk_bf16_f32 v19, v150, v151
	v_cvt_pk_bf16_f32 v20, v152, v153
	v_cvt_pk_bf16_f32 v21, v154, v155
	v_cvt_pk_bf16_f32 v22, v156, v157
	v_cvt_pk_bf16_f32 v23, v158, v159
	v_add_u32_e32 v181, 0x1c00000, v177
	global_store_dwordx4 v181, v[16:19], s[78:79]
	global_store_dwordx4 v181, v[20:23], s[78:79] offset:1024
	v_add_u32_e32 v236, 0x2000, v237
	s_mov_b64 exec, 1
	global_store_dword v236, v184, s[78:79]
	s_mov_b64 exec, -1
	s_waitcnt vmcnt(20)
	v_lshlrev_b32_e32 v144, 16, v32
	v_and_b32_e32 v145, 0xffff0000, v32
	v_lshlrev_b32_e32 v146, 16, v33
	v_and_b32_e32 v147, 0xffff0000, v33
	v_lshlrev_b32_e32 v148, 16, v34
	v_and_b32_e32 v149, 0xffff0000, v34
	v_lshlrev_b32_e32 v150, 16, v35
	v_and_b32_e32 v151, 0xffff0000, v35
	v_lshlrev_b32_e32 v152, 16, v36
	v_and_b32_e32 v153, 0xffff0000, v36
	v_lshlrev_b32_e32 v154, 16, v37
	v_and_b32_e32 v155, 0xffff0000, v37
	v_lshlrev_b32_e32 v156, 16, v38
	v_and_b32_e32 v157, 0xffff0000, v38
	v_lshlrev_b32_e32 v158, 16, v39
	v_and_b32_e32 v159, 0xffff0000, v39
	v_lshlrev_b32_e32 v160, 16, v40
	v_and_b32_e32 v161, 0xffff0000, v40
	v_lshlrev_b32_e32 v162, 16, v41
	v_and_b32_e32 v163, 0xffff0000, v41
	v_lshlrev_b32_e32 v164, 16, v42
	v_and_b32_e32 v165, 0xffff0000, v42
	v_lshlrev_b32_e32 v166, 16, v43
	v_and_b32_e32 v167, 0xffff0000, v43
	v_lshlrev_b32_e32 v168, 16, v44
	v_and_b32_e32 v169, 0xffff0000, v44
	v_lshlrev_b32_e32 v170, 16, v45
	v_and_b32_e32 v171, 0xffff0000, v45
	v_lshlrev_b32_e32 v172, 16, v46
	v_and_b32_e32 v173, 0xffff0000, v46
	v_lshlrev_b32_e32 v174, 16, v47
	v_and_b32_e32 v175, 0xffff0000, v47
	v_pk_mul_f32 v[252:253], v[160:161], v[160:161]
	v_pk_mul_f32 v[254:255], v[162:163], v[162:163]
	v_pk_fma_f32 v[252:253], v[164:165], v[164:165], v[252:253]
	v_pk_fma_f32 v[254:255], v[166:167], v[166:167], v[254:255]
	v_pk_fma_f32 v[252:253], v[168:169], v[168:169], v[252:253]
	v_pk_fma_f32 v[254:255], v[170:171], v[170:171], v[254:255]
	v_pk_fma_f32 v[252:253], v[172:173], v[172:173], v[252:253]
	v_pk_fma_f32 v[254:255], v[174:175], v[174:175], v[254:255]
	v_pk_add_f32 v[252:253], v[252:253], v[254:255]
	s_nop 0
	v_add_f32_e32 v183, v252, v253
	s_nop 1
	v_add_f32_dpp v183, v183, v183 quad_perm:[1,0,3,2] row_mask:0xf bank_mask:0xf bound_ctrl:1
	s_nop 1
	v_add_f32_dpp v183, v183, v183 quad_perm:[2,3,0,1] row_mask:0xf bank_mask:0xf bound_ctrl:1
	s_nop 1
	v_add_f32_dpp v183, v183, v183 row_half_mirror row_mask:0xf bank_mask:0xf bound_ctrl:1
	s_nop 1
	v_add_f32_dpp v183, v183, v183 row_mirror row_mask:0xf bank_mask:0xf bound_ctrl:1
	s_nop 1
	v_readlane_b32 s98, v183, 0
	v_readlane_b32 s99, v183, 16
	v_readlane_b32 s100, v183, 32
	v_readlane_b32 s101, v183, 48
	s_nop 1
	v_mov_b32_e32 v183, s98
	v_add_f32_e32 v183, s99, v183
	v_add_f32_e32 v183, s100, v183
	v_add_f32_e32 v183, s101, v183
	v_fmamk_f32 v183, v183, 0x3a800000, v182
	v_cmp_gt_f32_e32 vcc, 0x800000, v183
	v_mul_f32_e32 v181, 0x4b800000, v183
	s_nop 1
	v_cndmask_b32_e32 v183, v183, v181, vcc
	v_rsq_f32_e32 v183, v183
	s_nop 0
	v_mul_f32_e32 v181, 0x45800000, v183
	v_cndmask_b32_e32 v184, v183, v181, vcc
	v_mov_b32_e32 v185, v184
	v_pk_mul_f32 v[160:161], v[160:161], v[184:185]
	v_pk_mul_f32 v[162:163], v[162:163], v[184:185]
	v_pk_mul_f32 v[164:165], v[164:165], v[184:185]
	v_pk_mul_f32 v[166:167], v[166:167], v[184:185]
	v_pk_mul_f32 v[168:169], v[168:169], v[184:185]
	v_pk_mul_f32 v[170:171], v[170:171], v[184:185]
	v_pk_mul_f32 v[172:173], v[172:173], v[184:185]
	v_pk_mul_f32 v[174:175], v[174:175], v[184:185]
	v_pk_fma_f32 v[144:145], v[160:161], v[128:129], v[144:145]
	v_pk_fma_f32 v[146:147], v[162:163], v[130:131], v[146:147]
	v_pk_fma_f32 v[148:149], v[164:165], v[132:133], v[148:149]
	v_pk_fma_f32 v[150:151], v[166:167], v[134:135], v[150:151]
	v_pk_fma_f32 v[152:153], v[168:169], v[136:137], v[152:153]
	v_pk_fma_f32 v[154:155], v[170:171], v[138:139], v[154:155]
	v_pk_fma_f32 v[156:157], v[172:173], v[140:141], v[156:157]
	v_pk_fma_f32 v[158:159], v[174:175], v[142:143], v[158:159]
	v_pk_mul_f32 v[252:253], v[144:145], v[144:145]
	v_pk_mul_f32 v[254:255], v[146:147], v[146:147]
	v_pk_fma_f32 v[252:253], v[148:149], v[148:149], v[252:253]
	v_pk_fma_f32 v[254:255], v[150:151], v[150:151], v[254:255]
	v_pk_fma_f32 v[252:253], v[152:153], v[152:153], v[252:253]
	v_pk_fma_f32 v[254:255], v[154:155], v[154:155], v[254:255]
	v_pk_fma_f32 v[252:253], v[156:157], v[156:157], v[252:253]
	v_pk_fma_f32 v[254:255], v[158:159], v[158:159], v[254:255]
	v_pk_add_f32 v[252:253], v[252:253], v[254:255]
	s_nop 0
	v_add_f32_e32 v183, v252, v253
	s_nop 1
	v_add_f32_dpp v183, v183, v183 quad_perm:[1,0,3,2] row_mask:0xf bank_mask:0xf bound_ctrl:1
	s_nop 1
	v_add_f32_dpp v183, v183, v183 quad_perm:[2,3,0,1] row_mask:0xf bank_mask:0xf bound_ctrl:1
	s_nop 1
	v_add_f32_dpp v183, v183, v183 row_half_mirror row_mask:0xf bank_mask:0xf bound_ctrl:1
	s_nop 1
	v_add_f32_dpp v183, v183, v183 row_mirror row_mask:0xf bank_mask:0xf bound_ctrl:1
	s_nop 1
	v_readlane_b32 s98, v183, 0
	v_readlane_b32 s99, v183, 16
	v_readlane_b32 s100, v183, 32
	v_readlane_b32 s101, v183, 48
	s_nop 1
	v_mov_b32_e32 v183, s98
	v_add_f32_e32 v183, s99, v183
	v_add_f32_e32 v183, s100, v183
	v_add_f32_e32 v183, s101, v183
	v_fmamk_f32 v183, v183, 0x3a800000, v182
	v_cmp_gt_f32_e32 vcc, 0x800000, v183
	v_mul_f32_e32 v181, 0x4b800000, v183
	s_nop 1
	v_cndmask_b32_e32 v183, v183, v181, vcc
	v_rsq_f32_e32 v183, v183
	s_nop 0
	v_mul_f32_e32 v181, 0x45800000, v183
	v_cndmask_b32_e32 v184, v183, v181, vcc
	v_mov_b32_e32 v185, v184
	v_cvt_pk_bf16_f32 v32, v144, v145
	v_cvt_pk_bf16_f32 v33, v146, v147
	v_cvt_pk_bf16_f32 v34, v148, v149
	v_cvt_pk_bf16_f32 v35, v150, v151
	v_cvt_pk_bf16_f32 v36, v152, v153
	v_cvt_pk_bf16_f32 v37, v154, v155
	v_cvt_pk_bf16_f32 v38, v156, v157
	v_cvt_pk_bf16_f32 v39, v158, v159
	v_add_u32_e32 v181, 0x2000000, v177
	global_store_dwordx4 v181, v[32:35], s[78:79]
	global_store_dwordx4 v181, v[36:39], s[78:79] offset:1024
	v_add_u32_e32 v236, 0x4000, v237
	s_mov_b64 exec, 1
	global_store_dword v236, v184, s[78:79]
	s_mov_b64 exec, -1
	s_waitcnt vmcnt(16)
	v_lshlrev_b32_e32 v144, 16, v48
	v_and_b32_e32 v145, 0xffff0000, v48
	v_lshlrev_b32_e32 v146, 16, v49
	v_and_b32_e32 v147, 0xffff0000, v49
	v_lshlrev_b32_e32 v148, 16, v50
	v_and_b32_e32 v149, 0xffff0000, v50
	v_lshlrev_b32_e32 v150, 16, v51
	v_and_b32_e32 v151, 0xffff0000, v51
	v_lshlrev_b32_e32 v152, 16, v52
	v_and_b32_e32 v153, 0xffff0000, v52
	v_lshlrev_b32_e32 v154, 16, v53
	v_and_b32_e32 v155, 0xffff0000, v53
	v_lshlrev_b32_e32 v156, 16, v54
	v_and_b32_e32 v157, 0xffff0000, v54
	v_lshlrev_b32_e32 v158, 16, v55
	v_and_b32_e32 v159, 0xffff0000, v55
	v_lshlrev_b32_e32 v160, 16, v56
	v_and_b32_e32 v161, 0xffff0000, v56
	v_lshlrev_b32_e32 v162, 16, v57
	v_and_b32_e32 v163, 0xffff0000, v57
	v_lshlrev_b32_e32 v164, 16, v58
	v_and_b32_e32 v165, 0xffff0000, v58
	v_lshlrev_b32_e32 v166, 16, v59
	v_and_b32_e32 v167, 0xffff0000, v59
	v_lshlrev_b32_e32 v168, 16, v60
	v_and_b32_e32 v169, 0xffff0000, v60
	v_lshlrev_b32_e32 v170, 16, v61
	v_and_b32_e32 v171, 0xffff0000, v61
	v_lshlrev_b32_e32 v172, 16, v62
	v_and_b32_e32 v173, 0xffff0000, v62
	v_lshlrev_b32_e32 v174, 16, v63
	v_and_b32_e32 v175, 0xffff0000, v63
	v_pk_mul_f32 v[252:253], v[160:161], v[160:161]
	v_pk_mul_f32 v[254:255], v[162:163], v[162:163]
	v_pk_fma_f32 v[252:253], v[164:165], v[164:165], v[252:253]
	v_pk_fma_f32 v[254:255], v[166:167], v[166:167], v[254:255]
	v_pk_fma_f32 v[252:253], v[168:169], v[168:169], v[252:253]
	v_pk_fma_f32 v[254:255], v[170:171], v[170:171], v[254:255]
	v_pk_fma_f32 v[252:253], v[172:173], v[172:173], v[252:253]
	v_pk_fma_f32 v[254:255], v[174:175], v[174:175], v[254:255]
	v_pk_add_f32 v[252:253], v[252:253], v[254:255]
	s_nop 0
	v_add_f32_e32 v183, v252, v253
	s_nop 1
	v_add_f32_dpp v183, v183, v183 quad_perm:[1,0,3,2] row_mask:0xf bank_mask:0xf bound_ctrl:1
	s_nop 1
	v_add_f32_dpp v183, v183, v183 quad_perm:[2,3,0,1] row_mask:0xf bank_mask:0xf bound_ctrl:1
	s_nop 1
	v_add_f32_dpp v183, v183, v183 row_half_mirror row_mask:0xf bank_mask:0xf bound_ctrl:1
	s_nop 1
	v_add_f32_dpp v183, v183, v183 row_mirror row_mask:0xf bank_mask:0xf bound_ctrl:1
	s_nop 1
	v_readlane_b32 s98, v183, 0
	v_readlane_b32 s99, v183, 16
	v_readlane_b32 s100, v183, 32
	v_readlane_b32 s101, v183, 48
	s_nop 1
	v_mov_b32_e32 v183, s98
	v_add_f32_e32 v183, s99, v183
	v_add_f32_e32 v183, s100, v183
	v_add_f32_e32 v183, s101, v183
	v_fmamk_f32 v183, v183, 0x3a800000, v182
	v_cmp_gt_f32_e32 vcc, 0x800000, v183
	v_mul_f32_e32 v181, 0x4b800000, v183
	s_nop 1
	v_cndmask_b32_e32 v183, v183, v181, vcc
	v_rsq_f32_e32 v183, v183
	s_nop 0
	v_mul_f32_e32 v181, 0x45800000, v183
	v_cndmask_b32_e32 v184, v183, v181, vcc
	v_mov_b32_e32 v185, v184
	v_pk_mul_f32 v[160:161], v[160:161], v[184:185]
	v_pk_mul_f32 v[162:163], v[162:163], v[184:185]
	v_pk_mul_f32 v[164:165], v[164:165], v[184:185]
	v_pk_mul_f32 v[166:167], v[166:167], v[184:185]
	v_pk_mul_f32 v[168:169], v[168:169], v[184:185]
	v_pk_mul_f32 v[170:171], v[170:171], v[184:185]
	v_pk_mul_f32 v[172:173], v[172:173], v[184:185]
	v_pk_mul_f32 v[174:175], v[174:175], v[184:185]
	v_pk_fma_f32 v[144:145], v[160:161], v[128:129], v[144:145]
	v_pk_fma_f32 v[146:147], v[162:163], v[130:131], v[146:147]
	v_pk_fma_f32 v[148:149], v[164:165], v[132:133], v[148:149]
	v_pk_fma_f32 v[150:151], v[166:167], v[134:135], v[150:151]
	v_pk_fma_f32 v[152:153], v[168:169], v[136:137], v[152:153]
	v_pk_fma_f32 v[154:155], v[170:171], v[138:139], v[154:155]
	v_pk_fma_f32 v[156:157], v[172:173], v[140:141], v[156:157]
	v_pk_fma_f32 v[158:159], v[174:175], v[142:143], v[158:159]
	v_pk_mul_f32 v[252:253], v[144:145], v[144:145]
	v_pk_mul_f32 v[254:255], v[146:147], v[146:147]
	v_pk_fma_f32 v[252:253], v[148:149], v[148:149], v[252:253]
	v_pk_fma_f32 v[254:255], v[150:151], v[150:151], v[254:255]
	v_pk_fma_f32 v[252:253], v[152:153], v[152:153], v[252:253]
	v_pk_fma_f32 v[254:255], v[154:155], v[154:155], v[254:255]
	v_pk_fma_f32 v[252:253], v[156:157], v[156:157], v[252:253]
	v_pk_fma_f32 v[254:255], v[158:159], v[158:159], v[254:255]
	v_pk_add_f32 v[252:253], v[252:253], v[254:255]
	s_nop 0
	v_add_f32_e32 v183, v252, v253
	s_nop 1
	v_add_f32_dpp v183, v183, v183 quad_perm:[1,0,3,2] row_mask:0xf bank_mask:0xf bound_ctrl:1
	s_nop 1
	v_add_f32_dpp v183, v183, v183 quad_perm:[2,3,0,1] row_mask:0xf bank_mask:0xf bound_ctrl:1
	s_nop 1
	v_add_f32_dpp v183, v183, v183 row_half_mirror row_mask:0xf bank_mask:0xf bound_ctrl:1
	s_nop 1
	v_add_f32_dpp v183, v183, v183 row_mirror row_mask:0xf bank_mask:0xf bound_ctrl:1
	s_nop 1
	v_readlane_b32 s98, v183, 0
	v_readlane_b32 s99, v183, 16
	v_readlane_b32 s100, v183, 32
	v_readlane_b32 s101, v183, 48
	s_nop 1
	v_mov_b32_e32 v183, s98
	v_add_f32_e32 v183, s99, v183
	v_add_f32_e32 v183, s100, v183
	v_add_f32_e32 v183, s101, v183
	v_fmamk_f32 v183, v183, 0x3a800000, v182
	v_cmp_gt_f32_e32 vcc, 0x800000, v183
	v_mul_f32_e32 v181, 0x4b800000, v183
	s_nop 1
	v_cndmask_b32_e32 v183, v183, v181, vcc
	v_rsq_f32_e32 v183, v183
	s_nop 0
	v_mul_f32_e32 v181, 0x45800000, v183
	v_cndmask_b32_e32 v184, v183, v181, vcc
	v_mov_b32_e32 v185, v184
	v_cvt_pk_bf16_f32 v48, v144, v145
	v_cvt_pk_bf16_f32 v49, v146, v147
	v_cvt_pk_bf16_f32 v50, v148, v149
	v_cvt_pk_bf16_f32 v51, v150, v151
	v_cvt_pk_bf16_f32 v52, v152, v153
	v_cvt_pk_bf16_f32 v53, v154, v155
	v_cvt_pk_bf16_f32 v54, v156, v157
	v_cvt_pk_bf16_f32 v55, v158, v159
	v_add_u32_e32 v181, 0x2400000, v177
	global_store_dwordx4 v181, v[48:51], s[78:79]
	global_store_dwordx4 v181, v[52:55], s[78:79] offset:1024
	v_add_u32_e32 v236, 0x6000, v237
	s_mov_b64 exec, 1
	global_store_dword v236, v184, s[78:79]
	s_mov_b64 exec, -1
	s_waitcnt vmcnt(12)
	v_lshlrev_b32_e32 v144, 16, v64
	v_and_b32_e32 v145, 0xffff0000, v64
	v_lshlrev_b32_e32 v146, 16, v65
	v_and_b32_e32 v147, 0xffff0000, v65
	v_lshlrev_b32_e32 v148, 16, v66
	v_and_b32_e32 v149, 0xffff0000, v66
	v_lshlrev_b32_e32 v150, 16, v67
	v_and_b32_e32 v151, 0xffff0000, v67
	v_lshlrev_b32_e32 v152, 16, v68
	v_and_b32_e32 v153, 0xffff0000, v68
	v_lshlrev_b32_e32 v154, 16, v69
	v_and_b32_e32 v155, 0xffff0000, v69
	v_lshlrev_b32_e32 v156, 16, v70
	v_and_b32_e32 v157, 0xffff0000, v70
	v_lshlrev_b32_e32 v158, 16, v71
	v_and_b32_e32 v159, 0xffff0000, v71
	v_lshlrev_b32_e32 v160, 16, v72
	v_and_b32_e32 v161, 0xffff0000, v72
	v_lshlrev_b32_e32 v162, 16, v73
	v_and_b32_e32 v163, 0xffff0000, v73
	v_lshlrev_b32_e32 v164, 16, v74
	v_and_b32_e32 v165, 0xffff0000, v74
	v_lshlrev_b32_e32 v166, 16, v75
	v_and_b32_e32 v167, 0xffff0000, v75
	v_lshlrev_b32_e32 v168, 16, v76
	v_and_b32_e32 v169, 0xffff0000, v76
	v_lshlrev_b32_e32 v170, 16, v77
	v_and_b32_e32 v171, 0xffff0000, v77
	v_lshlrev_b32_e32 v172, 16, v78
	v_and_b32_e32 v173, 0xffff0000, v78
	v_lshlrev_b32_e32 v174, 16, v79
	v_and_b32_e32 v175, 0xffff0000, v79
	v_pk_mul_f32 v[252:253], v[160:161], v[160:161]
	v_pk_mul_f32 v[254:255], v[162:163], v[162:163]
	v_pk_fma_f32 v[252:253], v[164:165], v[164:165], v[252:253]
	v_pk_fma_f32 v[254:255], v[166:167], v[166:167], v[254:255]
	v_pk_fma_f32 v[252:253], v[168:169], v[168:169], v[252:253]
	v_pk_fma_f32 v[254:255], v[170:171], v[170:171], v[254:255]
	v_pk_fma_f32 v[252:253], v[172:173], v[172:173], v[252:253]
	v_pk_fma_f32 v[254:255], v[174:175], v[174:175], v[254:255]
	v_pk_add_f32 v[252:253], v[252:253], v[254:255]
	s_nop 0
	v_add_f32_e32 v183, v252, v253
	s_nop 1
	v_add_f32_dpp v183, v183, v183 quad_perm:[1,0,3,2] row_mask:0xf bank_mask:0xf bound_ctrl:1
	s_nop 1
	v_add_f32_dpp v183, v183, v183 quad_perm:[2,3,0,1] row_mask:0xf bank_mask:0xf bound_ctrl:1
	s_nop 1
	v_add_f32_dpp v183, v183, v183 row_half_mirror row_mask:0xf bank_mask:0xf bound_ctrl:1
	s_nop 1
	v_add_f32_dpp v183, v183, v183 row_mirror row_mask:0xf bank_mask:0xf bound_ctrl:1
	s_nop 1
	v_readlane_b32 s98, v183, 0
	v_readlane_b32 s99, v183, 16
	v_readlane_b32 s100, v183, 32
	v_readlane_b32 s101, v183, 48
	s_nop 1
	v_mov_b32_e32 v183, s98
	v_add_f32_e32 v183, s99, v183
	v_add_f32_e32 v183, s100, v183
	v_add_f32_e32 v183, s101, v183
	v_fmamk_f32 v183, v183, 0x3a800000, v182
	v_cmp_gt_f32_e32 vcc, 0x800000, v183
	v_mul_f32_e32 v181, 0x4b800000, v183
	s_nop 1
	v_cndmask_b32_e32 v183, v183, v181, vcc
	v_rsq_f32_e32 v183, v183
	s_nop 0
	v_mul_f32_e32 v181, 0x45800000, v183
	v_cndmask_b32_e32 v184, v183, v181, vcc
	v_mov_b32_e32 v185, v184
	v_pk_mul_f32 v[160:161], v[160:161], v[184:185]
	v_pk_mul_f32 v[162:163], v[162:163], v[184:185]
	v_pk_mul_f32 v[164:165], v[164:165], v[184:185]
	v_pk_mul_f32 v[166:167], v[166:167], v[184:185]
	v_pk_mul_f32 v[168:169], v[168:169], v[184:185]
	v_pk_mul_f32 v[170:171], v[170:171], v[184:185]
	v_pk_mul_f32 v[172:173], v[172:173], v[184:185]
	v_pk_mul_f32 v[174:175], v[174:175], v[184:185]
	v_pk_fma_f32 v[144:145], v[160:161], v[128:129], v[144:145]
	v_pk_fma_f32 v[146:147], v[162:163], v[130:131], v[146:147]
	v_pk_fma_f32 v[148:149], v[164:165], v[132:133], v[148:149]
	v_pk_fma_f32 v[150:151], v[166:167], v[134:135], v[150:151]
	v_pk_fma_f32 v[152:153], v[168:169], v[136:137], v[152:153]
	v_pk_fma_f32 v[154:155], v[170:171], v[138:139], v[154:155]
	v_pk_fma_f32 v[156:157], v[172:173], v[140:141], v[156:157]
	v_pk_fma_f32 v[158:159], v[174:175], v[142:143], v[158:159]
	v_pk_mul_f32 v[252:253], v[144:145], v[144:145]
	v_pk_mul_f32 v[254:255], v[146:147], v[146:147]
	v_pk_fma_f32 v[252:253], v[148:149], v[148:149], v[252:253]
	v_pk_fma_f32 v[254:255], v[150:151], v[150:151], v[254:255]
	v_pk_fma_f32 v[252:253], v[152:153], v[152:153], v[252:253]
	v_pk_fma_f32 v[254:255], v[154:155], v[154:155], v[254:255]
	v_pk_fma_f32 v[252:253], v[156:157], v[156:157], v[252:253]
	v_pk_fma_f32 v[254:255], v[158:159], v[158:159], v[254:255]
	v_pk_add_f32 v[252:253], v[252:253], v[254:255]
	s_nop 0
	v_add_f32_e32 v183, v252, v253
	s_nop 1
	v_add_f32_dpp v183, v183, v183 quad_perm:[1,0,3,2] row_mask:0xf bank_mask:0xf bound_ctrl:1
	s_nop 1
	v_add_f32_dpp v183, v183, v183 quad_perm:[2,3,0,1] row_mask:0xf bank_mask:0xf bound_ctrl:1
	s_nop 1
	v_add_f32_dpp v183, v183, v183 row_half_mirror row_mask:0xf bank_mask:0xf bound_ctrl:1
	s_nop 1
	v_add_f32_dpp v183, v183, v183 row_mirror row_mask:0xf bank_mask:0xf bound_ctrl:1
	s_nop 1
	v_readlane_b32 s98, v183, 0
	v_readlane_b32 s99, v183, 16
	v_readlane_b32 s100, v183, 32
	v_readlane_b32 s101, v183, 48
	s_nop 1
	v_mov_b32_e32 v183, s98
	v_add_f32_e32 v183, s99, v183
	v_add_f32_e32 v183, s100, v183
	v_add_f32_e32 v183, s101, v183
	v_fmamk_f32 v183, v183, 0x3a800000, v182
	v_cmp_gt_f32_e32 vcc, 0x800000, v183
	v_mul_f32_e32 v181, 0x4b800000, v183
	s_nop 1
	v_cndmask_b32_e32 v183, v183, v181, vcc
	v_rsq_f32_e32 v183, v183
	s_nop 0
	v_mul_f32_e32 v181, 0x45800000, v183
	v_cndmask_b32_e32 v184, v183, v181, vcc
	v_mov_b32_e32 v185, v184
	v_cvt_pk_bf16_f32 v64, v144, v145
	v_cvt_pk_bf16_f32 v65, v146, v147
	v_cvt_pk_bf16_f32 v66, v148, v149
	v_cvt_pk_bf16_f32 v67, v150, v151
	v_cvt_pk_bf16_f32 v68, v152, v153
	v_cvt_pk_bf16_f32 v69, v154, v155
	v_cvt_pk_bf16_f32 v70, v156, v157
	v_cvt_pk_bf16_f32 v71, v158, v159
	v_add_u32_e32 v181, 0x2800000, v177
	global_store_dwordx4 v181, v[64:67], s[78:79]
	global_store_dwordx4 v181, v[68:71], s[78:79] offset:1024
	v_add_u32_e32 v236, 0x8000, v237
	s_mov_b64 exec, 1
	global_store_dword v236, v184, s[78:79]
	s_mov_b64 exec, -1
	s_waitcnt vmcnt(8)
	v_lshlrev_b32_e32 v144, 16, v80
	v_and_b32_e32 v145, 0xffff0000, v80
	v_lshlrev_b32_e32 v146, 16, v81
	v_and_b32_e32 v147, 0xffff0000, v81
	v_lshlrev_b32_e32 v148, 16, v82
	v_and_b32_e32 v149, 0xffff0000, v82
	v_lshlrev_b32_e32 v150, 16, v83
	v_and_b32_e32 v151, 0xffff0000, v83
	v_lshlrev_b32_e32 v152, 16, v84
	v_and_b32_e32 v153, 0xffff0000, v84
	v_lshlrev_b32_e32 v154, 16, v85
	v_and_b32_e32 v155, 0xffff0000, v85
	v_lshlrev_b32_e32 v156, 16, v86
	v_and_b32_e32 v157, 0xffff0000, v86
	v_lshlrev_b32_e32 v158, 16, v87
	v_and_b32_e32 v159, 0xffff0000, v87
	v_lshlrev_b32_e32 v160, 16, v88
	v_and_b32_e32 v161, 0xffff0000, v88
	v_lshlrev_b32_e32 v162, 16, v89
	v_and_b32_e32 v163, 0xffff0000, v89
	v_lshlrev_b32_e32 v164, 16, v90
	v_and_b32_e32 v165, 0xffff0000, v90
	v_lshlrev_b32_e32 v166, 16, v91
	v_and_b32_e32 v167, 0xffff0000, v91
	v_lshlrev_b32_e32 v168, 16, v92
	v_and_b32_e32 v169, 0xffff0000, v92
	v_lshlrev_b32_e32 v170, 16, v93
	v_and_b32_e32 v171, 0xffff0000, v93
	v_lshlrev_b32_e32 v172, 16, v94
	v_and_b32_e32 v173, 0xffff0000, v94
	v_lshlrev_b32_e32 v174, 16, v95
	v_and_b32_e32 v175, 0xffff0000, v95
	v_pk_mul_f32 v[252:253], v[160:161], v[160:161]
	v_pk_mul_f32 v[254:255], v[162:163], v[162:163]
	v_pk_fma_f32 v[252:253], v[164:165], v[164:165], v[252:253]
	v_pk_fma_f32 v[254:255], v[166:167], v[166:167], v[254:255]
	v_pk_fma_f32 v[252:253], v[168:169], v[168:169], v[252:253]
	v_pk_fma_f32 v[254:255], v[170:171], v[170:171], v[254:255]
	v_pk_fma_f32 v[252:253], v[172:173], v[172:173], v[252:253]
	v_pk_fma_f32 v[254:255], v[174:175], v[174:175], v[254:255]
	v_pk_add_f32 v[252:253], v[252:253], v[254:255]
	s_nop 0
	v_add_f32_e32 v183, v252, v253
	s_nop 1
	v_add_f32_dpp v183, v183, v183 quad_perm:[1,0,3,2] row_mask:0xf bank_mask:0xf bound_ctrl:1
	s_nop 1
	v_add_f32_dpp v183, v183, v183 quad_perm:[2,3,0,1] row_mask:0xf bank_mask:0xf bound_ctrl:1
	s_nop 1
	v_add_f32_dpp v183, v183, v183 row_half_mirror row_mask:0xf bank_mask:0xf bound_ctrl:1
	s_nop 1
	v_add_f32_dpp v183, v183, v183 row_mirror row_mask:0xf bank_mask:0xf bound_ctrl:1
	s_nop 1
	v_readlane_b32 s98, v183, 0
	v_readlane_b32 s99, v183, 16
	v_readlane_b32 s100, v183, 32
	v_readlane_b32 s101, v183, 48
	s_nop 1
	v_mov_b32_e32 v183, s98
	v_add_f32_e32 v183, s99, v183
	v_add_f32_e32 v183, s100, v183
	v_add_f32_e32 v183, s101, v183
	v_fmamk_f32 v183, v183, 0x3a800000, v182
	v_cmp_gt_f32_e32 vcc, 0x800000, v183
	v_mul_f32_e32 v181, 0x4b800000, v183
	s_nop 1
	v_cndmask_b32_e32 v183, v183, v181, vcc
	v_rsq_f32_e32 v183, v183
	s_nop 0
	v_mul_f32_e32 v181, 0x45800000, v183
	v_cndmask_b32_e32 v184, v183, v181, vcc
	v_mov_b32_e32 v185, v184
	v_pk_mul_f32 v[160:161], v[160:161], v[184:185]
	v_pk_mul_f32 v[162:163], v[162:163], v[184:185]
	v_pk_mul_f32 v[164:165], v[164:165], v[184:185]
	v_pk_mul_f32 v[166:167], v[166:167], v[184:185]
	v_pk_mul_f32 v[168:169], v[168:169], v[184:185]
	v_pk_mul_f32 v[170:171], v[170:171], v[184:185]
	v_pk_mul_f32 v[172:173], v[172:173], v[184:185]
	v_pk_mul_f32 v[174:175], v[174:175], v[184:185]
	v_pk_fma_f32 v[144:145], v[160:161], v[128:129], v[144:145]
	v_pk_fma_f32 v[146:147], v[162:163], v[130:131], v[146:147]
	v_pk_fma_f32 v[148:149], v[164:165], v[132:133], v[148:149]
	v_pk_fma_f32 v[150:151], v[166:167], v[134:135], v[150:151]
	v_pk_fma_f32 v[152:153], v[168:169], v[136:137], v[152:153]
	v_pk_fma_f32 v[154:155], v[170:171], v[138:139], v[154:155]
	v_pk_fma_f32 v[156:157], v[172:173], v[140:141], v[156:157]
	v_pk_fma_f32 v[158:159], v[174:175], v[142:143], v[158:159]
	v_pk_mul_f32 v[252:253], v[144:145], v[144:145]
	v_pk_mul_f32 v[254:255], v[146:147], v[146:147]
	v_pk_fma_f32 v[252:253], v[148:149], v[148:149], v[252:253]
	v_pk_fma_f32 v[254:255], v[150:151], v[150:151], v[254:255]
	v_pk_fma_f32 v[252:253], v[152:153], v[152:153], v[252:253]
	v_pk_fma_f32 v[254:255], v[154:155], v[154:155], v[254:255]
	v_pk_fma_f32 v[252:253], v[156:157], v[156:157], v[252:253]
	v_pk_fma_f32 v[254:255], v[158:159], v[158:159], v[254:255]
	v_pk_add_f32 v[252:253], v[252:253], v[254:255]
	s_nop 0
	v_add_f32_e32 v183, v252, v253
	s_nop 1
	v_add_f32_dpp v183, v183, v183 quad_perm:[1,0,3,2] row_mask:0xf bank_mask:0xf bound_ctrl:1
	s_nop 1
	v_add_f32_dpp v183, v183, v183 quad_perm:[2,3,0,1] row_mask:0xf bank_mask:0xf bound_ctrl:1
	s_nop 1
	v_add_f32_dpp v183, v183, v183 row_half_mirror row_mask:0xf bank_mask:0xf bound_ctrl:1
	s_nop 1
	v_add_f32_dpp v183, v183, v183 row_mirror row_mask:0xf bank_mask:0xf bound_ctrl:1
	s_nop 1
	v_readlane_b32 s98, v183, 0
	v_readlane_b32 s99, v183, 16
	v_readlane_b32 s100, v183, 32
	v_readlane_b32 s101, v183, 48
	s_nop 1
	v_mov_b32_e32 v183, s98
	v_add_f32_e32 v183, s99, v183
	v_add_f32_e32 v183, s100, v183
	v_add_f32_e32 v183, s101, v183
	v_fmamk_f32 v183, v183, 0x3a800000, v182
	v_cmp_gt_f32_e32 vcc, 0x800000, v183
	v_mul_f32_e32 v181, 0x4b800000, v183
	s_nop 1
	v_cndmask_b32_e32 v183, v183, v181, vcc
	v_rsq_f32_e32 v183, v183
	s_nop 0
	v_mul_f32_e32 v181, 0x45800000, v183
	v_cndmask_b32_e32 v184, v183, v181, vcc
	v_mov_b32_e32 v185, v184
	v_cvt_pk_bf16_f32 v80, v144, v145
	v_cvt_pk_bf16_f32 v81, v146, v147
	v_cvt_pk_bf16_f32 v82, v148, v149
	v_cvt_pk_bf16_f32 v83, v150, v151
	v_cvt_pk_bf16_f32 v84, v152, v153
	v_cvt_pk_bf16_f32 v85, v154, v155
	v_cvt_pk_bf16_f32 v86, v156, v157
	v_cvt_pk_bf16_f32 v87, v158, v159
	v_add_u32_e32 v181, 0x2c00000, v177
	global_store_dwordx4 v181, v[80:83], s[78:79]
	global_store_dwordx4 v181, v[84:87], s[78:79] offset:1024
	v_add_u32_e32 v236, 0xa000, v237
	s_mov_b64 exec, 1
	global_store_dword v236, v184, s[78:79]
	s_mov_b64 exec, -1
	s_waitcnt vmcnt(4)
	v_lshlrev_b32_e32 v144, 16, v96
	v_and_b32_e32 v145, 0xffff0000, v96
	v_lshlrev_b32_e32 v146, 16, v97
	v_and_b32_e32 v147, 0xffff0000, v97
	v_lshlrev_b32_e32 v148, 16, v98
	v_and_b32_e32 v149, 0xffff0000, v98
	v_lshlrev_b32_e32 v150, 16, v99
	v_and_b32_e32 v151, 0xffff0000, v99
	v_lshlrev_b32_e32 v152, 16, v100
	v_and_b32_e32 v153, 0xffff0000, v100
	v_lshlrev_b32_e32 v154, 16, v101
	v_and_b32_e32 v155, 0xffff0000, v101
	v_lshlrev_b32_e32 v156, 16, v102
	v_and_b32_e32 v157, 0xffff0000, v102
	v_lshlrev_b32_e32 v158, 16, v103
	v_and_b32_e32 v159, 0xffff0000, v103
	v_lshlrev_b32_e32 v160, 16, v104
	v_and_b32_e32 v161, 0xffff0000, v104
	v_lshlrev_b32_e32 v162, 16, v105
	v_and_b32_e32 v163, 0xffff0000, v105
	v_lshlrev_b32_e32 v164, 16, v106
	v_and_b32_e32 v165, 0xffff0000, v106
	v_lshlrev_b32_e32 v166, 16, v107
	v_and_b32_e32 v167, 0xffff0000, v107
	v_lshlrev_b32_e32 v168, 16, v108
	v_and_b32_e32 v169, 0xffff0000, v108
	v_lshlrev_b32_e32 v170, 16, v109
	v_and_b32_e32 v171, 0xffff0000, v109
	v_lshlrev_b32_e32 v172, 16, v110
	v_and_b32_e32 v173, 0xffff0000, v110
	v_lshlrev_b32_e32 v174, 16, v111
	v_and_b32_e32 v175, 0xffff0000, v111
	v_pk_mul_f32 v[252:253], v[160:161], v[160:161]
	v_pk_mul_f32 v[254:255], v[162:163], v[162:163]
	v_pk_fma_f32 v[252:253], v[164:165], v[164:165], v[252:253]
	v_pk_fma_f32 v[254:255], v[166:167], v[166:167], v[254:255]
	v_pk_fma_f32 v[252:253], v[168:169], v[168:169], v[252:253]
	v_pk_fma_f32 v[254:255], v[170:171], v[170:171], v[254:255]
	v_pk_fma_f32 v[252:253], v[172:173], v[172:173], v[252:253]
	v_pk_fma_f32 v[254:255], v[174:175], v[174:175], v[254:255]
	v_pk_add_f32 v[252:253], v[252:253], v[254:255]
	s_nop 0
	v_add_f32_e32 v183, v252, v253
	s_nop 1
	v_add_f32_dpp v183, v183, v183 quad_perm:[1,0,3,2] row_mask:0xf bank_mask:0xf bound_ctrl:1
	s_nop 1
	v_add_f32_dpp v183, v183, v183 quad_perm:[2,3,0,1] row_mask:0xf bank_mask:0xf bound_ctrl:1
	s_nop 1
	v_add_f32_dpp v183, v183, v183 row_half_mirror row_mask:0xf bank_mask:0xf bound_ctrl:1
	s_nop 1
	v_add_f32_dpp v183, v183, v183 row_mirror row_mask:0xf bank_mask:0xf bound_ctrl:1
	s_nop 1
	v_readlane_b32 s98, v183, 0
	v_readlane_b32 s99, v183, 16
	v_readlane_b32 s100, v183, 32
	v_readlane_b32 s101, v183, 48
	s_nop 1
	v_mov_b32_e32 v183, s98
	v_add_f32_e32 v183, s99, v183
	v_add_f32_e32 v183, s100, v183
	v_add_f32_e32 v183, s101, v183
	v_fmamk_f32 v183, v183, 0x3a800000, v182
	v_cmp_gt_f32_e32 vcc, 0x800000, v183
	v_mul_f32_e32 v181, 0x4b800000, v183
	s_nop 1
	v_cndmask_b32_e32 v183, v183, v181, vcc
	v_rsq_f32_e32 v183, v183
	s_nop 0
	v_mul_f32_e32 v181, 0x45800000, v183
	v_cndmask_b32_e32 v184, v183, v181, vcc
	v_mov_b32_e32 v185, v184
	v_pk_mul_f32 v[160:161], v[160:161], v[184:185]
	v_pk_mul_f32 v[162:163], v[162:163], v[184:185]
	v_pk_mul_f32 v[164:165], v[164:165], v[184:185]
	v_pk_mul_f32 v[166:167], v[166:167], v[184:185]
	v_pk_mul_f32 v[168:169], v[168:169], v[184:185]
	v_pk_mul_f32 v[170:171], v[170:171], v[184:185]
	v_pk_mul_f32 v[172:173], v[172:173], v[184:185]
	v_pk_mul_f32 v[174:175], v[174:175], v[184:185]
	v_pk_fma_f32 v[144:145], v[160:161], v[128:129], v[144:145]
	v_pk_fma_f32 v[146:147], v[162:163], v[130:131], v[146:147]
	v_pk_fma_f32 v[148:149], v[164:165], v[132:133], v[148:149]
	v_pk_fma_f32 v[150:151], v[166:167], v[134:135], v[150:151]
	v_pk_fma_f32 v[152:153], v[168:169], v[136:137], v[152:153]
	v_pk_fma_f32 v[154:155], v[170:171], v[138:139], v[154:155]
	v_pk_fma_f32 v[156:157], v[172:173], v[140:141], v[156:157]
	v_pk_fma_f32 v[158:159], v[174:175], v[142:143], v[158:159]
	v_pk_mul_f32 v[252:253], v[144:145], v[144:145]
	v_pk_mul_f32 v[254:255], v[146:147], v[146:147]
	v_pk_fma_f32 v[252:253], v[148:149], v[148:149], v[252:253]
	v_pk_fma_f32 v[254:255], v[150:151], v[150:151], v[254:255]
	v_pk_fma_f32 v[252:253], v[152:153], v[152:153], v[252:253]
	v_pk_fma_f32 v[254:255], v[154:155], v[154:155], v[254:255]
	v_pk_fma_f32 v[252:253], v[156:157], v[156:157], v[252:253]
	v_pk_fma_f32 v[254:255], v[158:159], v[158:159], v[254:255]
	v_pk_add_f32 v[252:253], v[252:253], v[254:255]
	s_nop 0
	v_add_f32_e32 v183, v252, v253
	s_nop 1
	v_add_f32_dpp v183, v183, v183 quad_perm:[1,0,3,2] row_mask:0xf bank_mask:0xf bound_ctrl:1
	s_nop 1
	v_add_f32_dpp v183, v183, v183 quad_perm:[2,3,0,1] row_mask:0xf bank_mask:0xf bound_ctrl:1
	s_nop 1
	v_add_f32_dpp v183, v183, v183 row_half_mirror row_mask:0xf bank_mask:0xf bound_ctrl:1
	s_nop 1
	v_add_f32_dpp v183, v183, v183 row_mirror row_mask:0xf bank_mask:0xf bound_ctrl:1
	s_nop 1
	v_readlane_b32 s98, v183, 0
	v_readlane_b32 s99, v183, 16
	v_readlane_b32 s100, v183, 32
	v_readlane_b32 s101, v183, 48
	s_nop 1
	v_mov_b32_e32 v183, s98
	v_add_f32_e32 v183, s99, v183
	v_add_f32_e32 v183, s100, v183
	v_add_f32_e32 v183, s101, v183
	v_fmamk_f32 v183, v183, 0x3a800000, v182
	v_cmp_gt_f32_e32 vcc, 0x800000, v183
	v_mul_f32_e32 v181, 0x4b800000, v183
	s_nop 1
	v_cndmask_b32_e32 v183, v183, v181, vcc
	v_rsq_f32_e32 v183, v183
	s_nop 0
	v_mul_f32_e32 v181, 0x45800000, v183
	v_cndmask_b32_e32 v184, v183, v181, vcc
	v_mov_b32_e32 v185, v184
	v_cvt_pk_bf16_f32 v96, v144, v145
	v_cvt_pk_bf16_f32 v97, v146, v147
	v_cvt_pk_bf16_f32 v98, v148, v149
	v_cvt_pk_bf16_f32 v99, v150, v151
	v_cvt_pk_bf16_f32 v100, v152, v153
	v_cvt_pk_bf16_f32 v101, v154, v155
	v_cvt_pk_bf16_f32 v102, v156, v157
	v_cvt_pk_bf16_f32 v103, v158, v159
	v_add_u32_e32 v181, 0x3000000, v177
	global_store_dwordx4 v181, v[96:99], s[78:79]
	global_store_dwordx4 v181, v[100:103], s[78:79] offset:1024
	v_add_u32_e32 v236, 0xc000, v237
	s_mov_b64 exec, 1
	global_store_dword v236, v184, s[78:79]
	s_mov_b64 exec, -1
	s_waitcnt vmcnt(0)
	v_lshlrev_b32_e32 v144, 16, v112
	v_and_b32_e32 v145, 0xffff0000, v112
	v_lshlrev_b32_e32 v146, 16, v113
	v_and_b32_e32 v147, 0xffff0000, v113
	v_lshlrev_b32_e32 v148, 16, v114
	v_and_b32_e32 v149, 0xffff0000, v114
	v_lshlrev_b32_e32 v150, 16, v115
	v_and_b32_e32 v151, 0xffff0000, v115
	v_lshlrev_b32_e32 v152, 16, v116
	v_and_b32_e32 v153, 0xffff0000, v116
	v_lshlrev_b32_e32 v154, 16, v117
	v_and_b32_e32 v155, 0xffff0000, v117
	v_lshlrev_b32_e32 v156, 16, v118
	v_and_b32_e32 v157, 0xffff0000, v118
	v_lshlrev_b32_e32 v158, 16, v119
	v_and_b32_e32 v159, 0xffff0000, v119
	v_lshlrev_b32_e32 v160, 16, v120
	v_and_b32_e32 v161, 0xffff0000, v120
	v_lshlrev_b32_e32 v162, 16, v121
	v_and_b32_e32 v163, 0xffff0000, v121
	v_lshlrev_b32_e32 v164, 16, v122
	v_and_b32_e32 v165, 0xffff0000, v122
	v_lshlrev_b32_e32 v166, 16, v123
	v_and_b32_e32 v167, 0xffff0000, v123
	v_lshlrev_b32_e32 v168, 16, v124
	v_and_b32_e32 v169, 0xffff0000, v124
	v_lshlrev_b32_e32 v170, 16, v125
	v_and_b32_e32 v171, 0xffff0000, v125
	v_lshlrev_b32_e32 v172, 16, v126
	v_and_b32_e32 v173, 0xffff0000, v126
	v_lshlrev_b32_e32 v174, 16, v127
	v_and_b32_e32 v175, 0xffff0000, v127
	v_pk_mul_f32 v[252:253], v[160:161], v[160:161]
	v_pk_mul_f32 v[254:255], v[162:163], v[162:163]
	v_pk_fma_f32 v[252:253], v[164:165], v[164:165], v[252:253]
	v_pk_fma_f32 v[254:255], v[166:167], v[166:167], v[254:255]
	v_pk_fma_f32 v[252:253], v[168:169], v[168:169], v[252:253]
	v_pk_fma_f32 v[254:255], v[170:171], v[170:171], v[254:255]
	v_pk_fma_f32 v[252:253], v[172:173], v[172:173], v[252:253]
	v_pk_fma_f32 v[254:255], v[174:175], v[174:175], v[254:255]
	v_pk_add_f32 v[252:253], v[252:253], v[254:255]
	s_nop 0
	v_add_f32_e32 v183, v252, v253
	s_nop 1
	v_add_f32_dpp v183, v183, v183 quad_perm:[1,0,3,2] row_mask:0xf bank_mask:0xf bound_ctrl:1
	s_nop 1
	v_add_f32_dpp v183, v183, v183 quad_perm:[2,3,0,1] row_mask:0xf bank_mask:0xf bound_ctrl:1
	s_nop 1
	v_add_f32_dpp v183, v183, v183 row_half_mirror row_mask:0xf bank_mask:0xf bound_ctrl:1
	s_nop 1
	v_add_f32_dpp v183, v183, v183 row_mirror row_mask:0xf bank_mask:0xf bound_ctrl:1
	s_nop 1
	v_readlane_b32 s98, v183, 0
	v_readlane_b32 s99, v183, 16
	v_readlane_b32 s100, v183, 32
	v_readlane_b32 s101, v183, 48
	s_nop 1
	v_mov_b32_e32 v183, s98
	v_add_f32_e32 v183, s99, v183
	v_add_f32_e32 v183, s100, v183
	v_add_f32_e32 v183, s101, v183
	v_fmamk_f32 v183, v183, 0x3a800000, v182
	v_cmp_gt_f32_e32 vcc, 0x800000, v183
	v_mul_f32_e32 v181, 0x4b800000, v183
	s_nop 1
	v_cndmask_b32_e32 v183, v183, v181, vcc
	v_rsq_f32_e32 v183, v183
	s_nop 0
	v_mul_f32_e32 v181, 0x45800000, v183
	v_cndmask_b32_e32 v184, v183, v181, vcc
	v_mov_b32_e32 v185, v184
	v_pk_mul_f32 v[160:161], v[160:161], v[184:185]
	v_pk_mul_f32 v[162:163], v[162:163], v[184:185]
	v_pk_mul_f32 v[164:165], v[164:165], v[184:185]
	v_pk_mul_f32 v[166:167], v[166:167], v[184:185]
	v_pk_mul_f32 v[168:169], v[168:169], v[184:185]
	v_pk_mul_f32 v[170:171], v[170:171], v[184:185]
	v_pk_mul_f32 v[172:173], v[172:173], v[184:185]
	v_pk_mul_f32 v[174:175], v[174:175], v[184:185]
	v_pk_fma_f32 v[144:145], v[160:161], v[128:129], v[144:145]
	v_pk_fma_f32 v[146:147], v[162:163], v[130:131], v[146:147]
	v_pk_fma_f32 v[148:149], v[164:165], v[132:133], v[148:149]
	v_pk_fma_f32 v[150:151], v[166:167], v[134:135], v[150:151]
	v_pk_fma_f32 v[152:153], v[168:169], v[136:137], v[152:153]
	v_pk_fma_f32 v[154:155], v[170:171], v[138:139], v[154:155]
	v_pk_fma_f32 v[156:157], v[172:173], v[140:141], v[156:157]
	v_pk_fma_f32 v[158:159], v[174:175], v[142:143], v[158:159]
	v_pk_mul_f32 v[252:253], v[144:145], v[144:145]
	v_pk_mul_f32 v[254:255], v[146:147], v[146:147]
	v_pk_fma_f32 v[252:253], v[148:149], v[148:149], v[252:253]
	v_pk_fma_f32 v[254:255], v[150:151], v[150:151], v[254:255]
	v_pk_fma_f32 v[252:253], v[152:153], v[152:153], v[252:253]
	v_pk_fma_f32 v[254:255], v[154:155], v[154:155], v[254:255]
	v_pk_fma_f32 v[252:253], v[156:157], v[156:157], v[252:253]
	v_pk_fma_f32 v[254:255], v[158:159], v[158:159], v[254:255]
	v_pk_add_f32 v[252:253], v[252:253], v[254:255]
	s_nop 0
	v_add_f32_e32 v183, v252, v253
	s_nop 1
	v_add_f32_dpp v183, v183, v183 quad_perm:[1,0,3,2] row_mask:0xf bank_mask:0xf bound_ctrl:1
	s_nop 1
	v_add_f32_dpp v183, v183, v183 quad_perm:[2,3,0,1] row_mask:0xf bank_mask:0xf bound_ctrl:1
	s_nop 1
	v_add_f32_dpp v183, v183, v183 row_half_mirror row_mask:0xf bank_mask:0xf bound_ctrl:1
	s_nop 1
	v_add_f32_dpp v183, v183, v183 row_mirror row_mask:0xf bank_mask:0xf bound_ctrl:1
	s_nop 1
	v_readlane_b32 s98, v183, 0
	v_readlane_b32 s99, v183, 16
	v_readlane_b32 s100, v183, 32
	v_readlane_b32 s101, v183, 48
	s_nop 1
	v_mov_b32_e32 v183, s98
	v_add_f32_e32 v183, s99, v183
	v_add_f32_e32 v183, s100, v183
	v_add_f32_e32 v183, s101, v183
	v_fmamk_f32 v183, v183, 0x3a800000, v182
	v_cmp_gt_f32_e32 vcc, 0x800000, v183
	v_mul_f32_e32 v181, 0x4b800000, v183
	s_nop 1
	v_cndmask_b32_e32 v183, v183, v181, vcc
	v_rsq_f32_e32 v183, v183
	s_nop 0
	v_mul_f32_e32 v181, 0x45800000, v183
	v_cndmask_b32_e32 v184, v183, v181, vcc
	v_mov_b32_e32 v185, v184
	v_cvt_pk_bf16_f32 v112, v144, v145
	v_cvt_pk_bf16_f32 v113, v146, v147
	v_cvt_pk_bf16_f32 v114, v148, v149
	v_cvt_pk_bf16_f32 v115, v150, v151
	v_cvt_pk_bf16_f32 v116, v152, v153
	v_cvt_pk_bf16_f32 v117, v154, v155
	v_cvt_pk_bf16_f32 v118, v156, v157
	v_cvt_pk_bf16_f32 v119, v158, v159
	v_add_u32_e32 v181, 0x3400000, v177
	global_store_dwordx4 v181, v[112:115], s[78:79]
	global_store_dwordx4 v181, v[116:119], s[78:79] offset:1024
	v_add_u32_e32 v236, 0xe000, v237
	s_mov_b64 exec, 1
	global_store_dword v236, v184, s[78:79]
	s_mov_b64 exec, -1
	v_readfirstlane_b32 s98, v179
	s_nop 3
	s_and_b32 s99, s98, 3
	s_cmp_lg_u32 s99, 0
	s_cbranch_scc1 .Lmyxupd_done_5
	v_lshrrev_b32_e32 v179, 2, v179
	v_lshlrev_b32_e32 v177, 4, v176
	v_lshl_add_u32 v177, v179, 11, v177
	v_lshlrev_b32_e32 v237, 2, v179
	v_add_u32_e32 v237, 0x10000, v237
	v_add_u32_e32 v181, 0x3800000, v177
	global_load_dwordx4 v[240:243], v181, s[78:79]
	global_load_dwordx4 v[244:247], v181, s[78:79] offset:1024
	v_lshl_add_u32 v183, v179, 12, v180
	v_add_u32_e32 v183, 0xbf00000, v183
	v_add_u32_e32 v181, 0x0, v183
	global_load_dwordx4 v[0:3], v181, s[78:79]
	global_load_dwordx4 v[4:7], v181, s[78:79] offset:16
	global_load_dwordx4 v[8:11], v181, s[78:79] offset:2048
	global_load_dwordx4 v[12:15], v181, s[78:79] offset:2064
	v_add_u32_e32 v181, 0x200000, v183
	global_load_dwordx4 v[16:19], v181, s[78:79]
	global_load_dwordx4 v[20:23], v181, s[78:79] offset:16
	global_load_dwordx4 v[24:27], v181, s[78:79] offset:2048
	global_load_dwordx4 v[28:31], v181, s[78:79] offset:2064
	v_add_u32_e32 v181, 0x400000, v183
	global_load_dwordx4 v[32:35], v181, s[78:79]
	global_load_dwordx4 v[36:39], v181, s[78:79] offset:16
	global_load_dwordx4 v[40:43], v181, s[78:79] offset:2048
	global_load_dwordx4 v[44:47], v181, s[78:79] offset:2064
	v_add_u32_e32 v181, 0x600000, v183
	global_load_dwordx4 v[48:51], v181, s[78:79]
	global_load_dwordx4 v[52:55], v181, s[78:79] offset:16
	global_load_dwordx4 v[56:59], v181, s[78:79] offset:2048
	global_load_dwordx4 v[60:63], v181, s[78:79] offset:2064
	v_add_u32_e32 v181, 0x800000, v183
	global_load_dwordx4 v[64:67], v181, s[78:79]
	global_load_dwordx4 v[68:71], v181, s[78:79] offset:16
	global_load_dwordx4 v[72:75], v181, s[78:79] offset:2048
	global_load_dwordx4 v[76:79], v181, s[78:79] offset:2064
	v_add_u32_e32 v181, 0xa00000, v183
	global_load_dwordx4 v[80:83], v181, s[78:79]
	global_load_dwordx4 v[84:87], v181, s[78:79] offset:16
	global_load_dwordx4 v[88:91], v181, s[78:79] offset:2048
	global_load_dwordx4 v[92:95], v181, s[78:79] offset:2064
	v_add_u32_e32 v181, 0xc00000, v183
	global_load_dwordx4 v[96:99], v181, s[78:79]
	global_load_dwordx4 v[100:103], v181, s[78:79] offset:16
	global_load_dwordx4 v[104:107], v181, s[78:79] offset:2048
	global_load_dwordx4 v[108:111], v181, s[78:79] offset:2064
	v_add_u32_e32 v181, 0xe00000, v183
	global_load_dwordx4 v[112:115], v181, s[78:79]
	global_load_dwordx4 v[116:119], v181, s[78:79] offset:16
	global_load_dwordx4 v[120:123], v181, s[78:79] offset:2048
	global_load_dwordx4 v[124:127], v181, s[78:79] offset:2064
	s_waitcnt vmcnt(28)
	v_pk_add_f32 v[160:161], v[0:1], 0 op_sel_hi:[1,0]
	v_pk_add_f32 v[162:163], v[2:3], 0 op_sel_hi:[1,0]
	v_pk_add_f32 v[164:165], v[4:5], 0 op_sel_hi:[1,0]
	v_pk_add_f32 v[166:167], v[6:7], 0 op_sel_hi:[1,0]
	v_pk_add_f32 v[168:169], v[8:9], 0 op_sel_hi:[1,0]
	v_pk_add_f32 v[170:171], v[10:11], 0 op_sel_hi:[1,0]
	v_pk_add_f32 v[172:173], v[12:13], 0 op_sel_hi:[1,0]
	v_pk_add_f32 v[174:175], v[14:15], 0 op_sel_hi:[1,0]
	s_waitcnt vmcnt(24)
	v_pk_add_f32 v[160:161], v[160:161], v[16:17]
	v_pk_add_f32 v[162:163], v[162:163], v[18:19]
	v_pk_add_f32 v[164:165], v[164:165], v[20:21]
	v_pk_add_f32 v[166:167], v[166:167], v[22:23]
	v_pk_add_f32 v[168:169], v[168:169], v[24:25]
	v_pk_add_f32 v[170:171], v[170:171], v[26:27]
	v_pk_add_f32 v[172:173], v[172:173], v[28:29]
	v_pk_add_f32 v[174:175], v[174:175], v[30:31]
	s_waitcnt vmcnt(20)
	v_pk_add_f32 v[160:161], v[160:161], v[32:33]
	v_pk_add_f32 v[162:163], v[162:163], v[34:35]
	v_pk_add_f32 v[164:165], v[164:165], v[36:37]
	v_pk_add_f32 v[166:167], v[166:167], v[38:39]
	v_pk_add_f32 v[168:169], v[168:169], v[40:41]
	v_pk_add_f32 v[170:171], v[170:171], v[42:43]
	v_pk_add_f32 v[172:173], v[172:173], v[44:45]
	v_pk_add_f32 v[174:175], v[174:175], v[46:47]
	v_add_u32_e32 v181, 0x1000000, v183
	global_load_dwordx4 v[0:3], v181, s[78:79]
	global_load_dwordx4 v[4:7], v181, s[78:79] offset:16
	global_load_dwordx4 v[8:11], v181, s[78:79] offset:2048
	global_load_dwordx4 v[12:15], v181, s[78:79] offset:2064
	v_add_u32_e32 v181, 0x1200000, v183
	global_load_dwordx4 v[16:19], v181, s[78:79]
	global_load_dwordx4 v[20:23], v181, s[78:79] offset:16
	global_load_dwordx4 v[24:27], v181, s[78:79] offset:2048
	global_load_dwordx4 v[28:31], v181, s[78:79] offset:2064
	v_add_u32_e32 v181, 0x1400000, v183
	global_load_dwordx4 v[32:35], v181, s[78:79]
	global_load_dwordx4 v[36:39], v181, s[78:79] offset:16
	global_load_dwordx4 v[40:43], v181, s[78:79] offset:2048
	global_load_dwordx4 v[44:47], v181, s[78:79] offset:2064
	s_waitcnt vmcnt(28)
	v_pk_add_f32 v[160:161], v[160:161], v[48:49]
	v_pk_add_f32 v[162:163], v[162:163], v[50:51]
	v_pk_add_f32 v[164:165], v[164:165], v[52:53]
	v_pk_add_f32 v[166:167], v[166:167], v[54:55]
	v_pk_add_f32 v[168:169], v[168:169], v[56:57]
	v_pk_add_f32 v[170:171], v[170:171], v[58:59]
	v_pk_add_f32 v[172:173], v[172:173], v[60:61]
	v_pk_add_f32 v[174:175], v[174:175], v[62:63]
	s_waitcnt vmcnt(24)
	v_pk_add_f32 v[160:161], v[160:161], v[64:65]
	v_pk_add_f32 v[162:163], v[162:163], v[66:67]
	v_pk_add_f32 v[164:165], v[164:165], v[68:69]
	v_pk_add_f32 v[166:167], v[166:167], v[70:71]
	v_pk_add_f32 v[168:169], v[168:169], v[72:73]
	v_pk_add_f32 v[170:171], v[170:171], v[74:75]
	v_pk_add_f32 v[172:173], v[172:173], v[76:77]
	v_pk_add_f32 v[174:175], v[174:175], v[78:79]
	s_waitcnt vmcnt(20)
	v_pk_add_f32 v[160:161], v[160:161], v[80:81]
	v_pk_add_f32 v[162:163], v[162:163], v[82:83]
	v_pk_add_f32 v[164:165], v[164:165], v[84:85]
	v_pk_add_f32 v[166:167], v[166:167], v[86:87]
	v_pk_add_f32 v[168:169], v[168:169], v[88:89]
	v_pk_add_f32 v[170:171], v[170:171], v[90:91]
	v_pk_add_f32 v[172:173], v[172:173], v[92:93]
	v_pk_add_f32 v[174:175], v[174:175], v[94:95]
	s_waitcnt vmcnt(16)
	v_pk_add_f32 v[160:161], v[160:161], v[96:97]
	v_pk_add_f32 v[162:163], v[162:163], v[98:99]
	v_pk_add_f32 v[164:165], v[164:165], v[100:101]
	v_pk_add_f32 v[166:167], v[166:167], v[102:103]
	v_pk_add_f32 v[168:169], v[168:169], v[104:105]
	v_pk_add_f32 v[170:171], v[170:171], v[106:107]
	v_pk_add_f32 v[172:173], v[172:173], v[108:109]
	v_pk_add_f32 v[174:175], v[174:175], v[110:111]
	s_waitcnt vmcnt(12)
	v_pk_add_f32 v[160:161], v[160:161], v[112:113]
	v_pk_add_f32 v[162:163], v[162:163], v[114:115]
	v_pk_add_f32 v[164:165], v[164:165], v[116:117]
	v_pk_add_f32 v[166:167], v[166:167], v[118:119]
	v_pk_add_f32 v[168:169], v[168:169], v[120:121]
	v_pk_add_f32 v[170:171], v[170:171], v[122:123]
	v_pk_add_f32 v[172:173], v[172:173], v[124:125]
	v_pk_add_f32 v[174:175], v[174:175], v[126:127]
	v_lshlrev_b32_e32 v144, 16, v240
	v_and_b32_e32 v145, 0xffff0000, v240
	v_lshlrev_b32_e32 v146, 16, v241
	v_and_b32_e32 v147, 0xffff0000, v241
	v_lshlrev_b32_e32 v148, 16, v242
	v_and_b32_e32 v149, 0xffff0000, v242
	v_lshlrev_b32_e32 v150, 16, v243
	v_and_b32_e32 v151, 0xffff0000, v243
	v_lshlrev_b32_e32 v152, 16, v244
	v_and_b32_e32 v153, 0xffff0000, v244
	v_lshlrev_b32_e32 v154, 16, v245
	v_and_b32_e32 v155, 0xffff0000, v245
	v_lshlrev_b32_e32 v156, 16, v246
	v_and_b32_e32 v157, 0xffff0000, v246
	v_lshlrev_b32_e32 v158, 16, v247
	v_and_b32_e32 v159, 0xffff0000, v247
	s_waitcnt vmcnt(8)
	v_pk_add_f32 v[160:161], v[160:161], v[0:1]
	v_pk_add_f32 v[162:163], v[162:163], v[2:3]
	v_pk_add_f32 v[164:165], v[164:165], v[4:5]
	v_pk_add_f32 v[166:167], v[166:167], v[6:7]
	v_pk_add_f32 v[168:169], v[168:169], v[8:9]
	v_pk_add_f32 v[170:171], v[170:171], v[10:11]
	v_pk_add_f32 v[172:173], v[172:173], v[12:13]
	v_pk_add_f32 v[174:175], v[174:175], v[14:15]
	s_waitcnt vmcnt(4)
	v_pk_add_f32 v[160:161], v[160:161], v[16:17]
	v_pk_add_f32 v[162:163], v[162:163], v[18:19]
	v_pk_add_f32 v[164:165], v[164:165], v[20:21]
	v_pk_add_f32 v[166:167], v[166:167], v[22:23]
	v_pk_add_f32 v[168:169], v[168:169], v[24:25]
	v_pk_add_f32 v[170:171], v[170:171], v[26:27]
	v_pk_add_f32 v[172:173], v[172:173], v[28:29]
	v_pk_add_f32 v[174:175], v[174:175], v[30:31]
	s_waitcnt vmcnt(0)
	v_pk_add_f32 v[160:161], v[160:161], v[32:33]
	v_pk_add_f32 v[162:163], v[162:163], v[34:35]
	v_pk_add_f32 v[164:165], v[164:165], v[36:37]
	v_pk_add_f32 v[166:167], v[166:167], v[38:39]
	v_pk_add_f32 v[168:169], v[168:169], v[40:41]
	v_pk_add_f32 v[170:171], v[170:171], v[42:43]
	v_pk_add_f32 v[172:173], v[172:173], v[44:45]
	v_pk_add_f32 v[174:175], v[174:175], v[46:47]
	v_pk_mul_f32 v[252:253], v[160:161], v[160:161]
	v_pk_mul_f32 v[254:255], v[162:163], v[162:163]
	v_pk_fma_f32 v[252:253], v[164:165], v[164:165], v[252:253]
	v_pk_fma_f32 v[254:255], v[166:167], v[166:167], v[254:255]
	v_pk_fma_f32 v[252:253], v[168:169], v[168:169], v[252:253]
	v_pk_fma_f32 v[254:255], v[170:171], v[170:171], v[254:255]
	v_pk_fma_f32 v[252:253], v[172:173], v[172:173], v[252:253]
	v_pk_fma_f32 v[254:255], v[174:175], v[174:175], v[254:255]
	v_pk_add_f32 v[252:253], v[252:253], v[254:255]
	s_nop 0
	v_add_f32_e32 v183, v252, v253
	s_nop 1
	v_add_f32_dpp v183, v183, v183 quad_perm:[1,0,3,2] row_mask:0xf bank_mask:0xf bound_ctrl:1
	s_nop 1
	v_add_f32_dpp v183, v183, v183 quad_perm:[2,3,0,1] row_mask:0xf bank_mask:0xf bound_ctrl:1
	s_nop 1
	v_add_f32_dpp v183, v183, v183 row_half_mirror row_mask:0xf bank_mask:0xf bound_ctrl:1
	s_nop 1
	v_add_f32_dpp v183, v183, v183 row_mirror row_mask:0xf bank_mask:0xf bound_ctrl:1
	s_nop 1
	v_readlane_b32 s98, v183, 0
	v_readlane_b32 s99, v183, 16
	v_readlane_b32 s100, v183, 32
	v_readlane_b32 s101, v183, 48
	s_nop 1
	v_mov_b32_e32 v183, s98
	v_add_f32_e32 v183, s99, v183
	v_add_f32_e32 v183, s100, v183
	v_add_f32_e32 v183, s101, v183
	v_fmamk_f32 v183, v183, 0x3a800000, v182
	v_cmp_gt_f32_e32 vcc, 0x800000, v183
	v_mul_f32_e32 v181, 0x4b800000, v183
	s_nop 1
	v_cndmask_b32_e32 v183, v183, v181, vcc
	v_rsq_f32_e32 v183, v183
	s_nop 0
	v_mul_f32_e32 v181, 0x45800000, v183
	v_cndmask_b32_e32 v184, v183, v181, vcc
	v_mov_b32_e32 v185, v184
	v_pk_mul_f32 v[160:161], v[160:161], v[184:185]
	v_pk_mul_f32 v[162:163], v[162:163], v[184:185]
	v_pk_mul_f32 v[164:165], v[164:165], v[184:185]
	v_pk_mul_f32 v[166:167], v[166:167], v[184:185]
	v_pk_mul_f32 v[168:169], v[168:169], v[184:185]
	v_pk_mul_f32 v[170:171], v[170:171], v[184:185]
	v_pk_mul_f32 v[172:173], v[172:173], v[184:185]
	v_pk_mul_f32 v[174:175], v[174:175], v[184:185]
	v_pk_fma_f32 v[144:145], v[160:161], v[128:129], v[144:145]
	v_pk_fma_f32 v[146:147], v[162:163], v[130:131], v[146:147]
	v_pk_fma_f32 v[148:149], v[164:165], v[132:133], v[148:149]
	v_pk_fma_f32 v[150:151], v[166:167], v[134:135], v[150:151]
	v_pk_fma_f32 v[152:153], v[168:169], v[136:137], v[152:153]
	v_pk_fma_f32 v[154:155], v[170:171], v[138:139], v[154:155]
	v_pk_fma_f32 v[156:157], v[172:173], v[140:141], v[156:157]
	v_pk_fma_f32 v[158:159], v[174:175], v[142:143], v[158:159]
	v_pk_mul_f32 v[252:253], v[144:145], v[144:145]
	v_pk_mul_f32 v[254:255], v[146:147], v[146:147]
	v_pk_fma_f32 v[252:253], v[148:149], v[148:149], v[252:253]
	v_pk_fma_f32 v[254:255], v[150:151], v[150:151], v[254:255]
	v_pk_fma_f32 v[252:253], v[152:153], v[152:153], v[252:253]
	v_pk_fma_f32 v[254:255], v[154:155], v[154:155], v[254:255]
	v_pk_fma_f32 v[252:253], v[156:157], v[156:157], v[252:253]
	v_pk_fma_f32 v[254:255], v[158:159], v[158:159], v[254:255]
	v_pk_add_f32 v[252:253], v[252:253], v[254:255]
	s_nop 0
	v_add_f32_e32 v183, v252, v253
	s_nop 1
	v_add_f32_dpp v183, v183, v183 quad_perm:[1,0,3,2] row_mask:0xf bank_mask:0xf bound_ctrl:1
	s_nop 1
	v_add_f32_dpp v183, v183, v183 quad_perm:[2,3,0,1] row_mask:0xf bank_mask:0xf bound_ctrl:1
	s_nop 1
	v_add_f32_dpp v183, v183, v183 row_half_mirror row_mask:0xf bank_mask:0xf bound_ctrl:1
	s_nop 1
	v_add_f32_dpp v183, v183, v183 row_mirror row_mask:0xf bank_mask:0xf bound_ctrl:1
	s_nop 1
	v_readlane_b32 s98, v183, 0
	v_readlane_b32 s99, v183, 16
	v_readlane_b32 s100, v183, 32
	v_readlane_b32 s101, v183, 48
	s_nop 1
	v_mov_b32_e32 v183, s98
	v_add_f32_e32 v183, s99, v183
	v_add_f32_e32 v183, s100, v183
	v_add_f32_e32 v183, s101, v183
	v_fmamk_f32 v183, v183, 0x3a800000, v182
	v_cmp_gt_f32_e32 vcc, 0x800000, v183
	v_mul_f32_e32 v181, 0x4b800000, v183
	s_nop 1
	v_cndmask_b32_e32 v183, v183, v181, vcc
	v_rsq_f32_e32 v183, v183
	s_nop 0
	v_mul_f32_e32 v181, 0x45800000, v183
	v_cndmask_b32_e32 v184, v183, v181, vcc
	v_mov_b32_e32 v185, v184
	v_cvt_pk_bf16_f32 v0, v144, v145
	v_cvt_pk_bf16_f32 v1, v146, v147
	v_cvt_pk_bf16_f32 v2, v148, v149
	v_cvt_pk_bf16_f32 v3, v150, v151
	v_cvt_pk_bf16_f32 v4, v152, v153
	v_cvt_pk_bf16_f32 v5, v154, v155
	v_cvt_pk_bf16_f32 v6, v156, v157
	v_cvt_pk_bf16_f32 v7, v158, v159
	v_add_u32_e32 v181, 0x3800000, v177
	global_store_dwordx4 v181, v[0:3], s[78:79]
	global_store_dwordx4 v181, v[4:7], s[78:79] offset:1024
	v_add_u32_e32 v236, 0x10000, v237
	s_mov_b64 exec, 1
	global_store_dword v236, v184, s[78:79]
	s_mov_b64 exec, -1

.LBB0_2573:
	v_readlane_b32 s0, v235, 52
	v_readlane_b32 s1, v235, 53
	s_and_b64 vcc, exec, s[0:1]
	s_waitcnt lgkmcnt(0)
	s_barrier
	v_mbcnt_lo_u32_b32 v0, -1, 0
	v_mbcnt_hi_u32_b32 v0, -1, v0
	s_cbranch_vccnz .LBB0_2593
	v_lshlrev_b32_e32 v2, 3, v0
	v_ashrrev_i32_e32 v3, 31, v2
	v_readlane_b32 s4, v235, 4
	v_lshlrev_b64 v[4:5], 1, v[2:3]
	v_lshlrev_b64 v[2:3], 2, v[2:3]
	v_readlane_b32 s14, v235, 14
	v_readlane_b32 s15, v235, 15
	v_lshl_add_u64 v[62:63], s[90:91], 0, v[2:3]
	v_readlane_b32 s5, v235, 5
	v_readlane_b32 s6, v235, 6
	v_readlane_b32 s7, v235, 7
	v_readlane_b32 s8, v235, 8
	v_readlane_b32 s9, v235, 9
	v_readlane_b32 s10, v235, 10
	v_readlane_b32 s11, v235, 11
	v_readlane_b32 s12, v235, 12
	v_readlane_b32 s13, v235, 13
	v_readlane_b32 s16, v235, 16
	v_readlane_b32 s17, v235, 17
	v_readlane_b32 s18, v235, 18
	v_readlane_b32 s19, v235, 19
	v_lshl_add_u64 v[2:3], s[14:15], 0, v[2:3]
	s_mov_b64 s[0:1], 0x3000
	v_lshl_add_u64 v[60:61], s[86:87], 0, v[4:5]
	v_lshl_add_u64 v[64:65], s[54:55], 0, v[4:5]
	v_lshl_add_u64 v[66:67], v[2:3], 0, s[0:1]
	s_mov_b32 s1, 0
	v_cmp_eq_u32_e64 s[4:5], 0, v0
	s_mov_b64 s[6:7], 0x200000
	s_mov_b64 s[8:9], 0x200800
	s_mov_b64 s[10:11], 0x400000
	s_mov_b64 s[12:13], 0x400800
	s_mov_b64 s[14:15], 0x600000
	s_mov_b64 s[16:17], 0x600800
	s_mov_b64 s[18:19], 0x800000
	s_mov_b32 s48, 0x800000
	s_mov_b64 s[20:21], 0x800800
	s_mov_b64 s[22:23], 0xa00000
	s_mov_b64 s[24:25], 0xa00800
	s_mov_b64 s[26:27], 0xc00000
	s_mov_b64 s[28:29], 0xc00800
	s_mov_b64 s[30:31], 0xe00000
	s_mov_b64 s[36:37], 0xe00800
	v_mov_b32_e32 v104, 0
	v_mov_b32_e32 v105, 0x358637bd
	v_readlane_b32 s38, v235, 61
	v_readlane_b32 s39, v235, 62
	v_mbcnt_lo_u32_b32 v176, -1, 0
	v_mbcnt_hi_u32_b32 v176, -1, v176
	v_readlane_b32 s98, v235, 49
	v_readlane_b32 s99, v235, 20
	v_readlane_b32 s100, v235, 14
	v_readlane_b32 s101, v235, 15
	s_nop 3
	s_lshr_b32 vcc_lo, s98, 3
	s_and_b32 vcc_hi, vcc_lo, 7
	s_lshr_b32 vcc_lo, vcc_lo, 3
	s_lshl_b32 vcc_lo, vcc_lo, 3
	s_add_i32 vcc_lo, vcc_lo, s99
	s_lshl_b32 s98, vcc_hi, 8
	s_add_i32 s98, s98, vcc_lo
	s_mov_b32 s99, s98
	v_mov_b32_e32 v183, s99
	v_lshlrev_b32_e32 v177, 4, v176
	s_lshl_b32 s99, s99, 11
	v_add_u32_e32 v177, s99, v177
	v_add_u32_e32 v178, 0x1800000, v177
	v_add_u32_e32 v179, 0x9e00000, v177
	v_lshlrev_b32_e32 v180, 5, v176
	v_add_u32_e32 v181, 0x3000, v180
	global_load_dwordx4 v[128:131], v181, s[100:101]
	global_load_dwordx4 v[132:135], v181, s[100:101] offset:16
	global_load_dwordx4 v[136:139], v181, s[100:101] offset:2048
	global_load_dwordx4 v[140:143], v181, s[100:101] offset:2064
	v_mov_b32_e32 v182, 0x358637bd
	global_load_dwordx4 v[0:3], v178, s[78:79]
	global_load_dwordx4 v[4:7], v178, s[78:79] offset:1024
	global_load_dwordx4 v[8:11], v179, s[78:79]
	global_load_dwordx4 v[12:15], v179, s[78:79] offset:1024
	v_add_u32_e32 v178, 0x400000, v178
	v_add_u32_e32 v179, 0x400000, v179
	global_load_dwordx4 v[16:19], v178, s[78:79]
	global_load_dwordx4 v[20:23], v178, s[78:79] offset:1024
	global_load_dwordx4 v[24:27], v179, s[78:79]
	global_load_dwordx4 v[28:31], v179, s[78:79] offset:1024
	v_add_u32_e32 v178, 0x400000, v178
	v_add_u32_e32 v179, 0x400000, v179
	global_load_dwordx4 v[32:35], v178, s[78:79]
	global_load_dwordx4 v[36:39], v178, s[78:79] offset:1024
	global_load_dwordx4 v[40:43], v179, s[78:79]
	global_load_dwordx4 v[44:47], v179, s[78:79] offset:1024
	v_add_u32_e32 v178, 0x400000, v178
	v_add_u32_e32 v179, 0x400000, v179
	global_load_dwordx4 v[48:51], v178, s[78:79]
	global_load_dwordx4 v[52:55], v178, s[78:79] offset:1024
	global_load_dwordx4 v[56:59], v179, s[78:79]
	global_load_dwordx4 v[60:63], v179, s[78:79] offset:1024
	v_add_u32_e32 v178, 0x400000, v178
	v_add_u32_e32 v179, 0x400000, v179
	global_load_dwordx4 v[64:67], v178, s[78:79]
	global_load_dwordx4 v[68:71], v178, s[78:79] offset:1024
	global_load_dwordx4 v[72:75], v179, s[78:79]
	global_load_dwordx4 v[76:79], v179, s[78:79] offset:1024
	v_add_u32_e32 v178, 0x400000, v178
	v_add_u32_e32 v179, 0x400000, v179
	global_load_dwordx4 v[80:83], v178, s[78:79]
	global_load_dwordx4 v[84:87], v178, s[78:79] offset:1024
	global_load_dwordx4 v[88:91], v179, s[78:79]
	global_load_dwordx4 v[92:95], v179, s[78:79] offset:1024
	v_add_u32_e32 v178, 0x400000, v178
	v_add_u32_e32 v179, 0x400000, v179
	global_load_dwordx4 v[96:99], v178, s[78:79]
	global_load_dwordx4 v[100:103], v178, s[78:79] offset:1024
	global_load_dwordx4 v[104:107], v179, s[78:79]
	global_load_dwordx4 v[108:111], v179, s[78:79] offset:1024
	v_add_u32_e32 v178, 0x400000, v178
	v_add_u32_e32 v179, 0x400000, v179
	global_load_dwordx4 v[112:115], v178, s[78:79]
	global_load_dwordx4 v[116:119], v178, s[78:79] offset:1024
	global_load_dwordx4 v[120:123], v179, s[78:79]
	global_load_dwordx4 v[124:127], v179, s[78:79] offset:1024
	v_lshlrev_b32_e32 v237, 2, v183
	v_add_u32_e32 v237, 0x10000, v237
	v_mov_b32_e32 v179, s98
	s_waitcnt vmcnt(28)
	v_lshlrev_b32_e32 v144, 16, v0
	v_and_b32_e32 v145, 0xffff0000, v0
	v_lshlrev_b32_e32 v146, 16, v1
	v_and_b32_e32 v147, 0xffff0000, v1
	v_lshlrev_b32_e32 v148, 16, v2
	v_and_b32_e32 v149, 0xffff0000, v2
	v_lshlrev_b32_e32 v150, 16, v3
	v_and_b32_e32 v151, 0xffff0000, v3
	v_lshlrev_b32_e32 v152, 16, v4
	v_and_b32_e32 v153, 0xffff0000, v4
	v_lshlrev_b32_e32 v154, 16, v5
	v_and_b32_e32 v155, 0xffff0000, v5
	v_lshlrev_b32_e32 v156, 16, v6
	v_and_b32_e32 v157, 0xffff0000, v6
	v_lshlrev_b32_e32 v158, 16, v7
	v_and_b32_e32 v159, 0xffff0000, v7
	v_lshlrev_b32_e32 v160, 16, v8
	v_and_b32_e32 v161, 0xffff0000, v8
	v_lshlrev_b32_e32 v162, 16, v9
	v_and_b32_e32 v163, 0xffff0000, v9
	v_lshlrev_b32_e32 v164, 16, v10
	v_and_b32_e32 v165, 0xffff0000, v10
	v_lshlrev_b32_e32 v166, 16, v11
	v_and_b32_e32 v167, 0xffff0000, v11
	v_lshlrev_b32_e32 v168, 16, v12
	v_and_b32_e32 v169, 0xffff0000, v12
	v_lshlrev_b32_e32 v170, 16, v13
	v_and_b32_e32 v171, 0xffff0000, v13
	v_lshlrev_b32_e32 v172, 16, v14
	v_and_b32_e32 v173, 0xffff0000, v14
	v_lshlrev_b32_e32 v174, 16, v15
	v_and_b32_e32 v175, 0xffff0000, v15
	v_pk_mul_f32 v[252:253], v[160:161], v[160:161]
	v_pk_mul_f32 v[254:255], v[162:163], v[162:163]
	v_pk_fma_f32 v[252:253], v[164:165], v[164:165], v[252:253]
	v_pk_fma_f32 v[254:255], v[166:167], v[166:167], v[254:255]
	v_pk_fma_f32 v[252:253], v[168:169], v[168:169], v[252:253]
	v_pk_fma_f32 v[254:255], v[170:171], v[170:171], v[254:255]
	v_pk_fma_f32 v[252:253], v[172:173], v[172:173], v[252:253]
	v_pk_fma_f32 v[254:255], v[174:175], v[174:175], v[254:255]
	v_pk_add_f32 v[252:253], v[252:253], v[254:255]
	s_nop 0
	v_add_f32_e32 v183, v252, v253
	s_nop 1
	v_add_f32_dpp v183, v183, v183 quad_perm:[1,0,3,2] row_mask:0xf bank_mask:0xf bound_ctrl:1
	s_nop 1
	v_add_f32_dpp v183, v183, v183 quad_perm:[2,3,0,1] row_mask:0xf bank_mask:0xf bound_ctrl:1
	s_nop 1
	v_add_f32_dpp v183, v183, v183 row_half_mirror row_mask:0xf bank_mask:0xf bound_ctrl:1
	s_nop 1
	v_add_f32_dpp v183, v183, v183 row_mirror row_mask:0xf bank_mask:0xf bound_ctrl:1
	s_nop 1
	v_readlane_b32 s98, v183, 0
	v_readlane_b32 s99, v183, 16
	v_readlane_b32 s100, v183, 32
	v_readlane_b32 s101, v183, 48
	s_nop 1
	v_mov_b32_e32 v183, s98
	v_add_f32_e32 v183, s99, v183
	v_add_f32_e32 v183, s100, v183
	v_add_f32_e32 v183, s101, v183
	v_fmamk_f32 v183, v183, 0x3a800000, v182
	v_cmp_gt_f32_e32 vcc, 0x800000, v183
	v_mul_f32_e32 v181, 0x4b800000, v183
	s_nop 1
	v_cndmask_b32_e32 v183, v183, v181, vcc
	v_rsq_f32_e32 v183, v183
	s_nop 0
	v_mul_f32_e32 v181, 0x45800000, v183
	v_cndmask_b32_e32 v184, v183, v181, vcc
	v_mov_b32_e32 v185, v184
	v_pk_mul_f32 v[160:161], v[160:161], v[184:185]
	v_pk_mul_f32 v[162:163], v[162:163], v[184:185]
	v_pk_mul_f32 v[164:165], v[164:165], v[184:185]
	v_pk_mul_f32 v[166:167], v[166:167], v[184:185]
	v_pk_mul_f32 v[168:169], v[168:169], v[184:185]
	v_pk_mul_f32 v[170:171], v[170:171], v[184:185]
	v_pk_mul_f32 v[172:173], v[172:173], v[184:185]
	v_pk_mul_f32 v[174:175], v[174:175], v[184:185]
	v_pk_fma_f32 v[144:145], v[160:161], v[128:129], v[144:145]
	v_pk_fma_f32 v[146:147], v[162:163], v[130:131], v[146:147]
	v_pk_fma_f32 v[148:149], v[164:165], v[132:133], v[148:149]
	v_pk_fma_f32 v[150:151], v[166:167], v[134:135], v[150:151]
	v_pk_fma_f32 v[152:153], v[168:169], v[136:137], v[152:153]
	v_pk_fma_f32 v[154:155], v[170:171], v[138:139], v[154:155]
	v_pk_fma_f32 v[156:157], v[172:173], v[140:141], v[156:157]
	v_pk_fma_f32 v[158:159], v[174:175], v[142:143], v[158:159]
	v_pk_mul_f32 v[252:253], v[144:145], v[144:145]
	v_pk_mul_f32 v[254:255], v[146:147], v[146:147]
	v_pk_fma_f32 v[252:253], v[148:149], v[148:149], v[252:253]
	v_pk_fma_f32 v[254:255], v[150:151], v[150:151], v[254:255]
	v_pk_fma_f32 v[252:253], v[152:153], v[152:153], v[252:253]
	v_pk_fma_f32 v[254:255], v[154:155], v[154:155], v[254:255]
	v_pk_fma_f32 v[252:253], v[156:157], v[156:157], v[252:253]
	v_pk_fma_f32 v[254:255], v[158:159], v[158:159], v[254:255]
	v_pk_add_f32 v[252:253], v[252:253], v[254:255]
	s_nop 0
	v_add_f32_e32 v183, v252, v253
	s_nop 1
	v_add_f32_dpp v183, v183, v183 quad_perm:[1,0,3,2] row_mask:0xf bank_mask:0xf bound_ctrl:1
	s_nop 1
	v_add_f32_dpp v183, v183, v183 quad_perm:[2,3,0,1] row_mask:0xf bank_mask:0xf bound_ctrl:1
	s_nop 1
	v_add_f32_dpp v183, v183, v183 row_half_mirror row_mask:0xf bank_mask:0xf bound_ctrl:1
	s_nop 1
	v_add_f32_dpp v183, v183, v183 row_mirror row_mask:0xf bank_mask:0xf bound_ctrl:1
	s_nop 1
	v_readlane_b32 s98, v183, 0
	v_readlane_b32 s99, v183, 16
	v_readlane_b32 s100, v183, 32
	v_readlane_b32 s101, v183, 48
	s_nop 1
	v_mov_b32_e32 v183, s98
	v_add_f32_e32 v183, s99, v183
	v_add_f32_e32 v183, s100, v183
	v_add_f32_e32 v183, s101, v183
	v_fmamk_f32 v183, v183, 0x3a800000, v182
	v_cmp_gt_f32_e32 vcc, 0x800000, v183
	v_mul_f32_e32 v181, 0x4b800000, v183
	s_nop 1
	v_cndmask_b32_e32 v183, v183, v181, vcc
	v_rsq_f32_e32 v183, v183
	s_nop 0
	v_mul_f32_e32 v181, 0x45800000, v183
	v_cndmask_b32_e32 v184, v183, v181, vcc
	v_mov_b32_e32 v185, v184
	v_cvt_pk_bf16_f32 v0, v144, v145
	v_cvt_pk_bf16_f32 v1, v146, v147
	v_cvt_pk_bf16_f32 v2, v148, v149
	v_cvt_pk_bf16_f32 v3, v150, v151
	v_cvt_pk_bf16_f32 v4, v152, v153
	v_cvt_pk_bf16_f32 v5, v154, v155
	v_cvt_pk_bf16_f32 v6, v156, v157
	v_cvt_pk_bf16_f32 v7, v158, v159
	v_add_u32_e32 v181, 0x1800000, v177
	global_store_dwordx4 v181, v[0:3], s[78:79]
	global_store_dwordx4 v181, v[4:7], s[78:79] offset:1024
	v_add_u32_e32 v236, 0x0, v237
	s_mov_b64 exec, 1
	global_store_dword v236, v184, s[78:79]
	s_mov_b64 exec, -1
	s_waitcnt vmcnt(24)
	v_lshlrev_b32_e32 v144, 16, v16
	v_and_b32_e32 v145, 0xffff0000, v16
	v_lshlrev_b32_e32 v146, 16, v17
	v_and_b32_e32 v147, 0xffff0000, v17
	v_lshlrev_b32_e32 v148, 16, v18
	v_and_b32_e32 v149, 0xffff0000, v18
	v_lshlrev_b32_e32 v150, 16, v19
	v_and_b32_e32 v151, 0xffff0000, v19
	v_lshlrev_b32_e32 v152, 16, v20
	v_and_b32_e32 v153, 0xffff0000, v20
	v_lshlrev_b32_e32 v154, 16, v21
	v_and_b32_e32 v155, 0xffff0000, v21
	v_lshlrev_b32_e32 v156, 16, v22
	v_and_b32_e32 v157, 0xffff0000, v22
	v_lshlrev_b32_e32 v158, 16, v23
	v_and_b32_e32 v159, 0xffff0000, v23
	v_lshlrev_b32_e32 v160, 16, v24
	v_and_b32_e32 v161, 0xffff0000, v24
	v_lshlrev_b32_e32 v162, 16, v25
	v_and_b32_e32 v163, 0xffff0000, v25
	v_lshlrev_b32_e32 v164, 16, v26
	v_and_b32_e32 v165, 0xffff0000, v26
	v_lshlrev_b32_e32 v166, 16, v27
	v_and_b32_e32 v167, 0xffff0000, v27
	v_lshlrev_b32_e32 v168, 16, v28
	v_and_b32_e32 v169, 0xffff0000, v28
	v_lshlrev_b32_e32 v170, 16, v29
	v_and_b32_e32 v171, 0xffff0000, v29
	v_lshlrev_b32_e32 v172, 16, v30
	v_and_b32_e32 v173, 0xffff0000, v30
	v_lshlrev_b32_e32 v174, 16, v31
	v_and_b32_e32 v175, 0xffff0000, v31
	v_pk_mul_f32 v[252:253], v[160:161], v[160:161]
	v_pk_mul_f32 v[254:255], v[162:163], v[162:163]
	v_pk_fma_f32 v[252:253], v[164:165], v[164:165], v[252:253]
	v_pk_fma_f32 v[254:255], v[166:167], v[166:167], v[254:255]
	v_pk_fma_f32 v[252:253], v[168:169], v[168:169], v[252:253]
	v_pk_fma_f32 v[254:255], v[170:171], v[170:171], v[254:255]
	v_pk_fma_f32 v[252:253], v[172:173], v[172:173], v[252:253]
	v_pk_fma_f32 v[254:255], v[174:175], v[174:175], v[254:255]
	v_pk_add_f32 v[252:253], v[252:253], v[254:255]
	s_nop 0
	v_add_f32_e32 v183, v252, v253
	s_nop 1
	v_add_f32_dpp v183, v183, v183 quad_perm:[1,0,3,2] row_mask:0xf bank_mask:0xf bound_ctrl:1
	s_nop 1
	v_add_f32_dpp v183, v183, v183 quad_perm:[2,3,0,1] row_mask:0xf bank_mask:0xf bound_ctrl:1
	s_nop 1
	v_add_f32_dpp v183, v183, v183 row_half_mirror row_mask:0xf bank_mask:0xf bound_ctrl:1
	s_nop 1
	v_add_f32_dpp v183, v183, v183 row_mirror row_mask:0xf bank_mask:0xf bound_ctrl:1
	s_nop 1
	v_readlane_b32 s98, v183, 0
	v_readlane_b32 s99, v183, 16
	v_readlane_b32 s100, v183, 32
	v_readlane_b32 s101, v183, 48
	s_nop 1
	v_mov_b32_e32 v183, s98
	v_add_f32_e32 v183, s99, v183
	v_add_f32_e32 v183, s100, v183
	v_add_f32_e32 v183, s101, v183
	v_fmamk_f32 v183, v183, 0x3a800000, v182
	v_cmp_gt_f32_e32 vcc, 0x800000, v183
	v_mul_f32_e32 v181, 0x4b800000, v183
	s_nop 1
	v_cndmask_b32_e32 v183, v183, v181, vcc
	v_rsq_f32_e32 v183, v183
	s_nop 0
	v_mul_f32_e32 v181, 0x45800000, v183
	v_cndmask_b32_e32 v184, v183, v181, vcc
	v_mov_b32_e32 v185, v184
	v_pk_mul_f32 v[160:161], v[160:161], v[184:185]
	v_pk_mul_f32 v[162:163], v[162:163], v[184:185]
	v_pk_mul_f32 v[164:165], v[164:165], v[184:185]
	v_pk_mul_f32 v[166:167], v[166:167], v[184:185]
	v_pk_mul_f32 v[168:169], v[168:169], v[184:185]
	v_pk_mul_f32 v[170:171], v[170:171], v[184:185]
	v_pk_mul_f32 v[172:173], v[172:173], v[184:185]
	v_pk_mul_f32 v[174:175], v[174:175], v[184:185]
	v_pk_fma_f32 v[144:145], v[160:161], v[128:129], v[144:145]
	v_pk_fma_f32 v[146:147], v[162:163], v[130:131], v[146:147]
	v_pk_fma_f32 v[148:149], v[164:165], v[132:133], v[148:149]
	v_pk_fma_f32 v[150:151], v[166:167], v[134:135], v[150:151]
	v_pk_fma_f32 v[152:153], v[168:169], v[136:137], v[152:153]
	v_pk_fma_f32 v[154:155], v[170:171], v[138:139], v[154:155]
	v_pk_fma_f32 v[156:157], v[172:173], v[140:141], v[156:157]
	v_pk_fma_f32 v[158:159], v[174:175], v[142:143], v[158:159]
	v_pk_mul_f32 v[252:253], v[144:145], v[144:145]
	v_pk_mul_f32 v[254:255], v[146:147], v[146:147]
	v_pk_fma_f32 v[252:253], v[148:149], v[148:149], v[252:253]
	v_pk_fma_f32 v[254:255], v[150:151], v[150:151], v[254:255]
	v_pk_fma_f32 v[252:253], v[152:153], v[152:153], v[252:253]
	v_pk_fma_f32 v[254:255], v[154:155], v[154:155], v[254:255]
	v_pk_fma_f32 v[252:253], v[156:157], v[156:157], v[252:253]
	v_pk_fma_f32 v[254:255], v[158:159], v[158:159], v[254:255]
	v_pk_add_f32 v[252:253], v[252:253], v[254:255]
	s_nop 0
	v_add_f32_e32 v183, v252, v253
	s_nop 1
	v_add_f32_dpp v183, v183, v183 quad_perm:[1,0,3,2] row_mask:0xf bank_mask:0xf bound_ctrl:1
	s_nop 1
	v_add_f32_dpp v183, v183, v183 quad_perm:[2,3,0,1] row_mask:0xf bank_mask:0xf bound_ctrl:1
	s_nop 1
	v_add_f32_dpp v183, v183, v183 row_half_mirror row_mask:0xf bank_mask:0xf bound_ctrl:1
	s_nop 1
	v_add_f32_dpp v183, v183, v183 row_mirror row_mask:0xf bank_mask:0xf bound_ctrl:1
	s_nop 1
	v_readlane_b32 s98, v183, 0
	v_readlane_b32 s99, v183, 16
	v_readlane_b32 s100, v183, 32
	v_readlane_b32 s101, v183, 48
	s_nop 1
	v_mov_b32_e32 v183, s98
	v_add_f32_e32 v183, s99, v183
	v_add_f32_e32 v183, s100, v183
	v_add_f32_e32 v183, s101, v183
	v_fmamk_f32 v183, v183, 0x3a800000, v182
	v_cmp_gt_f32_e32 vcc, 0x800000, v183
	v_mul_f32_e32 v181, 0x4b800000, v183
	s_nop 1
	v_cndmask_b32_e32 v183, v183, v181, vcc
	v_rsq_f32_e32 v183, v183
	s_nop 0
	v_mul_f32_e32 v181, 0x45800000, v183
	v_cndmask_b32_e32 v184, v183, v181, vcc
	v_mov_b32_e32 v185, v184
	v_cvt_pk_bf16_f32 v16, v144, v145
	v_cvt_pk_bf16_f32 v17, v146, v147
	v_cvt_pk_bf16_f32 v18, v148, v149
	v_cvt_pk_bf16_f32 v19, v150, v151
	v_cvt_pk_bf16_f32 v20, v152, v153
	v_cvt_pk_bf16_f32 v21, v154, v155
	v_cvt_pk_bf16_f32 v22, v156, v157
	v_cvt_pk_bf16_f32 v23, v158, v159
	v_add_u32_e32 v181, 0x1c00000, v177
	global_store_dwordx4 v181, v[16:19], s[78:79]
	global_store_dwordx4 v181, v[20:23], s[78:79] offset:1024
	v_add_u32_e32 v236, 0x2000, v237
	s_mov_b64 exec, 1
	global_store_dword v236, v184, s[78:79]
	s_mov_b64 exec, -1
	s_waitcnt vmcnt(20)
	v_lshlrev_b32_e32 v144, 16, v32
	v_and_b32_e32 v145, 0xffff0000, v32
	v_lshlrev_b32_e32 v146, 16, v33
	v_and_b32_e32 v147, 0xffff0000, v33
	v_lshlrev_b32_e32 v148, 16, v34
	v_and_b32_e32 v149, 0xffff0000, v34
	v_lshlrev_b32_e32 v150, 16, v35
	v_and_b32_e32 v151, 0xffff0000, v35
	v_lshlrev_b32_e32 v152, 16, v36
	v_and_b32_e32 v153, 0xffff0000, v36
	v_lshlrev_b32_e32 v154, 16, v37
	v_and_b32_e32 v155, 0xffff0000, v37
	v_lshlrev_b32_e32 v156, 16, v38
	v_and_b32_e32 v157, 0xffff0000, v38
	v_lshlrev_b32_e32 v158, 16, v39
	v_and_b32_e32 v159, 0xffff0000, v39
	v_lshlrev_b32_e32 v160, 16, v40
	v_and_b32_e32 v161, 0xffff0000, v40
	v_lshlrev_b32_e32 v162, 16, v41
	v_and_b32_e32 v163, 0xffff0000, v41
	v_lshlrev_b32_e32 v164, 16, v42
	v_and_b32_e32 v165, 0xffff0000, v42
	v_lshlrev_b32_e32 v166, 16, v43
	v_and_b32_e32 v167, 0xffff0000, v43
	v_lshlrev_b32_e32 v168, 16, v44
	v_and_b32_e32 v169, 0xffff0000, v44
	v_lshlrev_b32_e32 v170, 16, v45
	v_and_b32_e32 v171, 0xffff0000, v45
	v_lshlrev_b32_e32 v172, 16, v46
	v_and_b32_e32 v173, 0xffff0000, v46
	v_lshlrev_b32_e32 v174, 16, v47
	v_and_b32_e32 v175, 0xffff0000, v47
	v_pk_mul_f32 v[252:253], v[160:161], v[160:161]
	v_pk_mul_f32 v[254:255], v[162:163], v[162:163]
	v_pk_fma_f32 v[252:253], v[164:165], v[164:165], v[252:253]
	v_pk_fma_f32 v[254:255], v[166:167], v[166:167], v[254:255]
	v_pk_fma_f32 v[252:253], v[168:169], v[168:169], v[252:253]
	v_pk_fma_f32 v[254:255], v[170:171], v[170:171], v[254:255]
	v_pk_fma_f32 v[252:253], v[172:173], v[172:173], v[252:253]
	v_pk_fma_f32 v[254:255], v[174:175], v[174:175], v[254:255]
	v_pk_add_f32 v[252:253], v[252:253], v[254:255]
	s_nop 0
	v_add_f32_e32 v183, v252, v253
	s_nop 1
	v_add_f32_dpp v183, v183, v183 quad_perm:[1,0,3,2] row_mask:0xf bank_mask:0xf bound_ctrl:1
	s_nop 1
	v_add_f32_dpp v183, v183, v183 quad_perm:[2,3,0,1] row_mask:0xf bank_mask:0xf bound_ctrl:1
	s_nop 1
	v_add_f32_dpp v183, v183, v183 row_half_mirror row_mask:0xf bank_mask:0xf bound_ctrl:1
	s_nop 1
	v_add_f32_dpp v183, v183, v183 row_mirror row_mask:0xf bank_mask:0xf bound_ctrl:1
	s_nop 1
	v_readlane_b32 s98, v183, 0
	v_readlane_b32 s99, v183, 16
	v_readlane_b32 s100, v183, 32
	v_readlane_b32 s101, v183, 48
	s_nop 1
	v_mov_b32_e32 v183, s98
	v_add_f32_e32 v183, s99, v183
	v_add_f32_e32 v183, s100, v183
	v_add_f32_e32 v183, s101, v183
	v_fmamk_f32 v183, v183, 0x3a800000, v182
	v_cmp_gt_f32_e32 vcc, 0x800000, v183
	v_mul_f32_e32 v181, 0x4b800000, v183
	s_nop 1
	v_cndmask_b32_e32 v183, v183, v181, vcc
	v_rsq_f32_e32 v183, v183
	s_nop 0
	v_mul_f32_e32 v181, 0x45800000, v183
	v_cndmask_b32_e32 v184, v183, v181, vcc
	v_mov_b32_e32 v185, v184
	v_pk_mul_f32 v[160:161], v[160:161], v[184:185]
	v_pk_mul_f32 v[162:163], v[162:163], v[184:185]
	v_pk_mul_f32 v[164:165], v[164:165], v[184:185]
	v_pk_mul_f32 v[166:167], v[166:167], v[184:185]
	v_pk_mul_f32 v[168:169], v[168:169], v[184:185]
	v_pk_mul_f32 v[170:171], v[170:171], v[184:185]
	v_pk_mul_f32 v[172:173], v[172:173], v[184:185]
	v_pk_mul_f32 v[174:175], v[174:175], v[184:185]
	v_pk_fma_f32 v[144:145], v[160:161], v[128:129], v[144:145]
	v_pk_fma_f32 v[146:147], v[162:163], v[130:131], v[146:147]
	v_pk_fma_f32 v[148:149], v[164:165], v[132:133], v[148:149]
	v_pk_fma_f32 v[150:151], v[166:167], v[134:135], v[150:151]
	v_pk_fma_f32 v[152:153], v[168:169], v[136:137], v[152:153]
	v_pk_fma_f32 v[154:155], v[170:171], v[138:139], v[154:155]
	v_pk_fma_f32 v[156:157], v[172:173], v[140:141], v[156:157]
	v_pk_fma_f32 v[158:159], v[174:175], v[142:143], v[158:159]
	v_pk_mul_f32 v[252:253], v[144:145], v[144:145]
	v_pk_mul_f32 v[254:255], v[146:147], v[146:147]
	v_pk_fma_f32 v[252:253], v[148:149], v[148:149], v[252:253]
	v_pk_fma_f32 v[254:255], v[150:151], v[150:151], v[254:255]
	v_pk_fma_f32 v[252:253], v[152:153], v[152:153], v[252:253]
	v_pk_fma_f32 v[254:255], v[154:155], v[154:155], v[254:255]
	v_pk_fma_f32 v[252:253], v[156:157], v[156:157], v[252:253]
	v_pk_fma_f32 v[254:255], v[158:159], v[158:159], v[254:255]
	v_pk_add_f32 v[252:253], v[252:253], v[254:255]
	s_nop 0
	v_add_f32_e32 v183, v252, v253
	s_nop 1
	v_add_f32_dpp v183, v183, v183 quad_perm:[1,0,3,2] row_mask:0xf bank_mask:0xf bound_ctrl:1
	s_nop 1
	v_add_f32_dpp v183, v183, v183 quad_perm:[2,3,0,1] row_mask:0xf bank_mask:0xf bound_ctrl:1
	s_nop 1
	v_add_f32_dpp v183, v183, v183 row_half_mirror row_mask:0xf bank_mask:0xf bound_ctrl:1
	s_nop 1
	v_add_f32_dpp v183, v183, v183 row_mirror row_mask:0xf bank_mask:0xf bound_ctrl:1
	s_nop 1
	v_readlane_b32 s98, v183, 0
	v_readlane_b32 s99, v183, 16
	v_readlane_b32 s100, v183, 32
	v_readlane_b32 s101, v183, 48
	s_nop 1
	v_mov_b32_e32 v183, s98
	v_add_f32_e32 v183, s99, v183
	v_add_f32_e32 v183, s100, v183
	v_add_f32_e32 v183, s101, v183
	v_fmamk_f32 v183, v183, 0x3a800000, v182
	v_cmp_gt_f32_e32 vcc, 0x800000, v183
	v_mul_f32_e32 v181, 0x4b800000, v183
	s_nop 1
	v_cndmask_b32_e32 v183, v183, v181, vcc
	v_rsq_f32_e32 v183, v183
	s_nop 0
	v_mul_f32_e32 v181, 0x45800000, v183
	v_cndmask_b32_e32 v184, v183, v181, vcc
	v_mov_b32_e32 v185, v184
	v_cvt_pk_bf16_f32 v32, v144, v145
	v_cvt_pk_bf16_f32 v33, v146, v147
	v_cvt_pk_bf16_f32 v34, v148, v149
	v_cvt_pk_bf16_f32 v35, v150, v151
	v_cvt_pk_bf16_f32 v36, v152, v153
	v_cvt_pk_bf16_f32 v37, v154, v155
	v_cvt_pk_bf16_f32 v38, v156, v157
	v_cvt_pk_bf16_f32 v39, v158, v159
	v_add_u32_e32 v181, 0x2000000, v177
	global_store_dwordx4 v181, v[32:35], s[78:79]
	global_store_dwordx4 v181, v[36:39], s[78:79] offset:1024
	v_add_u32_e32 v236, 0x4000, v237
	s_mov_b64 exec, 1
	global_store_dword v236, v184, s[78:79]
	s_mov_b64 exec, -1
	s_waitcnt vmcnt(16)
	v_lshlrev_b32_e32 v144, 16, v48
	v_and_b32_e32 v145, 0xffff0000, v48
	v_lshlrev_b32_e32 v146, 16, v49
	v_and_b32_e32 v147, 0xffff0000, v49
	v_lshlrev_b32_e32 v148, 16, v50
	v_and_b32_e32 v149, 0xffff0000, v50
	v_lshlrev_b32_e32 v150, 16, v51
	v_and_b32_e32 v151, 0xffff0000, v51
	v_lshlrev_b32_e32 v152, 16, v52
	v_and_b32_e32 v153, 0xffff0000, v52
	v_lshlrev_b32_e32 v154, 16, v53
	v_and_b32_e32 v155, 0xffff0000, v53
	v_lshlrev_b32_e32 v156, 16, v54
	v_and_b32_e32 v157, 0xffff0000, v54
	v_lshlrev_b32_e32 v158, 16, v55
	v_and_b32_e32 v159, 0xffff0000, v55
	v_lshlrev_b32_e32 v160, 16, v56
	v_and_b32_e32 v161, 0xffff0000, v56
	v_lshlrev_b32_e32 v162, 16, v57
	v_and_b32_e32 v163, 0xffff0000, v57
	v_lshlrev_b32_e32 v164, 16, v58
	v_and_b32_e32 v165, 0xffff0000, v58
	v_lshlrev_b32_e32 v166, 16, v59
	v_and_b32_e32 v167, 0xffff0000, v59
	v_lshlrev_b32_e32 v168, 16, v60
	v_and_b32_e32 v169, 0xffff0000, v60
	v_lshlrev_b32_e32 v170, 16, v61
	v_and_b32_e32 v171, 0xffff0000, v61
	v_lshlrev_b32_e32 v172, 16, v62
	v_and_b32_e32 v173, 0xffff0000, v62
	v_lshlrev_b32_e32 v174, 16, v63
	v_and_b32_e32 v175, 0xffff0000, v63
	v_pk_mul_f32 v[252:253], v[160:161], v[160:161]
	v_pk_mul_f32 v[254:255], v[162:163], v[162:163]
	v_pk_fma_f32 v[252:253], v[164:165], v[164:165], v[252:253]
	v_pk_fma_f32 v[254:255], v[166:167], v[166:167], v[254:255]
	v_pk_fma_f32 v[252:253], v[168:169], v[168:169], v[252:253]
	v_pk_fma_f32 v[254:255], v[170:171], v[170:171], v[254:255]
	v_pk_fma_f32 v[252:253], v[172:173], v[172:173], v[252:253]
	v_pk_fma_f32 v[254:255], v[174:175], v[174:175], v[254:255]
	v_pk_add_f32 v[252:253], v[252:253], v[254:255]
	s_nop 0
	v_add_f32_e32 v183, v252, v253
	s_nop 1
	v_add_f32_dpp v183, v183, v183 quad_perm:[1,0,3,2] row_mask:0xf bank_mask:0xf bound_ctrl:1
	s_nop 1
	v_add_f32_dpp v183, v183, v183 quad_perm:[2,3,0,1] row_mask:0xf bank_mask:0xf bound_ctrl:1
	s_nop 1
	v_add_f32_dpp v183, v183, v183 row_half_mirror row_mask:0xf bank_mask:0xf bound_ctrl:1
	s_nop 1
	v_add_f32_dpp v183, v183, v183 row_mirror row_mask:0xf bank_mask:0xf bound_ctrl:1
	s_nop 1
	v_readlane_b32 s98, v183, 0
	v_readlane_b32 s99, v183, 16
	v_readlane_b32 s100, v183, 32
	v_readlane_b32 s101, v183, 48
	s_nop 1
	v_mov_b32_e32 v183, s98
	v_add_f32_e32 v183, s99, v183
	v_add_f32_e32 v183, s100, v183
	v_add_f32_e32 v183, s101, v183
	v_fmamk_f32 v183, v183, 0x3a800000, v182
	v_cmp_gt_f32_e32 vcc, 0x800000, v183
	v_mul_f32_e32 v181, 0x4b800000, v183
	s_nop 1
	v_cndmask_b32_e32 v183, v183, v181, vcc
	v_rsq_f32_e32 v183, v183
	s_nop 0
	v_mul_f32_e32 v181, 0x45800000, v183
	v_cndmask_b32_e32 v184, v183, v181, vcc
	v_mov_b32_e32 v185, v184
	v_pk_mul_f32 v[160:161], v[160:161], v[184:185]
	v_pk_mul_f32 v[162:163], v[162:163], v[184:185]
	v_pk_mul_f32 v[164:165], v[164:165], v[184:185]
	v_pk_mul_f32 v[166:167], v[166:167], v[184:185]
	v_pk_mul_f32 v[168:169], v[168:169], v[184:185]
	v_pk_mul_f32 v[170:171], v[170:171], v[184:185]
	v_pk_mul_f32 v[172:173], v[172:173], v[184:185]
	v_pk_mul_f32 v[174:175], v[174:175], v[184:185]
	v_pk_fma_f32 v[144:145], v[160:161], v[128:129], v[144:145]
	v_pk_fma_f32 v[146:147], v[162:163], v[130:131], v[146:147]
	v_pk_fma_f32 v[148:149], v[164:165], v[132:133], v[148:149]
	v_pk_fma_f32 v[150:151], v[166:167], v[134:135], v[150:151]
	v_pk_fma_f32 v[152:153], v[168:169], v[136:137], v[152:153]
	v_pk_fma_f32 v[154:155], v[170:171], v[138:139], v[154:155]
	v_pk_fma_f32 v[156:157], v[172:173], v[140:141], v[156:157]
	v_pk_fma_f32 v[158:159], v[174:175], v[142:143], v[158:159]
	v_pk_mul_f32 v[252:253], v[144:145], v[144:145]
	v_pk_mul_f32 v[254:255], v[146:147], v[146:147]
	v_pk_fma_f32 v[252:253], v[148:149], v[148:149], v[252:253]
	v_pk_fma_f32 v[254:255], v[150:151], v[150:151], v[254:255]
	v_pk_fma_f32 v[252:253], v[152:153], v[152:153], v[252:253]
	v_pk_fma_f32 v[254:255], v[154:155], v[154:155], v[254:255]
	v_pk_fma_f32 v[252:253], v[156:157], v[156:157], v[252:253]
	v_pk_fma_f32 v[254:255], v[158:159], v[158:159], v[254:255]
	v_pk_add_f32 v[252:253], v[252:253], v[254:255]
	s_nop 0
	v_add_f32_e32 v183, v252, v253
	s_nop 1
	v_add_f32_dpp v183, v183, v183 quad_perm:[1,0,3,2] row_mask:0xf bank_mask:0xf bound_ctrl:1
	s_nop 1
	v_add_f32_dpp v183, v183, v183 quad_perm:[2,3,0,1] row_mask:0xf bank_mask:0xf bound_ctrl:1
	s_nop 1
	v_add_f32_dpp v183, v183, v183 row_half_mirror row_mask:0xf bank_mask:0xf bound_ctrl:1
	s_nop 1
	v_add_f32_dpp v183, v183, v183 row_mirror row_mask:0xf bank_mask:0xf bound_ctrl:1
	s_nop 1
	v_readlane_b32 s98, v183, 0
	v_readlane_b32 s99, v183, 16
	v_readlane_b32 s100, v183, 32
	v_readlane_b32 s101, v183, 48
	s_nop 1
	v_mov_b32_e32 v183, s98
	v_add_f32_e32 v183, s99, v183
	v_add_f32_e32 v183, s100, v183
	v_add_f32_e32 v183, s101, v183
	v_fmamk_f32 v183, v183, 0x3a800000, v182
	v_cmp_gt_f32_e32 vcc, 0x800000, v183
	v_mul_f32_e32 v181, 0x4b800000, v183
	s_nop 1
	v_cndmask_b32_e32 v183, v183, v181, vcc
	v_rsq_f32_e32 v183, v183
	s_nop 0
	v_mul_f32_e32 v181, 0x45800000, v183
	v_cndmask_b32_e32 v184, v183, v181, vcc
	v_mov_b32_e32 v185, v184
	v_cvt_pk_bf16_f32 v48, v144, v145
	v_cvt_pk_bf16_f32 v49, v146, v147
	v_cvt_pk_bf16_f32 v50, v148, v149
	v_cvt_pk_bf16_f32 v51, v150, v151
	v_cvt_pk_bf16_f32 v52, v152, v153
	v_cvt_pk_bf16_f32 v53, v154, v155
	v_cvt_pk_bf16_f32 v54, v156, v157
	v_cvt_pk_bf16_f32 v55, v158, v159
	v_add_u32_e32 v181, 0x2400000, v177
	global_store_dwordx4 v181, v[48:51], s[78:79]
	global_store_dwordx4 v181, v[52:55], s[78:79] offset:1024
	v_add_u32_e32 v236, 0x6000, v237
	s_mov_b64 exec, 1
	global_store_dword v236, v184, s[78:79]
	s_mov_b64 exec, -1
	s_waitcnt vmcnt(12)
	v_lshlrev_b32_e32 v144, 16, v64
	v_and_b32_e32 v145, 0xffff0000, v64
	v_lshlrev_b32_e32 v146, 16, v65
	v_and_b32_e32 v147, 0xffff0000, v65
	v_lshlrev_b32_e32 v148, 16, v66
	v_and_b32_e32 v149, 0xffff0000, v66
	v_lshlrev_b32_e32 v150, 16, v67
	v_and_b32_e32 v151, 0xffff0000, v67
	v_lshlrev_b32_e32 v152, 16, v68
	v_and_b32_e32 v153, 0xffff0000, v68
	v_lshlrev_b32_e32 v154, 16, v69
	v_and_b32_e32 v155, 0xffff0000, v69
	v_lshlrev_b32_e32 v156, 16, v70
	v_and_b32_e32 v157, 0xffff0000, v70
	v_lshlrev_b32_e32 v158, 16, v71
	v_and_b32_e32 v159, 0xffff0000, v71
	v_lshlrev_b32_e32 v160, 16, v72
	v_and_b32_e32 v161, 0xffff0000, v72
	v_lshlrev_b32_e32 v162, 16, v73
	v_and_b32_e32 v163, 0xffff0000, v73
	v_lshlrev_b32_e32 v164, 16, v74
	v_and_b32_e32 v165, 0xffff0000, v74
	v_lshlrev_b32_e32 v166, 16, v75
	v_and_b32_e32 v167, 0xffff0000, v75
	v_lshlrev_b32_e32 v168, 16, v76
	v_and_b32_e32 v169, 0xffff0000, v76
	v_lshlrev_b32_e32 v170, 16, v77
	v_and_b32_e32 v171, 0xffff0000, v77
	v_lshlrev_b32_e32 v172, 16, v78
	v_and_b32_e32 v173, 0xffff0000, v78
	v_lshlrev_b32_e32 v174, 16, v79
	v_and_b32_e32 v175, 0xffff0000, v79
	v_pk_mul_f32 v[252:253], v[160:161], v[160:161]
	v_pk_mul_f32 v[254:255], v[162:163], v[162:163]
	v_pk_fma_f32 v[252:253], v[164:165], v[164:165], v[252:253]
	v_pk_fma_f32 v[254:255], v[166:167], v[166:167], v[254:255]
	v_pk_fma_f32 v[252:253], v[168:169], v[168:169], v[252:253]
	v_pk_fma_f32 v[254:255], v[170:171], v[170:171], v[254:255]
	v_pk_fma_f32 v[252:253], v[172:173], v[172:173], v[252:253]
	v_pk_fma_f32 v[254:255], v[174:175], v[174:175], v[254:255]
	v_pk_add_f32 v[252:253], v[252:253], v[254:255]
	s_nop 0
	v_add_f32_e32 v183, v252, v253
	s_nop 1
	v_add_f32_dpp v183, v183, v183 quad_perm:[1,0,3,2] row_mask:0xf bank_mask:0xf bound_ctrl:1
	s_nop 1
	v_add_f32_dpp v183, v183, v183 quad_perm:[2,3,0,1] row_mask:0xf bank_mask:0xf bound_ctrl:1
	s_nop 1
	v_add_f32_dpp v183, v183, v183 row_half_mirror row_mask:0xf bank_mask:0xf bound_ctrl:1
	s_nop 1
	v_add_f32_dpp v183, v183, v183 row_mirror row_mask:0xf bank_mask:0xf bound_ctrl:1
	s_nop 1
	v_readlane_b32 s98, v183, 0
	v_readlane_b32 s99, v183, 16
	v_readlane_b32 s100, v183, 32
	v_readlane_b32 s101, v183, 48
	s_nop 1
	v_mov_b32_e32 v183, s98
	v_add_f32_e32 v183, s99, v183
	v_add_f32_e32 v183, s100, v183
	v_add_f32_e32 v183, s101, v183
	v_fmamk_f32 v183, v183, 0x3a800000, v182
	v_cmp_gt_f32_e32 vcc, 0x800000, v183
	v_mul_f32_e32 v181, 0x4b800000, v183
	s_nop 1
	v_cndmask_b32_e32 v183, v183, v181, vcc
	v_rsq_f32_e32 v183, v183
	s_nop 0
	v_mul_f32_e32 v181, 0x45800000, v183
	v_cndmask_b32_e32 v184, v183, v181, vcc
	v_mov_b32_e32 v185, v184
	v_pk_mul_f32 v[160:161], v[160:161], v[184:185]
	v_pk_mul_f32 v[162:163], v[162:163], v[184:185]
	v_pk_mul_f32 v[164:165], v[164:165], v[184:185]
	v_pk_mul_f32 v[166:167], v[166:167], v[184:185]
	v_pk_mul_f32 v[168:169], v[168:169], v[184:185]
	v_pk_mul_f32 v[170:171], v[170:171], v[184:185]
	v_pk_mul_f32 v[172:173], v[172:173], v[184:185]
	v_pk_mul_f32 v[174:175], v[174:175], v[184:185]
	v_pk_fma_f32 v[144:145], v[160:161], v[128:129], v[144:145]
	v_pk_fma_f32 v[146:147], v[162:163], v[130:131], v[146:147]
	v_pk_fma_f32 v[148:149], v[164:165], v[132:133], v[148:149]
	v_pk_fma_f32 v[150:151], v[166:167], v[134:135], v[150:151]
	v_pk_fma_f32 v[152:153], v[168:169], v[136:137], v[152:153]
	v_pk_fma_f32 v[154:155], v[170:171], v[138:139], v[154:155]
	v_pk_fma_f32 v[156:157], v[172:173], v[140:141], v[156:157]
	v_pk_fma_f32 v[158:159], v[174:175], v[142:143], v[158:159]
	v_pk_mul_f32 v[252:253], v[144:145], v[144:145]
	v_pk_mul_f32 v[254:255], v[146:147], v[146:147]
	v_pk_fma_f32 v[252:253], v[148:149], v[148:149], v[252:253]
	v_pk_fma_f32 v[254:255], v[150:151], v[150:151], v[254:255]
	v_pk_fma_f32 v[252:253], v[152:153], v[152:153], v[252:253]
	v_pk_fma_f32 v[254:255], v[154:155], v[154:155], v[254:255]
	v_pk_fma_f32 v[252:253], v[156:157], v[156:157], v[252:253]
	v_pk_fma_f32 v[254:255], v[158:159], v[158:159], v[254:255]
	v_pk_add_f32 v[252:253], v[252:253], v[254:255]
	s_nop 0
	v_add_f32_e32 v183, v252, v253
	s_nop 1
	v_add_f32_dpp v183, v183, v183 quad_perm:[1,0,3,2] row_mask:0xf bank_mask:0xf bound_ctrl:1
	s_nop 1
	v_add_f32_dpp v183, v183, v183 quad_perm:[2,3,0,1] row_mask:0xf bank_mask:0xf bound_ctrl:1
	s_nop 1
	v_add_f32_dpp v183, v183, v183 row_half_mirror row_mask:0xf bank_mask:0xf bound_ctrl:1
	s_nop 1
	v_add_f32_dpp v183, v183, v183 row_mirror row_mask:0xf bank_mask:0xf bound_ctrl:1
	s_nop 1
	v_readlane_b32 s98, v183, 0
	v_readlane_b32 s99, v183, 16
	v_readlane_b32 s100, v183, 32
	v_readlane_b32 s101, v183, 48
	s_nop 1
	v_mov_b32_e32 v183, s98
	v_add_f32_e32 v183, s99, v183
	v_add_f32_e32 v183, s100, v183
	v_add_f32_e32 v183, s101, v183
	v_fmamk_f32 v183, v183, 0x3a800000, v182
	v_cmp_gt_f32_e32 vcc, 0x800000, v183
	v_mul_f32_e32 v181, 0x4b800000, v183
	s_nop 1
	v_cndmask_b32_e32 v183, v183, v181, vcc
	v_rsq_f32_e32 v183, v183
	s_nop 0
	v_mul_f32_e32 v181, 0x45800000, v183
	v_cndmask_b32_e32 v184, v183, v181, vcc
	v_mov_b32_e32 v185, v184
	v_cvt_pk_bf16_f32 v64, v144, v145
	v_cvt_pk_bf16_f32 v65, v146, v147
	v_cvt_pk_bf16_f32 v66, v148, v149
	v_cvt_pk_bf16_f32 v67, v150, v151
	v_cvt_pk_bf16_f32 v68, v152, v153
	v_cvt_pk_bf16_f32 v69, v154, v155
	v_cvt_pk_bf16_f32 v70, v156, v157
	v_cvt_pk_bf16_f32 v71, v158, v159
	v_add_u32_e32 v181, 0x2800000, v177
	global_store_dwordx4 v181, v[64:67], s[78:79]
	global_store_dwordx4 v181, v[68:71], s[78:79] offset:1024
	v_add_u32_e32 v236, 0x8000, v237
	s_mov_b64 exec, 1
	global_store_dword v236, v184, s[78:79]
	s_mov_b64 exec, -1
	s_waitcnt vmcnt(8)
	v_lshlrev_b32_e32 v144, 16, v80
	v_and_b32_e32 v145, 0xffff0000, v80
	v_lshlrev_b32_e32 v146, 16, v81
	v_and_b32_e32 v147, 0xffff0000, v81
	v_lshlrev_b32_e32 v148, 16, v82
	v_and_b32_e32 v149, 0xffff0000, v82
	v_lshlrev_b32_e32 v150, 16, v83
	v_and_b32_e32 v151, 0xffff0000, v83
	v_lshlrev_b32_e32 v152, 16, v84
	v_and_b32_e32 v153, 0xffff0000, v84
	v_lshlrev_b32_e32 v154, 16, v85
	v_and_b32_e32 v155, 0xffff0000, v85
	v_lshlrev_b32_e32 v156, 16, v86
	v_and_b32_e32 v157, 0xffff0000, v86
	v_lshlrev_b32_e32 v158, 16, v87
	v_and_b32_e32 v159, 0xffff0000, v87
	v_lshlrev_b32_e32 v160, 16, v88
	v_and_b32_e32 v161, 0xffff0000, v88
	v_lshlrev_b32_e32 v162, 16, v89
	v_and_b32_e32 v163, 0xffff0000, v89
	v_lshlrev_b32_e32 v164, 16, v90
	v_and_b32_e32 v165, 0xffff0000, v90
	v_lshlrev_b32_e32 v166, 16, v91
	v_and_b32_e32 v167, 0xffff0000, v91
	v_lshlrev_b32_e32 v168, 16, v92
	v_and_b32_e32 v169, 0xffff0000, v92
	v_lshlrev_b32_e32 v170, 16, v93
	v_and_b32_e32 v171, 0xffff0000, v93
	v_lshlrev_b32_e32 v172, 16, v94
	v_and_b32_e32 v173, 0xffff0000, v94
	v_lshlrev_b32_e32 v174, 16, v95
	v_and_b32_e32 v175, 0xffff0000, v95
	v_pk_mul_f32 v[252:253], v[160:161], v[160:161]
	v_pk_mul_f32 v[254:255], v[162:163], v[162:163]
	v_pk_fma_f32 v[252:253], v[164:165], v[164:165], v[252:253]
	v_pk_fma_f32 v[254:255], v[166:167], v[166:167], v[254:255]
	v_pk_fma_f32 v[252:253], v[168:169], v[168:169], v[252:253]
	v_pk_fma_f32 v[254:255], v[170:171], v[170:171], v[254:255]
	v_pk_fma_f32 v[252:253], v[172:173], v[172:173], v[252:253]
	v_pk_fma_f32 v[254:255], v[174:175], v[174:175], v[254:255]
	v_pk_add_f32 v[252:253], v[252:253], v[254:255]
	s_nop 0
	v_add_f32_e32 v183, v252, v253
	s_nop 1
	v_add_f32_dpp v183, v183, v183 quad_perm:[1,0,3,2] row_mask:0xf bank_mask:0xf bound_ctrl:1
	s_nop 1
	v_add_f32_dpp v183, v183, v183 quad_perm:[2,3,0,1] row_mask:0xf bank_mask:0xf bound_ctrl:1
	s_nop 1
	v_add_f32_dpp v183, v183, v183 row_half_mirror row_mask:0xf bank_mask:0xf bound_ctrl:1
	s_nop 1
	v_add_f32_dpp v183, v183, v183 row_mirror row_mask:0xf bank_mask:0xf bound_ctrl:1
	s_nop 1
	v_readlane_b32 s98, v183, 0
	v_readlane_b32 s99, v183, 16
	v_readlane_b32 s100, v183, 32
	v_readlane_b32 s101, v183, 48
	s_nop 1
	v_mov_b32_e32 v183, s98
	v_add_f32_e32 v183, s99, v183
	v_add_f32_e32 v183, s100, v183
	v_add_f32_e32 v183, s101, v183
	v_fmamk_f32 v183, v183, 0x3a800000, v182
	v_cmp_gt_f32_e32 vcc, 0x800000, v183
	v_mul_f32_e32 v181, 0x4b800000, v183
	s_nop 1
	v_cndmask_b32_e32 v183, v183, v181, vcc
	v_rsq_f32_e32 v183, v183
	s_nop 0
	v_mul_f32_e32 v181, 0x45800000, v183
	v_cndmask_b32_e32 v184, v183, v181, vcc
	v_mov_b32_e32 v185, v184
	v_pk_mul_f32 v[160:161], v[160:161], v[184:185]
	v_pk_mul_f32 v[162:163], v[162:163], v[184:185]
	v_pk_mul_f32 v[164:165], v[164:165], v[184:185]
	v_pk_mul_f32 v[166:167], v[166:167], v[184:185]
	v_pk_mul_f32 v[168:169], v[168:169], v[184:185]
	v_pk_mul_f32 v[170:171], v[170:171], v[184:185]
	v_pk_mul_f32 v[172:173], v[172:173], v[184:185]
	v_pk_mul_f32 v[174:175], v[174:175], v[184:185]
	v_pk_fma_f32 v[144:145], v[160:161], v[128:129], v[144:145]
	v_pk_fma_f32 v[146:147], v[162:163], v[130:131], v[146:147]
	v_pk_fma_f32 v[148:149], v[164:165], v[132:133], v[148:149]
	v_pk_fma_f32 v[150:151], v[166:167], v[134:135], v[150:151]
	v_pk_fma_f32 v[152:153], v[168:169], v[136:137], v[152:153]
	v_pk_fma_f32 v[154:155], v[170:171], v[138:139], v[154:155]
	v_pk_fma_f32 v[156:157], v[172:173], v[140:141], v[156:157]
	v_pk_fma_f32 v[158:159], v[174:175], v[142:143], v[158:159]
	v_pk_mul_f32 v[252:253], v[144:145], v[144:145]
	v_pk_mul_f32 v[254:255], v[146:147], v[146:147]
	v_pk_fma_f32 v[252:253], v[148:149], v[148:149], v[252:253]
	v_pk_fma_f32 v[254:255], v[150:151], v[150:151], v[254:255]
	v_pk_fma_f32 v[252:253], v[152:153], v[152:153], v[252:253]
	v_pk_fma_f32 v[254:255], v[154:155], v[154:155], v[254:255]
	v_pk_fma_f32 v[252:253], v[156:157], v[156:157], v[252:253]
	v_pk_fma_f32 v[254:255], v[158:159], v[158:159], v[254:255]
	v_pk_add_f32 v[252:253], v[252:253], v[254:255]
	s_nop 0
	v_add_f32_e32 v183, v252, v253
	s_nop 1
	v_add_f32_dpp v183, v183, v183 quad_perm:[1,0,3,2] row_mask:0xf bank_mask:0xf bound_ctrl:1
	s_nop 1
	v_add_f32_dpp v183, v183, v183 quad_perm:[2,3,0,1] row_mask:0xf bank_mask:0xf bound_ctrl:1
	s_nop 1
	v_add_f32_dpp v183, v183, v183 row_half_mirror row_mask:0xf bank_mask:0xf bound_ctrl:1
	s_nop 1
	v_add_f32_dpp v183, v183, v183 row_mirror row_mask:0xf bank_mask:0xf bound_ctrl:1
	s_nop 1
	v_readlane_b32 s98, v183, 0
	v_readlane_b32 s99, v183, 16
	v_readlane_b32 s100, v183, 32
	v_readlane_b32 s101, v183, 48
	s_nop 1
	v_mov_b32_e32 v183, s98
	v_add_f32_e32 v183, s99, v183
	v_add_f32_e32 v183, s100, v183
	v_add_f32_e32 v183, s101, v183
	v_fmamk_f32 v183, v183, 0x3a800000, v182
	v_cmp_gt_f32_e32 vcc, 0x800000, v183
	v_mul_f32_e32 v181, 0x4b800000, v183
	s_nop 1
	v_cndmask_b32_e32 v183, v183, v181, vcc
	v_rsq_f32_e32 v183, v183
	s_nop 0
	v_mul_f32_e32 v181, 0x45800000, v183
	v_cndmask_b32_e32 v184, v183, v181, vcc
	v_mov_b32_e32 v185, v184
	v_cvt_pk_bf16_f32 v80, v144, v145
	v_cvt_pk_bf16_f32 v81, v146, v147
	v_cvt_pk_bf16_f32 v82, v148, v149
	v_cvt_pk_bf16_f32 v83, v150, v151
	v_cvt_pk_bf16_f32 v84, v152, v153
	v_cvt_pk_bf16_f32 v85, v154, v155
	v_cvt_pk_bf16_f32 v86, v156, v157
	v_cvt_pk_bf16_f32 v87, v158, v159
	v_add_u32_e32 v181, 0x2c00000, v177
	global_store_dwordx4 v181, v[80:83], s[78:79]
	global_store_dwordx4 v181, v[84:87], s[78:79] offset:1024
	v_add_u32_e32 v236, 0xa000, v237
	s_mov_b64 exec, 1
	global_store_dword v236, v184, s[78:79]
	s_mov_b64 exec, -1
	s_waitcnt vmcnt(4)
	v_lshlrev_b32_e32 v144, 16, v96
	v_and_b32_e32 v145, 0xffff0000, v96
	v_lshlrev_b32_e32 v146, 16, v97
	v_and_b32_e32 v147, 0xffff0000, v97
	v_lshlrev_b32_e32 v148, 16, v98
	v_and_b32_e32 v149, 0xffff0000, v98
	v_lshlrev_b32_e32 v150, 16, v99
	v_and_b32_e32 v151, 0xffff0000, v99
	v_lshlrev_b32_e32 v152, 16, v100
	v_and_b32_e32 v153, 0xffff0000, v100
	v_lshlrev_b32_e32 v154, 16, v101
	v_and_b32_e32 v155, 0xffff0000, v101
	v_lshlrev_b32_e32 v156, 16, v102
	v_and_b32_e32 v157, 0xffff0000, v102
	v_lshlrev_b32_e32 v158, 16, v103
	v_and_b32_e32 v159, 0xffff0000, v103
	v_lshlrev_b32_e32 v160, 16, v104
	v_and_b32_e32 v161, 0xffff0000, v104
	v_lshlrev_b32_e32 v162, 16, v105
	v_and_b32_e32 v163, 0xffff0000, v105
	v_lshlrev_b32_e32 v164, 16, v106
	v_and_b32_e32 v165, 0xffff0000, v106
	v_lshlrev_b32_e32 v166, 16, v107
	v_and_b32_e32 v167, 0xffff0000, v107
	v_lshlrev_b32_e32 v168, 16, v108
	v_and_b32_e32 v169, 0xffff0000, v108
	v_lshlrev_b32_e32 v170, 16, v109
	v_and_b32_e32 v171, 0xffff0000, v109
	v_lshlrev_b32_e32 v172, 16, v110
	v_and_b32_e32 v173, 0xffff0000, v110
	v_lshlrev_b32_e32 v174, 16, v111
	v_and_b32_e32 v175, 0xffff0000, v111
	v_pk_mul_f32 v[252:253], v[160:161], v[160:161]
	v_pk_mul_f32 v[254:255], v[162:163], v[162:163]
	v_pk_fma_f32 v[252:253], v[164:165], v[164:165], v[252:253]
	v_pk_fma_f32 v[254:255], v[166:167], v[166:167], v[254:255]
	v_pk_fma_f32 v[252:253], v[168:169], v[168:169], v[252:253]
	v_pk_fma_f32 v[254:255], v[170:171], v[170:171], v[254:255]
	v_pk_fma_f32 v[252:253], v[172:173], v[172:173], v[252:253]
	v_pk_fma_f32 v[254:255], v[174:175], v[174:175], v[254:255]
	v_pk_add_f32 v[252:253], v[252:253], v[254:255]
	s_nop 0
	v_add_f32_e32 v183, v252, v253
	s_nop 1
	v_add_f32_dpp v183, v183, v183 quad_perm:[1,0,3,2] row_mask:0xf bank_mask:0xf bound_ctrl:1
	s_nop 1
	v_add_f32_dpp v183, v183, v183 quad_perm:[2,3,0,1] row_mask:0xf bank_mask:0xf bound_ctrl:1
	s_nop 1
	v_add_f32_dpp v183, v183, v183 row_half_mirror row_mask:0xf bank_mask:0xf bound_ctrl:1
	s_nop 1
	v_add_f32_dpp v183, v183, v183 row_mirror row_mask:0xf bank_mask:0xf bound_ctrl:1
	s_nop 1
	v_readlane_b32 s98, v183, 0
	v_readlane_b32 s99, v183, 16
	v_readlane_b32 s100, v183, 32
	v_readlane_b32 s101, v183, 48
	s_nop 1
	v_mov_b32_e32 v183, s98
	v_add_f32_e32 v183, s99, v183
	v_add_f32_e32 v183, s100, v183
	v_add_f32_e32 v183, s101, v183
	v_fmamk_f32 v183, v183, 0x3a800000, v182
	v_cmp_gt_f32_e32 vcc, 0x800000, v183
	v_mul_f32_e32 v181, 0x4b800000, v183
	s_nop 1
	v_cndmask_b32_e32 v183, v183, v181, vcc
	v_rsq_f32_e32 v183, v183
	s_nop 0
	v_mul_f32_e32 v181, 0x45800000, v183
	v_cndmask_b32_e32 v184, v183, v181, vcc
	v_mov_b32_e32 v185, v184
	v_pk_mul_f32 v[160:161], v[160:161], v[184:185]
	v_pk_mul_f32 v[162:163], v[162:163], v[184:185]
	v_pk_mul_f32 v[164:165], v[164:165], v[184:185]
	v_pk_mul_f32 v[166:167], v[166:167], v[184:185]
	v_pk_mul_f32 v[168:169], v[168:169], v[184:185]
	v_pk_mul_f32 v[170:171], v[170:171], v[184:185]
	v_pk_mul_f32 v[172:173], v[172:173], v[184:185]
	v_pk_mul_f32 v[174:175], v[174:175], v[184:185]
	v_pk_fma_f32 v[144:145], v[160:161], v[128:129], v[144:145]
	v_pk_fma_f32 v[146:147], v[162:163], v[130:131], v[146:147]
	v_pk_fma_f32 v[148:149], v[164:165], v[132:133], v[148:149]
	v_pk_fma_f32 v[150:151], v[166:167], v[134:135], v[150:151]
	v_pk_fma_f32 v[152:153], v[168:169], v[136:137], v[152:153]
	v_pk_fma_f32 v[154:155], v[170:171], v[138:139], v[154:155]
	v_pk_fma_f32 v[156:157], v[172:173], v[140:141], v[156:157]
	v_pk_fma_f32 v[158:159], v[174:175], v[142:143], v[158:159]
	v_pk_mul_f32 v[252:253], v[144:145], v[144:145]
	v_pk_mul_f32 v[254:255], v[146:147], v[146:147]
	v_pk_fma_f32 v[252:253], v[148:149], v[148:149], v[252:253]
	v_pk_fma_f32 v[254:255], v[150:151], v[150:151], v[254:255]
	v_pk_fma_f32 v[252:253], v[152:153], v[152:153], v[252:253]
	v_pk_fma_f32 v[254:255], v[154:155], v[154:155], v[254:255]
	v_pk_fma_f32 v[252:253], v[156:157], v[156:157], v[252:253]
	v_pk_fma_f32 v[254:255], v[158:159], v[158:159], v[254:255]
	v_pk_add_f32 v[252:253], v[252:253], v[254:255]
	s_nop 0
	v_add_f32_e32 v183, v252, v253
	s_nop 1
	v_add_f32_dpp v183, v183, v183 quad_perm:[1,0,3,2] row_mask:0xf bank_mask:0xf bound_ctrl:1
	s_nop 1
	v_add_f32_dpp v183, v183, v183 quad_perm:[2,3,0,1] row_mask:0xf bank_mask:0xf bound_ctrl:1
	s_nop 1
	v_add_f32_dpp v183, v183, v183 row_half_mirror row_mask:0xf bank_mask:0xf bound_ctrl:1
	s_nop 1
	v_add_f32_dpp v183, v183, v183 row_mirror row_mask:0xf bank_mask:0xf bound_ctrl:1
	s_nop 1
	v_readlane_b32 s98, v183, 0
	v_readlane_b32 s99, v183, 16
	v_readlane_b32 s100, v183, 32
	v_readlane_b32 s101, v183, 48
	s_nop 1
	v_mov_b32_e32 v183, s98
	v_add_f32_e32 v183, s99, v183
	v_add_f32_e32 v183, s100, v183
	v_add_f32_e32 v183, s101, v183
	v_fmamk_f32 v183, v183, 0x3a800000, v182
	v_cmp_gt_f32_e32 vcc, 0x800000, v183
	v_mul_f32_e32 v181, 0x4b800000, v183
	s_nop 1
	v_cndmask_b32_e32 v183, v183, v181, vcc
	v_rsq_f32_e32 v183, v183
	s_nop 0
	v_mul_f32_e32 v181, 0x45800000, v183
	v_cndmask_b32_e32 v184, v183, v181, vcc
	v_mov_b32_e32 v185, v184
	v_cvt_pk_bf16_f32 v96, v144, v145
	v_cvt_pk_bf16_f32 v97, v146, v147
	v_cvt_pk_bf16_f32 v98, v148, v149
	v_cvt_pk_bf16_f32 v99, v150, v151
	v_cvt_pk_bf16_f32 v100, v152, v153
	v_cvt_pk_bf16_f32 v101, v154, v155
	v_cvt_pk_bf16_f32 v102, v156, v157
	v_cvt_pk_bf16_f32 v103, v158, v159
	v_add_u32_e32 v181, 0x3000000, v177
	global_store_dwordx4 v181, v[96:99], s[78:79]
	global_store_dwordx4 v181, v[100:103], s[78:79] offset:1024
	v_add_u32_e32 v236, 0xc000, v237
	s_mov_b64 exec, 1
	global_store_dword v236, v184, s[78:79]
	s_mov_b64 exec, -1
	s_waitcnt vmcnt(0)
	v_lshlrev_b32_e32 v144, 16, v112
	v_and_b32_e32 v145, 0xffff0000, v112
	v_lshlrev_b32_e32 v146, 16, v113
	v_and_b32_e32 v147, 0xffff0000, v113
	v_lshlrev_b32_e32 v148, 16, v114
	v_and_b32_e32 v149, 0xffff0000, v114
	v_lshlrev_b32_e32 v150, 16, v115
	v_and_b32_e32 v151, 0xffff0000, v115
	v_lshlrev_b32_e32 v152, 16, v116
	v_and_b32_e32 v153, 0xffff0000, v116
	v_lshlrev_b32_e32 v154, 16, v117
	v_and_b32_e32 v155, 0xffff0000, v117
	v_lshlrev_b32_e32 v156, 16, v118
	v_and_b32_e32 v157, 0xffff0000, v118
	v_lshlrev_b32_e32 v158, 16, v119
	v_and_b32_e32 v159, 0xffff0000, v119
	v_lshlrev_b32_e32 v160, 16, v120
	v_and_b32_e32 v161, 0xffff0000, v120
	v_lshlrev_b32_e32 v162, 16, v121
	v_and_b32_e32 v163, 0xffff0000, v121
	v_lshlrev_b32_e32 v164, 16, v122
	v_and_b32_e32 v165, 0xffff0000, v122
	v_lshlrev_b32_e32 v166, 16, v123
	v_and_b32_e32 v167, 0xffff0000, v123
	v_lshlrev_b32_e32 v168, 16, v124
	v_and_b32_e32 v169, 0xffff0000, v124
	v_lshlrev_b32_e32 v170, 16, v125
	v_and_b32_e32 v171, 0xffff0000, v125
	v_lshlrev_b32_e32 v172, 16, v126
	v_and_b32_e32 v173, 0xffff0000, v126
	v_lshlrev_b32_e32 v174, 16, v127
	v_and_b32_e32 v175, 0xffff0000, v127
	v_pk_mul_f32 v[252:253], v[160:161], v[160:161]
	v_pk_mul_f32 v[254:255], v[162:163], v[162:163]
	v_pk_fma_f32 v[252:253], v[164:165], v[164:165], v[252:253]
	v_pk_fma_f32 v[254:255], v[166:167], v[166:167], v[254:255]
	v_pk_fma_f32 v[252:253], v[168:169], v[168:169], v[252:253]
	v_pk_fma_f32 v[254:255], v[170:171], v[170:171], v[254:255]
	v_pk_fma_f32 v[252:253], v[172:173], v[172:173], v[252:253]
	v_pk_fma_f32 v[254:255], v[174:175], v[174:175], v[254:255]
	v_pk_add_f32 v[252:253], v[252:253], v[254:255]
	s_nop 0
	v_add_f32_e32 v183, v252, v253
	s_nop 1
	v_add_f32_dpp v183, v183, v183 quad_perm:[1,0,3,2] row_mask:0xf bank_mask:0xf bound_ctrl:1
	s_nop 1
	v_add_f32_dpp v183, v183, v183 quad_perm:[2,3,0,1] row_mask:0xf bank_mask:0xf bound_ctrl:1
	s_nop 1
	v_add_f32_dpp v183, v183, v183 row_half_mirror row_mask:0xf bank_mask:0xf bound_ctrl:1
	s_nop 1
	v_add_f32_dpp v183, v183, v183 row_mirror row_mask:0xf bank_mask:0xf bound_ctrl:1
	s_nop 1
	v_readlane_b32 s98, v183, 0
	v_readlane_b32 s99, v183, 16
	v_readlane_b32 s100, v183, 32
	v_readlane_b32 s101, v183, 48
	s_nop 1
	v_mov_b32_e32 v183, s98
	v_add_f32_e32 v183, s99, v183
	v_add_f32_e32 v183, s100, v183
	v_add_f32_e32 v183, s101, v183
	v_fmamk_f32 v183, v183, 0x3a800000, v182
	v_cmp_gt_f32_e32 vcc, 0x800000, v183
	v_mul_f32_e32 v181, 0x4b800000, v183
	s_nop 1
	v_cndmask_b32_e32 v183, v183, v181, vcc
	v_rsq_f32_e32 v183, v183
	s_nop 0
	v_mul_f32_e32 v181, 0x45800000, v183
	v_cndmask_b32_e32 v184, v183, v181, vcc
	v_mov_b32_e32 v185, v184
	v_pk_mul_f32 v[160:161], v[160:161], v[184:185]
	v_pk_mul_f32 v[162:163], v[162:163], v[184:185]
	v_pk_mul_f32 v[164:165], v[164:165], v[184:185]
	v_pk_mul_f32 v[166:167], v[166:167], v[184:185]
	v_pk_mul_f32 v[168:169], v[168:169], v[184:185]
	v_pk_mul_f32 v[170:171], v[170:171], v[184:185]
	v_pk_mul_f32 v[172:173], v[172:173], v[184:185]
	v_pk_mul_f32 v[174:175], v[174:175], v[184:185]
	v_pk_fma_f32 v[144:145], v[160:161], v[128:129], v[144:145]
	v_pk_fma_f32 v[146:147], v[162:163], v[130:131], v[146:147]
	v_pk_fma_f32 v[148:149], v[164:165], v[132:133], v[148:149]
	v_pk_fma_f32 v[150:151], v[166:167], v[134:135], v[150:151]
	v_pk_fma_f32 v[152:153], v[168:169], v[136:137], v[152:153]
	v_pk_fma_f32 v[154:155], v[170:171], v[138:139], v[154:155]
	v_pk_fma_f32 v[156:157], v[172:173], v[140:141], v[156:157]
	v_pk_fma_f32 v[158:159], v[174:175], v[142:143], v[158:159]
	v_pk_mul_f32 v[252:253], v[144:145], v[144:145]
	v_pk_mul_f32 v[254:255], v[146:147], v[146:147]
	v_pk_fma_f32 v[252:253], v[148:149], v[148:149], v[252:253]
	v_pk_fma_f32 v[254:255], v[150:151], v[150:151], v[254:255]
	v_pk_fma_f32 v[252:253], v[152:153], v[152:153], v[252:253]
	v_pk_fma_f32 v[254:255], v[154:155], v[154:155], v[254:255]
	v_pk_fma_f32 v[252:253], v[156:157], v[156:157], v[252:253]
	v_pk_fma_f32 v[254:255], v[158:159], v[158:159], v[254:255]
	v_pk_add_f32 v[252:253], v[252:253], v[254:255]
	s_nop 0
	v_add_f32_e32 v183, v252, v253
	s_nop 1
	v_add_f32_dpp v183, v183, v183 quad_perm:[1,0,3,2] row_mask:0xf bank_mask:0xf bound_ctrl:1
	s_nop 1
	v_add_f32_dpp v183, v183, v183 quad_perm:[2,3,0,1] row_mask:0xf bank_mask:0xf bound_ctrl:1
	s_nop 1
	v_add_f32_dpp v183, v183, v183 row_half_mirror row_mask:0xf bank_mask:0xf bound_ctrl:1
	s_nop 1
	v_add_f32_dpp v183, v183, v183 row_mirror row_mask:0xf bank_mask:0xf bound_ctrl:1
	s_nop 1
	v_readlane_b32 s98, v183, 0
	v_readlane_b32 s99, v183, 16
	v_readlane_b32 s100, v183, 32
	v_readlane_b32 s101, v183, 48
	s_nop 1
	v_mov_b32_e32 v183, s98
	v_add_f32_e32 v183, s99, v183
	v_add_f32_e32 v183, s100, v183
	v_add_f32_e32 v183, s101, v183
	v_fmamk_f32 v183, v183, 0x3a800000, v182
	v_cmp_gt_f32_e32 vcc, 0x800000, v183
	v_mul_f32_e32 v181, 0x4b800000, v183
	s_nop 1
	v_cndmask_b32_e32 v183, v183, v181, vcc
	v_rsq_f32_e32 v183, v183
	s_nop 0
	v_mul_f32_e32 v181, 0x45800000, v183
	v_cndmask_b32_e32 v184, v183, v181, vcc
	v_mov_b32_e32 v185, v184
	v_cvt_pk_bf16_f32 v112, v144, v145
	v_cvt_pk_bf16_f32 v113, v146, v147
	v_cvt_pk_bf16_f32 v114, v148, v149
	v_cvt_pk_bf16_f32 v115, v150, v151
	v_cvt_pk_bf16_f32 v116, v152, v153
	v_cvt_pk_bf16_f32 v117, v154, v155
	v_cvt_pk_bf16_f32 v118, v156, v157
	v_cvt_pk_bf16_f32 v119, v158, v159
	v_add_u32_e32 v181, 0x3400000, v177
	global_store_dwordx4 v181, v[112:115], s[78:79]
	global_store_dwordx4 v181, v[116:119], s[78:79] offset:1024
	v_add_u32_e32 v236, 0xe000, v237
	s_mov_b64 exec, 1
	global_store_dword v236, v184, s[78:79]
	s_mov_b64 exec, -1
	v_readfirstlane_b32 s98, v179
	s_nop 3
	s_and_b32 s99, s98, 3
	s_cmp_lg_u32 s99, 0
	s_cbranch_scc1 .Lmyxupd_done_6
	v_lshrrev_b32_e32 v179, 2, v179
	v_lshlrev_b32_e32 v177, 4, v176
	v_lshl_add_u32 v177, v179, 11, v177
	v_lshlrev_b32_e32 v237, 2, v179
	v_add_u32_e32 v237, 0x10000, v237
	v_add_u32_e32 v181, 0x3800000, v177
	global_load_dwordx4 v[240:243], v181, s[78:79]
	global_load_dwordx4 v[244:247], v181, s[78:79] offset:1024
	v_lshl_add_u32 v183, v179, 12, v180
	v_add_u32_e32 v183, 0xbf00000, v183
	v_add_u32_e32 v181, 0x0, v183
	global_load_dwordx4 v[0:3], v181, s[78:79]
	global_load_dwordx4 v[4:7], v181, s[78:79] offset:16
	global_load_dwordx4 v[8:11], v181, s[78:79] offset:2048
	global_load_dwordx4 v[12:15], v181, s[78:79] offset:2064
	v_add_u32_e32 v181, 0x200000, v183
	global_load_dwordx4 v[16:19], v181, s[78:79]
	global_load_dwordx4 v[20:23], v181, s[78:79] offset:16
	global_load_dwordx4 v[24:27], v181, s[78:79] offset:2048
	global_load_dwordx4 v[28:31], v181, s[78:79] offset:2064
	v_add_u32_e32 v181, 0x400000, v183
	global_load_dwordx4 v[32:35], v181, s[78:79]
	global_load_dwordx4 v[36:39], v181, s[78:79] offset:16
	global_load_dwordx4 v[40:43], v181, s[78:79] offset:2048
	global_load_dwordx4 v[44:47], v181, s[78:79] offset:2064
	v_add_u32_e32 v181, 0x600000, v183
	global_load_dwordx4 v[48:51], v181, s[78:79]
	global_load_dwordx4 v[52:55], v181, s[78:79] offset:16
	global_load_dwordx4 v[56:59], v181, s[78:79] offset:2048
	global_load_dwordx4 v[60:63], v181, s[78:79] offset:2064
	v_add_u32_e32 v181, 0x800000, v183
	global_load_dwordx4 v[64:67], v181, s[78:79]
	global_load_dwordx4 v[68:71], v181, s[78:79] offset:16
	global_load_dwordx4 v[72:75], v181, s[78:79] offset:2048
	global_load_dwordx4 v[76:79], v181, s[78:79] offset:2064
	v_add_u32_e32 v181, 0xa00000, v183
	global_load_dwordx4 v[80:83], v181, s[78:79]
	global_load_dwordx4 v[84:87], v181, s[78:79] offset:16
	global_load_dwordx4 v[88:91], v181, s[78:79] offset:2048
	global_load_dwordx4 v[92:95], v181, s[78:79] offset:2064
	v_add_u32_e32 v181, 0xc00000, v183
	global_load_dwordx4 v[96:99], v181, s[78:79]
	global_load_dwordx4 v[100:103], v181, s[78:79] offset:16
	global_load_dwordx4 v[104:107], v181, s[78:79] offset:2048
	global_load_dwordx4 v[108:111], v181, s[78:79] offset:2064
	v_add_u32_e32 v181, 0xe00000, v183
	global_load_dwordx4 v[112:115], v181, s[78:79]
	global_load_dwordx4 v[116:119], v181, s[78:79] offset:16
	global_load_dwordx4 v[120:123], v181, s[78:79] offset:2048
	global_load_dwordx4 v[124:127], v181, s[78:79] offset:2064
	s_waitcnt vmcnt(28)
	v_pk_add_f32 v[160:161], v[0:1], 0 op_sel_hi:[1,0]
	v_pk_add_f32 v[162:163], v[2:3], 0 op_sel_hi:[1,0]
	v_pk_add_f32 v[164:165], v[4:5], 0 op_sel_hi:[1,0]
	v_pk_add_f32 v[166:167], v[6:7], 0 op_sel_hi:[1,0]
	v_pk_add_f32 v[168:169], v[8:9], 0 op_sel_hi:[1,0]
	v_pk_add_f32 v[170:171], v[10:11], 0 op_sel_hi:[1,0]
	v_pk_add_f32 v[172:173], v[12:13], 0 op_sel_hi:[1,0]
	v_pk_add_f32 v[174:175], v[14:15], 0 op_sel_hi:[1,0]
	s_waitcnt vmcnt(24)
	v_pk_add_f32 v[160:161], v[160:161], v[16:17]
	v_pk_add_f32 v[162:163], v[162:163], v[18:19]
	v_pk_add_f32 v[164:165], v[164:165], v[20:21]
	v_pk_add_f32 v[166:167], v[166:167], v[22:23]
	v_pk_add_f32 v[168:169], v[168:169], v[24:25]
	v_pk_add_f32 v[170:171], v[170:171], v[26:27]
	v_pk_add_f32 v[172:173], v[172:173], v[28:29]
	v_pk_add_f32 v[174:175], v[174:175], v[30:31]
	s_waitcnt vmcnt(20)
	v_pk_add_f32 v[160:161], v[160:161], v[32:33]
	v_pk_add_f32 v[162:163], v[162:163], v[34:35]
	v_pk_add_f32 v[164:165], v[164:165], v[36:37]
	v_pk_add_f32 v[166:167], v[166:167], v[38:39]
	v_pk_add_f32 v[168:169], v[168:169], v[40:41]
	v_pk_add_f32 v[170:171], v[170:171], v[42:43]
	v_pk_add_f32 v[172:173], v[172:173], v[44:45]
	v_pk_add_f32 v[174:175], v[174:175], v[46:47]
	s_waitcnt vmcnt(16)
	v_pk_add_f32 v[160:161], v[160:161], v[48:49]
	v_pk_add_f32 v[162:163], v[162:163], v[50:51]
	v_pk_add_f32 v[164:165], v[164:165], v[52:53]
	v_pk_add_f32 v[166:167], v[166:167], v[54:55]
	v_pk_add_f32 v[168:169], v[168:169], v[56:57]
	v_pk_add_f32 v[170:171], v[170:171], v[58:59]
	v_pk_add_f32 v[172:173], v[172:173], v[60:61]
	v_pk_add_f32 v[174:175], v[174:175], v[62:63]
	s_waitcnt vmcnt(12)
	v_pk_add_f32 v[160:161], v[160:161], v[64:65]
	v_pk_add_f32 v[162:163], v[162:163], v[66:67]
	v_pk_add_f32 v[164:165], v[164:165], v[68:69]
	v_pk_add_f32 v[166:167], v[166:167], v[70:71]
	v_pk_add_f32 v[168:169], v[168:169], v[72:73]
	v_pk_add_f32 v[170:171], v[170:171], v[74:75]
	v_pk_add_f32 v[172:173], v[172:173], v[76:77]
	v_pk_add_f32 v[174:175], v[174:175], v[78:79]
	s_waitcnt vmcnt(8)
	v_pk_add_f32 v[160:161], v[160:161], v[80:81]
	v_pk_add_f32 v[162:163], v[162:163], v[82:83]
	v_pk_add_f32 v[164:165], v[164:165], v[84:85]
	v_pk_add_f32 v[166:167], v[166:167], v[86:87]
	v_pk_add_f32 v[168:169], v[168:169], v[88:89]
	v_pk_add_f32 v[170:171], v[170:171], v[90:91]
	v_pk_add_f32 v[172:173], v[172:173], v[92:93]
	v_pk_add_f32 v[174:175], v[174:175], v[94:95]
	s_waitcnt vmcnt(4)
	v_pk_add_f32 v[160:161], v[160:161], v[96:97]
	v_pk_add_f32 v[162:163], v[162:163], v[98:99]
	v_pk_add_f32 v[164:165], v[164:165], v[100:101]
	v_pk_add_f32 v[166:167], v[166:167], v[102:103]
	v_pk_add_f32 v[168:169], v[168:169], v[104:105]
	v_pk_add_f32 v[170:171], v[170:171], v[106:107]
	v_pk_add_f32 v[172:173], v[172:173], v[108:109]
	v_pk_add_f32 v[174:175], v[174:175], v[110:111]
	s_waitcnt vmcnt(0)
	v_pk_add_f32 v[160:161], v[160:161], v[112:113]
	v_pk_add_f32 v[162:163], v[162:163], v[114:115]
	v_pk_add_f32 v[164:165], v[164:165], v[116:117]
	v_pk_add_f32 v[166:167], v[166:167], v[118:119]
	v_pk_add_f32 v[168:169], v[168:169], v[120:121]
	v_pk_add_f32 v[170:171], v[170:171], v[122:123]
	v_pk_add_f32 v[172:173], v[172:173], v[124:125]
	v_pk_add_f32 v[174:175], v[174:175], v[126:127]
	v_lshlrev_b32_e32 v144, 16, v240
	v_and_b32_e32 v145, 0xffff0000, v240
	v_lshlrev_b32_e32 v146, 16, v241
	v_and_b32_e32 v147, 0xffff0000, v241
	v_lshlrev_b32_e32 v148, 16, v242
	v_and_b32_e32 v149, 0xffff0000, v242
	v_lshlrev_b32_e32 v150, 16, v243
	v_and_b32_e32 v151, 0xffff0000, v243
	v_lshlrev_b32_e32 v152, 16, v244
	v_and_b32_e32 v153, 0xffff0000, v244
	v_lshlrev_b32_e32 v154, 16, v245
	v_and_b32_e32 v155, 0xffff0000, v245
	v_lshlrev_b32_e32 v156, 16, v246
	v_and_b32_e32 v157, 0xffff0000, v246
	v_lshlrev_b32_e32 v158, 16, v247
	v_and_b32_e32 v159, 0xffff0000, v247
	v_pk_mul_f32 v[252:253], v[160:161], v[160:161]
	v_pk_mul_f32 v[254:255], v[162:163], v[162:163]
	v_pk_fma_f32 v[252:253], v[164:165], v[164:165], v[252:253]
	v_pk_fma_f32 v[254:255], v[166:167], v[166:167], v[254:255]
	v_pk_fma_f32 v[252:253], v[168:169], v[168:169], v[252:253]
	v_pk_fma_f32 v[254:255], v[170:171], v[170:171], v[254:255]
	v_pk_fma_f32 v[252:253], v[172:173], v[172:173], v[252:253]
	v_pk_fma_f32 v[254:255], v[174:175], v[174:175], v[254:255]
	v_pk_add_f32 v[252:253], v[252:253], v[254:255]
	s_nop 0
	v_add_f32_e32 v183, v252, v253
	s_nop 1
	v_add_f32_dpp v183, v183, v183 quad_perm:[1,0,3,2] row_mask:0xf bank_mask:0xf bound_ctrl:1
	s_nop 1
	v_add_f32_dpp v183, v183, v183 quad_perm:[2,3,0,1] row_mask:0xf bank_mask:0xf bound_ctrl:1
	s_nop 1
	v_add_f32_dpp v183, v183, v183 row_half_mirror row_mask:0xf bank_mask:0xf bound_ctrl:1
	s_nop 1
	v_add_f32_dpp v183, v183, v183 row_mirror row_mask:0xf bank_mask:0xf bound_ctrl:1
	s_nop 1
	v_readlane_b32 s98, v183, 0
	v_readlane_b32 s99, v183, 16
	v_readlane_b32 s100, v183, 32
	v_readlane_b32 s101, v183, 48
	s_nop 1
	v_mov_b32_e32 v183, s98
	v_add_f32_e32 v183, s99, v183
	v_add_f32_e32 v183, s100, v183
	v_add_f32_e32 v183, s101, v183
	v_fmamk_f32 v183, v183, 0x3a800000, v182
	v_cmp_gt_f32_e32 vcc, 0x800000, v183
	v_mul_f32_e32 v181, 0x4b800000, v183
	s_nop 1
	v_cndmask_b32_e32 v183, v183, v181, vcc
	v_rsq_f32_e32 v183, v183
	s_nop 0
	v_mul_f32_e32 v181, 0x45800000, v183
	v_cndmask_b32_e32 v184, v183, v181, vcc
	v_mov_b32_e32 v185, v184
	v_pk_mul_f32 v[160:161], v[160:161], v[184:185]
	v_pk_mul_f32 v[162:163], v[162:163], v[184:185]
	v_pk_mul_f32 v[164:165], v[164:165], v[184:185]
	v_pk_mul_f32 v[166:167], v[166:167], v[184:185]
	v_pk_mul_f32 v[168:169], v[168:169], v[184:185]
	v_pk_mul_f32 v[170:171], v[170:171], v[184:185]
	v_pk_mul_f32 v[172:173], v[172:173], v[184:185]
	v_pk_mul_f32 v[174:175], v[174:175], v[184:185]
	v_pk_fma_f32 v[144:145], v[160:161], v[128:129], v[144:145]
	v_pk_fma_f32 v[146:147], v[162:163], v[130:131], v[146:147]
	v_pk_fma_f32 v[148:149], v[164:165], v[132:133], v[148:149]
	v_pk_fma_f32 v[150:151], v[166:167], v[134:135], v[150:151]
	v_pk_fma_f32 v[152:153], v[168:169], v[136:137], v[152:153]
	v_pk_fma_f32 v[154:155], v[170:171], v[138:139], v[154:155]
	v_pk_fma_f32 v[156:157], v[172:173], v[140:141], v[156:157]
	v_pk_fma_f32 v[158:159], v[174:175], v[142:143], v[158:159]
	v_pk_mul_f32 v[252:253], v[144:145], v[144:145]
	v_pk_mul_f32 v[254:255], v[146:147], v[146:147]
	v_pk_fma_f32 v[252:253], v[148:149], v[148:149], v[252:253]
	v_pk_fma_f32 v[254:255], v[150:151], v[150:151], v[254:255]
	v_pk_fma_f32 v[252:253], v[152:153], v[152:153], v[252:253]
	v_pk_fma_f32 v[254:255], v[154:155], v[154:155], v[254:255]
	v_pk_fma_f32 v[252:253], v[156:157], v[156:157], v[252:253]
	v_pk_fma_f32 v[254:255], v[158:159], v[158:159], v[254:255]
	v_pk_add_f32 v[252:253], v[252:253], v[254:255]
	s_nop 0
	v_add_f32_e32 v183, v252, v253
	s_nop 1
	v_add_f32_dpp v183, v183, v183 quad_perm:[1,0,3,2] row_mask:0xf bank_mask:0xf bound_ctrl:1
	s_nop 1
	v_add_f32_dpp v183, v183, v183 quad_perm:[2,3,0,1] row_mask:0xf bank_mask:0xf bound_ctrl:1
	s_nop 1
	v_add_f32_dpp v183, v183, v183 row_half_mirror row_mask:0xf bank_mask:0xf bound_ctrl:1
	s_nop 1
	v_add_f32_dpp v183, v183, v183 row_mirror row_mask:0xf bank_mask:0xf bound_ctrl:1
	s_nop 1
	v_readlane_b32 s98, v183, 0
	v_readlane_b32 s99, v183, 16
	v_readlane_b32 s100, v183, 32
	v_readlane_b32 s101, v183, 48
	s_nop 1
	v_mov_b32_e32 v183, s98
	v_add_f32_e32 v183, s99, v183
	v_add_f32_e32 v183, s100, v183
	v_add_f32_e32 v183, s101, v183
	v_fmamk_f32 v183, v183, 0x3a800000, v182
	v_cmp_gt_f32_e32 vcc, 0x800000, v183
	v_mul_f32_e32 v181, 0x4b800000, v183
	s_nop 1
	v_cndmask_b32_e32 v183, v183, v181, vcc
	v_rsq_f32_e32 v183, v183
	s_nop 0
	v_mul_f32_e32 v181, 0x45800000, v183
	v_cndmask_b32_e32 v184, v183, v181, vcc
	v_mov_b32_e32 v185, v184
	v_cvt_pk_bf16_f32 v0, v144, v145
	v_cvt_pk_bf16_f32 v1, v146, v147
	v_cvt_pk_bf16_f32 v2, v148, v149
	v_cvt_pk_bf16_f32 v3, v150, v151
	v_cvt_pk_bf16_f32 v4, v152, v153
	v_cvt_pk_bf16_f32 v5, v154, v155
	v_cvt_pk_bf16_f32 v6, v156, v157
	v_cvt_pk_bf16_f32 v7, v158, v159
	v_add_u32_e32 v181, 0x3800000, v177
	global_store_dwordx4 v181, v[0:3], s[78:79]
	global_store_dwordx4 v181, v[4:7], s[78:79] offset:1024
	v_add_u32_e32 v236, 0x10000, v237
	s_mov_b64 exec, 1
	global_store_dword v236, v184, s[78:79]
	s_mov_b64 exec, -1

.LBB0_2849:
	v_readlane_b32 s0, v235, 52
	v_readlane_b32 s1, v235, 53
	s_and_b64 vcc, exec, s[0:1]
	s_waitcnt lgkmcnt(0)
	s_barrier
	v_mbcnt_lo_u32_b32 v0, -1, 0
	v_mbcnt_hi_u32_b32 v0, -1, v0
	s_cbranch_vccnz .LBB0_2864
	v_lshlrev_b32_e32 v0, 3, v0
	v_ashrrev_i32_e32 v1, 31, v0
	v_readlane_b32 s0, v235, 4
	v_lshlrev_b64 v[2:3], 1, v[0:1]
	v_lshlrev_b64 v[0:1], 2, v[0:1]
	v_readlane_b32 s1, v235, 5
	v_readlane_b32 s14, v235, 18
	v_readlane_b32 s15, v235, 19
	s_mov_b64 s[0:1], 0x3000
	v_readlane_b32 s2, v235, 6
	v_lshl_add_u64 v[4:5], s[14:15], 0, v[0:1]
	v_readlane_b32 s4, v235, 8
	v_readlane_b32 s5, v235, 9
	v_lshl_add_u64 v[50:51], v[4:5], 0, s[0:1]
	v_readlane_b32 s0, v235, 0
	s_ashr_i32 s25, s24, 31
	s_lshl_b32 s0, s0, 4
	s_add_i32 s2, s24, 0xffffc000
	s_lshl_b64 s[4:5], s[24:25], 11
	s_add_u32 s4, s78, s4
	v_readlane_b32 s1, v235, 1
	s_addc_u32 s5, s79, s5
	v_lshl_add_u64 v[44:45], s[86:87], 0, v[2:3]
	v_lshl_add_u64 v[48:49], s[54:55], 0, v[2:3]
	v_readlane_b32 s6, v235, 10
	v_readlane_b32 s7, v235, 11
	v_lshl_add_u64 v[2:3], s[4:5], 0, v[2:3]
	s_mov_b64 s[4:5], 0x9e00000
	s_ashr_i32 s1, s0, 31
	v_lshl_add_u64 v[56:57], v[2:3], 0, s[4:5]
	s_lshl_b64 s[4:5], s[0:1], 11
	s_lshl_b64 s[6:7], s[24:25], 12
	s_add_u32 s6, s76, s6
	s_addc_u32 s7, s77, s7
	v_lshl_add_u64 v[46:47], s[90:91], 0, v[0:1]
	v_readlane_b32 s3, v235, 7
	v_readlane_b32 s8, v235, 12
	v_readlane_b32 s9, v235, 13
	v_readlane_b32 s10, v235, 14
	v_readlane_b32 s11, v235, 15
	v_readlane_b32 s12, v235, 16
	v_readlane_b32 s13, v235, 17
	v_lshl_add_u64 v[52:53], s[74:75], 0, v[0:1]
	v_lshl_add_u64 v[54:55], s[76:77], 0, v[0:1]
	v_lshl_add_u64 v[0:1], s[6:7], 0, v[0:1]
	s_mov_b64 s[6:7], 0x810
	v_lshl_add_u64 v[58:59], v[0:1], 0, s[6:7]
	s_lshl_b64 s[6:7], s[0:1], 12
	s_mov_b32 s3, 0
	s_mov_b64 s[8:9], 0x200000
	s_mov_b64 s[10:11], 0x200800
	s_mov_b64 s[12:13], 0x400000
	s_mov_b64 s[14:15], 0x400800
	s_mov_b64 s[16:17], 0x600000
	s_mov_b64 s[18:19], 0x600800
	s_mov_b64 s[20:21], 0x800000
	s_mov_b32 s1, 0x800000
	s_mov_b64 s[22:23], 0x800800
	s_mov_b64 s[24:25], 0xa00000
	s_mov_b64 s[26:27], 0xa00800
	s_mov_b64 s[28:29], 0xc00000
	s_mov_b64 s[30:31], 0xc00800
	s_mov_b64 s[34:35], 0xe00000
	s_mov_b64 s[36:37], 0xe00800
	s_mov_b64 s[38:39], 0x1000000
	s_mov_b32 s60, 0x1000000
	s_mov_b64 s[40:41], 0x1000800
	s_mov_b64 s[42:43], 0x1200000
	s_mov_b32 s61, 0x1200000
	s_mov_b64 s[44:45], 0x1200800
	s_mov_b64 s[46:47], 0x1400000
	s_mov_b32 s62, 0x1400000
	s_mov_b64 s[48:49], 0x1400800
	v_mov_b32_e32 v100, 0x358637bd
	v_mbcnt_lo_u32_b32 v176, -1, 0
	v_mbcnt_hi_u32_b32 v176, -1, v176
	v_readlane_b32 s98, v235, 49
	v_readlane_b32 s99, v235, 20
	v_readlane_b32 s100, v235, 18
	v_readlane_b32 s101, v235, 19
	s_nop 3
	s_lshr_b32 vcc_lo, s98, 3
	s_and_b32 vcc_hi, vcc_lo, 7
	s_lshr_b32 vcc_lo, vcc_lo, 3
	s_lshl_b32 vcc_lo, vcc_lo, 3
	s_add_i32 vcc_lo, vcc_lo, s99
	s_lshl_b32 s98, vcc_hi, 8
	s_add_i32 s98, s98, vcc_lo
	s_mov_b32 s99, s98
	v_mov_b32_e32 v183, s99
	v_lshlrev_b32_e32 v177, 4, v176
	s_lshl_b32 s99, s99, 11
	v_add_u32_e32 v177, s99, v177
	v_add_u32_e32 v178, 0x1800000, v177
	v_add_u32_e32 v179, 0x9e00000, v177
	v_lshlrev_b32_e32 v180, 5, v176
	v_add_u32_e32 v181, 0x3000, v180
	global_load_dwordx4 v[128:131], v181, s[100:101]
	global_load_dwordx4 v[132:135], v181, s[100:101] offset:16
	global_load_dwordx4 v[136:139], v181, s[100:101] offset:2048
	global_load_dwordx4 v[140:143], v181, s[100:101] offset:2064
	global_load_dwordx4 v[236:239], v180, s[74:75]
	global_load_dwordx4 v[240:243], v180, s[74:75] offset:16
	global_load_dwordx4 v[244:247], v180, s[74:75] offset:2048
	global_load_dwordx4 v[248:251], v180, s[74:75] offset:2064
	v_mov_b32_e32 v182, 0x358637bd
	global_load_dwordx4 v[0:3], v178, s[78:79]
	global_load_dwordx4 v[4:7], v178, s[78:79] offset:1024
	global_load_dwordx4 v[8:11], v179, s[78:79]
	global_load_dwordx4 v[12:15], v179, s[78:79] offset:1024
	v_add_u32_e32 v178, 0x400000, v178
	v_add_u32_e32 v179, 0x400000, v179
	global_load_dwordx4 v[16:19], v178, s[78:79]
	global_load_dwordx4 v[20:23], v178, s[78:79] offset:1024
	global_load_dwordx4 v[24:27], v179, s[78:79]
	global_load_dwordx4 v[28:31], v179, s[78:79] offset:1024
	v_add_u32_e32 v178, 0x400000, v178
	v_add_u32_e32 v179, 0x400000, v179
	global_load_dwordx4 v[32:35], v178, s[78:79]
	global_load_dwordx4 v[36:39], v178, s[78:79] offset:1024
	global_load_dwordx4 v[40:43], v179, s[78:79]
	global_load_dwordx4 v[44:47], v179, s[78:79] offset:1024
	v_add_u32_e32 v178, 0x400000, v178
	v_add_u32_e32 v179, 0x400000, v179
	global_load_dwordx4 v[48:51], v178, s[78:79]
	global_load_dwordx4 v[52:55], v178, s[78:79] offset:1024
	global_load_dwordx4 v[56:59], v179, s[78:79]
	global_load_dwordx4 v[60:63], v179, s[78:79] offset:1024
	v_add_u32_e32 v178, 0x400000, v178
	v_add_u32_e32 v179, 0x400000, v179
	global_load_dwordx4 v[64:67], v178, s[78:79]
	global_load_dwordx4 v[68:71], v178, s[78:79] offset:1024
	global_load_dwordx4 v[72:75], v179, s[78:79]
	global_load_dwordx4 v[76:79], v179, s[78:79] offset:1024
	v_add_u32_e32 v178, 0x400000, v178
	v_add_u32_e32 v179, 0x400000, v179
	global_load_dwordx4 v[80:83], v178, s[78:79]
	global_load_dwordx4 v[84:87], v178, s[78:79] offset:1024
	global_load_dwordx4 v[88:91], v179, s[78:79]
	global_load_dwordx4 v[92:95], v179, s[78:79] offset:1024
	v_add_u32_e32 v178, 0x400000, v178
	v_add_u32_e32 v179, 0x400000, v179
	global_load_dwordx4 v[96:99], v178, s[78:79]
	global_load_dwordx4 v[100:103], v178, s[78:79] offset:1024
	global_load_dwordx4 v[104:107], v179, s[78:79]
	global_load_dwordx4 v[108:111], v179, s[78:79] offset:1024
	v_add_u32_e32 v178, 0x400000, v178
	v_add_u32_e32 v179, 0x400000, v179
	global_load_dwordx4 v[112:115], v178, s[78:79]
	global_load_dwordx4 v[116:119], v178, s[78:79] offset:1024
	global_load_dwordx4 v[120:123], v179, s[78:79]
	global_load_dwordx4 v[124:127], v179, s[78:79] offset:1024
	v_lshl_add_u32 v178, v183, 12, v180
	v_mov_b32_e32 v179, s98
	s_waitcnt vmcnt(28)
	v_lshlrev_b32_e32 v144, 16, v0
	v_and_b32_e32 v145, 0xffff0000, v0
	v_lshlrev_b32_e32 v146, 16, v1
	v_and_b32_e32 v147, 0xffff0000, v1
	v_lshlrev_b32_e32 v148, 16, v2
	v_and_b32_e32 v149, 0xffff0000, v2
	v_lshlrev_b32_e32 v150, 16, v3
	v_and_b32_e32 v151, 0xffff0000, v3
	v_lshlrev_b32_e32 v152, 16, v4
	v_and_b32_e32 v153, 0xffff0000, v4
	v_lshlrev_b32_e32 v154, 16, v5
	v_and_b32_e32 v155, 0xffff0000, v5
	v_lshlrev_b32_e32 v156, 16, v6
	v_and_b32_e32 v157, 0xffff0000, v6
	v_lshlrev_b32_e32 v158, 16, v7
	v_and_b32_e32 v159, 0xffff0000, v7
	v_lshlrev_b32_e32 v160, 16, v8
	v_and_b32_e32 v161, 0xffff0000, v8
	v_lshlrev_b32_e32 v162, 16, v9
	v_and_b32_e32 v163, 0xffff0000, v9
	v_lshlrev_b32_e32 v164, 16, v10
	v_and_b32_e32 v165, 0xffff0000, v10
	v_lshlrev_b32_e32 v166, 16, v11
	v_and_b32_e32 v167, 0xffff0000, v11
	v_lshlrev_b32_e32 v168, 16, v12
	v_and_b32_e32 v169, 0xffff0000, v12
	v_lshlrev_b32_e32 v170, 16, v13
	v_and_b32_e32 v171, 0xffff0000, v13
	v_lshlrev_b32_e32 v172, 16, v14
	v_and_b32_e32 v173, 0xffff0000, v14
	v_lshlrev_b32_e32 v174, 16, v15
	v_and_b32_e32 v175, 0xffff0000, v15
	v_pk_mul_f32 v[252:253], v[160:161], v[160:161]
	v_pk_mul_f32 v[254:255], v[162:163], v[162:163]
	v_pk_fma_f32 v[252:253], v[164:165], v[164:165], v[252:253]
	v_pk_fma_f32 v[254:255], v[166:167], v[166:167], v[254:255]
	v_pk_fma_f32 v[252:253], v[168:169], v[168:169], v[252:253]
	v_pk_fma_f32 v[254:255], v[170:171], v[170:171], v[254:255]
	v_pk_fma_f32 v[252:253], v[172:173], v[172:173], v[252:253]
	v_pk_fma_f32 v[254:255], v[174:175], v[174:175], v[254:255]
	v_pk_add_f32 v[252:253], v[252:253], v[254:255]
	s_nop 0
	v_add_f32_e32 v183, v252, v253
	s_nop 1
	v_add_f32_dpp v183, v183, v183 quad_perm:[1,0,3,2] row_mask:0xf bank_mask:0xf bound_ctrl:1
	s_nop 1
	v_add_f32_dpp v183, v183, v183 quad_perm:[2,3,0,1] row_mask:0xf bank_mask:0xf bound_ctrl:1
	s_nop 1
	v_add_f32_dpp v183, v183, v183 row_half_mirror row_mask:0xf bank_mask:0xf bound_ctrl:1
	s_nop 1
	v_add_f32_dpp v183, v183, v183 row_mirror row_mask:0xf bank_mask:0xf bound_ctrl:1
	s_nop 1
	v_readlane_b32 s98, v183, 0
	v_readlane_b32 s99, v183, 16
	v_readlane_b32 s100, v183, 32
	v_readlane_b32 s101, v183, 48
	s_nop 1
	v_mov_b32_e32 v183, s98
	v_add_f32_e32 v183, s99, v183
	v_add_f32_e32 v183, s100, v183
	v_add_f32_e32 v183, s101, v183
	v_fmamk_f32 v183, v183, 0x3a800000, v182
	v_cmp_gt_f32_e32 vcc, 0x800000, v183
	v_mul_f32_e32 v181, 0x4b800000, v183
	s_nop 1
	v_cndmask_b32_e32 v183, v183, v181, vcc
	v_rsq_f32_e32 v183, v183
	s_nop 0
	v_mul_f32_e32 v181, 0x45800000, v183
	v_cndmask_b32_e32 v184, v183, v181, vcc
	v_mov_b32_e32 v185, v184
	v_pk_mul_f32 v[160:161], v[160:161], v[184:185]
	v_pk_mul_f32 v[162:163], v[162:163], v[184:185]
	v_pk_mul_f32 v[164:165], v[164:165], v[184:185]
	v_pk_mul_f32 v[166:167], v[166:167], v[184:185]
	v_pk_mul_f32 v[168:169], v[168:169], v[184:185]
	v_pk_mul_f32 v[170:171], v[170:171], v[184:185]
	v_pk_mul_f32 v[172:173], v[172:173], v[184:185]
	v_pk_mul_f32 v[174:175], v[174:175], v[184:185]
	v_pk_fma_f32 v[144:145], v[160:161], v[128:129], v[144:145]
	v_pk_fma_f32 v[146:147], v[162:163], v[130:131], v[146:147]
	v_pk_fma_f32 v[148:149], v[164:165], v[132:133], v[148:149]
	v_pk_fma_f32 v[150:151], v[166:167], v[134:135], v[150:151]
	v_pk_fma_f32 v[152:153], v[168:169], v[136:137], v[152:153]
	v_pk_fma_f32 v[154:155], v[170:171], v[138:139], v[154:155]
	v_pk_fma_f32 v[156:157], v[172:173], v[140:141], v[156:157]
	v_pk_fma_f32 v[158:159], v[174:175], v[142:143], v[158:159]
	v_pk_mul_f32 v[252:253], v[144:145], v[144:145]
	v_pk_mul_f32 v[254:255], v[146:147], v[146:147]
	v_pk_fma_f32 v[252:253], v[148:149], v[148:149], v[252:253]
	v_pk_fma_f32 v[254:255], v[150:151], v[150:151], v[254:255]
	v_pk_fma_f32 v[252:253], v[152:153], v[152:153], v[252:253]
	v_pk_fma_f32 v[254:255], v[154:155], v[154:155], v[254:255]
	v_pk_fma_f32 v[252:253], v[156:157], v[156:157], v[252:253]
	v_pk_fma_f32 v[254:255], v[158:159], v[158:159], v[254:255]
	v_pk_add_f32 v[252:253], v[252:253], v[254:255]
	s_nop 0
	v_add_f32_e32 v183, v252, v253
	s_nop 1
	v_add_f32_dpp v183, v183, v183 quad_perm:[1,0,3,2] row_mask:0xf bank_mask:0xf bound_ctrl:1
	s_nop 1
	v_add_f32_dpp v183, v183, v183 quad_perm:[2,3,0,1] row_mask:0xf bank_mask:0xf bound_ctrl:1
	s_nop 1
	v_add_f32_dpp v183, v183, v183 row_half_mirror row_mask:0xf bank_mask:0xf bound_ctrl:1
	s_nop 1
	v_add_f32_dpp v183, v183, v183 row_mirror row_mask:0xf bank_mask:0xf bound_ctrl:1
	s_nop 1
	v_readlane_b32 s98, v183, 0
	v_readlane_b32 s99, v183, 16
	v_readlane_b32 s100, v183, 32
	v_readlane_b32 s101, v183, 48
	s_nop 1
	v_mov_b32_e32 v183, s98
	v_add_f32_e32 v183, s99, v183
	v_add_f32_e32 v183, s100, v183
	v_add_f32_e32 v183, s101, v183
	v_fmamk_f32 v183, v183, 0x3a800000, v182
	v_cmp_gt_f32_e32 vcc, 0x800000, v183
	v_mul_f32_e32 v181, 0x4b800000, v183
	s_nop 1
	v_cndmask_b32_e32 v183, v183, v181, vcc
	v_rsq_f32_e32 v183, v183
	s_nop 0
	v_mul_f32_e32 v181, 0x45800000, v183
	v_cndmask_b32_e32 v184, v183, v181, vcc
	v_mov_b32_e32 v185, v184
	v_pk_mul_f32 v[144:145], v[144:145], v[184:185]
	v_pk_mul_f32 v[146:147], v[146:147], v[184:185]
	v_pk_mul_f32 v[148:149], v[148:149], v[184:185]
	v_pk_mul_f32 v[150:151], v[150:151], v[184:185]
	v_pk_mul_f32 v[152:153], v[152:153], v[184:185]
	v_pk_mul_f32 v[154:155], v[154:155], v[184:185]
	v_pk_mul_f32 v[156:157], v[156:157], v[184:185]
	v_pk_mul_f32 v[158:159], v[158:159], v[184:185]
	v_pk_mul_f32 v[144:145], v[144:145], v[236:237]
	v_pk_mul_f32 v[146:147], v[146:147], v[238:239]
	v_pk_mul_f32 v[148:149], v[148:149], v[240:241]
	v_pk_mul_f32 v[150:151], v[150:151], v[242:243]
	v_pk_mul_f32 v[152:153], v[152:153], v[244:245]
	v_pk_mul_f32 v[154:155], v[154:155], v[246:247]
	v_pk_mul_f32 v[156:157], v[156:157], v[248:249]
	v_pk_mul_f32 v[158:159], v[158:159], v[250:251]
	v_add_u32_e32 v181, 0x0, v178
	global_store_dwordx4 v181, v[144:147], s[76:77]
	global_store_dwordx4 v181, v[148:151], s[76:77] offset:16
	global_store_dwordx4 v181, v[152:155], s[76:77] offset:2048
	global_store_dwordx4 v181, v[156:159], s[76:77] offset:2064
	s_nop 1
	s_waitcnt vmcnt(24)
	v_lshlrev_b32_e32 v144, 16, v16
	v_and_b32_e32 v145, 0xffff0000, v16
	v_lshlrev_b32_e32 v146, 16, v17
	v_and_b32_e32 v147, 0xffff0000, v17
	v_lshlrev_b32_e32 v148, 16, v18
	v_and_b32_e32 v149, 0xffff0000, v18
	v_lshlrev_b32_e32 v150, 16, v19
	v_and_b32_e32 v151, 0xffff0000, v19
	v_lshlrev_b32_e32 v152, 16, v20
	v_and_b32_e32 v153, 0xffff0000, v20
	v_lshlrev_b32_e32 v154, 16, v21
	v_and_b32_e32 v155, 0xffff0000, v21
	v_lshlrev_b32_e32 v156, 16, v22
	v_and_b32_e32 v157, 0xffff0000, v22
	v_lshlrev_b32_e32 v158, 16, v23
	v_and_b32_e32 v159, 0xffff0000, v23
	v_lshlrev_b32_e32 v160, 16, v24
	v_and_b32_e32 v161, 0xffff0000, v24
	v_lshlrev_b32_e32 v162, 16, v25
	v_and_b32_e32 v163, 0xffff0000, v25
	v_lshlrev_b32_e32 v164, 16, v26
	v_and_b32_e32 v165, 0xffff0000, v26
	v_lshlrev_b32_e32 v166, 16, v27
	v_and_b32_e32 v167, 0xffff0000, v27
	v_lshlrev_b32_e32 v168, 16, v28
	v_and_b32_e32 v169, 0xffff0000, v28
	v_lshlrev_b32_e32 v170, 16, v29
	v_and_b32_e32 v171, 0xffff0000, v29
	v_lshlrev_b32_e32 v172, 16, v30
	v_and_b32_e32 v173, 0xffff0000, v30
	v_lshlrev_b32_e32 v174, 16, v31
	v_and_b32_e32 v175, 0xffff0000, v31
	v_pk_mul_f32 v[252:253], v[160:161], v[160:161]
	v_pk_mul_f32 v[254:255], v[162:163], v[162:163]
	v_pk_fma_f32 v[252:253], v[164:165], v[164:165], v[252:253]
	v_pk_fma_f32 v[254:255], v[166:167], v[166:167], v[254:255]
	v_pk_fma_f32 v[252:253], v[168:169], v[168:169], v[252:253]
	v_pk_fma_f32 v[254:255], v[170:171], v[170:171], v[254:255]
	v_pk_fma_f32 v[252:253], v[172:173], v[172:173], v[252:253]
	v_pk_fma_f32 v[254:255], v[174:175], v[174:175], v[254:255]
	v_pk_add_f32 v[252:253], v[252:253], v[254:255]
	s_nop 0
	v_add_f32_e32 v183, v252, v253
	s_nop 1
	v_add_f32_dpp v183, v183, v183 quad_perm:[1,0,3,2] row_mask:0xf bank_mask:0xf bound_ctrl:1
	s_nop 1
	v_add_f32_dpp v183, v183, v183 quad_perm:[2,3,0,1] row_mask:0xf bank_mask:0xf bound_ctrl:1
	s_nop 1
	v_add_f32_dpp v183, v183, v183 row_half_mirror row_mask:0xf bank_mask:0xf bound_ctrl:1
	s_nop 1
	v_add_f32_dpp v183, v183, v183 row_mirror row_mask:0xf bank_mask:0xf bound_ctrl:1
	s_nop 1
	v_readlane_b32 s98, v183, 0
	v_readlane_b32 s99, v183, 16
	v_readlane_b32 s100, v183, 32
	v_readlane_b32 s101, v183, 48
	s_nop 1
	v_mov_b32_e32 v183, s98
	v_add_f32_e32 v183, s99, v183
	v_add_f32_e32 v183, s100, v183
	v_add_f32_e32 v183, s101, v183
	v_fmamk_f32 v183, v183, 0x3a800000, v182
	v_cmp_gt_f32_e32 vcc, 0x800000, v183
	v_mul_f32_e32 v181, 0x4b800000, v183
	s_nop 1
	v_cndmask_b32_e32 v183, v183, v181, vcc
	v_rsq_f32_e32 v183, v183
	s_nop 0
	v_mul_f32_e32 v181, 0x45800000, v183
	v_cndmask_b32_e32 v184, v183, v181, vcc
	v_mov_b32_e32 v185, v184
	v_pk_mul_f32 v[160:161], v[160:161], v[184:185]
	v_pk_mul_f32 v[162:163], v[162:163], v[184:185]
	v_pk_mul_f32 v[164:165], v[164:165], v[184:185]
	v_pk_mul_f32 v[166:167], v[166:167], v[184:185]
	v_pk_mul_f32 v[168:169], v[168:169], v[184:185]
	v_pk_mul_f32 v[170:171], v[170:171], v[184:185]
	v_pk_mul_f32 v[172:173], v[172:173], v[184:185]
	v_pk_mul_f32 v[174:175], v[174:175], v[184:185]
	v_pk_fma_f32 v[144:145], v[160:161], v[128:129], v[144:145]
	v_pk_fma_f32 v[146:147], v[162:163], v[130:131], v[146:147]
	v_pk_fma_f32 v[148:149], v[164:165], v[132:133], v[148:149]
	v_pk_fma_f32 v[150:151], v[166:167], v[134:135], v[150:151]
	v_pk_fma_f32 v[152:153], v[168:169], v[136:137], v[152:153]
	v_pk_fma_f32 v[154:155], v[170:171], v[138:139], v[154:155]
	v_pk_fma_f32 v[156:157], v[172:173], v[140:141], v[156:157]
	v_pk_fma_f32 v[158:159], v[174:175], v[142:143], v[158:159]
	v_pk_mul_f32 v[252:253], v[144:145], v[144:145]
	v_pk_mul_f32 v[254:255], v[146:147], v[146:147]
	v_pk_fma_f32 v[252:253], v[148:149], v[148:149], v[252:253]
	v_pk_fma_f32 v[254:255], v[150:151], v[150:151], v[254:255]
	v_pk_fma_f32 v[252:253], v[152:153], v[152:153], v[252:253]
	v_pk_fma_f32 v[254:255], v[154:155], v[154:155], v[254:255]
	v_pk_fma_f32 v[252:253], v[156:157], v[156:157], v[252:253]
	v_pk_fma_f32 v[254:255], v[158:159], v[158:159], v[254:255]
	v_pk_add_f32 v[252:253], v[252:253], v[254:255]
	s_nop 0
	v_add_f32_e32 v183, v252, v253
	s_nop 1
	v_add_f32_dpp v183, v183, v183 quad_perm:[1,0,3,2] row_mask:0xf bank_mask:0xf bound_ctrl:1
	s_nop 1
	v_add_f32_dpp v183, v183, v183 quad_perm:[2,3,0,1] row_mask:0xf bank_mask:0xf bound_ctrl:1
	s_nop 1
	v_add_f32_dpp v183, v183, v183 row_half_mirror row_mask:0xf bank_mask:0xf bound_ctrl:1
	s_nop 1
	v_add_f32_dpp v183, v183, v183 row_mirror row_mask:0xf bank_mask:0xf bound_ctrl:1
	s_nop 1
	v_readlane_b32 s98, v183, 0
	v_readlane_b32 s99, v183, 16
	v_readlane_b32 s100, v183, 32
	v_readlane_b32 s101, v183, 48
	s_nop 1
	v_mov_b32_e32 v183, s98
	v_add_f32_e32 v183, s99, v183
	v_add_f32_e32 v183, s100, v183
	v_add_f32_e32 v183, s101, v183
	v_fmamk_f32 v183, v183, 0x3a800000, v182
	v_cmp_gt_f32_e32 vcc, 0x800000, v183
	v_mul_f32_e32 v181, 0x4b800000, v183
	s_nop 1
	v_cndmask_b32_e32 v183, v183, v181, vcc
	v_rsq_f32_e32 v183, v183
	s_nop 0
	v_mul_f32_e32 v181, 0x45800000, v183
	v_cndmask_b32_e32 v184, v183, v181, vcc
	v_mov_b32_e32 v185, v184
	v_pk_mul_f32 v[144:145], v[144:145], v[184:185]
	v_pk_mul_f32 v[146:147], v[146:147], v[184:185]
	v_pk_mul_f32 v[148:149], v[148:149], v[184:185]
	v_pk_mul_f32 v[150:151], v[150:151], v[184:185]
	v_pk_mul_f32 v[152:153], v[152:153], v[184:185]
	v_pk_mul_f32 v[154:155], v[154:155], v[184:185]
	v_pk_mul_f32 v[156:157], v[156:157], v[184:185]
	v_pk_mul_f32 v[158:159], v[158:159], v[184:185]
	v_pk_mul_f32 v[144:145], v[144:145], v[236:237]
	v_pk_mul_f32 v[146:147], v[146:147], v[238:239]
	v_pk_mul_f32 v[148:149], v[148:149], v[240:241]
	v_pk_mul_f32 v[150:151], v[150:151], v[242:243]
	v_pk_mul_f32 v[152:153], v[152:153], v[244:245]
	v_pk_mul_f32 v[154:155], v[154:155], v[246:247]
	v_pk_mul_f32 v[156:157], v[156:157], v[248:249]
	v_pk_mul_f32 v[158:159], v[158:159], v[250:251]
	v_add_u32_e32 v181, 0x800000, v178
	global_store_dwordx4 v181, v[144:147], s[76:77]
	global_store_dwordx4 v181, v[148:151], s[76:77] offset:16
	global_store_dwordx4 v181, v[152:155], s[76:77] offset:2048
	global_store_dwordx4 v181, v[156:159], s[76:77] offset:2064
	s_nop 1
	s_waitcnt vmcnt(20)
	v_lshlrev_b32_e32 v144, 16, v32
	v_and_b32_e32 v145, 0xffff0000, v32
	v_lshlrev_b32_e32 v146, 16, v33
	v_and_b32_e32 v147, 0xffff0000, v33
	v_lshlrev_b32_e32 v148, 16, v34
	v_and_b32_e32 v149, 0xffff0000, v34
	v_lshlrev_b32_e32 v150, 16, v35
	v_and_b32_e32 v151, 0xffff0000, v35
	v_lshlrev_b32_e32 v152, 16, v36
	v_and_b32_e32 v153, 0xffff0000, v36
	v_lshlrev_b32_e32 v154, 16, v37
	v_and_b32_e32 v155, 0xffff0000, v37
	v_lshlrev_b32_e32 v156, 16, v38
	v_and_b32_e32 v157, 0xffff0000, v38
	v_lshlrev_b32_e32 v158, 16, v39
	v_and_b32_e32 v159, 0xffff0000, v39
	v_lshlrev_b32_e32 v160, 16, v40
	v_and_b32_e32 v161, 0xffff0000, v40
	v_lshlrev_b32_e32 v162, 16, v41
	v_and_b32_e32 v163, 0xffff0000, v41
	v_lshlrev_b32_e32 v164, 16, v42
	v_and_b32_e32 v165, 0xffff0000, v42
	v_lshlrev_b32_e32 v166, 16, v43
	v_and_b32_e32 v167, 0xffff0000, v43
	v_lshlrev_b32_e32 v168, 16, v44
	v_and_b32_e32 v169, 0xffff0000, v44
	v_lshlrev_b32_e32 v170, 16, v45
	v_and_b32_e32 v171, 0xffff0000, v45
	v_lshlrev_b32_e32 v172, 16, v46
	v_and_b32_e32 v173, 0xffff0000, v46
	v_lshlrev_b32_e32 v174, 16, v47
	v_and_b32_e32 v175, 0xffff0000, v47
	v_pk_mul_f32 v[252:253], v[160:161], v[160:161]
	v_pk_mul_f32 v[254:255], v[162:163], v[162:163]
	v_pk_fma_f32 v[252:253], v[164:165], v[164:165], v[252:253]
	v_pk_fma_f32 v[254:255], v[166:167], v[166:167], v[254:255]
	v_pk_fma_f32 v[252:253], v[168:169], v[168:169], v[252:253]
	v_pk_fma_f32 v[254:255], v[170:171], v[170:171], v[254:255]
	v_pk_fma_f32 v[252:253], v[172:173], v[172:173], v[252:253]
	v_pk_fma_f32 v[254:255], v[174:175], v[174:175], v[254:255]
	v_pk_add_f32 v[252:253], v[252:253], v[254:255]
	s_nop 0
	v_add_f32_e32 v183, v252, v253
	s_nop 1
	v_add_f32_dpp v183, v183, v183 quad_perm:[1,0,3,2] row_mask:0xf bank_mask:0xf bound_ctrl:1
	s_nop 1
	v_add_f32_dpp v183, v183, v183 quad_perm:[2,3,0,1] row_mask:0xf bank_mask:0xf bound_ctrl:1
	s_nop 1
	v_add_f32_dpp v183, v183, v183 row_half_mirror row_mask:0xf bank_mask:0xf bound_ctrl:1
	s_nop 1
	v_add_f32_dpp v183, v183, v183 row_mirror row_mask:0xf bank_mask:0xf bound_ctrl:1
	s_nop 1
	v_readlane_b32 s98, v183, 0
	v_readlane_b32 s99, v183, 16
	v_readlane_b32 s100, v183, 32
	v_readlane_b32 s101, v183, 48
	s_nop 1
	v_mov_b32_e32 v183, s98
	v_add_f32_e32 v183, s99, v183
	v_add_f32_e32 v183, s100, v183
	v_add_f32_e32 v183, s101, v183
	v_fmamk_f32 v183, v183, 0x3a800000, v182
	v_cmp_gt_f32_e32 vcc, 0x800000, v183
	v_mul_f32_e32 v181, 0x4b800000, v183
	s_nop 1
	v_cndmask_b32_e32 v183, v183, v181, vcc
	v_rsq_f32_e32 v183, v183
	s_nop 0
	v_mul_f32_e32 v181, 0x45800000, v183
	v_cndmask_b32_e32 v184, v183, v181, vcc
	v_mov_b32_e32 v185, v184
	v_pk_mul_f32 v[160:161], v[160:161], v[184:185]
	v_pk_mul_f32 v[162:163], v[162:163], v[184:185]
	v_pk_mul_f32 v[164:165], v[164:165], v[184:185]
	v_pk_mul_f32 v[166:167], v[166:167], v[184:185]
	v_pk_mul_f32 v[168:169], v[168:169], v[184:185]
	v_pk_mul_f32 v[170:171], v[170:171], v[184:185]
	v_pk_mul_f32 v[172:173], v[172:173], v[184:185]
	v_pk_mul_f32 v[174:175], v[174:175], v[184:185]
	v_pk_fma_f32 v[144:145], v[160:161], v[128:129], v[144:145]
	v_pk_fma_f32 v[146:147], v[162:163], v[130:131], v[146:147]
	v_pk_fma_f32 v[148:149], v[164:165], v[132:133], v[148:149]
	v_pk_fma_f32 v[150:151], v[166:167], v[134:135], v[150:151]
	v_pk_fma_f32 v[152:153], v[168:169], v[136:137], v[152:153]
	v_pk_fma_f32 v[154:155], v[170:171], v[138:139], v[154:155]
	v_pk_fma_f32 v[156:157], v[172:173], v[140:141], v[156:157]
	v_pk_fma_f32 v[158:159], v[174:175], v[142:143], v[158:159]
	v_pk_mul_f32 v[252:253], v[144:145], v[144:145]
	v_pk_mul_f32 v[254:255], v[146:147], v[146:147]
	v_pk_fma_f32 v[252:253], v[148:149], v[148:149], v[252:253]
	v_pk_fma_f32 v[254:255], v[150:151], v[150:151], v[254:255]
	v_pk_fma_f32 v[252:253], v[152:153], v[152:153], v[252:253]
	v_pk_fma_f32 v[254:255], v[154:155], v[154:155], v[254:255]
	v_pk_fma_f32 v[252:253], v[156:157], v[156:157], v[252:253]
	v_pk_fma_f32 v[254:255], v[158:159], v[158:159], v[254:255]
	v_pk_add_f32 v[252:253], v[252:253], v[254:255]
	s_nop 0
	v_add_f32_e32 v183, v252, v253
	s_nop 1
	v_add_f32_dpp v183, v183, v183 quad_perm:[1,0,3,2] row_mask:0xf bank_mask:0xf bound_ctrl:1
	s_nop 1
	v_add_f32_dpp v183, v183, v183 quad_perm:[2,3,0,1] row_mask:0xf bank_mask:0xf bound_ctrl:1
	s_nop 1
	v_add_f32_dpp v183, v183, v183 row_half_mirror row_mask:0xf bank_mask:0xf bound_ctrl:1
	s_nop 1
	v_add_f32_dpp v183, v183, v183 row_mirror row_mask:0xf bank_mask:0xf bound_ctrl:1
	s_nop 1
	v_readlane_b32 s98, v183, 0
	v_readlane_b32 s99, v183, 16
	v_readlane_b32 s100, v183, 32
	v_readlane_b32 s101, v183, 48
	s_nop 1
	v_mov_b32_e32 v183, s98
	v_add_f32_e32 v183, s99, v183
	v_add_f32_e32 v183, s100, v183
	v_add_f32_e32 v183, s101, v183
	v_fmamk_f32 v183, v183, 0x3a800000, v182
	v_cmp_gt_f32_e32 vcc, 0x800000, v183
	v_mul_f32_e32 v181, 0x4b800000, v183
	s_nop 1
	v_cndmask_b32_e32 v183, v183, v181, vcc
	v_rsq_f32_e32 v183, v183
	s_nop 0
	v_mul_f32_e32 v181, 0x45800000, v183
	v_cndmask_b32_e32 v184, v183, v181, vcc
	v_mov_b32_e32 v185, v184
	v_pk_mul_f32 v[144:145], v[144:145], v[184:185]
	v_pk_mul_f32 v[146:147], v[146:147], v[184:185]
	v_pk_mul_f32 v[148:149], v[148:149], v[184:185]
	v_pk_mul_f32 v[150:151], v[150:151], v[184:185]
	v_pk_mul_f32 v[152:153], v[152:153], v[184:185]
	v_pk_mul_f32 v[154:155], v[154:155], v[184:185]
	v_pk_mul_f32 v[156:157], v[156:157], v[184:185]
	v_pk_mul_f32 v[158:159], v[158:159], v[184:185]
	v_pk_mul_f32 v[144:145], v[144:145], v[236:237]
	v_pk_mul_f32 v[146:147], v[146:147], v[238:239]
	v_pk_mul_f32 v[148:149], v[148:149], v[240:241]
	v_pk_mul_f32 v[150:151], v[150:151], v[242:243]
	v_pk_mul_f32 v[152:153], v[152:153], v[244:245]
	v_pk_mul_f32 v[154:155], v[154:155], v[246:247]
	v_pk_mul_f32 v[156:157], v[156:157], v[248:249]
	v_pk_mul_f32 v[158:159], v[158:159], v[250:251]
	v_add_u32_e32 v181, 0x1000000, v178
	global_store_dwordx4 v181, v[144:147], s[76:77]
	global_store_dwordx4 v181, v[148:151], s[76:77] offset:16
	global_store_dwordx4 v181, v[152:155], s[76:77] offset:2048
	global_store_dwordx4 v181, v[156:159], s[76:77] offset:2064
	s_nop 1
	s_waitcnt vmcnt(16)
	v_lshlrev_b32_e32 v144, 16, v48
	v_and_b32_e32 v145, 0xffff0000, v48
	v_lshlrev_b32_e32 v146, 16, v49
	v_and_b32_e32 v147, 0xffff0000, v49
	v_lshlrev_b32_e32 v148, 16, v50
	v_and_b32_e32 v149, 0xffff0000, v50
	v_lshlrev_b32_e32 v150, 16, v51
	v_and_b32_e32 v151, 0xffff0000, v51
	v_lshlrev_b32_e32 v152, 16, v52
	v_and_b32_e32 v153, 0xffff0000, v52
	v_lshlrev_b32_e32 v154, 16, v53
	v_and_b32_e32 v155, 0xffff0000, v53
	v_lshlrev_b32_e32 v156, 16, v54
	v_and_b32_e32 v157, 0xffff0000, v54
	v_lshlrev_b32_e32 v158, 16, v55
	v_and_b32_e32 v159, 0xffff0000, v55
	v_lshlrev_b32_e32 v160, 16, v56
	v_and_b32_e32 v161, 0xffff0000, v56
	v_lshlrev_b32_e32 v162, 16, v57
	v_and_b32_e32 v163, 0xffff0000, v57
	v_lshlrev_b32_e32 v164, 16, v58
	v_and_b32_e32 v165, 0xffff0000, v58
	v_lshlrev_b32_e32 v166, 16, v59
	v_and_b32_e32 v167, 0xffff0000, v59
	v_lshlrev_b32_e32 v168, 16, v60
	v_and_b32_e32 v169, 0xffff0000, v60
	v_lshlrev_b32_e32 v170, 16, v61
	v_and_b32_e32 v171, 0xffff0000, v61
	v_lshlrev_b32_e32 v172, 16, v62
	v_and_b32_e32 v173, 0xffff0000, v62
	v_lshlrev_b32_e32 v174, 16, v63
	v_and_b32_e32 v175, 0xffff0000, v63
	v_pk_mul_f32 v[252:253], v[160:161], v[160:161]
	v_pk_mul_f32 v[254:255], v[162:163], v[162:163]
	v_pk_fma_f32 v[252:253], v[164:165], v[164:165], v[252:253]
	v_pk_fma_f32 v[254:255], v[166:167], v[166:167], v[254:255]
	v_pk_fma_f32 v[252:253], v[168:169], v[168:169], v[252:253]
	v_pk_fma_f32 v[254:255], v[170:171], v[170:171], v[254:255]
	v_pk_fma_f32 v[252:253], v[172:173], v[172:173], v[252:253]
	v_pk_fma_f32 v[254:255], v[174:175], v[174:175], v[254:255]
	v_pk_add_f32 v[252:253], v[252:253], v[254:255]
	s_nop 0
	v_add_f32_e32 v183, v252, v253
	s_nop 1
	v_add_f32_dpp v183, v183, v183 quad_perm:[1,0,3,2] row_mask:0xf bank_mask:0xf bound_ctrl:1
	s_nop 1
	v_add_f32_dpp v183, v183, v183 quad_perm:[2,3,0,1] row_mask:0xf bank_mask:0xf bound_ctrl:1
	s_nop 1
	v_add_f32_dpp v183, v183, v183 row_half_mirror row_mask:0xf bank_mask:0xf bound_ctrl:1
	s_nop 1
	v_add_f32_dpp v183, v183, v183 row_mirror row_mask:0xf bank_mask:0xf bound_ctrl:1
	s_nop 1
	v_readlane_b32 s98, v183, 0
	v_readlane_b32 s99, v183, 16
	v_readlane_b32 s100, v183, 32
	v_readlane_b32 s101, v183, 48
	s_nop 1
	v_mov_b32_e32 v183, s98
	v_add_f32_e32 v183, s99, v183
	v_add_f32_e32 v183, s100, v183
	v_add_f32_e32 v183, s101, v183
	v_fmamk_f32 v183, v183, 0x3a800000, v182
	v_cmp_gt_f32_e32 vcc, 0x800000, v183
	v_mul_f32_e32 v181, 0x4b800000, v183
	s_nop 1
	v_cndmask_b32_e32 v183, v183, v181, vcc
	v_rsq_f32_e32 v183, v183
	s_nop 0
	v_mul_f32_e32 v181, 0x45800000, v183
	v_cndmask_b32_e32 v184, v183, v181, vcc
	v_mov_b32_e32 v185, v184
	v_pk_mul_f32 v[160:161], v[160:161], v[184:185]
	v_pk_mul_f32 v[162:163], v[162:163], v[184:185]
	v_pk_mul_f32 v[164:165], v[164:165], v[184:185]
	v_pk_mul_f32 v[166:167], v[166:167], v[184:185]
	v_pk_mul_f32 v[168:169], v[168:169], v[184:185]
	v_pk_mul_f32 v[170:171], v[170:171], v[184:185]
	v_pk_mul_f32 v[172:173], v[172:173], v[184:185]
	v_pk_mul_f32 v[174:175], v[174:175], v[184:185]
	v_pk_fma_f32 v[144:145], v[160:161], v[128:129], v[144:145]
	v_pk_fma_f32 v[146:147], v[162:163], v[130:131], v[146:147]
	v_pk_fma_f32 v[148:149], v[164:165], v[132:133], v[148:149]
	v_pk_fma_f32 v[150:151], v[166:167], v[134:135], v[150:151]
	v_pk_fma_f32 v[152:153], v[168:169], v[136:137], v[152:153]
	v_pk_fma_f32 v[154:155], v[170:171], v[138:139], v[154:155]
	v_pk_fma_f32 v[156:157], v[172:173], v[140:141], v[156:157]
	v_pk_fma_f32 v[158:159], v[174:175], v[142:143], v[158:159]
	v_pk_mul_f32 v[252:253], v[144:145], v[144:145]
	v_pk_mul_f32 v[254:255], v[146:147], v[146:147]
	v_pk_fma_f32 v[252:253], v[148:149], v[148:149], v[252:253]
	v_pk_fma_f32 v[254:255], v[150:151], v[150:151], v[254:255]
	v_pk_fma_f32 v[252:253], v[152:153], v[152:153], v[252:253]
	v_pk_fma_f32 v[254:255], v[154:155], v[154:155], v[254:255]
	v_pk_fma_f32 v[252:253], v[156:157], v[156:157], v[252:253]
	v_pk_fma_f32 v[254:255], v[158:159], v[158:159], v[254:255]
	v_pk_add_f32 v[252:253], v[252:253], v[254:255]
	s_nop 0
	v_add_f32_e32 v183, v252, v253
	s_nop 1
	v_add_f32_dpp v183, v183, v183 quad_perm:[1,0,3,2] row_mask:0xf bank_mask:0xf bound_ctrl:1
	s_nop 1
	v_add_f32_dpp v183, v183, v183 quad_perm:[2,3,0,1] row_mask:0xf bank_mask:0xf bound_ctrl:1
	s_nop 1
	v_add_f32_dpp v183, v183, v183 row_half_mirror row_mask:0xf bank_mask:0xf bound_ctrl:1
	s_nop 1
	v_add_f32_dpp v183, v183, v183 row_mirror row_mask:0xf bank_mask:0xf bound_ctrl:1
	s_nop 1
	v_readlane_b32 s98, v183, 0
	v_readlane_b32 s99, v183, 16
	v_readlane_b32 s100, v183, 32
	v_readlane_b32 s101, v183, 48
	s_nop 1
	v_mov_b32_e32 v183, s98
	v_add_f32_e32 v183, s99, v183
	v_add_f32_e32 v183, s100, v183
	v_add_f32_e32 v183, s101, v183
	v_fmamk_f32 v183, v183, 0x3a800000, v182
	v_cmp_gt_f32_e32 vcc, 0x800000, v183
	v_mul_f32_e32 v181, 0x4b800000, v183
	s_nop 1
	v_cndmask_b32_e32 v183, v183, v181, vcc
	v_rsq_f32_e32 v183, v183
	s_nop 0
	v_mul_f32_e32 v181, 0x45800000, v183
	v_cndmask_b32_e32 v184, v183, v181, vcc
	v_mov_b32_e32 v185, v184
	v_pk_mul_f32 v[144:145], v[144:145], v[184:185]
	v_pk_mul_f32 v[146:147], v[146:147], v[184:185]
	v_pk_mul_f32 v[148:149], v[148:149], v[184:185]
	v_pk_mul_f32 v[150:151], v[150:151], v[184:185]
	v_pk_mul_f32 v[152:153], v[152:153], v[184:185]
	v_pk_mul_f32 v[154:155], v[154:155], v[184:185]
	v_pk_mul_f32 v[156:157], v[156:157], v[184:185]
	v_pk_mul_f32 v[158:159], v[158:159], v[184:185]
	v_pk_mul_f32 v[144:145], v[144:145], v[236:237]
	v_pk_mul_f32 v[146:147], v[146:147], v[238:239]
	v_pk_mul_f32 v[148:149], v[148:149], v[240:241]
	v_pk_mul_f32 v[150:151], v[150:151], v[242:243]
	v_pk_mul_f32 v[152:153], v[152:153], v[244:245]
	v_pk_mul_f32 v[154:155], v[154:155], v[246:247]
	v_pk_mul_f32 v[156:157], v[156:157], v[248:249]
	v_pk_mul_f32 v[158:159], v[158:159], v[250:251]
	v_add_u32_e32 v181, 0x1800000, v178
	global_store_dwordx4 v181, v[144:147], s[76:77]
	global_store_dwordx4 v181, v[148:151], s[76:77] offset:16
	global_store_dwordx4 v181, v[152:155], s[76:77] offset:2048
	global_store_dwordx4 v181, v[156:159], s[76:77] offset:2064
	s_nop 1
	s_waitcnt vmcnt(12)
	v_lshlrev_b32_e32 v144, 16, v64
	v_and_b32_e32 v145, 0xffff0000, v64
	v_lshlrev_b32_e32 v146, 16, v65
	v_and_b32_e32 v147, 0xffff0000, v65
	v_lshlrev_b32_e32 v148, 16, v66
	v_and_b32_e32 v149, 0xffff0000, v66
	v_lshlrev_b32_e32 v150, 16, v67
	v_and_b32_e32 v151, 0xffff0000, v67
	v_lshlrev_b32_e32 v152, 16, v68
	v_and_b32_e32 v153, 0xffff0000, v68
	v_lshlrev_b32_e32 v154, 16, v69
	v_and_b32_e32 v155, 0xffff0000, v69
	v_lshlrev_b32_e32 v156, 16, v70
	v_and_b32_e32 v157, 0xffff0000, v70
	v_lshlrev_b32_e32 v158, 16, v71
	v_and_b32_e32 v159, 0xffff0000, v71
	v_lshlrev_b32_e32 v160, 16, v72
	v_and_b32_e32 v161, 0xffff0000, v72
	v_lshlrev_b32_e32 v162, 16, v73
	v_and_b32_e32 v163, 0xffff0000, v73
	v_lshlrev_b32_e32 v164, 16, v74
	v_and_b32_e32 v165, 0xffff0000, v74
	v_lshlrev_b32_e32 v166, 16, v75
	v_and_b32_e32 v167, 0xffff0000, v75
	v_lshlrev_b32_e32 v168, 16, v76
	v_and_b32_e32 v169, 0xffff0000, v76
	v_lshlrev_b32_e32 v170, 16, v77
	v_and_b32_e32 v171, 0xffff0000, v77
	v_lshlrev_b32_e32 v172, 16, v78
	v_and_b32_e32 v173, 0xffff0000, v78
	v_lshlrev_b32_e32 v174, 16, v79
	v_and_b32_e32 v175, 0xffff0000, v79
	v_pk_mul_f32 v[252:253], v[160:161], v[160:161]
	v_pk_mul_f32 v[254:255], v[162:163], v[162:163]
	v_pk_fma_f32 v[252:253], v[164:165], v[164:165], v[252:253]
	v_pk_fma_f32 v[254:255], v[166:167], v[166:167], v[254:255]
	v_pk_fma_f32 v[252:253], v[168:169], v[168:169], v[252:253]
	v_pk_fma_f32 v[254:255], v[170:171], v[170:171], v[254:255]
	v_pk_fma_f32 v[252:253], v[172:173], v[172:173], v[252:253]
	v_pk_fma_f32 v[254:255], v[174:175], v[174:175], v[254:255]
	v_pk_add_f32 v[252:253], v[252:253], v[254:255]
	s_nop 0
	v_add_f32_e32 v183, v252, v253
	s_nop 1
	v_add_f32_dpp v183, v183, v183 quad_perm:[1,0,3,2] row_mask:0xf bank_mask:0xf bound_ctrl:1
	s_nop 1
	v_add_f32_dpp v183, v183, v183 quad_perm:[2,3,0,1] row_mask:0xf bank_mask:0xf bound_ctrl:1
	s_nop 1
	v_add_f32_dpp v183, v183, v183 row_half_mirror row_mask:0xf bank_mask:0xf bound_ctrl:1
	s_nop 1
	v_add_f32_dpp v183, v183, v183 row_mirror row_mask:0xf bank_mask:0xf bound_ctrl:1
	s_nop 1
	v_readlane_b32 s98, v183, 0
	v_readlane_b32 s99, v183, 16
	v_readlane_b32 s100, v183, 32
	v_readlane_b32 s101, v183, 48
	s_nop 1
	v_mov_b32_e32 v183, s98
	v_add_f32_e32 v183, s99, v183
	v_add_f32_e32 v183, s100, v183
	v_add_f32_e32 v183, s101, v183
	v_fmamk_f32 v183, v183, 0x3a800000, v182
	v_cmp_gt_f32_e32 vcc, 0x800000, v183
	v_mul_f32_e32 v181, 0x4b800000, v183
	s_nop 1
	v_cndmask_b32_e32 v183, v183, v181, vcc
	v_rsq_f32_e32 v183, v183
	s_nop 0
	v_mul_f32_e32 v181, 0x45800000, v183
	v_cndmask_b32_e32 v184, v183, v181, vcc
	v_mov_b32_e32 v185, v184
	v_pk_mul_f32 v[160:161], v[160:161], v[184:185]
	v_pk_mul_f32 v[162:163], v[162:163], v[184:185]
	v_pk_mul_f32 v[164:165], v[164:165], v[184:185]
	v_pk_mul_f32 v[166:167], v[166:167], v[184:185]
	v_pk_mul_f32 v[168:169], v[168:169], v[184:185]
	v_pk_mul_f32 v[170:171], v[170:171], v[184:185]
	v_pk_mul_f32 v[172:173], v[172:173], v[184:185]
	v_pk_mul_f32 v[174:175], v[174:175], v[184:185]
	v_pk_fma_f32 v[144:145], v[160:161], v[128:129], v[144:145]
	v_pk_fma_f32 v[146:147], v[162:163], v[130:131], v[146:147]
	v_pk_fma_f32 v[148:149], v[164:165], v[132:133], v[148:149]
	v_pk_fma_f32 v[150:151], v[166:167], v[134:135], v[150:151]
	v_pk_fma_f32 v[152:153], v[168:169], v[136:137], v[152:153]
	v_pk_fma_f32 v[154:155], v[170:171], v[138:139], v[154:155]
	v_pk_fma_f32 v[156:157], v[172:173], v[140:141], v[156:157]
	v_pk_fma_f32 v[158:159], v[174:175], v[142:143], v[158:159]
	v_pk_mul_f32 v[252:253], v[144:145], v[144:145]
	v_pk_mul_f32 v[254:255], v[146:147], v[146:147]
	v_pk_fma_f32 v[252:253], v[148:149], v[148:149], v[252:253]
	v_pk_fma_f32 v[254:255], v[150:151], v[150:151], v[254:255]
	v_pk_fma_f32 v[252:253], v[152:153], v[152:153], v[252:253]
	v_pk_fma_f32 v[254:255], v[154:155], v[154:155], v[254:255]
	v_pk_fma_f32 v[252:253], v[156:157], v[156:157], v[252:253]
	v_pk_fma_f32 v[254:255], v[158:159], v[158:159], v[254:255]
	v_pk_add_f32 v[252:253], v[252:253], v[254:255]
	s_nop 0
	v_add_f32_e32 v183, v252, v253
	s_nop 1
	v_add_f32_dpp v183, v183, v183 quad_perm:[1,0,3,2] row_mask:0xf bank_mask:0xf bound_ctrl:1
	s_nop 1
	v_add_f32_dpp v183, v183, v183 quad_perm:[2,3,0,1] row_mask:0xf bank_mask:0xf bound_ctrl:1
	s_nop 1
	v_add_f32_dpp v183, v183, v183 row_half_mirror row_mask:0xf bank_mask:0xf bound_ctrl:1
	s_nop 1
	v_add_f32_dpp v183, v183, v183 row_mirror row_mask:0xf bank_mask:0xf bound_ctrl:1
	s_nop 1
	v_readlane_b32 s98, v183, 0
	v_readlane_b32 s99, v183, 16
	v_readlane_b32 s100, v183, 32
	v_readlane_b32 s101, v183, 48
	s_nop 1
	v_mov_b32_e32 v183, s98
	v_add_f32_e32 v183, s99, v183
	v_add_f32_e32 v183, s100, v183
	v_add_f32_e32 v183, s101, v183
	v_fmamk_f32 v183, v183, 0x3a800000, v182
	v_cmp_gt_f32_e32 vcc, 0x800000, v183
	v_mul_f32_e32 v181, 0x4b800000, v183
	s_nop 1
	v_cndmask_b32_e32 v183, v183, v181, vcc
	v_rsq_f32_e32 v183, v183
	s_nop 0
	v_mul_f32_e32 v181, 0x45800000, v183
	v_cndmask_b32_e32 v184, v183, v181, vcc
	v_mov_b32_e32 v185, v184
	v_pk_mul_f32 v[144:145], v[144:145], v[184:185]
	v_pk_mul_f32 v[146:147], v[146:147], v[184:185]
	v_pk_mul_f32 v[148:149], v[148:149], v[184:185]
	v_pk_mul_f32 v[150:151], v[150:151], v[184:185]
	v_pk_mul_f32 v[152:153], v[152:153], v[184:185]
	v_pk_mul_f32 v[154:155], v[154:155], v[184:185]
	v_pk_mul_f32 v[156:157], v[156:157], v[184:185]
	v_pk_mul_f32 v[158:159], v[158:159], v[184:185]
	v_pk_mul_f32 v[144:145], v[144:145], v[236:237]
	v_pk_mul_f32 v[146:147], v[146:147], v[238:239]
	v_pk_mul_f32 v[148:149], v[148:149], v[240:241]
	v_pk_mul_f32 v[150:151], v[150:151], v[242:243]
	v_pk_mul_f32 v[152:153], v[152:153], v[244:245]
	v_pk_mul_f32 v[154:155], v[154:155], v[246:247]
	v_pk_mul_f32 v[156:157], v[156:157], v[248:249]
	v_pk_mul_f32 v[158:159], v[158:159], v[250:251]
	v_add_u32_e32 v181, 0x2000000, v178
	global_store_dwordx4 v181, v[144:147], s[76:77]
	global_store_dwordx4 v181, v[148:151], s[76:77] offset:16
	global_store_dwordx4 v181, v[152:155], s[76:77] offset:2048
	global_store_dwordx4 v181, v[156:159], s[76:77] offset:2064
	s_nop 1
	s_waitcnt vmcnt(8)
	v_lshlrev_b32_e32 v144, 16, v80
	v_and_b32_e32 v145, 0xffff0000, v80
	v_lshlrev_b32_e32 v146, 16, v81
	v_and_b32_e32 v147, 0xffff0000, v81
	v_lshlrev_b32_e32 v148, 16, v82
	v_and_b32_e32 v149, 0xffff0000, v82
	v_lshlrev_b32_e32 v150, 16, v83
	v_and_b32_e32 v151, 0xffff0000, v83
	v_lshlrev_b32_e32 v152, 16, v84
	v_and_b32_e32 v153, 0xffff0000, v84
	v_lshlrev_b32_e32 v154, 16, v85
	v_and_b32_e32 v155, 0xffff0000, v85
	v_lshlrev_b32_e32 v156, 16, v86
	v_and_b32_e32 v157, 0xffff0000, v86
	v_lshlrev_b32_e32 v158, 16, v87
	v_and_b32_e32 v159, 0xffff0000, v87
	v_lshlrev_b32_e32 v160, 16, v88
	v_and_b32_e32 v161, 0xffff0000, v88
	v_lshlrev_b32_e32 v162, 16, v89
	v_and_b32_e32 v163, 0xffff0000, v89
	v_lshlrev_b32_e32 v164, 16, v90
	v_and_b32_e32 v165, 0xffff0000, v90
	v_lshlrev_b32_e32 v166, 16, v91
	v_and_b32_e32 v167, 0xffff0000, v91
	v_lshlrev_b32_e32 v168, 16, v92
	v_and_b32_e32 v169, 0xffff0000, v92
	v_lshlrev_b32_e32 v170, 16, v93
	v_and_b32_e32 v171, 0xffff0000, v93
	v_lshlrev_b32_e32 v172, 16, v94
	v_and_b32_e32 v173, 0xffff0000, v94
	v_lshlrev_b32_e32 v174, 16, v95
	v_and_b32_e32 v175, 0xffff0000, v95
	v_pk_mul_f32 v[252:253], v[160:161], v[160:161]
	v_pk_mul_f32 v[254:255], v[162:163], v[162:163]
	v_pk_fma_f32 v[252:253], v[164:165], v[164:165], v[252:253]
	v_pk_fma_f32 v[254:255], v[166:167], v[166:167], v[254:255]
	v_pk_fma_f32 v[252:253], v[168:169], v[168:169], v[252:253]
	v_pk_fma_f32 v[254:255], v[170:171], v[170:171], v[254:255]
	v_pk_fma_f32 v[252:253], v[172:173], v[172:173], v[252:253]
	v_pk_fma_f32 v[254:255], v[174:175], v[174:175], v[254:255]
	v_pk_add_f32 v[252:253], v[252:253], v[254:255]
	s_nop 0
	v_add_f32_e32 v183, v252, v253
	s_nop 1
	v_add_f32_dpp v183, v183, v183 quad_perm:[1,0,3,2] row_mask:0xf bank_mask:0xf bound_ctrl:1
	s_nop 1
	v_add_f32_dpp v183, v183, v183 quad_perm:[2,3,0,1] row_mask:0xf bank_mask:0xf bound_ctrl:1
	s_nop 1
	v_add_f32_dpp v183, v183, v183 row_half_mirror row_mask:0xf bank_mask:0xf bound_ctrl:1
	s_nop 1
	v_add_f32_dpp v183, v183, v183 row_mirror row_mask:0xf bank_mask:0xf bound_ctrl:1
	s_nop 1
	v_readlane_b32 s98, v183, 0
	v_readlane_b32 s99, v183, 16
	v_readlane_b32 s100, v183, 32
	v_readlane_b32 s101, v183, 48
	s_nop 1
	v_mov_b32_e32 v183, s98
	v_add_f32_e32 v183, s99, v183
	v_add_f32_e32 v183, s100, v183
	v_add_f32_e32 v183, s101, v183
	v_fmamk_f32 v183, v183, 0x3a800000, v182
	v_cmp_gt_f32_e32 vcc, 0x800000, v183
	v_mul_f32_e32 v181, 0x4b800000, v183
	s_nop 1
	v_cndmask_b32_e32 v183, v183, v181, vcc
	v_rsq_f32_e32 v183, v183
	s_nop 0
	v_mul_f32_e32 v181, 0x45800000, v183
	v_cndmask_b32_e32 v184, v183, v181, vcc
	v_mov_b32_e32 v185, v184
	v_pk_mul_f32 v[160:161], v[160:161], v[184:185]
	v_pk_mul_f32 v[162:163], v[162:163], v[184:185]
	v_pk_mul_f32 v[164:165], v[164:165], v[184:185]
	v_pk_mul_f32 v[166:167], v[166:167], v[184:185]
	v_pk_mul_f32 v[168:169], v[168:169], v[184:185]
	v_pk_mul_f32 v[170:171], v[170:171], v[184:185]
	v_pk_mul_f32 v[172:173], v[172:173], v[184:185]
	v_pk_mul_f32 v[174:175], v[174:175], v[184:185]
	v_pk_fma_f32 v[144:145], v[160:161], v[128:129], v[144:145]
	v_pk_fma_f32 v[146:147], v[162:163], v[130:131], v[146:147]
	v_pk_fma_f32 v[148:149], v[164:165], v[132:133], v[148:149]
	v_pk_fma_f32 v[150:151], v[166:167], v[134:135], v[150:151]
	v_pk_fma_f32 v[152:153], v[168:169], v[136:137], v[152:153]
	v_pk_fma_f32 v[154:155], v[170:171], v[138:139], v[154:155]
	v_pk_fma_f32 v[156:157], v[172:173], v[140:141], v[156:157]
	v_pk_fma_f32 v[158:159], v[174:175], v[142:143], v[158:159]
	v_pk_mul_f32 v[252:253], v[144:145], v[144:145]
	v_pk_mul_f32 v[254:255], v[146:147], v[146:147]
	v_pk_fma_f32 v[252:253], v[148:149], v[148:149], v[252:253]
	v_pk_fma_f32 v[254:255], v[150:151], v[150:151], v[254:255]
	v_pk_fma_f32 v[252:253], v[152:153], v[152:153], v[252:253]
	v_pk_fma_f32 v[254:255], v[154:155], v[154:155], v[254:255]
	v_pk_fma_f32 v[252:253], v[156:157], v[156:157], v[252:253]
	v_pk_fma_f32 v[254:255], v[158:159], v[158:159], v[254:255]
	v_pk_add_f32 v[252:253], v[252:253], v[254:255]
	s_nop 0
	v_add_f32_e32 v183, v252, v253
	s_nop 1
	v_add_f32_dpp v183, v183, v183 quad_perm:[1,0,3,2] row_mask:0xf bank_mask:0xf bound_ctrl:1
	s_nop 1
	v_add_f32_dpp v183, v183, v183 quad_perm:[2,3,0,1] row_mask:0xf bank_mask:0xf bound_ctrl:1
	s_nop 1
	v_add_f32_dpp v183, v183, v183 row_half_mirror row_mask:0xf bank_mask:0xf bound_ctrl:1
	s_nop 1
	v_add_f32_dpp v183, v183, v183 row_mirror row_mask:0xf bank_mask:0xf bound_ctrl:1
	s_nop 1
	v_readlane_b32 s98, v183, 0
	v_readlane_b32 s99, v183, 16
	v_readlane_b32 s100, v183, 32
	v_readlane_b32 s101, v183, 48
	s_nop 1
	v_mov_b32_e32 v183, s98
	v_add_f32_e32 v183, s99, v183
	v_add_f32_e32 v183, s100, v183
	v_add_f32_e32 v183, s101, v183
	v_fmamk_f32 v183, v183, 0x3a800000, v182
	v_cmp_gt_f32_e32 vcc, 0x800000, v183
	v_mul_f32_e32 v181, 0x4b800000, v183
	s_nop 1
	v_cndmask_b32_e32 v183, v183, v181, vcc
	v_rsq_f32_e32 v183, v183
	s_nop 0
	v_mul_f32_e32 v181, 0x45800000, v183
	v_cndmask_b32_e32 v184, v183, v181, vcc
	v_mov_b32_e32 v185, v184
	v_pk_mul_f32 v[144:145], v[144:145], v[184:185]
	v_pk_mul_f32 v[146:147], v[146:147], v[184:185]
	v_pk_mul_f32 v[148:149], v[148:149], v[184:185]
	v_pk_mul_f32 v[150:151], v[150:151], v[184:185]
	v_pk_mul_f32 v[152:153], v[152:153], v[184:185]
	v_pk_mul_f32 v[154:155], v[154:155], v[184:185]
	v_pk_mul_f32 v[156:157], v[156:157], v[184:185]
	v_pk_mul_f32 v[158:159], v[158:159], v[184:185]
	v_pk_mul_f32 v[144:145], v[144:145], v[236:237]
	v_pk_mul_f32 v[146:147], v[146:147], v[238:239]
	v_pk_mul_f32 v[148:149], v[148:149], v[240:241]
	v_pk_mul_f32 v[150:151], v[150:151], v[242:243]
	v_pk_mul_f32 v[152:153], v[152:153], v[244:245]
	v_pk_mul_f32 v[154:155], v[154:155], v[246:247]
	v_pk_mul_f32 v[156:157], v[156:157], v[248:249]
	v_pk_mul_f32 v[158:159], v[158:159], v[250:251]
	v_add_u32_e32 v181, 0x2800000, v178
	global_store_dwordx4 v181, v[144:147], s[76:77]
	global_store_dwordx4 v181, v[148:151], s[76:77] offset:16
	global_store_dwordx4 v181, v[152:155], s[76:77] offset:2048
	global_store_dwordx4 v181, v[156:159], s[76:77] offset:2064
	s_nop 1
	s_waitcnt vmcnt(4)
	v_lshlrev_b32_e32 v144, 16, v96
	v_and_b32_e32 v145, 0xffff0000, v96
	v_lshlrev_b32_e32 v146, 16, v97
	v_and_b32_e32 v147, 0xffff0000, v97
	v_lshlrev_b32_e32 v148, 16, v98
	v_and_b32_e32 v149, 0xffff0000, v98
	v_lshlrev_b32_e32 v150, 16, v99
	v_and_b32_e32 v151, 0xffff0000, v99
	v_lshlrev_b32_e32 v152, 16, v100
	v_and_b32_e32 v153, 0xffff0000, v100
	v_lshlrev_b32_e32 v154, 16, v101
	v_and_b32_e32 v155, 0xffff0000, v101
	v_lshlrev_b32_e32 v156, 16, v102
	v_and_b32_e32 v157, 0xffff0000, v102
	v_lshlrev_b32_e32 v158, 16, v103
	v_and_b32_e32 v159, 0xffff0000, v103
	v_lshlrev_b32_e32 v160, 16, v104
	v_and_b32_e32 v161, 0xffff0000, v104
	v_lshlrev_b32_e32 v162, 16, v105
	v_and_b32_e32 v163, 0xffff0000, v105
	v_lshlrev_b32_e32 v164, 16, v106
	v_and_b32_e32 v165, 0xffff0000, v106
	v_lshlrev_b32_e32 v166, 16, v107
	v_and_b32_e32 v167, 0xffff0000, v107
	v_lshlrev_b32_e32 v168, 16, v108
	v_and_b32_e32 v169, 0xffff0000, v108
	v_lshlrev_b32_e32 v170, 16, v109
	v_and_b32_e32 v171, 0xffff0000, v109
	v_lshlrev_b32_e32 v172, 16, v110
	v_and_b32_e32 v173, 0xffff0000, v110
	v_lshlrev_b32_e32 v174, 16, v111
	v_and_b32_e32 v175, 0xffff0000, v111
	v_pk_mul_f32 v[252:253], v[160:161], v[160:161]
	v_pk_mul_f32 v[254:255], v[162:163], v[162:163]
	v_pk_fma_f32 v[252:253], v[164:165], v[164:165], v[252:253]
	v_pk_fma_f32 v[254:255], v[166:167], v[166:167], v[254:255]
	v_pk_fma_f32 v[252:253], v[168:169], v[168:169], v[252:253]
	v_pk_fma_f32 v[254:255], v[170:171], v[170:171], v[254:255]
	v_pk_fma_f32 v[252:253], v[172:173], v[172:173], v[252:253]
	v_pk_fma_f32 v[254:255], v[174:175], v[174:175], v[254:255]
	v_pk_add_f32 v[252:253], v[252:253], v[254:255]
	s_nop 0
	v_add_f32_e32 v183, v252, v253
	s_nop 1
	v_add_f32_dpp v183, v183, v183 quad_perm:[1,0,3,2] row_mask:0xf bank_mask:0xf bound_ctrl:1
	s_nop 1
	v_add_f32_dpp v183, v183, v183 quad_perm:[2,3,0,1] row_mask:0xf bank_mask:0xf bound_ctrl:1
	s_nop 1
	v_add_f32_dpp v183, v183, v183 row_half_mirror row_mask:0xf bank_mask:0xf bound_ctrl:1
	s_nop 1
	v_add_f32_dpp v183, v183, v183 row_mirror row_mask:0xf bank_mask:0xf bound_ctrl:1
	s_nop 1
	v_readlane_b32 s98, v183, 0
	v_readlane_b32 s99, v183, 16
	v_readlane_b32 s100, v183, 32
	v_readlane_b32 s101, v183, 48
	s_nop 1
	v_mov_b32_e32 v183, s98
	v_add_f32_e32 v183, s99, v183
	v_add_f32_e32 v183, s100, v183
	v_add_f32_e32 v183, s101, v183
	v_fmamk_f32 v183, v183, 0x3a800000, v182
	v_cmp_gt_f32_e32 vcc, 0x800000, v183
	v_mul_f32_e32 v181, 0x4b800000, v183
	s_nop 1
	v_cndmask_b32_e32 v183, v183, v181, vcc
	v_rsq_f32_e32 v183, v183
	s_nop 0
	v_mul_f32_e32 v181, 0x45800000, v183
	v_cndmask_b32_e32 v184, v183, v181, vcc
	v_mov_b32_e32 v185, v184
	v_pk_mul_f32 v[160:161], v[160:161], v[184:185]
	v_pk_mul_f32 v[162:163], v[162:163], v[184:185]
	v_pk_mul_f32 v[164:165], v[164:165], v[184:185]
	v_pk_mul_f32 v[166:167], v[166:167], v[184:185]
	v_pk_mul_f32 v[168:169], v[168:169], v[184:185]
	v_pk_mul_f32 v[170:171], v[170:171], v[184:185]
	v_pk_mul_f32 v[172:173], v[172:173], v[184:185]
	v_pk_mul_f32 v[174:175], v[174:175], v[184:185]
	v_pk_fma_f32 v[144:145], v[160:161], v[128:129], v[144:145]
	v_pk_fma_f32 v[146:147], v[162:163], v[130:131], v[146:147]
	v_pk_fma_f32 v[148:149], v[164:165], v[132:133], v[148:149]
	v_pk_fma_f32 v[150:151], v[166:167], v[134:135], v[150:151]
	v_pk_fma_f32 v[152:153], v[168:169], v[136:137], v[152:153]
	v_pk_fma_f32 v[154:155], v[170:171], v[138:139], v[154:155]
	v_pk_fma_f32 v[156:157], v[172:173], v[140:141], v[156:157]
	v_pk_fma_f32 v[158:159], v[174:175], v[142:143], v[158:159]
	v_pk_mul_f32 v[252:253], v[144:145], v[144:145]
	v_pk_mul_f32 v[254:255], v[146:147], v[146:147]
	v_pk_fma_f32 v[252:253], v[148:149], v[148:149], v[252:253]
	v_pk_fma_f32 v[254:255], v[150:151], v[150:151], v[254:255]
	v_pk_fma_f32 v[252:253], v[152:153], v[152:153], v[252:253]
	v_pk_fma_f32 v[254:255], v[154:155], v[154:155], v[254:255]
	v_pk_fma_f32 v[252:253], v[156:157], v[156:157], v[252:253]
	v_pk_fma_f32 v[254:255], v[158:159], v[158:159], v[254:255]
	v_pk_add_f32 v[252:253], v[252:253], v[254:255]
	s_nop 0
	v_add_f32_e32 v183, v252, v253
	s_nop 1
	v_add_f32_dpp v183, v183, v183 quad_perm:[1,0,3,2] row_mask:0xf bank_mask:0xf bound_ctrl:1
	s_nop 1
	v_add_f32_dpp v183, v183, v183 quad_perm:[2,3,0,1] row_mask:0xf bank_mask:0xf bound_ctrl:1
	s_nop 1
	v_add_f32_dpp v183, v183, v183 row_half_mirror row_mask:0xf bank_mask:0xf bound_ctrl:1
	s_nop 1
	v_add_f32_dpp v183, v183, v183 row_mirror row_mask:0xf bank_mask:0xf bound_ctrl:1
	s_nop 1
	v_readlane_b32 s98, v183, 0
	v_readlane_b32 s99, v183, 16
	v_readlane_b32 s100, v183, 32
	v_readlane_b32 s101, v183, 48
	s_nop 1
	v_mov_b32_e32 v183, s98
	v_add_f32_e32 v183, s99, v183
	v_add_f32_e32 v183, s100, v183
	v_add_f32_e32 v183, s101, v183
	v_fmamk_f32 v183, v183, 0x3a800000, v182
	v_cmp_gt_f32_e32 vcc, 0x800000, v183
	v_mul_f32_e32 v181, 0x4b800000, v183
	s_nop 1
	v_cndmask_b32_e32 v183, v183, v181, vcc
	v_rsq_f32_e32 v183, v183
	s_nop 0
	v_mul_f32_e32 v181, 0x45800000, v183
	v_cndmask_b32_e32 v184, v183, v181, vcc
	v_mov_b32_e32 v185, v184
	v_pk_mul_f32 v[144:145], v[144:145], v[184:185]
	v_pk_mul_f32 v[146:147], v[146:147], v[184:185]
	v_pk_mul_f32 v[148:149], v[148:149], v[184:185]
	v_pk_mul_f32 v[150:151], v[150:151], v[184:185]
	v_pk_mul_f32 v[152:153], v[152:153], v[184:185]
	v_pk_mul_f32 v[154:155], v[154:155], v[184:185]
	v_pk_mul_f32 v[156:157], v[156:157], v[184:185]
	v_pk_mul_f32 v[158:159], v[158:159], v[184:185]
	v_pk_mul_f32 v[144:145], v[144:145], v[236:237]
	v_pk_mul_f32 v[146:147], v[146:147], v[238:239]
	v_pk_mul_f32 v[148:149], v[148:149], v[240:241]
	v_pk_mul_f32 v[150:151], v[150:151], v[242:243]
	v_pk_mul_f32 v[152:153], v[152:153], v[244:245]
	v_pk_mul_f32 v[154:155], v[154:155], v[246:247]
	v_pk_mul_f32 v[156:157], v[156:157], v[248:249]
	v_pk_mul_f32 v[158:159], v[158:159], v[250:251]
	v_add_u32_e32 v181, 0x3000000, v178
	global_store_dwordx4 v181, v[144:147], s[76:77]
	global_store_dwordx4 v181, v[148:151], s[76:77] offset:16
	global_store_dwordx4 v181, v[152:155], s[76:77] offset:2048
	global_store_dwordx4 v181, v[156:159], s[76:77] offset:2064
	s_nop 1
	s_waitcnt vmcnt(0)
	v_lshlrev_b32_e32 v144, 16, v112
	v_and_b32_e32 v145, 0xffff0000, v112
	v_lshlrev_b32_e32 v146, 16, v113
	v_and_b32_e32 v147, 0xffff0000, v113
	v_lshlrev_b32_e32 v148, 16, v114
	v_and_b32_e32 v149, 0xffff0000, v114
	v_lshlrev_b32_e32 v150, 16, v115
	v_and_b32_e32 v151, 0xffff0000, v115
	v_lshlrev_b32_e32 v152, 16, v116
	v_and_b32_e32 v153, 0xffff0000, v116
	v_lshlrev_b32_e32 v154, 16, v117
	v_and_b32_e32 v155, 0xffff0000, v117
	v_lshlrev_b32_e32 v156, 16, v118
	v_and_b32_e32 v157, 0xffff0000, v118
	v_lshlrev_b32_e32 v158, 16, v119
	v_and_b32_e32 v159, 0xffff0000, v119
	v_lshlrev_b32_e32 v160, 16, v120
	v_and_b32_e32 v161, 0xffff0000, v120
	v_lshlrev_b32_e32 v162, 16, v121
	v_and_b32_e32 v163, 0xffff0000, v121
	v_lshlrev_b32_e32 v164, 16, v122
	v_and_b32_e32 v165, 0xffff0000, v122
	v_lshlrev_b32_e32 v166, 16, v123
	v_and_b32_e32 v167, 0xffff0000, v123
	v_lshlrev_b32_e32 v168, 16, v124
	v_and_b32_e32 v169, 0xffff0000, v124
	v_lshlrev_b32_e32 v170, 16, v125
	v_and_b32_e32 v171, 0xffff0000, v125
	v_lshlrev_b32_e32 v172, 16, v126
	v_and_b32_e32 v173, 0xffff0000, v126
	v_lshlrev_b32_e32 v174, 16, v127
	v_and_b32_e32 v175, 0xffff0000, v127
	v_pk_mul_f32 v[252:253], v[160:161], v[160:161]
	v_pk_mul_f32 v[254:255], v[162:163], v[162:163]
	v_pk_fma_f32 v[252:253], v[164:165], v[164:165], v[252:253]
	v_pk_fma_f32 v[254:255], v[166:167], v[166:167], v[254:255]
	v_pk_fma_f32 v[252:253], v[168:169], v[168:169], v[252:253]
	v_pk_fma_f32 v[254:255], v[170:171], v[170:171], v[254:255]
	v_pk_fma_f32 v[252:253], v[172:173], v[172:173], v[252:253]
	v_pk_fma_f32 v[254:255], v[174:175], v[174:175], v[254:255]
	v_pk_add_f32 v[252:253], v[252:253], v[254:255]
	s_nop 0
	v_add_f32_e32 v183, v252, v253
	s_nop 1
	v_add_f32_dpp v183, v183, v183 quad_perm:[1,0,3,2] row_mask:0xf bank_mask:0xf bound_ctrl:1
	s_nop 1
	v_add_f32_dpp v183, v183, v183 quad_perm:[2,3,0,1] row_mask:0xf bank_mask:0xf bound_ctrl:1
	s_nop 1
	v_add_f32_dpp v183, v183, v183 row_half_mirror row_mask:0xf bank_mask:0xf bound_ctrl:1
	s_nop 1
	v_add_f32_dpp v183, v183, v183 row_mirror row_mask:0xf bank_mask:0xf bound_ctrl:1
	s_nop 1
	v_readlane_b32 s98, v183, 0
	v_readlane_b32 s99, v183, 16
	v_readlane_b32 s100, v183, 32
	v_readlane_b32 s101, v183, 48
	s_nop 1
	v_mov_b32_e32 v183, s98
	v_add_f32_e32 v183, s99, v183
	v_add_f32_e32 v183, s100, v183
	v_add_f32_e32 v183, s101, v183
	v_fmamk_f32 v183, v183, 0x3a800000, v182
	v_cmp_gt_f32_e32 vcc, 0x800000, v183
	v_mul_f32_e32 v181, 0x4b800000, v183
	s_nop 1
	v_cndmask_b32_e32 v183, v183, v181, vcc
	v_rsq_f32_e32 v183, v183
	s_nop 0
	v_mul_f32_e32 v181, 0x45800000, v183
	v_cndmask_b32_e32 v184, v183, v181, vcc
	v_mov_b32_e32 v185, v184
	v_pk_mul_f32 v[160:161], v[160:161], v[184:185]
	v_pk_mul_f32 v[162:163], v[162:163], v[184:185]
	v_pk_mul_f32 v[164:165], v[164:165], v[184:185]
	v_pk_mul_f32 v[166:167], v[166:167], v[184:185]
	v_pk_mul_f32 v[168:169], v[168:169], v[184:185]
	v_pk_mul_f32 v[170:171], v[170:171], v[184:185]
	v_pk_mul_f32 v[172:173], v[172:173], v[184:185]
	v_pk_mul_f32 v[174:175], v[174:175], v[184:185]
	v_pk_fma_f32 v[144:145], v[160:161], v[128:129], v[144:145]
	v_pk_fma_f32 v[146:147], v[162:163], v[130:131], v[146:147]
	v_pk_fma_f32 v[148:149], v[164:165], v[132:133], v[148:149]
	v_pk_fma_f32 v[150:151], v[166:167], v[134:135], v[150:151]
	v_pk_fma_f32 v[152:153], v[168:169], v[136:137], v[152:153]
	v_pk_fma_f32 v[154:155], v[170:171], v[138:139], v[154:155]
	v_pk_fma_f32 v[156:157], v[172:173], v[140:141], v[156:157]
	v_pk_fma_f32 v[158:159], v[174:175], v[142:143], v[158:159]
	v_pk_mul_f32 v[252:253], v[144:145], v[144:145]
	v_pk_mul_f32 v[254:255], v[146:147], v[146:147]
	v_pk_fma_f32 v[252:253], v[148:149], v[148:149], v[252:253]
	v_pk_fma_f32 v[254:255], v[150:151], v[150:151], v[254:255]
	v_pk_fma_f32 v[252:253], v[152:153], v[152:153], v[252:253]
	v_pk_fma_f32 v[254:255], v[154:155], v[154:155], v[254:255]
	v_pk_fma_f32 v[252:253], v[156:157], v[156:157], v[252:253]
	v_pk_fma_f32 v[254:255], v[158:159], v[158:159], v[254:255]
	v_pk_add_f32 v[252:253], v[252:253], v[254:255]
	s_nop 0
	v_add_f32_e32 v183, v252, v253
	s_nop 1
	v_add_f32_dpp v183, v183, v183 quad_perm:[1,0,3,2] row_mask:0xf bank_mask:0xf bound_ctrl:1
	s_nop 1
	v_add_f32_dpp v183, v183, v183 quad_perm:[2,3,0,1] row_mask:0xf bank_mask:0xf bound_ctrl:1
	s_nop 1
	v_add_f32_dpp v183, v183, v183 row_half_mirror row_mask:0xf bank_mask:0xf bound_ctrl:1
	s_nop 1
	v_add_f32_dpp v183, v183, v183 row_mirror row_mask:0xf bank_mask:0xf bound_ctrl:1
	s_nop 1
	v_readlane_b32 s98, v183, 0
	v_readlane_b32 s99, v183, 16
	v_readlane_b32 s100, v183, 32
	v_readlane_b32 s101, v183, 48
	s_nop 1
	v_mov_b32_e32 v183, s98
	v_add_f32_e32 v183, s99, v183
	v_add_f32_e32 v183, s100, v183
	v_add_f32_e32 v183, s101, v183
	v_fmamk_f32 v183, v183, 0x3a800000, v182
	v_cmp_gt_f32_e32 vcc, 0x800000, v183
	v_mul_f32_e32 v181, 0x4b800000, v183
	s_nop 1
	v_cndmask_b32_e32 v183, v183, v181, vcc
	v_rsq_f32_e32 v183, v183
	s_nop 0
	v_mul_f32_e32 v181, 0x45800000, v183
	v_cndmask_b32_e32 v184, v183, v181, vcc
	v_mov_b32_e32 v185, v184
	v_pk_mul_f32 v[144:145], v[144:145], v[184:185]
	v_pk_mul_f32 v[146:147], v[146:147], v[184:185]
	v_pk_mul_f32 v[148:149], v[148:149], v[184:185]
	v_pk_mul_f32 v[150:151], v[150:151], v[184:185]
	v_pk_mul_f32 v[152:153], v[152:153], v[184:185]
	v_pk_mul_f32 v[154:155], v[154:155], v[184:185]
	v_pk_mul_f32 v[156:157], v[156:157], v[184:185]
	v_pk_mul_f32 v[158:159], v[158:159], v[184:185]
	v_pk_mul_f32 v[144:145], v[144:145], v[236:237]
	v_pk_mul_f32 v[146:147], v[146:147], v[238:239]
	v_pk_mul_f32 v[148:149], v[148:149], v[240:241]
	v_pk_mul_f32 v[150:151], v[150:151], v[242:243]
	v_pk_mul_f32 v[152:153], v[152:153], v[244:245]
	v_pk_mul_f32 v[154:155], v[154:155], v[246:247]
	v_pk_mul_f32 v[156:157], v[156:157], v[248:249]
	v_pk_mul_f32 v[158:159], v[158:159], v[250:251]
	v_add_u32_e32 v181, 0x3800000, v178
	global_store_dwordx4 v181, v[144:147], s[76:77]
	global_store_dwordx4 v181, v[148:151], s[76:77] offset:16
	global_store_dwordx4 v181, v[152:155], s[76:77] offset:2048
	global_store_dwordx4 v181, v[156:159], s[76:77] offset:2064
	s_nop 1
	v_readfirstlane_b32 s98, v179
	s_nop 3
	s_and_b32 s99, s98, 3
	s_cmp_lg_u32 s99, 0
	s_cbranch_scc1 .Lmyxupd_done_7
	v_lshrrev_b32_e32 v179, 2, v179
	v_lshlrev_b32_e32 v177, 4, v176
	v_lshl_add_u32 v177, v179, 11, v177
	v_lshl_add_u32 v178, v179, 12, v180
	v_add_u32_e32 v181, 0x3800000, v177
	global_load_dwordx4 v[194:197], v181, s[78:79]
	global_load_dwordx4 v[198:201], v181, s[78:79] offset:1024
	v_lshl_add_u32 v183, v179, 12, v180
	v_add_u32_e32 v183, 0xbf00000, v183
	v_add_u32_e32 v181, 0x0, v183
	global_load_dwordx4 v[0:3], v181, s[78:79]
	global_load_dwordx4 v[4:7], v181, s[78:79] offset:16
	global_load_dwordx4 v[8:11], v181, s[78:79] offset:2048
	global_load_dwordx4 v[12:15], v181, s[78:79] offset:2064
	v_add_u32_e32 v181, 0x200000, v183
	global_load_dwordx4 v[16:19], v181, s[78:79]
	global_load_dwordx4 v[20:23], v181, s[78:79] offset:16
	global_load_dwordx4 v[24:27], v181, s[78:79] offset:2048
	global_load_dwordx4 v[28:31], v181, s[78:79] offset:2064
	v_add_u32_e32 v181, 0x400000, v183
	global_load_dwordx4 v[32:35], v181, s[78:79]
	global_load_dwordx4 v[36:39], v181, s[78:79] offset:16
	global_load_dwordx4 v[40:43], v181, s[78:79] offset:2048
	global_load_dwordx4 v[44:47], v181, s[78:79] offset:2064
	v_add_u32_e32 v181, 0x600000, v183
	global_load_dwordx4 v[48:51], v181, s[78:79]
	global_load_dwordx4 v[52:55], v181, s[78:79] offset:16
	global_load_dwordx4 v[56:59], v181, s[78:79] offset:2048
	global_load_dwordx4 v[60:63], v181, s[78:79] offset:2064
	v_add_u32_e32 v181, 0x800000, v183
	global_load_dwordx4 v[64:67], v181, s[78:79]
	global_load_dwordx4 v[68:71], v181, s[78:79] offset:16
	global_load_dwordx4 v[72:75], v181, s[78:79] offset:2048
	global_load_dwordx4 v[76:79], v181, s[78:79] offset:2064
	v_add_u32_e32 v181, 0xa00000, v183
	global_load_dwordx4 v[80:83], v181, s[78:79]
	global_load_dwordx4 v[84:87], v181, s[78:79] offset:16
	global_load_dwordx4 v[88:91], v181, s[78:79] offset:2048
	global_load_dwordx4 v[92:95], v181, s[78:79] offset:2064
	v_add_u32_e32 v181, 0xc00000, v183
	global_load_dwordx4 v[96:99], v181, s[78:79]
	global_load_dwordx4 v[100:103], v181, s[78:79] offset:16
	global_load_dwordx4 v[104:107], v181, s[78:79] offset:2048
	global_load_dwordx4 v[108:111], v181, s[78:79] offset:2064
	v_add_u32_e32 v181, 0xe00000, v183
	global_load_dwordx4 v[112:115], v181, s[78:79]
	global_load_dwordx4 v[116:119], v181, s[78:79] offset:16
	global_load_dwordx4 v[120:123], v181, s[78:79] offset:2048
	global_load_dwordx4 v[124:127], v181, s[78:79] offset:2064
	s_waitcnt vmcnt(28)
	v_pk_add_f32 v[160:161], v[0:1], 0 op_sel_hi:[1,0]
	v_pk_add_f32 v[162:163], v[2:3], 0 op_sel_hi:[1,0]
	v_pk_add_f32 v[164:165], v[4:5], 0 op_sel_hi:[1,0]
	v_pk_add_f32 v[166:167], v[6:7], 0 op_sel_hi:[1,0]
	v_pk_add_f32 v[168:169], v[8:9], 0 op_sel_hi:[1,0]
	v_pk_add_f32 v[170:171], v[10:11], 0 op_sel_hi:[1,0]
	v_pk_add_f32 v[172:173], v[12:13], 0 op_sel_hi:[1,0]
	v_pk_add_f32 v[174:175], v[14:15], 0 op_sel_hi:[1,0]
	s_waitcnt vmcnt(24)
	v_pk_add_f32 v[160:161], v[160:161], v[16:17]
	v_pk_add_f32 v[162:163], v[162:163], v[18:19]
	v_pk_add_f32 v[164:165], v[164:165], v[20:21]
	v_pk_add_f32 v[166:167], v[166:167], v[22:23]
	v_pk_add_f32 v[168:169], v[168:169], v[24:25]
	v_pk_add_f32 v[170:171], v[170:171], v[26:27]
	v_pk_add_f32 v[172:173], v[172:173], v[28:29]
	v_pk_add_f32 v[174:175], v[174:175], v[30:31]
	s_waitcnt vmcnt(20)
	v_pk_add_f32 v[160:161], v[160:161], v[32:33]
	v_pk_add_f32 v[162:163], v[162:163], v[34:35]
	v_pk_add_f32 v[164:165], v[164:165], v[36:37]
	v_pk_add_f32 v[166:167], v[166:167], v[38:39]
	v_pk_add_f32 v[168:169], v[168:169], v[40:41]
	v_pk_add_f32 v[170:171], v[170:171], v[42:43]
	v_pk_add_f32 v[172:173], v[172:173], v[44:45]
	v_pk_add_f32 v[174:175], v[174:175], v[46:47]
	v_add_u32_e32 v181, 0x1000000, v183
	global_load_dwordx4 v[0:3], v181, s[78:79]
	global_load_dwordx4 v[4:7], v181, s[78:79] offset:16
	global_load_dwordx4 v[8:11], v181, s[78:79] offset:2048
	global_load_dwordx4 v[12:15], v181, s[78:79] offset:2064
	v_add_u32_e32 v181, 0x1200000, v183
	global_load_dwordx4 v[16:19], v181, s[78:79]
	global_load_dwordx4 v[20:23], v181, s[78:79] offset:16
	global_load_dwordx4 v[24:27], v181, s[78:79] offset:2048
	global_load_dwordx4 v[28:31], v181, s[78:79] offset:2064
	v_add_u32_e32 v181, 0x1400000, v183
	global_load_dwordx4 v[32:35], v181, s[78:79]
	global_load_dwordx4 v[36:39], v181, s[78:79] offset:16
	global_load_dwordx4 v[40:43], v181, s[78:79] offset:2048
	global_load_dwordx4 v[44:47], v181, s[78:79] offset:2064
	s_waitcnt vmcnt(28)
	v_pk_add_f32 v[160:161], v[160:161], v[48:49]
	v_pk_add_f32 v[162:163], v[162:163], v[50:51]
	v_pk_add_f32 v[164:165], v[164:165], v[52:53]
	v_pk_add_f32 v[166:167], v[166:167], v[54:55]
	v_pk_add_f32 v[168:169], v[168:169], v[56:57]
	v_pk_add_f32 v[170:171], v[170:171], v[58:59]
	v_pk_add_f32 v[172:173], v[172:173], v[60:61]
	v_pk_add_f32 v[174:175], v[174:175], v[62:63]
	s_waitcnt vmcnt(24)
	v_pk_add_f32 v[160:161], v[160:161], v[64:65]
	v_pk_add_f32 v[162:163], v[162:163], v[66:67]
	v_pk_add_f32 v[164:165], v[164:165], v[68:69]
	v_pk_add_f32 v[166:167], v[166:167], v[70:71]
	v_pk_add_f32 v[168:169], v[168:169], v[72:73]
	v_pk_add_f32 v[170:171], v[170:171], v[74:75]
	v_pk_add_f32 v[172:173], v[172:173], v[76:77]
	v_pk_add_f32 v[174:175], v[174:175], v[78:79]
	s_waitcnt vmcnt(20)
	v_pk_add_f32 v[160:161], v[160:161], v[80:81]
	v_pk_add_f32 v[162:163], v[162:163], v[82:83]
	v_pk_add_f32 v[164:165], v[164:165], v[84:85]
	v_pk_add_f32 v[166:167], v[166:167], v[86:87]
	v_pk_add_f32 v[168:169], v[168:169], v[88:89]
	v_pk_add_f32 v[170:171], v[170:171], v[90:91]
	v_pk_add_f32 v[172:173], v[172:173], v[92:93]
	v_pk_add_f32 v[174:175], v[174:175], v[94:95]
	s_waitcnt vmcnt(16)
	v_pk_add_f32 v[160:161], v[160:161], v[96:97]
	v_pk_add_f32 v[162:163], v[162:163], v[98:99]
	v_pk_add_f32 v[164:165], v[164:165], v[100:101]
	v_pk_add_f32 v[166:167], v[166:167], v[102:103]
	v_pk_add_f32 v[168:169], v[168:169], v[104:105]
	v_pk_add_f32 v[170:171], v[170:171], v[106:107]
	v_pk_add_f32 v[172:173], v[172:173], v[108:109]
	v_pk_add_f32 v[174:175], v[174:175], v[110:111]
	s_waitcnt vmcnt(12)
	v_pk_add_f32 v[160:161], v[160:161], v[112:113]
	v_pk_add_f32 v[162:163], v[162:163], v[114:115]
	v_pk_add_f32 v[164:165], v[164:165], v[116:117]
	v_pk_add_f32 v[166:167], v[166:167], v[118:119]
	v_pk_add_f32 v[168:169], v[168:169], v[120:121]
	v_pk_add_f32 v[170:171], v[170:171], v[122:123]
	v_pk_add_f32 v[172:173], v[172:173], v[124:125]
	v_pk_add_f32 v[174:175], v[174:175], v[126:127]
	v_lshlrev_b32_e32 v144, 16, v194
	v_and_b32_e32 v145, 0xffff0000, v194
	v_lshlrev_b32_e32 v146, 16, v195
	v_and_b32_e32 v147, 0xffff0000, v195
	v_lshlrev_b32_e32 v148, 16, v196
	v_and_b32_e32 v149, 0xffff0000, v196
	v_lshlrev_b32_e32 v150, 16, v197
	v_and_b32_e32 v151, 0xffff0000, v197
	v_lshlrev_b32_e32 v152, 16, v198
	v_and_b32_e32 v153, 0xffff0000, v198
	v_lshlrev_b32_e32 v154, 16, v199
	v_and_b32_e32 v155, 0xffff0000, v199
	v_lshlrev_b32_e32 v156, 16, v200
	v_and_b32_e32 v157, 0xffff0000, v200
	v_lshlrev_b32_e32 v158, 16, v201
	v_and_b32_e32 v159, 0xffff0000, v201
	s_waitcnt vmcnt(8)
	v_pk_add_f32 v[160:161], v[160:161], v[0:1]
	v_pk_add_f32 v[162:163], v[162:163], v[2:3]
	v_pk_add_f32 v[164:165], v[164:165], v[4:5]
	v_pk_add_f32 v[166:167], v[166:167], v[6:7]
	v_pk_add_f32 v[168:169], v[168:169], v[8:9]
	v_pk_add_f32 v[170:171], v[170:171], v[10:11]
	v_pk_add_f32 v[172:173], v[172:173], v[12:13]
	v_pk_add_f32 v[174:175], v[174:175], v[14:15]
	s_waitcnt vmcnt(4)
	v_pk_add_f32 v[160:161], v[160:161], v[16:17]
	v_pk_add_f32 v[162:163], v[162:163], v[18:19]
	v_pk_add_f32 v[164:165], v[164:165], v[20:21]
	v_pk_add_f32 v[166:167], v[166:167], v[22:23]
	v_pk_add_f32 v[168:169], v[168:169], v[24:25]
	v_pk_add_f32 v[170:171], v[170:171], v[26:27]
	v_pk_add_f32 v[172:173], v[172:173], v[28:29]
	v_pk_add_f32 v[174:175], v[174:175], v[30:31]
	s_waitcnt vmcnt(0)
	v_pk_add_f32 v[160:161], v[160:161], v[32:33]
	v_pk_add_f32 v[162:163], v[162:163], v[34:35]
	v_pk_add_f32 v[164:165], v[164:165], v[36:37]
	v_pk_add_f32 v[166:167], v[166:167], v[38:39]
	v_pk_add_f32 v[168:169], v[168:169], v[40:41]
	v_pk_add_f32 v[170:171], v[170:171], v[42:43]
	v_pk_add_f32 v[172:173], v[172:173], v[44:45]
	v_pk_add_f32 v[174:175], v[174:175], v[46:47]
	v_pk_mul_f32 v[252:253], v[160:161], v[160:161]
	v_pk_mul_f32 v[254:255], v[162:163], v[162:163]
	v_pk_fma_f32 v[252:253], v[164:165], v[164:165], v[252:253]
	v_pk_fma_f32 v[254:255], v[166:167], v[166:167], v[254:255]
	v_pk_fma_f32 v[252:253], v[168:169], v[168:169], v[252:253]
	v_pk_fma_f32 v[254:255], v[170:171], v[170:171], v[254:255]
	v_pk_fma_f32 v[252:253], v[172:173], v[172:173], v[252:253]
	v_pk_fma_f32 v[254:255], v[174:175], v[174:175], v[254:255]
	v_pk_add_f32 v[252:253], v[252:253], v[254:255]
	s_nop 0
	v_add_f32_e32 v183, v252, v253
	s_nop 1
	v_add_f32_dpp v183, v183, v183 quad_perm:[1,0,3,2] row_mask:0xf bank_mask:0xf bound_ctrl:1
	s_nop 1
	v_add_f32_dpp v183, v183, v183 quad_perm:[2,3,0,1] row_mask:0xf bank_mask:0xf bound_ctrl:1
	s_nop 1
	v_add_f32_dpp v183, v183, v183 row_half_mirror row_mask:0xf bank_mask:0xf bound_ctrl:1
	s_nop 1
	v_add_f32_dpp v183, v183, v183 row_mirror row_mask:0xf bank_mask:0xf bound_ctrl:1
	s_nop 1
	v_readlane_b32 s98, v183, 0
	v_readlane_b32 s99, v183, 16
	v_readlane_b32 s100, v183, 32
	v_readlane_b32 s101, v183, 48
	s_nop 1
	v_mov_b32_e32 v183, s98
	v_add_f32_e32 v183, s99, v183
	v_add_f32_e32 v183, s100, v183
	v_add_f32_e32 v183, s101, v183
	v_fmamk_f32 v183, v183, 0x3a800000, v182
	v_cmp_gt_f32_e32 vcc, 0x800000, v183
	v_mul_f32_e32 v181, 0x4b800000, v183
	s_nop 1
	v_cndmask_b32_e32 v183, v183, v181, vcc
	v_rsq_f32_e32 v183, v183
	s_nop 0
	v_mul_f32_e32 v181, 0x45800000, v183
	v_cndmask_b32_e32 v184, v183, v181, vcc
	v_mov_b32_e32 v185, v184
	v_pk_mul_f32 v[160:161], v[160:161], v[184:185]
	v_pk_mul_f32 v[162:163], v[162:163], v[184:185]
	v_pk_mul_f32 v[164:165], v[164:165], v[184:185]
	v_pk_mul_f32 v[166:167], v[166:167], v[184:185]
	v_pk_mul_f32 v[168:169], v[168:169], v[184:185]
	v_pk_mul_f32 v[170:171], v[170:171], v[184:185]
	v_pk_mul_f32 v[172:173], v[172:173], v[184:185]
	v_pk_mul_f32 v[174:175], v[174:175], v[184:185]
	v_pk_fma_f32 v[144:145], v[160:161], v[128:129], v[144:145]
	v_pk_fma_f32 v[146:147], v[162:163], v[130:131], v[146:147]
	v_pk_fma_f32 v[148:149], v[164:165], v[132:133], v[148:149]
	v_pk_fma_f32 v[150:151], v[166:167], v[134:135], v[150:151]
	v_pk_fma_f32 v[152:153], v[168:169], v[136:137], v[152:153]
	v_pk_fma_f32 v[154:155], v[170:171], v[138:139], v[154:155]
	v_pk_fma_f32 v[156:157], v[172:173], v[140:141], v[156:157]
	v_pk_fma_f32 v[158:159], v[174:175], v[142:143], v[158:159]
	v_pk_mul_f32 v[252:253], v[144:145], v[144:145]
	v_pk_mul_f32 v[254:255], v[146:147], v[146:147]
	v_pk_fma_f32 v[252:253], v[148:149], v[148:149], v[252:253]
	v_pk_fma_f32 v[254:255], v[150:151], v[150:151], v[254:255]
	v_pk_fma_f32 v[252:253], v[152:153], v[152:153], v[252:253]
	v_pk_fma_f32 v[254:255], v[154:155], v[154:155], v[254:255]
	v_pk_fma_f32 v[252:253], v[156:157], v[156:157], v[252:253]
	v_pk_fma_f32 v[254:255], v[158:159], v[158:159], v[254:255]
	v_pk_add_f32 v[252:253], v[252:253], v[254:255]
	s_nop 0
	v_add_f32_e32 v183, v252, v253
	s_nop 1
	v_add_f32_dpp v183, v183, v183 quad_perm:[1,0,3,2] row_mask:0xf bank_mask:0xf bound_ctrl:1
	s_nop 1
	v_add_f32_dpp v183, v183, v183 quad_perm:[2,3,0,1] row_mask:0xf bank_mask:0xf bound_ctrl:1
	s_nop 1
	v_add_f32_dpp v183, v183, v183 row_half_mirror row_mask:0xf bank_mask:0xf bound_ctrl:1
	s_nop 1
	v_add_f32_dpp v183, v183, v183 row_mirror row_mask:0xf bank_mask:0xf bound_ctrl:1
	s_nop 1
	v_readlane_b32 s98, v183, 0
	v_readlane_b32 s99, v183, 16
	v_readlane_b32 s100, v183, 32
	v_readlane_b32 s101, v183, 48
	s_nop 1
	v_mov_b32_e32 v183, s98
	v_add_f32_e32 v183, s99, v183
	v_add_f32_e32 v183, s100, v183
	v_add_f32_e32 v183, s101, v183
	v_fmamk_f32 v183, v183, 0x3a800000, v182
	v_cmp_gt_f32_e32 vcc, 0x800000, v183
	v_mul_f32_e32 v181, 0x4b800000, v183
	s_nop 1
	v_cndmask_b32_e32 v183, v183, v181, vcc
	v_rsq_f32_e32 v183, v183
	s_nop 0
	v_mul_f32_e32 v181, 0x45800000, v183
	v_cndmask_b32_e32 v184, v183, v181, vcc
	v_mov_b32_e32 v185, v184
	v_pk_mul_f32 v[144:145], v[144:145], v[184:185]
	v_pk_mul_f32 v[146:147], v[146:147], v[184:185]
	v_pk_mul_f32 v[148:149], v[148:149], v[184:185]
	v_pk_mul_f32 v[150:151], v[150:151], v[184:185]
	v_pk_mul_f32 v[152:153], v[152:153], v[184:185]
	v_pk_mul_f32 v[154:155], v[154:155], v[184:185]
	v_pk_mul_f32 v[156:157], v[156:157], v[184:185]
	v_pk_mul_f32 v[158:159], v[158:159], v[184:185]
	v_pk_mul_f32 v[144:145], v[144:145], v[236:237]
	v_pk_mul_f32 v[146:147], v[146:147], v[238:239]
	v_pk_mul_f32 v[148:149], v[148:149], v[240:241]
	v_pk_mul_f32 v[150:151], v[150:151], v[242:243]
	v_pk_mul_f32 v[152:153], v[152:153], v[244:245]
	v_pk_mul_f32 v[154:155], v[154:155], v[246:247]
	v_pk_mul_f32 v[156:157], v[156:157], v[248:249]
	v_pk_mul_f32 v[158:159], v[158:159], v[250:251]
	v_add_u32_e32 v181, 0x4000000, v178
	global_store_dwordx4 v181, v[144:147], s[76:77]
	global_store_dwordx4 v181, v[148:151], s[76:77] offset:16
	global_store_dwordx4 v181, v[152:155], s[76:77] offset:2048
	global_store_dwordx4 v181, v[156:159], s[76:77] offset:2064
	s_nop 1
